# GEMM MFMA clusters in snake order (one source operand changes per MFMA)
# speedup vs baseline: 1.0051x; 1.0051x over previous
; #define PG8_STAGE(bufoff, gbase, voff) do { _Pragma("unroll") for (int _i = 0; _i < 2; ++_i) \
;         __builtin_amdgcn_global_load_lds((const unsigned*)((const char*)(gbase) + (voff)[_i]), (LAS unsigned*)(lds + (bufoff) + ldsw + _i * 8192), 16, 0, 0); } while (0)
; #define PG8_LDA(dst, b, h) do { _Pragma("unroll") for (int m = 0; m < 4; ++m) _Pragma("unroll") for (int k = 0; k < 2; ++k) dst[m][k] = *(const LAS bf16x8*)(lds + PG8_SA(b, h) + aoff + m * 2048 + k * 1024); } while (0)
; #define PG8_LDB(dst, b, h) do { _Pragma("unroll") for (int n = 0; n < 2; ++n) _Pragma("unroll") for (int k = 0; k < 2; ++k) dst[n][k] = *(const LAS bf16x8*)(lds + PG8_SB(b, h) + boff + n * 2048 + k * 1024); } while (0)
; #define PG8_MMA(ai, bj, At, Bt) do { __builtin_amdgcn_s_setprio(1); _Pragma("unroll") for (int m = 0; m < 4; ++m) _Pragma("unroll") for (int n = 0; n < 2; ++n) _Pragma("unroll") for (int k = 0; k < 2; ++k) \
;         acc[ai][bj][m][n] = __builtin_amdgcn_mfma_f32_16x16x32_bf16(Bt[n][k], At[m][k], acc[ai][bj][m][n], 0, 0, 0); __builtin_amdgcn_s_setprio(0); } while (0)
; #define PG8_WAIT_V(n) asm volatile("s_waitcnt vmcnt(" #n ")" ::: "memory")
; #define PG8_WAIT_L(n) asm volatile("s_waitcnt lgkmcnt(" #n ")" ::: "memory")
; #define PG8_BAR __builtin_amdgcn_s_barrier()
; #define PG8_SCHED __builtin_amdgcn_sched_barrier(0)
; template <class Epi>
; __device__ __forceinline__ void gemm_phase(LAS unsigned char* lds, const Gemm g, int G, int c, const Epi& E) {
;     ...
;             const char* a1 = cA + (size_t)(t + 1) * kstep;
;             const char* a2 = last ? nA : cA + (size_t)(t + 2) * kstep; const char* b2 = last ? nB : cB + (size_t)(t + 2) * kstep;
;             const char* a3 = a2 + kstep; const char* b3 = b2 + kstep;
;             PG8_LDB(B0, 0, 0); PG8_LDB(B1, 0, 1); PG8_SCHED; PG8_LDA(At, 0, 0); PG8_STAGE(PG8_SA(1, 1), a1 + hstepA, voffA);
;             PG8_WAIT_V(8); PG8_WAIT_L(0); PG8_BAR; PG8_MMA(0, 0, At, B0); PG8_MMA(0, 1, At, B1); PG8_BAR; PG8_SCHED;
;             PG8_LDA(At, 0, 1); PG8_STAGE(PG8_SB(0, 0), b2, voffB); PG8_STAGE(PG8_SB(0, 1), b2 + hstepB, voffB); PG8_STAGE(PG8_SA(0, 0), a2, voffA);
;             PG8_WAIT_V(8); PG8_WAIT_L(0); PG8_BAR; PG8_MMA(1, 0, At, B0); PG8_MMA(1, 1, At, B1); PG8_BAR; PG8_SCHED;
.LBB0_236:
	ds_read_b128 v[146:149], v152
	ds_read_b128 v[158:161], v152 offset:1024
	ds_read_b128 v[162:165], v152 offset:2048
	ds_read_b128 v[166:169], v152 offset:3072
	ds_read_b128 v[170:173], v153
	ds_read_b128 v[174:177], v153 offset:1024
	ds_read_b128 v[178:181], v153 offset:2048
	ds_read_b128 v[182:185], v153 offset:3072
	s_add_u32 s33, s4, 0xfffc0080
	s_addc_u32 s54, s5, -1
	s_cmp_eq_u32 s85, 12
	s_cselect_b32 s57, s47, s54
	s_cselect_b32 s56, s46, s33
	s_cselect_b32 s55, s7, s84
	s_cselect_b32 s54, s43, s45
	v_lshl_add_u64 v[218:219], s[4:5], 0, v[138:139]
	s_add_i32 m0, s11, 0xc000
	ds_read_b128 v[186:189], v154
	ds_read_b128 v[190:193], v154 offset:1024
	ds_read_b128 v[194:197], v154 offset:2048
	ds_read_b128 v[198:201], v154 offset:3072
	ds_read_b128 v[202:205], v154 offset:4096
	ds_read_b128 v[206:209], v154 offset:5120
	ds_read_b128 v[210:213], v154 offset:6144
	ds_read_b128 v[214:217], v154 offset:7168
	global_load_lds_dwordx4 v[218:219], off
	v_lshl_add_u64 v[218:219], s[4:5], 0, v[140:141]
	s_add_i32 m0, s11, 0xe000
	s_nop 0
	global_load_lds_dwordx4 v[218:219], off
	s_waitcnt vmcnt(8)
	s_waitcnt lgkmcnt(0)
	s_barrier
	s_setprio 1
	s_waitcnt lgkmcnt(0)
	v_mfma_f32_16x16x32_bf16 v[126:129], v[146:149], v[186:189], v[126:129]
	v_mfma_f32_16x16x32_bf16 v[122:125], v[162:165], v[186:189], v[122:125]
	v_mfma_f32_16x16x32_bf16 v[106:109], v[162:165], v[194:197], v[106:109]
	v_mfma_f32_16x16x32_bf16 v[110:113], v[146:149], v[194:197], v[110:113]
	v_mfma_f32_16x16x32_bf16 v[94:97], v[146:149], v[202:205], v[94:97]
	v_mfma_f32_16x16x32_bf16 v[90:93], v[162:165], v[202:205], v[90:93]
	v_mfma_f32_16x16x32_bf16 v[74:77], v[162:165], v[210:213], v[74:77]
	v_mfma_f32_16x16x32_bf16 v[78:81], v[146:149], v[210:213], v[78:81]
	v_mfma_f32_16x16x32_bf16 v[126:129], v[158:161], v[190:193], v[126:129]
	v_mfma_f32_16x16x32_bf16 v[122:125], v[166:169], v[190:193], v[122:125]
	v_mfma_f32_16x16x32_bf16 v[106:109], v[166:169], v[198:201], v[106:109]
	v_mfma_f32_16x16x32_bf16 v[110:113], v[158:161], v[198:201], v[110:113]
	v_mfma_f32_16x16x32_bf16 v[94:97], v[158:161], v[206:209], v[94:97]
	v_mfma_f32_16x16x32_bf16 v[90:93], v[166:169], v[206:209], v[90:93]
	v_mfma_f32_16x16x32_bf16 v[74:77], v[166:169], v[214:217], v[74:77]
	v_mfma_f32_16x16x32_bf16 v[78:81], v[158:161], v[214:217], v[78:81]
	s_setprio 0
	s_setprio 1
	v_mfma_f32_16x16x32_bf16 v[118:121], v[170:173], v[186:189], v[118:121]
	v_mfma_f32_16x16x32_bf16 v[114:117], v[178:181], v[186:189], v[114:117]
	v_mfma_f32_16x16x32_bf16 v[98:101], v[178:181], v[194:197], v[98:101]
	v_mfma_f32_16x16x32_bf16 v[102:105], v[170:173], v[194:197], v[102:105]
	v_mfma_f32_16x16x32_bf16 v[86:89], v[170:173], v[202:205], v[86:89]
	v_mfma_f32_16x16x32_bf16 v[82:85], v[178:181], v[202:205], v[82:85]
	v_mfma_f32_16x16x32_bf16 v[66:69], v[178:181], v[210:213], v[66:69]
	v_mfma_f32_16x16x32_bf16 v[70:73], v[170:173], v[210:213], v[70:73]
	v_mfma_f32_16x16x32_bf16 v[118:121], v[174:177], v[190:193], v[118:121]
	v_mfma_f32_16x16x32_bf16 v[114:117], v[182:185], v[190:193], v[114:117]
	v_mfma_f32_16x16x32_bf16 v[98:101], v[182:185], v[198:201], v[98:101]
	v_mfma_f32_16x16x32_bf16 v[102:105], v[174:177], v[198:201], v[102:105]
	v_mfma_f32_16x16x32_bf16 v[86:89], v[174:177], v[206:209], v[86:89]
	v_mfma_f32_16x16x32_bf16 v[82:85], v[182:185], v[206:209], v[82:85]
	v_mfma_f32_16x16x32_bf16 v[66:69], v[182:185], v[214:217], v[66:69]
	v_mfma_f32_16x16x32_bf16 v[70:73], v[174:177], v[214:217], v[70:73]
	s_setprio 0
	s_barrier
	s_add_i32 s33, s79, s60
	v_lshl_add_u64 v[218:219], s[54:55], 0, v[132:133]
	s_mov_b32 m0, s33
	ds_read_b128 v[186:189], v154 offset:16384
	ds_read_b128 v[190:193], v154 offset:17408
	ds_read_b128 v[194:197], v154 offset:18432
	ds_read_b128 v[198:201], v154 offset:19456
	ds_read_b128 v[202:205], v154 offset:20480
	ds_read_b128 v[206:209], v154 offset:21504
	ds_read_b128 v[210:213], v154 offset:22528
	ds_read_b128 v[214:217], v154 offset:23552
	global_load_lds_dwordx4 v[218:219], off
	s_add_i32 m0, s33, 0x2000
	s_add_u32 s62, s54, 0x40000
	v_lshl_add_u64 v[220:221], s[54:55], 0, v[136:137]
	s_addc_u32 s63, s55, 0
	s_add_i32 s33, s80, s60
	global_load_lds_dwordx4 v[220:221], off
	v_lshl_add_u64 v[222:223], s[62:63], 0, v[132:133]
	s_mov_b32 m0, s33
	v_lshl_add_u64 v[224:225], s[56:57], 0, v[134:135]
	global_load_lds_dwordx4 v[222:223], off
	v_lshl_add_u64 v[222:223], s[62:63], 0, v[136:137]
	s_add_i32 m0, s33, 0x2000
	s_nop 0
	global_load_lds_dwordx4 v[222:223], off
	v_lshl_add_u64 v[222:223], s[56:57], 0, v[130:131]
	s_mov_b32 m0, s11
	s_nop 0
	global_load_lds_dwordx4 v[222:223], off
	s_mov_b32 m0, s61
	s_nop 0
	global_load_lds_dwordx4 v[224:225], off
	s_waitcnt vmcnt(8)
	s_waitcnt lgkmcnt(0)
	s_barrier
; #define PG8_STAGE(bufoff, gbase, voff) do { _Pragma("unroll") for (int _i = 0; _i < 2; ++_i) \
;         __builtin_amdgcn_global_load_lds((const unsigned*)((const char*)(gbase) + (voff)[_i]), (LAS unsigned*)(lds + (bufoff) + ldsw + _i * 8192), 16, 0, 0); } while (0)
; #define PG8_LDA(dst, b, h) do { _Pragma("unroll") for (int m = 0; m < 4; ++m) _Pragma("unroll") for (int k = 0; k < 2; ++k) dst[m][k] = *(const LAS bf16x8*)(lds + PG8_SA(b, h) + aoff + m * 2048 + k * 1024); } while (0)
; #define PG8_LDB(dst, b, h) do { _Pragma("unroll") for (int n = 0; n < 2; ++n) _Pragma("unroll") for (int k = 0; k < 2; ++k) dst[n][k] = *(const LAS bf16x8*)(lds + PG8_SB(b, h) + boff + n * 2048 + k * 1024); } while (0)
; #define PG8_MMA(ai, bj, At, Bt) do { __builtin_amdgcn_s_setprio(1); _Pragma("unroll") for (int m = 0; m < 4; ++m) _Pragma("unroll") for (int n = 0; n < 2; ++n) _Pragma("unroll") for (int k = 0; k < 2; ++k) \
;         acc[ai][bj][m][n] = __builtin_amdgcn_mfma_f32_16x16x32_bf16(Bt[n][k], At[m][k], acc[ai][bj][m][n], 0, 0, 0); __builtin_amdgcn_s_setprio(0); } while (0)
; #define PG8_WAIT_V(n) asm volatile("s_waitcnt vmcnt(" #n ")" ::: "memory")
; #define PG8_WAIT_L(n) asm volatile("s_waitcnt lgkmcnt(" #n ")" ::: "memory")
; #define PG8_BAR __builtin_amdgcn_s_barrier()
; #define PG8_SCHED __builtin_amdgcn_sched_barrier(0)
; template <class Epi>
; __device__ __forceinline__ void gemm_phase(LAS unsigned char* lds, const Gemm g, int G, int c, const Epi& E) {
;     ...
;             PG8_WAIT_V(8); PG8_WAIT_L(0); PG8_BAR; PG8_MMA(1, 0, At, B0); PG8_MMA(1, 1, At, B1); PG8_BAR; PG8_SCHED;
;             PG8_LDB(B0, 1, 0); PG8_LDB(B1, 1, 1); PG8_SCHED; PG8_LDA(At, 1, 0); PG8_STAGE(PG8_SA(0, 1), a2 + hstepA, voffA);
;             PG8_WAIT_V(8); PG8_WAIT_L(0); PG8_BAR; PG8_MMA(0, 0, At, B0); PG8_MMA(0, 1, At, B1); PG8_BAR; PG8_SCHED;
	s_setprio 1
	s_waitcnt lgkmcnt(0)
	v_mfma_f32_16x16x32_bf16 v[62:65], v[146:149], v[186:189], v[62:65]
	v_mfma_f32_16x16x32_bf16 v[58:61], v[162:165], v[186:189], v[58:61]
	v_mfma_f32_16x16x32_bf16 v[42:45], v[162:165], v[194:197], v[42:45]
	v_mfma_f32_16x16x32_bf16 v[46:49], v[146:149], v[194:197], v[46:49]
	v_mfma_f32_16x16x32_bf16 v[30:33], v[146:149], v[202:205], v[30:33]
	v_mfma_f32_16x16x32_bf16 v[26:29], v[162:165], v[202:205], v[26:29]
	v_mfma_f32_16x16x32_bf16 v[10:13], v[162:165], v[210:213], v[10:13]
	v_mfma_f32_16x16x32_bf16 v[14:17], v[146:149], v[210:213], v[14:17]
	v_mfma_f32_16x16x32_bf16 v[62:65], v[158:161], v[190:193], v[62:65]
	v_mfma_f32_16x16x32_bf16 v[58:61], v[166:169], v[190:193], v[58:61]
	v_mfma_f32_16x16x32_bf16 v[42:45], v[166:169], v[198:201], v[42:45]
	v_mfma_f32_16x16x32_bf16 v[46:49], v[158:161], v[198:201], v[46:49]
	v_mfma_f32_16x16x32_bf16 v[30:33], v[158:161], v[206:209], v[30:33]
	v_mfma_f32_16x16x32_bf16 v[26:29], v[166:169], v[206:209], v[26:29]
	v_mfma_f32_16x16x32_bf16 v[10:13], v[166:169], v[214:217], v[10:13]
	v_mfma_f32_16x16x32_bf16 v[14:17], v[158:161], v[214:217], v[14:17]
	s_setprio 0
	s_setprio 1
	v_mfma_f32_16x16x32_bf16 v[54:57], v[170:173], v[186:189], v[54:57]
	v_mfma_f32_16x16x32_bf16 v[50:53], v[178:181], v[186:189], v[50:53]
	v_mfma_f32_16x16x32_bf16 v[34:37], v[178:181], v[194:197], v[34:37]
	v_mfma_f32_16x16x32_bf16 v[38:41], v[170:173], v[194:197], v[38:41]
	v_mfma_f32_16x16x32_bf16 v[22:25], v[170:173], v[202:205], v[22:25]
	v_mfma_f32_16x16x32_bf16 v[18:21], v[178:181], v[202:205], v[18:21]
	v_mfma_f32_16x16x32_bf16 v[2:5], v[178:181], v[210:213], v[2:5]
	v_mfma_f32_16x16x32_bf16 v[6:9], v[170:173], v[210:213], v[6:9]
	v_mfma_f32_16x16x32_bf16 v[54:57], v[174:177], v[190:193], v[54:57]
	v_mfma_f32_16x16x32_bf16 v[50:53], v[182:185], v[190:193], v[50:53]
	v_mfma_f32_16x16x32_bf16 v[34:37], v[182:185], v[198:201], v[34:37]
	v_mfma_f32_16x16x32_bf16 v[38:41], v[174:177], v[198:201], v[38:41]
	v_mfma_f32_16x16x32_bf16 v[22:25], v[174:177], v[206:209], v[22:25]
	v_mfma_f32_16x16x32_bf16 v[18:21], v[182:185], v[206:209], v[18:21]
	v_mfma_f32_16x16x32_bf16 v[2:5], v[182:185], v[214:217], v[2:5]
	v_mfma_f32_16x16x32_bf16 v[6:9], v[174:177], v[214:217], v[6:9]
	s_setprio 0
	s_barrier
	s_add_i32 s33, 0, 0x18000
	v_add_u32_e32 v157, s33, v151
	s_add_i32 s62, 0, 0x1c000
	ds_read_b128 v[146:149], v157
	ds_read_b128 v[158:161], v157 offset:1024
	ds_read_b128 v[162:165], v157 offset:2048
	ds_read_b128 v[166:169], v157 offset:3072
	v_add_u32_e32 v157, s62, v151
	ds_read_b128 v[170:173], v157
	ds_read_b128 v[174:177], v157 offset:1024
	ds_read_b128 v[178:181], v157 offset:2048
	ds_read_b128 v[182:185], v157 offset:3072
	s_add_u32 s56, s56, 0x40000
	s_addc_u32 s57, s57, 0
	s_mov_b32 m0, s66
	v_lshl_add_u64 v[226:227], s[56:57], 0, v[130:131]
	ds_read_b128 v[186:189], v154 offset:32768
	ds_read_b128 v[190:193], v154 offset:33792
	ds_read_b128 v[194:197], v154 offset:34816
	ds_read_b128 v[198:201], v154 offset:35840
	ds_read_b128 v[202:205], v154 offset:36864
	ds_read_b128 v[206:209], v154 offset:37888
	ds_read_b128 v[210:213], v154 offset:38912
	ds_read_b128 v[214:217], v154 offset:39936
	global_load_lds_dwordx4 v[226:227], off
	v_lshl_add_u64 v[226:227], s[56:57], 0, v[134:135]
	s_mov_b32 m0, s67
	s_nop 0
	global_load_lds_dwordx4 v[226:227], off
	s_waitcnt vmcnt(8)
	s_waitcnt lgkmcnt(0)
	s_barrier
	s_setprio 1
	s_waitcnt lgkmcnt(0)
	v_mfma_f32_16x16x32_bf16 v[126:129], v[146:149], v[186:189], v[126:129]
	v_mfma_f32_16x16x32_bf16 v[122:125], v[162:165], v[186:189], v[122:125]
	v_mfma_f32_16x16x32_bf16 v[106:109], v[162:165], v[194:197], v[106:109]
	v_mfma_f32_16x16x32_bf16 v[110:113], v[146:149], v[194:197], v[110:113]
	v_mfma_f32_16x16x32_bf16 v[94:97], v[146:149], v[202:205], v[94:97]
	v_mfma_f32_16x16x32_bf16 v[90:93], v[162:165], v[202:205], v[90:93]
	v_mfma_f32_16x16x32_bf16 v[74:77], v[162:165], v[210:213], v[74:77]
	v_mfma_f32_16x16x32_bf16 v[78:81], v[146:149], v[210:213], v[78:81]
	v_mfma_f32_16x16x32_bf16 v[126:129], v[158:161], v[190:193], v[126:129]
	v_mfma_f32_16x16x32_bf16 v[122:125], v[166:169], v[190:193], v[122:125]
	v_mfma_f32_16x16x32_bf16 v[106:109], v[166:169], v[198:201], v[106:109]
	v_mfma_f32_16x16x32_bf16 v[110:113], v[158:161], v[198:201], v[110:113]
	v_mfma_f32_16x16x32_bf16 v[94:97], v[158:161], v[206:209], v[94:97]
	v_mfma_f32_16x16x32_bf16 v[90:93], v[166:169], v[206:209], v[90:93]
	v_mfma_f32_16x16x32_bf16 v[74:77], v[166:169], v[214:217], v[74:77]
	v_mfma_f32_16x16x32_bf16 v[78:81], v[158:161], v[214:217], v[78:81]
	s_setprio 0
	s_setprio 1
	v_mfma_f32_16x16x32_bf16 v[118:121], v[170:173], v[186:189], v[118:121]
	v_mfma_f32_16x16x32_bf16 v[114:117], v[178:181], v[186:189], v[114:117]
	v_mfma_f32_16x16x32_bf16 v[98:101], v[178:181], v[194:197], v[98:101]
	v_mfma_f32_16x16x32_bf16 v[102:105], v[170:173], v[194:197], v[102:105]
	v_mfma_f32_16x16x32_bf16 v[86:89], v[170:173], v[202:205], v[86:89]
	v_mfma_f32_16x16x32_bf16 v[82:85], v[178:181], v[202:205], v[82:85]
	v_mfma_f32_16x16x32_bf16 v[66:69], v[178:181], v[210:213], v[66:69]
	v_mfma_f32_16x16x32_bf16 v[70:73], v[170:173], v[210:213], v[70:73]
	v_mfma_f32_16x16x32_bf16 v[118:121], v[174:177], v[190:193], v[118:121]
	v_mfma_f32_16x16x32_bf16 v[114:117], v[182:185], v[190:193], v[114:117]
	v_mfma_f32_16x16x32_bf16 v[98:101], v[182:185], v[198:201], v[98:101]
	v_mfma_f32_16x16x32_bf16 v[102:105], v[174:177], v[198:201], v[102:105]
	v_mfma_f32_16x16x32_bf16 v[86:89], v[174:177], v[206:209], v[86:89]
	v_mfma_f32_16x16x32_bf16 v[82:85], v[182:185], v[206:209], v[82:85]
	v_mfma_f32_16x16x32_bf16 v[66:69], v[182:185], v[214:217], v[66:69]
	v_mfma_f32_16x16x32_bf16 v[70:73], v[174:177], v[214:217], v[70:73]
	s_setprio 0
	s_barrier
; #define PG8_STAGE(bufoff, gbase, voff) do { _Pragma("unroll") for (int _i = 0; _i < 2; ++_i) \
;         __builtin_amdgcn_global_load_lds((const unsigned*)((const char*)(gbase) + (voff)[_i]), (LAS unsigned*)(lds + (bufoff) + ldsw + _i * 8192), 16, 0, 0); } while (0)
; #define PG8_LDA(dst, b, h) do { _Pragma("unroll") for (int m = 0; m < 4; ++m) _Pragma("unroll") for (int k = 0; k < 2; ++k) dst[m][k] = *(const LAS bf16x8*)(lds + PG8_SA(b, h) + aoff + m * 2048 + k * 1024); } while (0)
; #define PG8_MMA(ai, bj, At, Bt) do { __builtin_amdgcn_s_setprio(1); _Pragma("unroll") for (int m = 0; m < 4; ++m) _Pragma("unroll") for (int n = 0; n < 2; ++n) _Pragma("unroll") for (int k = 0; k < 2; ++k) \
;         acc[ai][bj][m][n] = __builtin_amdgcn_mfma_f32_16x16x32_bf16(Bt[n][k], At[m][k], acc[ai][bj][m][n], 0, 0, 0); __builtin_amdgcn_s_setprio(0); } while (0)
; #define PG8_WAIT_V(n) asm volatile("s_waitcnt vmcnt(" #n ")" ::: "memory")
; #define PG8_WAIT_L(n) asm volatile("s_waitcnt lgkmcnt(" #n ")" ::: "memory")
; #define PG8_BAR __builtin_amdgcn_s_barrier()
; #define PG8_SCHED __builtin_amdgcn_sched_barrier(0)
; template <class Epi>
; __device__ __forceinline__ void gemm_phase(LAS unsigned char* lds, const Gemm g, int G, int c, const Epi& E) {
;     ...
;             PG8_LDA(At, 1, 1); PG8_STAGE(PG8_SB(1, 0), b3, voffB); PG8_STAGE(PG8_SB(1, 1), b3 + hstepB, voffB); PG8_STAGE(PG8_SA(1, 0), a3, voffA);
;             PG8_WAIT_V(8); PG8_WAIT_L(0); PG8_BAR; PG8_MMA(1, 0, At, B0); PG8_MMA(1, 1, At, B1); PG8_BAR; PG8_SCHED;
;         }
;         if (wr == 0) PG8_BAR;
	s_add_i32 s33, s33, s60
	v_lshl_add_u64 v[218:219], v[218:219], 0, s[20:21]
	s_mov_b32 m0, s33
	ds_read_b128 v[186:189], v154 offset:49152
	ds_read_b128 v[190:193], v154 offset:50176
	ds_read_b128 v[194:197], v154 offset:51200
	ds_read_b128 v[198:201], v154 offset:52224
	ds_read_b128 v[202:205], v154 offset:53248
	ds_read_b128 v[206:209], v154 offset:54272
	ds_read_b128 v[210:213], v154 offset:55296
	ds_read_b128 v[214:217], v154 offset:56320
	global_load_lds_dwordx4 v[218:219], off
	s_add_i32 m0, s33, 0x2000
	s_add_u32 s54, s54, 0x40080
	v_lshl_add_u64 v[218:219], v[220:221], 0, s[20:21]
	s_addc_u32 s55, s55, 0
	s_add_i32 s33, s62, s60
	global_load_lds_dwordx4 v[218:219], off
	v_lshl_add_u64 v[218:219], s[54:55], 0, v[132:133]
	s_mov_b32 m0, s33
	s_nop 0
	global_load_lds_dwordx4 v[218:219], off
	v_lshl_add_u64 v[218:219], s[54:55], 0, v[136:137]
	s_add_i32 m0, s33, 0x2000
	s_nop 0
	global_load_lds_dwordx4 v[218:219], off
	v_lshl_add_u64 v[218:219], v[222:223], 0, s[20:21]
	s_mov_b32 m0, s71
	s_nop 0
	global_load_lds_dwordx4 v[218:219], off
	v_lshl_add_u64 v[218:219], v[224:225], 0, s[20:21]
	s_mov_b32 m0, s72
	s_nop 0
	global_load_lds_dwordx4 v[218:219], off
	s_waitcnt vmcnt(8)
	s_waitcnt lgkmcnt(0)
	s_barrier
	s_setprio 1
	s_waitcnt lgkmcnt(0)
	v_mfma_f32_16x16x32_bf16 v[62:65], v[146:149], v[186:189], v[62:65]
	v_mfma_f32_16x16x32_bf16 v[58:61], v[162:165], v[186:189], v[58:61]
	v_mfma_f32_16x16x32_bf16 v[42:45], v[162:165], v[194:197], v[42:45]
	v_mfma_f32_16x16x32_bf16 v[46:49], v[146:149], v[194:197], v[46:49]
	v_mfma_f32_16x16x32_bf16 v[30:33], v[146:149], v[202:205], v[30:33]
	v_mfma_f32_16x16x32_bf16 v[26:29], v[162:165], v[202:205], v[26:29]
	v_mfma_f32_16x16x32_bf16 v[10:13], v[162:165], v[210:213], v[10:13]
	v_mfma_f32_16x16x32_bf16 v[14:17], v[146:149], v[210:213], v[14:17]
	v_mfma_f32_16x16x32_bf16 v[62:65], v[158:161], v[190:193], v[62:65]
	v_mfma_f32_16x16x32_bf16 v[58:61], v[166:169], v[190:193], v[58:61]
	v_mfma_f32_16x16x32_bf16 v[42:45], v[166:169], v[198:201], v[42:45]
	v_mfma_f32_16x16x32_bf16 v[46:49], v[158:161], v[198:201], v[46:49]
	v_mfma_f32_16x16x32_bf16 v[30:33], v[158:161], v[206:209], v[30:33]
	v_mfma_f32_16x16x32_bf16 v[26:29], v[166:169], v[206:209], v[26:29]
	v_mfma_f32_16x16x32_bf16 v[10:13], v[166:169], v[214:217], v[10:13]
	v_mfma_f32_16x16x32_bf16 v[14:17], v[158:161], v[214:217], v[14:17]
	s_setprio 0
	s_setprio 1
	v_mfma_f32_16x16x32_bf16 v[54:57], v[170:173], v[186:189], v[54:57]
	v_mfma_f32_16x16x32_bf16 v[50:53], v[178:181], v[186:189], v[50:53]
	v_mfma_f32_16x16x32_bf16 v[34:37], v[178:181], v[194:197], v[34:37]
	v_mfma_f32_16x16x32_bf16 v[38:41], v[170:173], v[194:197], v[38:41]
	v_mfma_f32_16x16x32_bf16 v[22:25], v[170:173], v[202:205], v[22:25]
	v_mfma_f32_16x16x32_bf16 v[18:21], v[178:181], v[202:205], v[18:21]
	v_mfma_f32_16x16x32_bf16 v[2:5], v[178:181], v[210:213], v[2:5]
	v_mfma_f32_16x16x32_bf16 v[6:9], v[170:173], v[210:213], v[6:9]
	v_mfma_f32_16x16x32_bf16 v[54:57], v[174:177], v[190:193], v[54:57]
	v_mfma_f32_16x16x32_bf16 v[50:53], v[182:185], v[190:193], v[50:53]
	v_mfma_f32_16x16x32_bf16 v[34:37], v[182:185], v[198:201], v[34:37]
	v_mfma_f32_16x16x32_bf16 v[38:41], v[174:177], v[198:201], v[38:41]
	v_mfma_f32_16x16x32_bf16 v[22:25], v[174:177], v[206:209], v[22:25]
	v_mfma_f32_16x16x32_bf16 v[18:21], v[182:185], v[206:209], v[18:21]
	v_mfma_f32_16x16x32_bf16 v[2:5], v[182:185], v[214:217], v[2:5]
	v_mfma_f32_16x16x32_bf16 v[6:9], v[174:177], v[214:217], v[6:9]
	s_setprio 0
	s_barrier
	s_add_i32 s85, s85, 2
	s_add_u32 s4, s4, 0x100
	s_addc_u32 s5, s5, 0
	s_add_u32 s45, s45, 0x100
	s_addc_u32 s84, s84, 0
	s_cmp_gt_u32 s85, 13
	s_cbranch_scc0 .LBB0_236
	s_and_b64 vcc, exec, s[22:23]
	s_cbranch_vccz .LBB0_239
	s_barrier

; #define PG8_STAGE(bufoff, gbase, voff) do { _Pragma("unroll") for (int _i = 0; _i < 2; ++_i) \
;         __builtin_amdgcn_global_load_lds((const unsigned*)((const char*)(gbase) + (voff)[_i]), (LAS unsigned*)(lds + (bufoff) + ldsw + _i * 8192), 16, 0, 0); } while (0)
; #define PG8_LDA(dst, b, h) do { _Pragma("unroll") for (int m = 0; m < 4; ++m) _Pragma("unroll") for (int k = 0; k < 2; ++k) dst[m][k] = *(const LAS bf16x8*)(lds + PG8_SA(b, h) + aoff + m * 2048 + k * 1024); } while (0)
; #define PG8_LDB(dst, b, h) do { _Pragma("unroll") for (int n = 0; n < 2; ++n) _Pragma("unroll") for (int k = 0; k < 2; ++k) dst[n][k] = *(const LAS bf16x8*)(lds + PG8_SB(b, h) + boff + n * 2048 + k * 1024); } while (0)
; #define PG8_MMA(ai, bj, At, Bt) do { __builtin_amdgcn_s_setprio(1); _Pragma("unroll") for (int m = 0; m < 4; ++m) _Pragma("unroll") for (int n = 0; n < 2; ++n) _Pragma("unroll") for (int k = 0; k < 2; ++k) \
;         acc[ai][bj][m][n] = __builtin_amdgcn_mfma_f32_16x16x32_bf16(Bt[n][k], At[m][k], acc[ai][bj][m][n], 0, 0, 0); __builtin_amdgcn_s_setprio(0); } while (0)
; #define PG8_BAR __builtin_amdgcn_s_barrier()
; template <class Epi>
; __device__ __forceinline__ void gemm_phase(LAS unsigned char* lds, const Gemm g, int G, int c, const Epi& E) {
;     ...
;         const char* nA = has_next ? (const char*)(g.A + (size_t)nxt.pb * g.sA) + (size_t)nxt.pm * 2 * hstepA : cA;
;         const char* nB = has_next ? (const char*)(g.Bt + (size_t)nxt.pb * g.sB) + (size_t)nxt.pn * 2 * hstepB : cB;
; #pragma nounroll
;         for (int t = 0; t < nt; t += 2) {
;             const bool last = (t == nt - 2);
;             const char* a1 = cA + (size_t)(t + 1) * kstep;
;             const char* a2 = last ? nA : cA + (size_t)(t + 2) * kstep; const char* b2 = last ? nB : cB + (size_t)(t + 2) * kstep;
;             const char* a3 = a2 + kstep; const char* b3 = b2 + kstep;
;             PG8_LDB(B0, 0, 0); PG8_LDB(B1, 0, 1); PG8_SCHED; PG8_LDA(At, 0, 0); PG8_STAGE(PG8_SA(1, 1), a1 + hstepA, voffA);
;             PG8_WAIT_V(8); PG8_WAIT_L(0); PG8_BAR; PG8_MMA(0, 0, At, B0); PG8_MMA(0, 1, At, B1); PG8_BAR; PG8_SCHED;
;             PG8_LDA(At, 0, 1); PG8_STAGE(PG8_SB(0, 0), b2, voffB); PG8_STAGE(PG8_SB(0, 1), b2 + hstepB, voffB); PG8_STAGE(PG8_SA(0, 0), a2, voffA);
;             PG8_WAIT_V(8); PG8_WAIT_L(0); PG8_BAR; PG8_MMA(1, 0, At, B0); PG8_MMA(1, 1, At, B1); PG8_BAR; PG8_SCHED;
.LBB0_368:
	s_add_u32 s33, s20, s13
	s_addc_u32 s42, s21, 0
	s_add_u32 s43, s33, 0x100
	s_addc_u32 s44, s42, 0
	s_and_b64 s[38:39], s[24:25], exec
	s_cselect_b32 s45, s5, s44
	s_cselect_b32 s44, s4, s43
	s_add_u32 s13, s18, s13
	s_addc_u32 s38, s19, 0
	s_add_u32 s13, s13, 0x100
	s_addc_u32 s38, s38, 0
	s_and_b64 s[24:25], s[24:25], exec
	s_cselect_b32 s47, s17, s38
	s_cselect_b32 s46, s16, s13
	s_add_u32 s54, s33, 0xb0080
	s_addc_u32 s55, s42, 0
	s_add_i32 s65, s81, s56
	ds_read_b128 v[142:145], v148
	ds_read_b128 v[152:155], v148 offset:1024
	ds_read_b128 v[156:159], v148 offset:2048
	ds_read_b128 v[160:163], v148 offset:3072
	ds_read_b128 v[164:167], v149
	ds_read_b128 v[168:171], v149 offset:1024
	ds_read_b128 v[172:175], v149 offset:2048
	ds_read_b128 v[176:179], v149 offset:3072
	s_add_i32 m0, s57, 0xc000
	s_add_i32 s74, s57, 0xe000
	s_add_i32 s62, s65, 0x2000
	s_add_u32 s52, s46, 0xb0000
	s_addc_u32 s53, s47, 0
	s_add_i32 s64, s82, s56
	s_add_i32 s63, s64, 0x2000
	s_add_i32 s73, 0, 0x18000
	s_add_i32 s33, 0, 0x1c000
	s_add_u32 s42, s44, 0xb0000
	s_addc_u32 s43, s45, 0
	s_add_i32 s88, s73, s56
	s_add_i32 s38, s88, 0x2000
	s_add_u32 s24, s46, 0xb0080
	s_addc_u32 s25, s47, 0
	s_add_i32 s39, s33, s56
	s_add_i32 s13, s39, 0x2000
	v_lshl_add_u64 v[212:213], s[54:55], 0, v[136:137]
	ds_read_b128 v[180:183], v150
	ds_read_b128 v[184:187], v150 offset:1024
	ds_read_b128 v[188:191], v150 offset:2048
	ds_read_b128 v[192:195], v150 offset:3072
	ds_read_b128 v[196:199], v150 offset:4096
	ds_read_b128 v[200:203], v150 offset:5120
	ds_read_b128 v[204:207], v150 offset:6144
	ds_read_b128 v[208:211], v150 offset:7168
	global_load_lds_dwordx4 v[212:213], off
	v_lshl_add_u64 v[212:213], s[54:55], 0, v[132:133]
	s_mov_b32 m0, s74
	s_nop 0
	global_load_lds_dwordx4 v[212:213], off
	s_waitcnt vmcnt(8)
	s_waitcnt lgkmcnt(0)
	s_barrier
	s_setprio 1
	s_waitcnt lgkmcnt(0)
	v_mfma_f32_16x16x32_bf16 v[126:129], v[142:145], v[180:183], v[126:129]
	v_mfma_f32_16x16x32_bf16 v[122:125], v[156:159], v[180:183], v[122:125]
	v_mfma_f32_16x16x32_bf16 v[110:113], v[156:159], v[188:191], v[110:113]
	v_mfma_f32_16x16x32_bf16 v[118:121], v[142:145], v[188:191], v[118:121]
	v_mfma_f32_16x16x32_bf16 v[102:105], v[142:145], v[196:199], v[102:105]
	v_mfma_f32_16x16x32_bf16 v[94:97], v[156:159], v[196:199], v[94:97]
	v_mfma_f32_16x16x32_bf16 v[78:81], v[156:159], v[204:207], v[78:81]
	v_mfma_f32_16x16x32_bf16 v[86:89], v[142:145], v[204:207], v[86:89]
	v_mfma_f32_16x16x32_bf16 v[126:129], v[152:155], v[184:187], v[126:129]
	v_mfma_f32_16x16x32_bf16 v[122:125], v[160:163], v[184:187], v[122:125]
	v_mfma_f32_16x16x32_bf16 v[110:113], v[160:163], v[192:195], v[110:113]
	v_mfma_f32_16x16x32_bf16 v[118:121], v[152:155], v[192:195], v[118:121]
	v_mfma_f32_16x16x32_bf16 v[102:105], v[152:155], v[200:203], v[102:105]
	v_mfma_f32_16x16x32_bf16 v[94:97], v[160:163], v[200:203], v[94:97]
	v_mfma_f32_16x16x32_bf16 v[78:81], v[160:163], v[208:211], v[78:81]
	v_mfma_f32_16x16x32_bf16 v[86:89], v[152:155], v[208:211], v[86:89]
	s_setprio 0
	s_setprio 1
	v_mfma_f32_16x16x32_bf16 v[114:117], v[164:167], v[180:183], v[114:117]
	v_mfma_f32_16x16x32_bf16 v[106:109], v[172:175], v[180:183], v[106:109]
	v_mfma_f32_16x16x32_bf16 v[90:93], v[172:175], v[188:191], v[90:93]
	v_mfma_f32_16x16x32_bf16 v[98:101], v[164:167], v[188:191], v[98:101]
	v_mfma_f32_16x16x32_bf16 v[82:85], v[164:167], v[196:199], v[82:85]
	v_mfma_f32_16x16x32_bf16 v[74:77], v[172:175], v[196:199], v[74:77]
	v_mfma_f32_16x16x32_bf16 v[66:69], v[172:175], v[204:207], v[66:69]
	v_mfma_f32_16x16x32_bf16 v[70:73], v[164:167], v[204:207], v[70:73]
	v_mfma_f32_16x16x32_bf16 v[114:117], v[168:171], v[184:187], v[114:117]
	v_mfma_f32_16x16x32_bf16 v[106:109], v[176:179], v[184:187], v[106:109]
	v_mfma_f32_16x16x32_bf16 v[90:93], v[176:179], v[192:195], v[90:93]
	v_mfma_f32_16x16x32_bf16 v[98:101], v[168:171], v[192:195], v[98:101]
	v_mfma_f32_16x16x32_bf16 v[82:85], v[168:171], v[200:203], v[82:85]
	v_mfma_f32_16x16x32_bf16 v[74:77], v[176:179], v[200:203], v[74:77]
	v_mfma_f32_16x16x32_bf16 v[66:69], v[176:179], v[208:211], v[66:69]
	v_mfma_f32_16x16x32_bf16 v[70:73], v[168:171], v[208:211], v[70:73]
	s_setprio 0
	s_barrier
	s_mov_b32 m0, s65
	v_lshl_add_u64 v[212:213], s[46:47], 0, v[134:135]
	ds_read_b128 v[180:183], v150 offset:16384
	ds_read_b128 v[184:187], v150 offset:17408
	ds_read_b128 v[188:191], v150 offset:18432
	ds_read_b128 v[192:195], v150 offset:19456
	ds_read_b128 v[196:199], v150 offset:20480
	ds_read_b128 v[200:203], v150 offset:21504
	ds_read_b128 v[204:207], v150 offset:22528
	ds_read_b128 v[208:211], v150 offset:23552
	global_load_lds_dwordx4 v[212:213], off
	v_lshl_add_u64 v[214:215], s[46:47], 0, v[130:131]
	s_mov_b32 m0, s62
	v_lshl_add_u64 v[216:217], s[52:53], 0, v[134:135]
	global_load_lds_dwordx4 v[214:215], off
	s_mov_b32 m0, s64
	v_lshl_add_u64 v[218:219], s[44:45], 0, v[132:133]
	global_load_lds_dwordx4 v[216:217], off
	v_lshl_add_u64 v[216:217], s[52:53], 0, v[130:131]
	s_mov_b32 m0, s63
	s_nop 0
	global_load_lds_dwordx4 v[216:217], off
	v_lshl_add_u64 v[216:217], s[44:45], 0, v[136:137]
	s_mov_b32 m0, s57
	s_nop 0
	global_load_lds_dwordx4 v[216:217], off
	s_mov_b32 m0, s58
	s_nop 0
	global_load_lds_dwordx4 v[218:219], off
	s_waitcnt vmcnt(8)
	s_waitcnt lgkmcnt(0)
	s_barrier
; #define PG8_STAGE(bufoff, gbase, voff) do { _Pragma("unroll") for (int _i = 0; _i < 2; ++_i) \
;         __builtin_amdgcn_global_load_lds((const unsigned*)((const char*)(gbase) + (voff)[_i]), (LAS unsigned*)(lds + (bufoff) + ldsw + _i * 8192), 16, 0, 0); } while (0)
; #define PG8_LDA(dst, b, h) do { _Pragma("unroll") for (int m = 0; m < 4; ++m) _Pragma("unroll") for (int k = 0; k < 2; ++k) dst[m][k] = *(const LAS bf16x8*)(lds + PG8_SA(b, h) + aoff + m * 2048 + k * 1024); } while (0)
; #define PG8_LDB(dst, b, h) do { _Pragma("unroll") for (int n = 0; n < 2; ++n) _Pragma("unroll") for (int k = 0; k < 2; ++k) dst[n][k] = *(const LAS bf16x8*)(lds + PG8_SB(b, h) + boff + n * 2048 + k * 1024); } while (0)
; #define PG8_MMA(ai, bj, At, Bt) do { __builtin_amdgcn_s_setprio(1); _Pragma("unroll") for (int m = 0; m < 4; ++m) _Pragma("unroll") for (int n = 0; n < 2; ++n) _Pragma("unroll") for (int k = 0; k < 2; ++k) \
;         acc[ai][bj][m][n] = __builtin_amdgcn_mfma_f32_16x16x32_bf16(Bt[n][k], At[m][k], acc[ai][bj][m][n], 0, 0, 0); __builtin_amdgcn_s_setprio(0); } while (0)
; #define PG8_WAIT_V(n) asm volatile("s_waitcnt vmcnt(" #n ")" ::: "memory")
; #define PG8_WAIT_L(n) asm volatile("s_waitcnt lgkmcnt(" #n ")" ::: "memory")
; #define PG8_BAR __builtin_amdgcn_s_barrier()
; #define PG8_SCHED __builtin_amdgcn_sched_barrier(0)
; template <class Epi>
; __device__ __forceinline__ void gemm_phase(LAS unsigned char* lds, const Gemm g, int G, int c, const Epi& E) {
;     ...
;             PG8_WAIT_V(8); PG8_WAIT_L(0); PG8_BAR; PG8_MMA(1, 0, At, B0); PG8_MMA(1, 1, At, B1); PG8_BAR; PG8_SCHED;
;             PG8_LDB(B0, 1, 0); PG8_LDB(B1, 1, 1); PG8_SCHED; PG8_LDA(At, 1, 0); PG8_STAGE(PG8_SA(0, 1), a2 + hstepA, voffA);
;             PG8_WAIT_V(8); PG8_WAIT_L(0); PG8_BAR; PG8_MMA(0, 0, At, B0); PG8_MMA(0, 1, At, B1); PG8_BAR; PG8_SCHED;
	s_setprio 1
	s_waitcnt lgkmcnt(0)
	v_mfma_f32_16x16x32_bf16 v[62:65], v[142:145], v[180:183], v[62:65]
	v_mfma_f32_16x16x32_bf16 v[58:61], v[156:159], v[180:183], v[58:61]
	v_mfma_f32_16x16x32_bf16 v[46:49], v[156:159], v[188:191], v[46:49]
	v_mfma_f32_16x16x32_bf16 v[54:57], v[142:145], v[188:191], v[54:57]
	v_mfma_f32_16x16x32_bf16 v[38:41], v[142:145], v[196:199], v[38:41]
	v_mfma_f32_16x16x32_bf16 v[30:33], v[156:159], v[196:199], v[30:33]
	v_mfma_f32_16x16x32_bf16 v[14:17], v[156:159], v[204:207], v[14:17]
	v_mfma_f32_16x16x32_bf16 v[22:25], v[142:145], v[204:207], v[22:25]
	v_mfma_f32_16x16x32_bf16 v[62:65], v[152:155], v[184:187], v[62:65]
	v_mfma_f32_16x16x32_bf16 v[58:61], v[160:163], v[184:187], v[58:61]
	v_mfma_f32_16x16x32_bf16 v[46:49], v[160:163], v[192:195], v[46:49]
	v_mfma_f32_16x16x32_bf16 v[54:57], v[152:155], v[192:195], v[54:57]
	v_mfma_f32_16x16x32_bf16 v[38:41], v[152:155], v[200:203], v[38:41]
	v_mfma_f32_16x16x32_bf16 v[30:33], v[160:163], v[200:203], v[30:33]
	v_mfma_f32_16x16x32_bf16 v[14:17], v[160:163], v[208:211], v[14:17]
	v_mfma_f32_16x16x32_bf16 v[22:25], v[152:155], v[208:211], v[22:25]
	s_setprio 0
	s_setprio 1
	v_mfma_f32_16x16x32_bf16 v[50:53], v[164:167], v[180:183], v[50:53]
	v_mfma_f32_16x16x32_bf16 v[42:45], v[172:175], v[180:183], v[42:45]
	v_mfma_f32_16x16x32_bf16 v[26:29], v[172:175], v[188:191], v[26:29]
	v_mfma_f32_16x16x32_bf16 v[34:37], v[164:167], v[188:191], v[34:37]
	v_mfma_f32_16x16x32_bf16 v[18:21], v[164:167], v[196:199], v[18:21]
	v_mfma_f32_16x16x32_bf16 v[10:13], v[172:175], v[196:199], v[10:13]
	v_mfma_f32_16x16x32_bf16 v[2:5], v[172:175], v[204:207], v[2:5]
	v_mfma_f32_16x16x32_bf16 v[6:9], v[164:167], v[204:207], v[6:9]
	v_mfma_f32_16x16x32_bf16 v[50:53], v[168:171], v[184:187], v[50:53]
	v_mfma_f32_16x16x32_bf16 v[42:45], v[176:179], v[184:187], v[42:45]
	v_mfma_f32_16x16x32_bf16 v[26:29], v[176:179], v[192:195], v[26:29]
	v_mfma_f32_16x16x32_bf16 v[34:37], v[168:171], v[192:195], v[34:37]
	v_mfma_f32_16x16x32_bf16 v[18:21], v[168:171], v[200:203], v[18:21]
	v_mfma_f32_16x16x32_bf16 v[10:13], v[176:179], v[200:203], v[10:13]
	v_mfma_f32_16x16x32_bf16 v[2:5], v[176:179], v[208:211], v[2:5]
	v_mfma_f32_16x16x32_bf16 v[6:9], v[168:171], v[208:211], v[6:9]
	s_setprio 0
	s_barrier
	v_add_u32_e32 v151, s73, v147
	ds_read_b128 v[142:145], v151
	ds_read_b128 v[152:155], v151 offset:1024
	ds_read_b128 v[156:159], v151 offset:2048
	ds_read_b128 v[160:163], v151 offset:3072
	v_add_u32_e32 v151, s33, v147
	ds_read_b128 v[164:167], v151
	ds_read_b128 v[168:171], v151 offset:1024
	ds_read_b128 v[172:175], v151 offset:2048
	ds_read_b128 v[176:179], v151 offset:3072
	s_mov_b32 m0, s59
	v_lshl_add_u64 v[220:221], s[42:43], 0, v[136:137]
	ds_read_b128 v[180:183], v150 offset:32768
	ds_read_b128 v[184:187], v150 offset:33792
	ds_read_b128 v[188:191], v150 offset:34816
	ds_read_b128 v[192:195], v150 offset:35840
	ds_read_b128 v[196:199], v150 offset:36864
	ds_read_b128 v[200:203], v150 offset:37888
	ds_read_b128 v[204:207], v150 offset:38912
	ds_read_b128 v[208:211], v150 offset:39936
	global_load_lds_dwordx4 v[220:221], off
	v_lshl_add_u64 v[220:221], s[42:43], 0, v[132:133]
	s_mov_b32 m0, s60
	s_nop 0
	global_load_lds_dwordx4 v[220:221], off
	s_waitcnt vmcnt(8)
	s_waitcnt lgkmcnt(0)
	s_barrier
	s_setprio 1
	s_waitcnt lgkmcnt(0)
	v_mfma_f32_16x16x32_bf16 v[126:129], v[142:145], v[180:183], v[126:129]
	v_mfma_f32_16x16x32_bf16 v[122:125], v[156:159], v[180:183], v[122:125]
	v_mfma_f32_16x16x32_bf16 v[110:113], v[156:159], v[188:191], v[110:113]
	v_mfma_f32_16x16x32_bf16 v[118:121], v[142:145], v[188:191], v[118:121]
	v_mfma_f32_16x16x32_bf16 v[102:105], v[142:145], v[196:199], v[102:105]
	v_mfma_f32_16x16x32_bf16 v[94:97], v[156:159], v[196:199], v[94:97]
	v_mfma_f32_16x16x32_bf16 v[78:81], v[156:159], v[204:207], v[78:81]
	v_mfma_f32_16x16x32_bf16 v[86:89], v[142:145], v[204:207], v[86:89]
	v_mfma_f32_16x16x32_bf16 v[126:129], v[152:155], v[184:187], v[126:129]
	v_mfma_f32_16x16x32_bf16 v[122:125], v[160:163], v[184:187], v[122:125]
	v_mfma_f32_16x16x32_bf16 v[110:113], v[160:163], v[192:195], v[110:113]
	v_mfma_f32_16x16x32_bf16 v[118:121], v[152:155], v[192:195], v[118:121]
	v_mfma_f32_16x16x32_bf16 v[102:105], v[152:155], v[200:203], v[102:105]
	v_mfma_f32_16x16x32_bf16 v[94:97], v[160:163], v[200:203], v[94:97]
	v_mfma_f32_16x16x32_bf16 v[78:81], v[160:163], v[208:211], v[78:81]
	v_mfma_f32_16x16x32_bf16 v[86:89], v[152:155], v[208:211], v[86:89]
	s_setprio 0
	s_setprio 1
	v_mfma_f32_16x16x32_bf16 v[114:117], v[164:167], v[180:183], v[114:117]
	v_mfma_f32_16x16x32_bf16 v[106:109], v[172:175], v[180:183], v[106:109]
	v_mfma_f32_16x16x32_bf16 v[90:93], v[172:175], v[188:191], v[90:93]
	v_mfma_f32_16x16x32_bf16 v[98:101], v[164:167], v[188:191], v[98:101]
	v_mfma_f32_16x16x32_bf16 v[82:85], v[164:167], v[196:199], v[82:85]
	v_mfma_f32_16x16x32_bf16 v[74:77], v[172:175], v[196:199], v[74:77]
	v_mfma_f32_16x16x32_bf16 v[66:69], v[172:175], v[204:207], v[66:69]
	v_mfma_f32_16x16x32_bf16 v[70:73], v[164:167], v[204:207], v[70:73]
	v_mfma_f32_16x16x32_bf16 v[114:117], v[168:171], v[184:187], v[114:117]
	v_mfma_f32_16x16x32_bf16 v[106:109], v[176:179], v[184:187], v[106:109]
	v_mfma_f32_16x16x32_bf16 v[90:93], v[176:179], v[192:195], v[90:93]
	v_mfma_f32_16x16x32_bf16 v[98:101], v[168:171], v[192:195], v[98:101]
	v_mfma_f32_16x16x32_bf16 v[82:85], v[168:171], v[200:203], v[82:85]
	v_mfma_f32_16x16x32_bf16 v[74:77], v[176:179], v[200:203], v[74:77]
	v_mfma_f32_16x16x32_bf16 v[66:69], v[176:179], v[208:211], v[66:69]
	v_mfma_f32_16x16x32_bf16 v[70:73], v[168:171], v[208:211], v[70:73]
	s_setprio 0
	s_barrier
; #define PG8_STAGE(bufoff, gbase, voff) do { _Pragma("unroll") for (int _i = 0; _i < 2; ++_i) \
;         __builtin_amdgcn_global_load_lds((const unsigned*)((const char*)(gbase) + (voff)[_i]), (LAS unsigned*)(lds + (bufoff) + ldsw + _i * 8192), 16, 0, 0); } while (0)
; #define PG8_LDA(dst, b, h) do { _Pragma("unroll") for (int m = 0; m < 4; ++m) _Pragma("unroll") for (int k = 0; k < 2; ++k) dst[m][k] = *(const LAS bf16x8*)(lds + PG8_SA(b, h) + aoff + m * 2048 + k * 1024); } while (0)
; #define PG8_MMA(ai, bj, At, Bt) do { __builtin_amdgcn_s_setprio(1); _Pragma("unroll") for (int m = 0; m < 4; ++m) _Pragma("unroll") for (int n = 0; n < 2; ++n) _Pragma("unroll") for (int k = 0; k < 2; ++k) \
;         acc[ai][bj][m][n] = __builtin_amdgcn_mfma_f32_16x16x32_bf16(Bt[n][k], At[m][k], acc[ai][bj][m][n], 0, 0, 0); __builtin_amdgcn_s_setprio(0); } while (0)
; #define PG8_WAIT_V(n) asm volatile("s_waitcnt vmcnt(" #n ")" ::: "memory")
; #define PG8_WAIT_L(n) asm volatile("s_waitcnt lgkmcnt(" #n ")" ::: "memory")
; #define PG8_BAR __builtin_amdgcn_s_barrier()
; #define PG8_SCHED __builtin_amdgcn_sched_barrier(0)
; template <class Epi>
; __device__ __forceinline__ void gemm_phase(LAS unsigned char* lds, const Gemm g, int G, int c, const Epi& E) {
;     ...
;             PG8_LDA(At, 1, 1); PG8_STAGE(PG8_SB(1, 0), b3, voffB); PG8_STAGE(PG8_SB(1, 1), b3 + hstepB, voffB); PG8_STAGE(PG8_SA(1, 0), a3, voffA);
;             PG8_WAIT_V(8); PG8_WAIT_L(0); PG8_BAR; PG8_MMA(1, 0, At, B0); PG8_MMA(1, 1, At, B1); PG8_BAR; PG8_SCHED;
;         }
;         if (wr == 0) PG8_BAR;
	s_mov_b32 m0, s88
	v_lshl_add_u64 v[212:213], v[212:213], 0, s[8:9]
	ds_read_b128 v[180:183], v150 offset:49152
	ds_read_b128 v[184:187], v150 offset:50176
	ds_read_b128 v[188:191], v150 offset:51200
	ds_read_b128 v[192:195], v150 offset:52224
	ds_read_b128 v[196:199], v150 offset:53248
	ds_read_b128 v[200:203], v150 offset:54272
	ds_read_b128 v[204:207], v150 offset:55296
	ds_read_b128 v[208:211], v150 offset:56320
	global_load_lds_dwordx4 v[212:213], off
	v_lshl_add_u64 v[212:213], v[214:215], 0, s[8:9]
	s_mov_b32 m0, s38
	s_nop 0
	global_load_lds_dwordx4 v[212:213], off
	v_lshl_add_u64 v[212:213], s[24:25], 0, v[134:135]
	s_mov_b32 m0, s39
	s_nop 0
	global_load_lds_dwordx4 v[212:213], off
	v_lshl_add_u64 v[212:213], s[24:25], 0, v[130:131]
	s_mov_b32 m0, s13
	s_nop 0
	global_load_lds_dwordx4 v[212:213], off
	v_lshl_add_u64 v[212:213], v[216:217], 0, s[8:9]
	s_mov_b32 m0, s79
	s_nop 0
	global_load_lds_dwordx4 v[212:213], off
	v_lshl_add_u64 v[212:213], v[218:219], 0, s[8:9]
	s_mov_b32 m0, s80
	s_nop 0
	global_load_lds_dwordx4 v[212:213], off
	s_waitcnt vmcnt(8)
	s_waitcnt lgkmcnt(0)
	s_barrier
	s_setprio 1
	s_waitcnt lgkmcnt(0)
	v_mfma_f32_16x16x32_bf16 v[62:65], v[142:145], v[180:183], v[62:65]
	v_mfma_f32_16x16x32_bf16 v[58:61], v[156:159], v[180:183], v[58:61]
	v_mfma_f32_16x16x32_bf16 v[46:49], v[156:159], v[188:191], v[46:49]
	v_mfma_f32_16x16x32_bf16 v[54:57], v[142:145], v[188:191], v[54:57]
	v_mfma_f32_16x16x32_bf16 v[38:41], v[142:145], v[196:199], v[38:41]
	v_mfma_f32_16x16x32_bf16 v[30:33], v[156:159], v[196:199], v[30:33]
	v_mfma_f32_16x16x32_bf16 v[14:17], v[156:159], v[204:207], v[14:17]
	v_mfma_f32_16x16x32_bf16 v[22:25], v[142:145], v[204:207], v[22:25]
	v_mfma_f32_16x16x32_bf16 v[62:65], v[152:155], v[184:187], v[62:65]
	v_mfma_f32_16x16x32_bf16 v[58:61], v[160:163], v[184:187], v[58:61]
	v_mfma_f32_16x16x32_bf16 v[46:49], v[160:163], v[192:195], v[46:49]
	v_mfma_f32_16x16x32_bf16 v[54:57], v[152:155], v[192:195], v[54:57]
	v_mfma_f32_16x16x32_bf16 v[38:41], v[152:155], v[200:203], v[38:41]
	v_mfma_f32_16x16x32_bf16 v[30:33], v[160:163], v[200:203], v[30:33]
	v_mfma_f32_16x16x32_bf16 v[14:17], v[160:163], v[208:211], v[14:17]
	v_mfma_f32_16x16x32_bf16 v[22:25], v[152:155], v[208:211], v[22:25]
	s_setprio 0
	s_setprio 1
	v_mfma_f32_16x16x32_bf16 v[50:53], v[164:167], v[180:183], v[50:53]
	v_mfma_f32_16x16x32_bf16 v[42:45], v[172:175], v[180:183], v[42:45]
	v_mfma_f32_16x16x32_bf16 v[26:29], v[172:175], v[188:191], v[26:29]
	v_mfma_f32_16x16x32_bf16 v[34:37], v[164:167], v[188:191], v[34:37]
	v_mfma_f32_16x16x32_bf16 v[18:21], v[164:167], v[196:199], v[18:21]
	v_mfma_f32_16x16x32_bf16 v[10:13], v[172:175], v[196:199], v[10:13]
	v_mfma_f32_16x16x32_bf16 v[2:5], v[172:175], v[204:207], v[2:5]
	v_mfma_f32_16x16x32_bf16 v[6:9], v[164:167], v[204:207], v[6:9]
	v_mfma_f32_16x16x32_bf16 v[50:53], v[168:171], v[184:187], v[50:53]
	v_mfma_f32_16x16x32_bf16 v[42:45], v[176:179], v[184:187], v[42:45]
	v_mfma_f32_16x16x32_bf16 v[26:29], v[176:179], v[192:195], v[26:29]
	v_mfma_f32_16x16x32_bf16 v[34:37], v[168:171], v[192:195], v[34:37]
	v_mfma_f32_16x16x32_bf16 v[18:21], v[168:171], v[200:203], v[18:21]
	v_mfma_f32_16x16x32_bf16 v[10:13], v[176:179], v[200:203], v[10:13]
	v_mfma_f32_16x16x32_bf16 v[2:5], v[176:179], v[208:211], v[2:5]
	v_mfma_f32_16x16x32_bf16 v[6:9], v[168:171], v[208:211], v[6:9]
	s_setprio 0
	s_barrier
	s_movk_i32 s13, 0x100
	s_andn2_b64 vcc, exec, s[22:23]
	s_mov_b64 s[24:25], -1
	s_mov_b64 s[22:23], 0
	s_cbranch_vccz .LBB0_368
	s_and_b64 vcc, exec, s[10:11]
	s_cbranch_vccz .LBB0_371
	s_barrier

; #define PG8_STAGE(bufoff, gbase, voff) do { _Pragma("unroll") for (int _i = 0; _i < 2; ++_i) \
;         __builtin_amdgcn_global_load_lds((const unsigned*)((const char*)(gbase) + (voff)[_i]), (LAS unsigned*)(lds + (bufoff) + ldsw + _i * 8192), 16, 0, 0); } while (0)
; #define PG8_LDA(dst, b, h) do { _Pragma("unroll") for (int m = 0; m < 4; ++m) _Pragma("unroll") for (int k = 0; k < 2; ++k) dst[m][k] = *(const LAS bf16x8*)(lds + PG8_SA(b, h) + aoff + m * 2048 + k * 1024); } while (0)
; #define PG8_LDB(dst, b, h) do { _Pragma("unroll") for (int n = 0; n < 2; ++n) _Pragma("unroll") for (int k = 0; k < 2; ++k) dst[n][k] = *(const LAS bf16x8*)(lds + PG8_SB(b, h) + boff + n * 2048 + k * 1024); } while (0)
; #define PG8_MMA(ai, bj, At, Bt) do { __builtin_amdgcn_s_setprio(1); _Pragma("unroll") for (int m = 0; m < 4; ++m) _Pragma("unroll") for (int n = 0; n < 2; ++n) _Pragma("unroll") for (int k = 0; k < 2; ++k) \
;         acc[ai][bj][m][n] = __builtin_amdgcn_mfma_f32_16x16x32_bf16(Bt[n][k], At[m][k], acc[ai][bj][m][n], 0, 0, 0); __builtin_amdgcn_s_setprio(0); } while (0)
; #define PG8_BAR __builtin_amdgcn_s_barrier()
; template <class Epi>
; __device__ __forceinline__ void gemm_phase(LAS unsigned char* lds, const Gemm g, int G, int c, const Epi& E) {
;     ...
;         const char* nA = has_next ? (const char*)(g.A + (size_t)nxt.pb * g.sA) + (size_t)nxt.pm * 2 * hstepA : cA;
;         const char* nB = has_next ? (const char*)(g.Bt + (size_t)nxt.pb * g.sB) + (size_t)nxt.pn * 2 * hstepB : cB;
; #pragma nounroll
;         for (int t = 0; t < nt; t += 2) {
;             const bool last = (t == nt - 2);
;             const char* a1 = cA + (size_t)(t + 1) * kstep;
;             const char* a2 = last ? nA : cA + (size_t)(t + 2) * kstep; const char* b2 = last ? nB : cB + (size_t)(t + 2) * kstep;
;             const char* a3 = a2 + kstep; const char* b3 = b2 + kstep;
;             PG8_LDB(B0, 0, 0); PG8_LDB(B1, 0, 1); PG8_SCHED; PG8_LDA(At, 0, 0); PG8_STAGE(PG8_SA(1, 1), a1 + hstepA, voffA);
;             PG8_WAIT_V(8); PG8_WAIT_L(0); PG8_BAR; PG8_MMA(0, 0, At, B0); PG8_MMA(0, 1, At, B1); PG8_BAR; PG8_SCHED;
;             PG8_LDA(At, 0, 1); PG8_STAGE(PG8_SB(0, 0), b2, voffB); PG8_STAGE(PG8_SB(0, 1), b2 + hstepB, voffB); PG8_STAGE(PG8_SA(0, 0), a2, voffA);
;             PG8_WAIT_V(8); PG8_WAIT_L(0); PG8_BAR; PG8_MMA(1, 0, At, B0); PG8_MMA(1, 1, At, B1); PG8_BAR; PG8_SCHED;
.LBB0_390:
	s_add_u32 s33, s8, s38
	s_addc_u32 s39, s9, 0
	s_add_u32 s56, s33, 0x100
	s_addc_u32 s57, s39, 0
	s_and_b64 s[54:55], s[10:11], exec
	s_cselect_b32 s57, s47, s57
	s_cselect_b32 s56, s46, s56
	s_add_u32 s38, s6, s38
	s_addc_u32 s54, s7, 0
	s_add_u32 s38, s38, 0x100
	s_addc_u32 s54, s54, 0
	s_and_b64 s[10:11], s[10:11], exec
	s_cselect_b32 s59, s53, s54
	s_cselect_b32 s58, s52, s38
	s_add_u32 s66, s33, 0xb0080
	s_addc_u32 s67, s39, 0
	s_add_i32 s65, s87, s14
	ds_read_b128 v[142:145], v160
	ds_read_b128 v[146:149], v160 offset:1024
	ds_read_b128 v[150:153], v160 offset:2048
	ds_read_b128 v[154:157], v160 offset:3072
	ds_read_b128 v[166:169], v161
	ds_read_b128 v[170:173], v161 offset:1024
	ds_read_b128 v[174:177], v161 offset:2048
	ds_read_b128 v[178:181], v161 offset:3072
	s_add_i32 m0, s78, 0xc000
	s_add_i32 s74, s78, 0xe000
	s_add_i32 s62, s65, 0x2000
	s_add_u32 s60, s58, 0xb0000
	s_addc_u32 s61, s59, 0
	s_add_i32 s64, s88, s14
	s_add_i32 s63, s64, 0x2000
	s_add_i32 s73, 0, 0x18000
	s_add_i32 s33, 0, 0x1c000
	s_add_u32 s54, s56, 0xb0000
	s_addc_u32 s55, s57, 0
	s_add_i32 vcc_hi, s73, s14
	s_add_i32 s39, vcc_hi, 0x2000
	s_add_u32 s10, s58, 0xb0080
	s_addc_u32 s11, s59, 0
	s_add_i32 vcc_lo, s33, s14
	s_add_i32 s38, vcc_lo, 0x2000
	v_lshl_add_u64 v[214:215], s[66:67], 0, v[130:131]
	ds_read_b128 v[182:185], v162
	ds_read_b128 v[186:189], v162 offset:1024
	ds_read_b128 v[190:193], v162 offset:2048
	ds_read_b128 v[194:197], v162 offset:3072
	ds_read_b128 v[198:201], v162 offset:4096
	ds_read_b128 v[202:205], v162 offset:5120
	ds_read_b128 v[206:209], v162 offset:6144
	ds_read_b128 v[210:213], v162 offset:7168
	global_load_lds_dwordx4 v[214:215], off
	v_lshl_add_u64 v[214:215], s[66:67], 0, v[134:135]
	s_mov_b32 m0, s74
	s_nop 0
	global_load_lds_dwordx4 v[214:215], off
	s_waitcnt vmcnt(8)
	s_waitcnt lgkmcnt(0)
	s_barrier
	s_setprio 1
	s_waitcnt lgkmcnt(0)
	v_mfma_f32_16x16x32_bf16 v[126:129], v[142:145], v[182:185], v[126:129]
	v_mfma_f32_16x16x32_bf16 v[122:125], v[150:153], v[182:185], v[122:125]
	v_mfma_f32_16x16x32_bf16 v[106:109], v[150:153], v[190:193], v[106:109]
	v_mfma_f32_16x16x32_bf16 v[110:113], v[142:145], v[190:193], v[110:113]
	v_mfma_f32_16x16x32_bf16 v[94:97], v[142:145], v[198:201], v[94:97]
	v_mfma_f32_16x16x32_bf16 v[90:93], v[150:153], v[198:201], v[90:93]
	v_mfma_f32_16x16x32_bf16 v[74:77], v[150:153], v[206:209], v[74:77]
	v_mfma_f32_16x16x32_bf16 v[78:81], v[142:145], v[206:209], v[78:81]
	v_mfma_f32_16x16x32_bf16 v[126:129], v[146:149], v[186:189], v[126:129]
	v_mfma_f32_16x16x32_bf16 v[122:125], v[154:157], v[186:189], v[122:125]
	v_mfma_f32_16x16x32_bf16 v[106:109], v[154:157], v[194:197], v[106:109]
	v_mfma_f32_16x16x32_bf16 v[110:113], v[146:149], v[194:197], v[110:113]
	v_mfma_f32_16x16x32_bf16 v[94:97], v[146:149], v[202:205], v[94:97]
	v_mfma_f32_16x16x32_bf16 v[90:93], v[154:157], v[202:205], v[90:93]
	v_mfma_f32_16x16x32_bf16 v[74:77], v[154:157], v[210:213], v[74:77]
	v_mfma_f32_16x16x32_bf16 v[78:81], v[146:149], v[210:213], v[78:81]
	s_setprio 0
	s_setprio 1
	v_mfma_f32_16x16x32_bf16 v[118:121], v[166:169], v[182:185], v[118:121]
	v_mfma_f32_16x16x32_bf16 v[114:117], v[174:177], v[182:185], v[114:117]
	v_mfma_f32_16x16x32_bf16 v[98:101], v[174:177], v[190:193], v[98:101]
	v_mfma_f32_16x16x32_bf16 v[102:105], v[166:169], v[190:193], v[102:105]
	v_mfma_f32_16x16x32_bf16 v[86:89], v[166:169], v[198:201], v[86:89]
	v_mfma_f32_16x16x32_bf16 v[82:85], v[174:177], v[198:201], v[82:85]
	v_mfma_f32_16x16x32_bf16 v[66:69], v[174:177], v[206:209], v[66:69]
	v_mfma_f32_16x16x32_bf16 v[70:73], v[166:169], v[206:209], v[70:73]
	v_mfma_f32_16x16x32_bf16 v[118:121], v[170:173], v[186:189], v[118:121]
	v_mfma_f32_16x16x32_bf16 v[114:117], v[178:181], v[186:189], v[114:117]
	v_mfma_f32_16x16x32_bf16 v[98:101], v[178:181], v[194:197], v[98:101]
	v_mfma_f32_16x16x32_bf16 v[102:105], v[170:173], v[194:197], v[102:105]
	v_mfma_f32_16x16x32_bf16 v[86:89], v[170:173], v[202:205], v[86:89]
	v_mfma_f32_16x16x32_bf16 v[82:85], v[178:181], v[202:205], v[82:85]
	v_mfma_f32_16x16x32_bf16 v[66:69], v[178:181], v[210:213], v[66:69]
	v_mfma_f32_16x16x32_bf16 v[70:73], v[170:173], v[210:213], v[70:73]
	s_setprio 0
	s_barrier
	s_mov_b32 m0, s65
	v_lshl_add_u64 v[214:215], s[58:59], 0, v[132:133]
	ds_read_b128 v[182:185], v162 offset:16384
	ds_read_b128 v[186:189], v162 offset:17408
	ds_read_b128 v[190:193], v162 offset:18432
	ds_read_b128 v[194:197], v162 offset:19456
	ds_read_b128 v[198:201], v162 offset:20480
	ds_read_b128 v[202:205], v162 offset:21504
	ds_read_b128 v[206:209], v162 offset:22528
	ds_read_b128 v[210:213], v162 offset:23552
	global_load_lds_dwordx4 v[214:215], off
	v_lshl_add_u64 v[216:217], s[58:59], 0, v[136:137]
	s_mov_b32 m0, s62
	v_lshl_add_u64 v[218:219], s[60:61], 0, v[132:133]
	global_load_lds_dwordx4 v[216:217], off
	s_mov_b32 m0, s64
	v_lshl_add_u64 v[220:221], s[56:57], 0, v[134:135]
	global_load_lds_dwordx4 v[218:219], off
	v_lshl_add_u64 v[218:219], s[60:61], 0, v[136:137]
	s_mov_b32 m0, s63
	s_nop 0
	global_load_lds_dwordx4 v[218:219], off
	v_lshl_add_u64 v[218:219], s[56:57], 0, v[130:131]
	s_mov_b32 m0, s78
	s_nop 0
	global_load_lds_dwordx4 v[218:219], off
	s_mov_b32 m0, s79
	s_nop 0
	global_load_lds_dwordx4 v[220:221], off
	s_waitcnt vmcnt(8)
	s_waitcnt lgkmcnt(0)
	s_barrier
; #define PG8_STAGE(bufoff, gbase, voff) do { _Pragma("unroll") for (int _i = 0; _i < 2; ++_i) \
;         __builtin_amdgcn_global_load_lds((const unsigned*)((const char*)(gbase) + (voff)[_i]), (LAS unsigned*)(lds + (bufoff) + ldsw + _i * 8192), 16, 0, 0); } while (0)
; #define PG8_LDA(dst, b, h) do { _Pragma("unroll") for (int m = 0; m < 4; ++m) _Pragma("unroll") for (int k = 0; k < 2; ++k) dst[m][k] = *(const LAS bf16x8*)(lds + PG8_SA(b, h) + aoff + m * 2048 + k * 1024); } while (0)
; #define PG8_LDB(dst, b, h) do { _Pragma("unroll") for (int n = 0; n < 2; ++n) _Pragma("unroll") for (int k = 0; k < 2; ++k) dst[n][k] = *(const LAS bf16x8*)(lds + PG8_SB(b, h) + boff + n * 2048 + k * 1024); } while (0)
; #define PG8_MMA(ai, bj, At, Bt) do { __builtin_amdgcn_s_setprio(1); _Pragma("unroll") for (int m = 0; m < 4; ++m) _Pragma("unroll") for (int n = 0; n < 2; ++n) _Pragma("unroll") for (int k = 0; k < 2; ++k) \
;         acc[ai][bj][m][n] = __builtin_amdgcn_mfma_f32_16x16x32_bf16(Bt[n][k], At[m][k], acc[ai][bj][m][n], 0, 0, 0); __builtin_amdgcn_s_setprio(0); } while (0)
; #define PG8_WAIT_V(n) asm volatile("s_waitcnt vmcnt(" #n ")" ::: "memory")
; #define PG8_WAIT_L(n) asm volatile("s_waitcnt lgkmcnt(" #n ")" ::: "memory")
; #define PG8_BAR __builtin_amdgcn_s_barrier()
; #define PG8_SCHED __builtin_amdgcn_sched_barrier(0)
; template <class Epi>
; __device__ __forceinline__ void gemm_phase(LAS unsigned char* lds, const Gemm g, int G, int c, const Epi& E) {
;     ...
;             PG8_WAIT_V(8); PG8_WAIT_L(0); PG8_BAR; PG8_MMA(1, 0, At, B0); PG8_MMA(1, 1, At, B1); PG8_BAR; PG8_SCHED;
;             PG8_LDB(B0, 1, 0); PG8_LDB(B1, 1, 1); PG8_SCHED; PG8_LDA(At, 1, 0); PG8_STAGE(PG8_SA(0, 1), a2 + hstepA, voffA);
;             PG8_WAIT_V(8); PG8_WAIT_L(0); PG8_BAR; PG8_MMA(0, 0, At, B0); PG8_MMA(0, 1, At, B1); PG8_BAR; PG8_SCHED;
	s_setprio 1
	s_waitcnt lgkmcnt(0)
	v_mfma_f32_16x16x32_bf16 v[62:65], v[142:145], v[182:185], v[62:65]
	v_mfma_f32_16x16x32_bf16 v[58:61], v[150:153], v[182:185], v[58:61]
	v_mfma_f32_16x16x32_bf16 v[42:45], v[150:153], v[190:193], v[42:45]
	v_mfma_f32_16x16x32_bf16 v[46:49], v[142:145], v[190:193], v[46:49]
	v_mfma_f32_16x16x32_bf16 v[30:33], v[142:145], v[198:201], v[30:33]
	v_mfma_f32_16x16x32_bf16 v[26:29], v[150:153], v[198:201], v[26:29]
	v_mfma_f32_16x16x32_bf16 v[10:13], v[150:153], v[206:209], v[10:13]
	v_mfma_f32_16x16x32_bf16 v[14:17], v[142:145], v[206:209], v[14:17]
	v_mfma_f32_16x16x32_bf16 v[62:65], v[146:149], v[186:189], v[62:65]
	v_mfma_f32_16x16x32_bf16 v[58:61], v[154:157], v[186:189], v[58:61]
	v_mfma_f32_16x16x32_bf16 v[42:45], v[154:157], v[194:197], v[42:45]
	v_mfma_f32_16x16x32_bf16 v[46:49], v[146:149], v[194:197], v[46:49]
	v_mfma_f32_16x16x32_bf16 v[30:33], v[146:149], v[202:205], v[30:33]
	v_mfma_f32_16x16x32_bf16 v[26:29], v[154:157], v[202:205], v[26:29]
	v_mfma_f32_16x16x32_bf16 v[10:13], v[154:157], v[210:213], v[10:13]
	v_mfma_f32_16x16x32_bf16 v[14:17], v[146:149], v[210:213], v[14:17]
	s_setprio 0
	s_setprio 1
	v_mfma_f32_16x16x32_bf16 v[54:57], v[166:169], v[182:185], v[54:57]
	v_mfma_f32_16x16x32_bf16 v[50:53], v[174:177], v[182:185], v[50:53]
	v_mfma_f32_16x16x32_bf16 v[34:37], v[174:177], v[190:193], v[34:37]
	v_mfma_f32_16x16x32_bf16 v[38:41], v[166:169], v[190:193], v[38:41]
	v_mfma_f32_16x16x32_bf16 v[22:25], v[166:169], v[198:201], v[22:25]
	v_mfma_f32_16x16x32_bf16 v[18:21], v[174:177], v[198:201], v[18:21]
	v_mfma_f32_16x16x32_bf16 v[2:5], v[174:177], v[206:209], v[2:5]
	v_mfma_f32_16x16x32_bf16 v[6:9], v[166:169], v[206:209], v[6:9]
	v_mfma_f32_16x16x32_bf16 v[54:57], v[170:173], v[186:189], v[54:57]
	v_mfma_f32_16x16x32_bf16 v[50:53], v[178:181], v[186:189], v[50:53]
	v_mfma_f32_16x16x32_bf16 v[34:37], v[178:181], v[194:197], v[34:37]
	v_mfma_f32_16x16x32_bf16 v[38:41], v[170:173], v[194:197], v[38:41]
	v_mfma_f32_16x16x32_bf16 v[22:25], v[170:173], v[202:205], v[22:25]
	v_mfma_f32_16x16x32_bf16 v[18:21], v[178:181], v[202:205], v[18:21]
	v_mfma_f32_16x16x32_bf16 v[2:5], v[178:181], v[210:213], v[2:5]
	v_mfma_f32_16x16x32_bf16 v[6:9], v[170:173], v[210:213], v[6:9]
	s_setprio 0
	s_barrier
	v_add_u32_e32 v154, s73, v159
	v_add_u32_e32 v178, s33, v159
	ds_read_b128 v[142:145], v154
	ds_read_b128 v[146:149], v154 offset:1024
	ds_read_b128 v[150:153], v154 offset:2048
	ds_read_b128 v[154:157], v154 offset:3072
	ds_read_b128 v[166:169], v178
	ds_read_b128 v[170:173], v178 offset:1024
	ds_read_b128 v[174:177], v178 offset:2048
	ds_read_b128 v[178:181], v178 offset:3072
	s_mov_b32 m0, s80
	v_lshl_add_u64 v[222:223], s[54:55], 0, v[130:131]
	ds_read_b128 v[182:185], v162 offset:32768
	ds_read_b128 v[186:189], v162 offset:33792
	ds_read_b128 v[190:193], v162 offset:34816
	ds_read_b128 v[194:197], v162 offset:35840
	ds_read_b128 v[198:201], v162 offset:36864
	ds_read_b128 v[202:205], v162 offset:37888
	ds_read_b128 v[206:209], v162 offset:38912
	ds_read_b128 v[210:213], v162 offset:39936
	global_load_lds_dwordx4 v[222:223], off
	v_lshl_add_u64 v[222:223], s[54:55], 0, v[134:135]
	s_mov_b32 m0, s81
	s_nop 0
	global_load_lds_dwordx4 v[222:223], off
	s_waitcnt vmcnt(8)
	s_waitcnt lgkmcnt(0)
	s_barrier
	s_setprio 1
	s_waitcnt lgkmcnt(0)
	v_mfma_f32_16x16x32_bf16 v[126:129], v[142:145], v[182:185], v[126:129]
	v_mfma_f32_16x16x32_bf16 v[122:125], v[150:153], v[182:185], v[122:125]
	v_mfma_f32_16x16x32_bf16 v[106:109], v[150:153], v[190:193], v[106:109]
	v_mfma_f32_16x16x32_bf16 v[110:113], v[142:145], v[190:193], v[110:113]
	v_mfma_f32_16x16x32_bf16 v[94:97], v[142:145], v[198:201], v[94:97]
	v_mfma_f32_16x16x32_bf16 v[90:93], v[150:153], v[198:201], v[90:93]
	v_mfma_f32_16x16x32_bf16 v[74:77], v[150:153], v[206:209], v[74:77]
	v_mfma_f32_16x16x32_bf16 v[78:81], v[142:145], v[206:209], v[78:81]
	v_mfma_f32_16x16x32_bf16 v[126:129], v[146:149], v[186:189], v[126:129]
	v_mfma_f32_16x16x32_bf16 v[122:125], v[154:157], v[186:189], v[122:125]
	v_mfma_f32_16x16x32_bf16 v[106:109], v[154:157], v[194:197], v[106:109]
	v_mfma_f32_16x16x32_bf16 v[110:113], v[146:149], v[194:197], v[110:113]
	v_mfma_f32_16x16x32_bf16 v[94:97], v[146:149], v[202:205], v[94:97]
	v_mfma_f32_16x16x32_bf16 v[90:93], v[154:157], v[202:205], v[90:93]
	v_mfma_f32_16x16x32_bf16 v[74:77], v[154:157], v[210:213], v[74:77]
	v_mfma_f32_16x16x32_bf16 v[78:81], v[146:149], v[210:213], v[78:81]
	s_setprio 0
	s_setprio 1
	v_mfma_f32_16x16x32_bf16 v[118:121], v[166:169], v[182:185], v[118:121]
	v_mfma_f32_16x16x32_bf16 v[114:117], v[174:177], v[182:185], v[114:117]
	v_mfma_f32_16x16x32_bf16 v[98:101], v[174:177], v[190:193], v[98:101]
	v_mfma_f32_16x16x32_bf16 v[102:105], v[166:169], v[190:193], v[102:105]
	v_mfma_f32_16x16x32_bf16 v[86:89], v[166:169], v[198:201], v[86:89]
	v_mfma_f32_16x16x32_bf16 v[82:85], v[174:177], v[198:201], v[82:85]
	v_mfma_f32_16x16x32_bf16 v[66:69], v[174:177], v[206:209], v[66:69]
	v_mfma_f32_16x16x32_bf16 v[70:73], v[166:169], v[206:209], v[70:73]
	v_mfma_f32_16x16x32_bf16 v[118:121], v[170:173], v[186:189], v[118:121]
	v_mfma_f32_16x16x32_bf16 v[114:117], v[178:181], v[186:189], v[114:117]
	v_mfma_f32_16x16x32_bf16 v[98:101], v[178:181], v[194:197], v[98:101]
	v_mfma_f32_16x16x32_bf16 v[102:105], v[170:173], v[194:197], v[102:105]
	v_mfma_f32_16x16x32_bf16 v[86:89], v[170:173], v[202:205], v[86:89]
	v_mfma_f32_16x16x32_bf16 v[82:85], v[178:181], v[202:205], v[82:85]
	v_mfma_f32_16x16x32_bf16 v[66:69], v[178:181], v[210:213], v[66:69]
	v_mfma_f32_16x16x32_bf16 v[70:73], v[170:173], v[210:213], v[70:73]
	s_setprio 0
	s_barrier
; #define PG8_STAGE(bufoff, gbase, voff) do { _Pragma("unroll") for (int _i = 0; _i < 2; ++_i) \
;         __builtin_amdgcn_global_load_lds((const unsigned*)((const char*)(gbase) + (voff)[_i]), (LAS unsigned*)(lds + (bufoff) + ldsw + _i * 8192), 16, 0, 0); } while (0)
; #define PG8_LDA(dst, b, h) do { _Pragma("unroll") for (int m = 0; m < 4; ++m) _Pragma("unroll") for (int k = 0; k < 2; ++k) dst[m][k] = *(const LAS bf16x8*)(lds + PG8_SA(b, h) + aoff + m * 2048 + k * 1024); } while (0)
; #define PG8_MMA(ai, bj, At, Bt) do { __builtin_amdgcn_s_setprio(1); _Pragma("unroll") for (int m = 0; m < 4; ++m) _Pragma("unroll") for (int n = 0; n < 2; ++n) _Pragma("unroll") for (int k = 0; k < 2; ++k) \
;         acc[ai][bj][m][n] = __builtin_amdgcn_mfma_f32_16x16x32_bf16(Bt[n][k], At[m][k], acc[ai][bj][m][n], 0, 0, 0); __builtin_amdgcn_s_setprio(0); } while (0)
; #define PG8_WAIT_V(n) asm volatile("s_waitcnt vmcnt(" #n ")" ::: "memory")
; #define PG8_WAIT_L(n) asm volatile("s_waitcnt lgkmcnt(" #n ")" ::: "memory")
; #define PG8_BAR __builtin_amdgcn_s_barrier()
; #define PG8_SCHED __builtin_amdgcn_sched_barrier(0)
; template <class Epi>
; __device__ __forceinline__ void gemm_phase(LAS unsigned char* lds, const Gemm g, int G, int c, const Epi& E) {
;     ...
;             PG8_LDA(At, 1, 1); PG8_STAGE(PG8_SB(1, 0), b3, voffB); PG8_STAGE(PG8_SB(1, 1), b3 + hstepB, voffB); PG8_STAGE(PG8_SA(1, 0), a3, voffA);
;             PG8_WAIT_V(8); PG8_WAIT_L(0); PG8_BAR; PG8_MMA(1, 0, At, B0); PG8_MMA(1, 1, At, B1); PG8_BAR; PG8_SCHED;
;         }
;         if (wr == 0) PG8_BAR;
	s_mov_b32 m0, vcc_hi
	v_lshl_add_u64 v[214:215], v[214:215], 0, s[24:25]
	ds_read_b128 v[182:185], v162 offset:49152
	ds_read_b128 v[186:189], v162 offset:50176
	ds_read_b128 v[190:193], v162 offset:51200
	ds_read_b128 v[194:197], v162 offset:52224
	ds_read_b128 v[198:201], v162 offset:53248
	ds_read_b128 v[202:205], v162 offset:54272
	ds_read_b128 v[206:209], v162 offset:55296
	ds_read_b128 v[210:213], v162 offset:56320
	global_load_lds_dwordx4 v[214:215], off
	v_lshl_add_u64 v[214:215], v[216:217], 0, s[24:25]
	s_mov_b32 m0, s39
	s_nop 0
	global_load_lds_dwordx4 v[214:215], off
	v_lshl_add_u64 v[214:215], s[10:11], 0, v[132:133]
	s_mov_b32 m0, vcc_lo
	s_nop 0
	global_load_lds_dwordx4 v[214:215], off
	v_lshl_add_u64 v[214:215], s[10:11], 0, v[136:137]
	s_mov_b32 m0, s38
	s_nop 0
	global_load_lds_dwordx4 v[214:215], off
	v_lshl_add_u64 v[214:215], v[218:219], 0, s[24:25]
	s_mov_b32 m0, s85
	s_nop 0
	global_load_lds_dwordx4 v[214:215], off
	v_lshl_add_u64 v[214:215], v[220:221], 0, s[24:25]
	s_mov_b32 m0, s86
	s_nop 0
	global_load_lds_dwordx4 v[214:215], off
	s_waitcnt vmcnt(8)
	s_waitcnt lgkmcnt(0)
	s_barrier
	s_setprio 1
	s_waitcnt lgkmcnt(0)
	v_mfma_f32_16x16x32_bf16 v[62:65], v[142:145], v[182:185], v[62:65]
	v_mfma_f32_16x16x32_bf16 v[58:61], v[150:153], v[182:185], v[58:61]
	v_mfma_f32_16x16x32_bf16 v[42:45], v[150:153], v[190:193], v[42:45]
	v_mfma_f32_16x16x32_bf16 v[46:49], v[142:145], v[190:193], v[46:49]
	v_mfma_f32_16x16x32_bf16 v[30:33], v[142:145], v[198:201], v[30:33]
	v_mfma_f32_16x16x32_bf16 v[26:29], v[150:153], v[198:201], v[26:29]
	v_mfma_f32_16x16x32_bf16 v[10:13], v[150:153], v[206:209], v[10:13]
	v_mfma_f32_16x16x32_bf16 v[14:17], v[142:145], v[206:209], v[14:17]
	v_mfma_f32_16x16x32_bf16 v[62:65], v[146:149], v[186:189], v[62:65]
	v_mfma_f32_16x16x32_bf16 v[58:61], v[154:157], v[186:189], v[58:61]
	v_mfma_f32_16x16x32_bf16 v[42:45], v[154:157], v[194:197], v[42:45]
	v_mfma_f32_16x16x32_bf16 v[46:49], v[146:149], v[194:197], v[46:49]
	v_mfma_f32_16x16x32_bf16 v[30:33], v[146:149], v[202:205], v[30:33]
	v_mfma_f32_16x16x32_bf16 v[26:29], v[154:157], v[202:205], v[26:29]
	v_mfma_f32_16x16x32_bf16 v[10:13], v[154:157], v[210:213], v[10:13]
	v_mfma_f32_16x16x32_bf16 v[14:17], v[146:149], v[210:213], v[14:17]
	s_setprio 0
	s_setprio 1
	v_mfma_f32_16x16x32_bf16 v[54:57], v[166:169], v[182:185], v[54:57]
	v_mfma_f32_16x16x32_bf16 v[50:53], v[174:177], v[182:185], v[50:53]
	v_mfma_f32_16x16x32_bf16 v[34:37], v[174:177], v[190:193], v[34:37]
	v_mfma_f32_16x16x32_bf16 v[38:41], v[166:169], v[190:193], v[38:41]
	v_mfma_f32_16x16x32_bf16 v[22:25], v[166:169], v[198:201], v[22:25]
	v_mfma_f32_16x16x32_bf16 v[18:21], v[174:177], v[198:201], v[18:21]
	v_mfma_f32_16x16x32_bf16 v[2:5], v[174:177], v[206:209], v[2:5]
	v_mfma_f32_16x16x32_bf16 v[6:9], v[166:169], v[206:209], v[6:9]
	v_mfma_f32_16x16x32_bf16 v[54:57], v[170:173], v[186:189], v[54:57]
	v_mfma_f32_16x16x32_bf16 v[50:53], v[178:181], v[186:189], v[50:53]
	v_mfma_f32_16x16x32_bf16 v[34:37], v[178:181], v[194:197], v[34:37]
	v_mfma_f32_16x16x32_bf16 v[38:41], v[170:173], v[194:197], v[38:41]
	v_mfma_f32_16x16x32_bf16 v[22:25], v[170:173], v[202:205], v[22:25]
	v_mfma_f32_16x16x32_bf16 v[18:21], v[178:181], v[202:205], v[18:21]
	v_mfma_f32_16x16x32_bf16 v[2:5], v[178:181], v[210:213], v[2:5]
	v_mfma_f32_16x16x32_bf16 v[6:9], v[170:173], v[210:213], v[6:9]
	s_setprio 0
	s_barrier
	s_movk_i32 s38, 0x100
	s_andn2_b64 vcc, exec, s[4:5]
	s_mov_b64 s[10:11], -1
	s_mov_b64 s[4:5], 0
	s_cbranch_vccz .LBB0_390
	s_and_b64 vcc, exec, s[44:45]
	s_cbranch_vccz .LBB0_393
	s_barrier

; #define PG8_STAGE(bufoff, gbase, voff) do { _Pragma("unroll") for (int _i = 0; _i < 2; ++_i) \
;         __builtin_amdgcn_global_load_lds((const unsigned*)((const char*)(gbase) + (voff)[_i]), (LAS unsigned*)(lds + (bufoff) + ldsw + _i * 8192), 16, 0, 0); } while (0)
; #define PG8_LDA(dst, b, h) do { _Pragma("unroll") for (int m = 0; m < 4; ++m) _Pragma("unroll") for (int k = 0; k < 2; ++k) dst[m][k] = *(const LAS bf16x8*)(lds + PG8_SA(b, h) + aoff + m * 2048 + k * 1024); } while (0)
; #define PG8_LDB(dst, b, h) do { _Pragma("unroll") for (int n = 0; n < 2; ++n) _Pragma("unroll") for (int k = 0; k < 2; ++k) dst[n][k] = *(const LAS bf16x8*)(lds + PG8_SB(b, h) + boff + n * 2048 + k * 1024); } while (0)
; #define PG8_MMA(ai, bj, At, Bt) do { __builtin_amdgcn_s_setprio(1); _Pragma("unroll") for (int m = 0; m < 4; ++m) _Pragma("unroll") for (int n = 0; n < 2; ++n) _Pragma("unroll") for (int k = 0; k < 2; ++k) \
;         acc[ai][bj][m][n] = __builtin_amdgcn_mfma_f32_16x16x32_bf16(Bt[n][k], At[m][k], acc[ai][bj][m][n], 0, 0, 0); __builtin_amdgcn_s_setprio(0); } while (0)
; #define PG8_BAR __builtin_amdgcn_s_barrier()
; template <class Epi>
; __device__ __forceinline__ void gemm_phase(LAS unsigned char* lds, const Gemm g, int G, int c, const Epi& E) {
;     ...
;         const char* nA = has_next ? (const char*)(g.A + (size_t)nxt.pb * g.sA) + (size_t)nxt.pm * 2 * hstepA : cA;
;         const char* nB = has_next ? (const char*)(g.Bt + (size_t)nxt.pb * g.sB) + (size_t)nxt.pn * 2 * hstepB : cB;
; #pragma nounroll
;         for (int t = 0; t < nt; t += 2) {
;             const bool last = (t == nt - 2);
;             const char* a1 = cA + (size_t)(t + 1) * kstep;
;             const char* a2 = last ? nA : cA + (size_t)(t + 2) * kstep; const char* b2 = last ? nB : cB + (size_t)(t + 2) * kstep;
;             const char* a3 = a2 + kstep; const char* b3 = b2 + kstep;
;             PG8_LDB(B0, 0, 0); PG8_LDB(B1, 0, 1); PG8_SCHED; PG8_LDA(At, 0, 0); PG8_STAGE(PG8_SA(1, 1), a1 + hstepA, voffA);
;             PG8_WAIT_V(8); PG8_WAIT_L(0); PG8_BAR; PG8_MMA(0, 0, At, B0); PG8_MMA(0, 1, At, B1); PG8_BAR; PG8_SCHED;
;             PG8_LDA(At, 0, 1); PG8_STAGE(PG8_SB(0, 0), b2, voffB); PG8_STAGE(PG8_SB(0, 1), b2 + hstepB, voffB); PG8_STAGE(PG8_SA(0, 0), a2, voffA);
;             PG8_WAIT_V(8); PG8_WAIT_L(0); PG8_BAR; PG8_MMA(1, 0, At, B0); PG8_MMA(1, 1, At, B1); PG8_BAR; PG8_SCHED;
.LBB0_476:
	s_add_u32 s33, s8, s38
	s_addc_u32 s39, s9, 0
	s_add_u32 s56, s33, 0x100
	s_addc_u32 s57, s39, 0
	s_and_b64 s[54:55], s[10:11], exec
	s_cselect_b32 s57, s47, s57
	s_cselect_b32 s56, s46, s56
	s_add_u32 s38, s6, s38
	s_addc_u32 s54, s7, 0
	s_add_u32 s38, s38, 0x100
	s_addc_u32 s54, s54, 0
	s_and_b64 s[10:11], s[10:11], exec
	s_cselect_b32 s59, s53, s54
	s_cselect_b32 s58, s52, s38
	s_add_u32 s66, s33, 0xb0080
	ds_read_b128 v[130:133], v166
	ds_read_b128 v[134:137], v166 offset:1024
	ds_read_b128 v[150:153], v166 offset:2048
	ds_read_b128 v[154:157], v166 offset:3072
	ds_read_b128 v[158:161], v167
	ds_read_b128 v[172:175], v167 offset:1024
	ds_read_b128 v[176:179], v167 offset:2048
	ds_read_b128 v[180:183], v167 offset:3072
	s_addc_u32 s67, s39, 0
	s_add_i32 s63, s95, s83
	s_add_i32 m0, s86, 0xc000
	s_add_i32 s64, s86, 0xe000
	s_add_i32 s74, s63, 0x2000
	s_add_u32 s60, s58, 0xb0000
	s_addc_u32 s61, s59, 0
	s_add_i32 s75, s96, s83
	s_add_i32 s62, s75, 0x2000
	s_add_i32 vcc_hi, 0, 0x18000
	s_add_i32 vcc_lo, 0, 0x1c000
	s_add_u32 s54, s56, 0xb0000
	s_addc_u32 s55, s57, 0
	s_add_i32 s39, vcc_hi, s83
	s_add_i32 s73, s39, 0x2000
	s_add_u32 s10, s58, 0xb0080
	s_addc_u32 s11, s59, 0
	s_add_i32 s38, vcc_lo, s83
	s_add_i32 s33, s38, 0x2000
	v_lshl_add_u64 v[162:163], s[66:67], 0, v[138:139]
	ds_read_b128 v[184:187], v168
	ds_read_b128 v[188:191], v168 offset:1024
	ds_read_b128 v[192:195], v168 offset:2048
	ds_read_b128 v[196:199], v168 offset:3072
	ds_read_b128 v[200:203], v168 offset:4096
	ds_read_b128 v[204:207], v168 offset:5120
	ds_read_b128 v[208:211], v168 offset:6144
	ds_read_b128 v[212:215], v168 offset:7168
	global_load_lds_dwordx4 v[162:163], off
	v_lshl_add_u64 v[162:163], s[66:67], 0, v[142:143]
	s_mov_b32 m0, s64
	s_nop 0
	global_load_lds_dwordx4 v[162:163], off
	s_waitcnt vmcnt(8)
	s_waitcnt lgkmcnt(0)
	s_barrier
	s_setprio 1
	s_waitcnt lgkmcnt(0)
	v_mfma_f32_16x16x32_bf16 v[126:129], v[130:133], v[184:187], v[126:129]
	v_mfma_f32_16x16x32_bf16 v[122:125], v[150:153], v[184:187], v[122:125]
	v_mfma_f32_16x16x32_bf16 v[106:109], v[150:153], v[192:195], v[106:109]
	v_mfma_f32_16x16x32_bf16 v[110:113], v[130:133], v[192:195], v[110:113]
	v_mfma_f32_16x16x32_bf16 v[94:97], v[130:133], v[200:203], v[94:97]
	v_mfma_f32_16x16x32_bf16 v[90:93], v[150:153], v[200:203], v[90:93]
	v_mfma_f32_16x16x32_bf16 v[74:77], v[150:153], v[208:211], v[74:77]
	v_mfma_f32_16x16x32_bf16 v[78:81], v[130:133], v[208:211], v[78:81]
	v_mfma_f32_16x16x32_bf16 v[126:129], v[134:137], v[188:191], v[126:129]
	v_mfma_f32_16x16x32_bf16 v[122:125], v[154:157], v[188:191], v[122:125]
	v_mfma_f32_16x16x32_bf16 v[106:109], v[154:157], v[196:199], v[106:109]
	v_mfma_f32_16x16x32_bf16 v[110:113], v[134:137], v[196:199], v[110:113]
	v_mfma_f32_16x16x32_bf16 v[94:97], v[134:137], v[204:207], v[94:97]
	v_mfma_f32_16x16x32_bf16 v[90:93], v[154:157], v[204:207], v[90:93]
	v_mfma_f32_16x16x32_bf16 v[74:77], v[154:157], v[212:215], v[74:77]
	v_mfma_f32_16x16x32_bf16 v[78:81], v[134:137], v[212:215], v[78:81]
	s_setprio 0
	s_setprio 1
	v_mfma_f32_16x16x32_bf16 v[118:121], v[158:161], v[184:187], v[118:121]
	v_mfma_f32_16x16x32_bf16 v[114:117], v[176:179], v[184:187], v[114:117]
	v_mfma_f32_16x16x32_bf16 v[98:101], v[176:179], v[192:195], v[98:101]
	v_mfma_f32_16x16x32_bf16 v[102:105], v[158:161], v[192:195], v[102:105]
	v_mfma_f32_16x16x32_bf16 v[86:89], v[158:161], v[200:203], v[86:89]
	v_mfma_f32_16x16x32_bf16 v[82:85], v[176:179], v[200:203], v[82:85]
	v_mfma_f32_16x16x32_bf16 v[66:69], v[176:179], v[208:211], v[66:69]
	v_mfma_f32_16x16x32_bf16 v[70:73], v[158:161], v[208:211], v[70:73]
	v_mfma_f32_16x16x32_bf16 v[118:121], v[172:175], v[188:191], v[118:121]
	v_mfma_f32_16x16x32_bf16 v[114:117], v[180:183], v[188:191], v[114:117]
	v_mfma_f32_16x16x32_bf16 v[98:101], v[180:183], v[196:199], v[98:101]
	v_mfma_f32_16x16x32_bf16 v[102:105], v[172:175], v[196:199], v[102:105]
	v_mfma_f32_16x16x32_bf16 v[86:89], v[172:175], v[204:207], v[86:89]
	v_mfma_f32_16x16x32_bf16 v[82:85], v[180:183], v[204:207], v[82:85]
	v_mfma_f32_16x16x32_bf16 v[66:69], v[180:183], v[212:215], v[66:69]
	v_mfma_f32_16x16x32_bf16 v[70:73], v[172:175], v[212:215], v[70:73]
	s_setprio 0
	s_barrier
	s_mov_b32 m0, s63
	v_lshl_add_u64 v[162:163], s[58:59], 0, v[140:141]
	ds_read_b128 v[184:187], v168 offset:16384
	ds_read_b128 v[188:191], v168 offset:17408
	ds_read_b128 v[192:195], v168 offset:18432
	ds_read_b128 v[196:199], v168 offset:19456
	ds_read_b128 v[200:203], v168 offset:20480
	ds_read_b128 v[204:207], v168 offset:21504
	ds_read_b128 v[208:211], v168 offset:22528
	ds_read_b128 v[212:215], v168 offset:23552
	global_load_lds_dwordx4 v[162:163], off
	v_lshl_add_u64 v[216:217], s[58:59], 0, v[144:145]
	s_mov_b32 m0, s74
	v_lshl_add_u64 v[218:219], s[60:61], 0, v[140:141]
	global_load_lds_dwordx4 v[216:217], off
	s_mov_b32 m0, s75
	v_lshl_add_u64 v[220:221], s[56:57], 0, v[142:143]
	global_load_lds_dwordx4 v[218:219], off
	v_lshl_add_u64 v[218:219], s[60:61], 0, v[144:145]
	s_mov_b32 m0, s62
	s_nop 0
	global_load_lds_dwordx4 v[218:219], off
	v_lshl_add_u64 v[218:219], s[56:57], 0, v[138:139]
	s_mov_b32 m0, s86
	s_nop 0
	global_load_lds_dwordx4 v[218:219], off
	s_mov_b32 m0, s87
	s_nop 0
	global_load_lds_dwordx4 v[220:221], off
	s_waitcnt vmcnt(8)
	s_waitcnt lgkmcnt(0)
	s_barrier
; #define PG8_STAGE(bufoff, gbase, voff) do { _Pragma("unroll") for (int _i = 0; _i < 2; ++_i) \
;         __builtin_amdgcn_global_load_lds((const unsigned*)((const char*)(gbase) + (voff)[_i]), (LAS unsigned*)(lds + (bufoff) + ldsw + _i * 8192), 16, 0, 0); } while (0)
; #define PG8_LDA(dst, b, h) do { _Pragma("unroll") for (int m = 0; m < 4; ++m) _Pragma("unroll") for (int k = 0; k < 2; ++k) dst[m][k] = *(const LAS bf16x8*)(lds + PG8_SA(b, h) + aoff + m * 2048 + k * 1024); } while (0)
; #define PG8_LDB(dst, b, h) do { _Pragma("unroll") for (int n = 0; n < 2; ++n) _Pragma("unroll") for (int k = 0; k < 2; ++k) dst[n][k] = *(const LAS bf16x8*)(lds + PG8_SB(b, h) + boff + n * 2048 + k * 1024); } while (0)
; #define PG8_MMA(ai, bj, At, Bt) do { __builtin_amdgcn_s_setprio(1); _Pragma("unroll") for (int m = 0; m < 4; ++m) _Pragma("unroll") for (int n = 0; n < 2; ++n) _Pragma("unroll") for (int k = 0; k < 2; ++k) \
;         acc[ai][bj][m][n] = __builtin_amdgcn_mfma_f32_16x16x32_bf16(Bt[n][k], At[m][k], acc[ai][bj][m][n], 0, 0, 0); __builtin_amdgcn_s_setprio(0); } while (0)
; #define PG8_WAIT_V(n) asm volatile("s_waitcnt vmcnt(" #n ")" ::: "memory")
; #define PG8_WAIT_L(n) asm volatile("s_waitcnt lgkmcnt(" #n ")" ::: "memory")
; #define PG8_BAR __builtin_amdgcn_s_barrier()
; #define PG8_SCHED __builtin_amdgcn_sched_barrier(0)
; template <class Epi>
; __device__ __forceinline__ void gemm_phase(LAS unsigned char* lds, const Gemm g, int G, int c, const Epi& E) {
;     ...
;             PG8_WAIT_V(8); PG8_WAIT_L(0); PG8_BAR; PG8_MMA(1, 0, At, B0); PG8_MMA(1, 1, At, B1); PG8_BAR; PG8_SCHED;
;             PG8_LDB(B0, 1, 0); PG8_LDB(B1, 1, 1); PG8_SCHED; PG8_LDA(At, 1, 0); PG8_STAGE(PG8_SA(0, 1), a2 + hstepA, voffA);
;             PG8_WAIT_V(8); PG8_WAIT_L(0); PG8_BAR; PG8_MMA(0, 0, At, B0); PG8_MMA(0, 1, At, B1); PG8_BAR; PG8_SCHED;
	s_setprio 1
	s_waitcnt lgkmcnt(0)
	v_mfma_f32_16x16x32_bf16 v[62:65], v[130:133], v[184:187], v[62:65]
	v_mfma_f32_16x16x32_bf16 v[58:61], v[150:153], v[184:187], v[58:61]
	v_mfma_f32_16x16x32_bf16 v[42:45], v[150:153], v[192:195], v[42:45]
	v_mfma_f32_16x16x32_bf16 v[46:49], v[130:133], v[192:195], v[46:49]
	v_mfma_f32_16x16x32_bf16 v[30:33], v[130:133], v[200:203], v[30:33]
	v_mfma_f32_16x16x32_bf16 v[26:29], v[150:153], v[200:203], v[26:29]
	v_mfma_f32_16x16x32_bf16 v[10:13], v[150:153], v[208:211], v[10:13]
	v_mfma_f32_16x16x32_bf16 v[14:17], v[130:133], v[208:211], v[14:17]
	v_mfma_f32_16x16x32_bf16 v[62:65], v[134:137], v[188:191], v[62:65]
	v_mfma_f32_16x16x32_bf16 v[58:61], v[154:157], v[188:191], v[58:61]
	v_mfma_f32_16x16x32_bf16 v[42:45], v[154:157], v[196:199], v[42:45]
	v_mfma_f32_16x16x32_bf16 v[46:49], v[134:137], v[196:199], v[46:49]
	v_mfma_f32_16x16x32_bf16 v[30:33], v[134:137], v[204:207], v[30:33]
	v_mfma_f32_16x16x32_bf16 v[26:29], v[154:157], v[204:207], v[26:29]
	v_mfma_f32_16x16x32_bf16 v[10:13], v[154:157], v[212:215], v[10:13]
	v_mfma_f32_16x16x32_bf16 v[14:17], v[134:137], v[212:215], v[14:17]
	s_setprio 0
	s_setprio 1
	v_mfma_f32_16x16x32_bf16 v[54:57], v[158:161], v[184:187], v[54:57]
	v_mfma_f32_16x16x32_bf16 v[50:53], v[176:179], v[184:187], v[50:53]
	v_mfma_f32_16x16x32_bf16 v[34:37], v[176:179], v[192:195], v[34:37]
	v_mfma_f32_16x16x32_bf16 v[38:41], v[158:161], v[192:195], v[38:41]
	v_mfma_f32_16x16x32_bf16 v[22:25], v[158:161], v[200:203], v[22:25]
	v_mfma_f32_16x16x32_bf16 v[18:21], v[176:179], v[200:203], v[18:21]
	v_mfma_f32_16x16x32_bf16 v[2:5], v[176:179], v[208:211], v[2:5]
	v_mfma_f32_16x16x32_bf16 v[6:9], v[158:161], v[208:211], v[6:9]
	v_mfma_f32_16x16x32_bf16 v[54:57], v[172:175], v[188:191], v[54:57]
	v_mfma_f32_16x16x32_bf16 v[50:53], v[180:183], v[188:191], v[50:53]
	v_mfma_f32_16x16x32_bf16 v[34:37], v[180:183], v[196:199], v[34:37]
	v_mfma_f32_16x16x32_bf16 v[38:41], v[172:175], v[196:199], v[38:41]
	v_mfma_f32_16x16x32_bf16 v[22:25], v[172:175], v[204:207], v[22:25]
	v_mfma_f32_16x16x32_bf16 v[18:21], v[180:183], v[204:207], v[18:21]
	v_mfma_f32_16x16x32_bf16 v[2:5], v[180:183], v[212:215], v[2:5]
	v_mfma_f32_16x16x32_bf16 v[6:9], v[172:175], v[212:215], v[6:9]
	s_setprio 0
	s_barrier
	v_add_u32_e32 v154, vcc_hi, v165
	v_add_u32_e32 v180, vcc_lo, v165
	ds_read_b128 v[130:133], v154
	ds_read_b128 v[134:137], v154 offset:1024
	ds_read_b128 v[150:153], v154 offset:2048
	ds_read_b128 v[154:157], v154 offset:3072
	ds_read_b128 v[158:161], v180
	ds_read_b128 v[172:175], v180 offset:1024
	ds_read_b128 v[176:179], v180 offset:2048
	ds_read_b128 v[180:183], v180 offset:3072
	s_mov_b32 m0, s88
	v_lshl_add_u64 v[222:223], s[54:55], 0, v[138:139]
	ds_read_b128 v[184:187], v168 offset:32768
	ds_read_b128 v[188:191], v168 offset:33792
	ds_read_b128 v[192:195], v168 offset:34816
	ds_read_b128 v[196:199], v168 offset:35840
	ds_read_b128 v[200:203], v168 offset:36864
	ds_read_b128 v[204:207], v168 offset:37888
	ds_read_b128 v[208:211], v168 offset:38912
	ds_read_b128 v[212:215], v168 offset:39936
	global_load_lds_dwordx4 v[222:223], off
	v_lshl_add_u64 v[222:223], s[54:55], 0, v[142:143]
	s_mov_b32 m0, s89
	s_nop 0
	global_load_lds_dwordx4 v[222:223], off
	s_waitcnt vmcnt(8)
	s_waitcnt lgkmcnt(0)
	s_barrier
	s_setprio 1
	s_waitcnt lgkmcnt(0)
	v_mfma_f32_16x16x32_bf16 v[126:129], v[130:133], v[184:187], v[126:129]
	v_mfma_f32_16x16x32_bf16 v[122:125], v[150:153], v[184:187], v[122:125]
	v_mfma_f32_16x16x32_bf16 v[106:109], v[150:153], v[192:195], v[106:109]
	v_mfma_f32_16x16x32_bf16 v[110:113], v[130:133], v[192:195], v[110:113]
	v_mfma_f32_16x16x32_bf16 v[94:97], v[130:133], v[200:203], v[94:97]
	v_mfma_f32_16x16x32_bf16 v[90:93], v[150:153], v[200:203], v[90:93]
	v_mfma_f32_16x16x32_bf16 v[74:77], v[150:153], v[208:211], v[74:77]
	v_mfma_f32_16x16x32_bf16 v[78:81], v[130:133], v[208:211], v[78:81]
	v_mfma_f32_16x16x32_bf16 v[126:129], v[134:137], v[188:191], v[126:129]
	v_mfma_f32_16x16x32_bf16 v[122:125], v[154:157], v[188:191], v[122:125]
	v_mfma_f32_16x16x32_bf16 v[106:109], v[154:157], v[196:199], v[106:109]
	v_mfma_f32_16x16x32_bf16 v[110:113], v[134:137], v[196:199], v[110:113]
	v_mfma_f32_16x16x32_bf16 v[94:97], v[134:137], v[204:207], v[94:97]
	v_mfma_f32_16x16x32_bf16 v[90:93], v[154:157], v[204:207], v[90:93]
	v_mfma_f32_16x16x32_bf16 v[74:77], v[154:157], v[212:215], v[74:77]
	v_mfma_f32_16x16x32_bf16 v[78:81], v[134:137], v[212:215], v[78:81]
	s_setprio 0
	s_setprio 1
	v_mfma_f32_16x16x32_bf16 v[118:121], v[158:161], v[184:187], v[118:121]
	v_mfma_f32_16x16x32_bf16 v[114:117], v[176:179], v[184:187], v[114:117]
	v_mfma_f32_16x16x32_bf16 v[98:101], v[176:179], v[192:195], v[98:101]
	v_mfma_f32_16x16x32_bf16 v[102:105], v[158:161], v[192:195], v[102:105]
	v_mfma_f32_16x16x32_bf16 v[86:89], v[158:161], v[200:203], v[86:89]
	v_mfma_f32_16x16x32_bf16 v[82:85], v[176:179], v[200:203], v[82:85]
	v_mfma_f32_16x16x32_bf16 v[66:69], v[176:179], v[208:211], v[66:69]
	v_mfma_f32_16x16x32_bf16 v[70:73], v[158:161], v[208:211], v[70:73]
	v_mfma_f32_16x16x32_bf16 v[118:121], v[172:175], v[188:191], v[118:121]
	v_mfma_f32_16x16x32_bf16 v[114:117], v[180:183], v[188:191], v[114:117]
	v_mfma_f32_16x16x32_bf16 v[98:101], v[180:183], v[196:199], v[98:101]
	v_mfma_f32_16x16x32_bf16 v[102:105], v[172:175], v[196:199], v[102:105]
	v_mfma_f32_16x16x32_bf16 v[86:89], v[172:175], v[204:207], v[86:89]
	v_mfma_f32_16x16x32_bf16 v[82:85], v[180:183], v[204:207], v[82:85]
	v_mfma_f32_16x16x32_bf16 v[66:69], v[180:183], v[212:215], v[66:69]
	v_mfma_f32_16x16x32_bf16 v[70:73], v[172:175], v[212:215], v[70:73]
	s_setprio 0
	s_barrier
; #define PG8_STAGE(bufoff, gbase, voff) do { _Pragma("unroll") for (int _i = 0; _i < 2; ++_i) \
;         __builtin_amdgcn_global_load_lds((const unsigned*)((const char*)(gbase) + (voff)[_i]), (LAS unsigned*)(lds + (bufoff) + ldsw + _i * 8192), 16, 0, 0); } while (0)
; #define PG8_LDA(dst, b, h) do { _Pragma("unroll") for (int m = 0; m < 4; ++m) _Pragma("unroll") for (int k = 0; k < 2; ++k) dst[m][k] = *(const LAS bf16x8*)(lds + PG8_SA(b, h) + aoff + m * 2048 + k * 1024); } while (0)
; #define PG8_MMA(ai, bj, At, Bt) do { __builtin_amdgcn_s_setprio(1); _Pragma("unroll") for (int m = 0; m < 4; ++m) _Pragma("unroll") for (int n = 0; n < 2; ++n) _Pragma("unroll") for (int k = 0; k < 2; ++k) \
;         acc[ai][bj][m][n] = __builtin_amdgcn_mfma_f32_16x16x32_bf16(Bt[n][k], At[m][k], acc[ai][bj][m][n], 0, 0, 0); __builtin_amdgcn_s_setprio(0); } while (0)
; #define PG8_WAIT_V(n) asm volatile("s_waitcnt vmcnt(" #n ")" ::: "memory")
; #define PG8_WAIT_L(n) asm volatile("s_waitcnt lgkmcnt(" #n ")" ::: "memory")
; #define PG8_BAR __builtin_amdgcn_s_barrier()
; #define PG8_SCHED __builtin_amdgcn_sched_barrier(0)
; template <class Epi>
; __device__ __forceinline__ void gemm_phase(LAS unsigned char* lds, const Gemm g, int G, int c, const Epi& E) {
;     ...
;             PG8_LDA(At, 1, 1); PG8_STAGE(PG8_SB(1, 0), b3, voffB); PG8_STAGE(PG8_SB(1, 1), b3 + hstepB, voffB); PG8_STAGE(PG8_SA(1, 0), a3, voffA);
;             PG8_WAIT_V(8); PG8_WAIT_L(0); PG8_BAR; PG8_MMA(1, 0, At, B0); PG8_MMA(1, 1, At, B1); PG8_BAR; PG8_SCHED;
;         }
;         if (wr == 0) PG8_BAR;
	s_mov_b32 m0, s39
	v_lshl_add_u64 v[162:163], v[162:163], 0, s[24:25]
	ds_read_b128 v[184:187], v168 offset:49152
	ds_read_b128 v[188:191], v168 offset:50176
	ds_read_b128 v[192:195], v168 offset:51200
	ds_read_b128 v[196:199], v168 offset:52224
	ds_read_b128 v[200:203], v168 offset:53248
	ds_read_b128 v[204:207], v168 offset:54272
	ds_read_b128 v[208:211], v168 offset:55296
	ds_read_b128 v[212:215], v168 offset:56320
	global_load_lds_dwordx4 v[162:163], off
	v_lshl_add_u64 v[162:163], v[216:217], 0, s[24:25]
	s_mov_b32 m0, s73
	s_nop 0
	global_load_lds_dwordx4 v[162:163], off
	v_lshl_add_u64 v[162:163], s[10:11], 0, v[140:141]
	s_mov_b32 m0, s38
	s_nop 0
	global_load_lds_dwordx4 v[162:163], off
	v_lshl_add_u64 v[162:163], s[10:11], 0, v[144:145]
	s_mov_b32 m0, s33
	s_nop 0
	global_load_lds_dwordx4 v[162:163], off
	v_lshl_add_u64 v[162:163], v[218:219], 0, s[24:25]
	s_mov_b32 m0, s93
	s_nop 0
	global_load_lds_dwordx4 v[162:163], off
	v_lshl_add_u64 v[162:163], v[220:221], 0, s[24:25]
	s_mov_b32 m0, s94
	s_nop 0
	global_load_lds_dwordx4 v[162:163], off
	s_waitcnt vmcnt(8)
	s_waitcnt lgkmcnt(0)
	s_barrier
	s_setprio 1
	s_waitcnt lgkmcnt(0)
	v_mfma_f32_16x16x32_bf16 v[62:65], v[130:133], v[184:187], v[62:65]
	v_mfma_f32_16x16x32_bf16 v[58:61], v[150:153], v[184:187], v[58:61]
	v_mfma_f32_16x16x32_bf16 v[42:45], v[150:153], v[192:195], v[42:45]
	v_mfma_f32_16x16x32_bf16 v[46:49], v[130:133], v[192:195], v[46:49]
	v_mfma_f32_16x16x32_bf16 v[30:33], v[130:133], v[200:203], v[30:33]
	v_mfma_f32_16x16x32_bf16 v[26:29], v[150:153], v[200:203], v[26:29]
	v_mfma_f32_16x16x32_bf16 v[10:13], v[150:153], v[208:211], v[10:13]
	v_mfma_f32_16x16x32_bf16 v[14:17], v[130:133], v[208:211], v[14:17]
	v_mfma_f32_16x16x32_bf16 v[62:65], v[134:137], v[188:191], v[62:65]
	v_mfma_f32_16x16x32_bf16 v[58:61], v[154:157], v[188:191], v[58:61]
	v_mfma_f32_16x16x32_bf16 v[42:45], v[154:157], v[196:199], v[42:45]
	v_mfma_f32_16x16x32_bf16 v[46:49], v[134:137], v[196:199], v[46:49]
	v_mfma_f32_16x16x32_bf16 v[30:33], v[134:137], v[204:207], v[30:33]
	v_mfma_f32_16x16x32_bf16 v[26:29], v[154:157], v[204:207], v[26:29]
	v_mfma_f32_16x16x32_bf16 v[10:13], v[154:157], v[212:215], v[10:13]
	v_mfma_f32_16x16x32_bf16 v[14:17], v[134:137], v[212:215], v[14:17]
	s_setprio 0
	s_setprio 1
	v_mfma_f32_16x16x32_bf16 v[54:57], v[158:161], v[184:187], v[54:57]
	v_mfma_f32_16x16x32_bf16 v[50:53], v[176:179], v[184:187], v[50:53]
	v_mfma_f32_16x16x32_bf16 v[34:37], v[176:179], v[192:195], v[34:37]
	v_mfma_f32_16x16x32_bf16 v[38:41], v[158:161], v[192:195], v[38:41]
	v_mfma_f32_16x16x32_bf16 v[22:25], v[158:161], v[200:203], v[22:25]
	v_mfma_f32_16x16x32_bf16 v[18:21], v[176:179], v[200:203], v[18:21]
	v_mfma_f32_16x16x32_bf16 v[2:5], v[176:179], v[208:211], v[2:5]
	v_mfma_f32_16x16x32_bf16 v[6:9], v[158:161], v[208:211], v[6:9]
	v_mfma_f32_16x16x32_bf16 v[54:57], v[172:175], v[188:191], v[54:57]
	v_mfma_f32_16x16x32_bf16 v[50:53], v[180:183], v[188:191], v[50:53]
	v_mfma_f32_16x16x32_bf16 v[34:37], v[180:183], v[196:199], v[34:37]
	v_mfma_f32_16x16x32_bf16 v[38:41], v[172:175], v[196:199], v[38:41]
	v_mfma_f32_16x16x32_bf16 v[22:25], v[172:175], v[204:207], v[22:25]
	v_mfma_f32_16x16x32_bf16 v[18:21], v[180:183], v[204:207], v[18:21]
	v_mfma_f32_16x16x32_bf16 v[2:5], v[180:183], v[212:215], v[2:5]
	v_mfma_f32_16x16x32_bf16 v[6:9], v[172:175], v[212:215], v[6:9]
	s_setprio 0
	s_barrier
	s_movk_i32 s38, 0x100
	s_andn2_b64 vcc, exec, s[4:5]
	s_mov_b64 s[10:11], -1
	s_mov_b64 s[4:5], 0
	s_cbranch_vccz .LBB0_476
	s_and_b64 vcc, exec, s[44:45]
	s_cbranch_vccz .LBB0_479
	s_barrier

; #define PG8_STAGE(bufoff, gbase, voff) do { _Pragma("unroll") for (int _i = 0; _i < 2; ++_i) \
;         __builtin_amdgcn_global_load_lds((const unsigned*)((const char*)(gbase) + (voff)[_i]), (LAS unsigned*)(lds + (bufoff) + ldsw + _i * 8192), 16, 0, 0); } while (0)
; #define PG8_LDA(dst, b, h) do { _Pragma("unroll") for (int m = 0; m < 4; ++m) _Pragma("unroll") for (int k = 0; k < 2; ++k) dst[m][k] = *(const LAS bf16x8*)(lds + PG8_SA(b, h) + aoff + m * 2048 + k * 1024); } while (0)
; #define PG8_LDB(dst, b, h) do { _Pragma("unroll") for (int n = 0; n < 2; ++n) _Pragma("unroll") for (int k = 0; k < 2; ++k) dst[n][k] = *(const LAS bf16x8*)(lds + PG8_SB(b, h) + boff + n * 2048 + k * 1024); } while (0)
; #define PG8_MMA(ai, bj, At, Bt) do { __builtin_amdgcn_s_setprio(1); _Pragma("unroll") for (int m = 0; m < 4; ++m) _Pragma("unroll") for (int n = 0; n < 2; ++n) _Pragma("unroll") for (int k = 0; k < 2; ++k) \
;         acc[ai][bj][m][n] = __builtin_amdgcn_mfma_f32_16x16x32_bf16(Bt[n][k], At[m][k], acc[ai][bj][m][n], 0, 0, 0); __builtin_amdgcn_s_setprio(0); } while (0)
; #define PG8_WAIT_V(n) asm volatile("s_waitcnt vmcnt(" #n ")" ::: "memory")
; #define PG8_WAIT_L(n) asm volatile("s_waitcnt lgkmcnt(" #n ")" ::: "memory")
; #define PG8_BAR __builtin_amdgcn_s_barrier()
; #define PG8_SCHED __builtin_amdgcn_sched_barrier(0)
; template <class Epi>
; __device__ __forceinline__ void gemm_phase(LAS unsigned char* lds, const Gemm g, int G, int c, const Epi& E) {
;     ...
;             const bool last = (t == nt - 2);
;             const char* a1 = cA + (size_t)(t + 1) * kstep;
;             const char* a2 = last ? nA : cA + (size_t)(t + 2) * kstep; const char* b2 = last ? nB : cB + (size_t)(t + 2) * kstep;
;             const char* a3 = a2 + kstep; const char* b3 = b2 + kstep;
;             PG8_LDB(B0, 0, 0); PG8_LDB(B1, 0, 1); PG8_SCHED; PG8_LDA(At, 0, 0); PG8_STAGE(PG8_SA(1, 1), a1 + hstepA, voffA);
;             PG8_WAIT_V(8); PG8_WAIT_L(0); PG8_BAR; PG8_MMA(0, 0, At, B0); PG8_MMA(0, 1, At, B1); PG8_BAR; PG8_SCHED;
;             PG8_LDA(At, 0, 1); PG8_STAGE(PG8_SB(0, 0), b2, voffB); PG8_STAGE(PG8_SB(0, 1), b2 + hstepB, voffB); PG8_STAGE(PG8_SA(0, 0), a2, voffA);
.LBB0_594:
	s_add_u32 s33, s8, s38
	s_addc_u32 s62, s9, 0
	s_add_u32 s39, s33, 0x100
	s_addc_u32 s58, s62, 0
	s_and_b64 s[56:57], s[54:55], exec
	s_cselect_b32 s59, s45, s58
	s_cselect_b32 s58, s44, s39
	s_add_u32 s38, s6, s38
	s_addc_u32 s39, s7, 0
	s_add_u32 s56, s38, 0x100
	s_addc_u32 s57, s39, 0
	s_and_b64 s[38:39], s[54:55], exec
	s_cselect_b32 s61, s47, s57
	s_cselect_b32 s60, s46, s56
	s_add_u32 s68, s33, 0xb0080
	s_addc_u32 s69, s62, 0
	s_add_i32 s63, s86, s23
	ds_read_b128 v[142:145], v166
	ds_read_b128 v[146:149], v166 offset:1024
	ds_read_b128 v[150:153], v166 offset:2048
	ds_read_b128 v[154:157], v166 offset:3072
	ds_read_b128 v[158:161], v167
	ds_read_b128 v[170:173], v167 offset:1024
	ds_read_b128 v[174:177], v167 offset:2048
	ds_read_b128 v[178:181], v167 offset:3072
	s_add_i32 m0, s72, 0xc000
	s_add_i32 s64, s72, 0xe000
	s_add_i32 s74, s63, 0x2000
	s_add_u32 s66, s60, 0xb0000
	s_addc_u32 s67, s61, 0
	s_add_i32 s62, s87, s23
	s_add_i32 s75, s62, 0x2000
	s_add_i32 s97, 0, 0x18000
	s_add_i32 s33, 0, 0x1c000
	s_add_u32 s56, s58, 0xb0000
	s_addc_u32 s57, s59, 0
	s_add_i32 s96, s97, s23
	s_add_i32 s39, s96, 0x2000
	s_add_u32 s54, s60, 0xb0080
	s_addc_u32 s55, s61, 0
	s_add_i32 s95, s33, s23
	s_add_i32 s38, s95, 0x2000
	v_lshl_add_u64 v[162:163], s[68:69], 0, v[136:137]
	ds_read_b128 v[182:185], v168
	ds_read_b128 v[186:189], v168 offset:1024
	ds_read_b128 v[190:193], v168 offset:2048
	ds_read_b128 v[194:197], v168 offset:3072
	ds_read_b128 v[198:201], v168 offset:4096
	ds_read_b128 v[202:205], v168 offset:5120
	ds_read_b128 v[206:209], v168 offset:6144
	ds_read_b128 v[210:213], v168 offset:7168
	global_load_lds_dwordx4 v[162:163], off
	v_lshl_add_u64 v[162:163], s[68:69], 0, v[132:133]
	s_mov_b32 m0, s64
	s_nop 0
	global_load_lds_dwordx4 v[162:163], off
	s_waitcnt vmcnt(8)
	s_waitcnt lgkmcnt(0)
	s_barrier
	s_setprio 1
	s_waitcnt lgkmcnt(0)
	v_mfma_f32_16x16x32_bf16 v[126:129], v[142:145], v[182:185], v[126:129]
	v_mfma_f32_16x16x32_bf16 v[122:125], v[150:153], v[182:185], v[122:125]
	v_mfma_f32_16x16x32_bf16 v[106:109], v[150:153], v[190:193], v[106:109]
	v_mfma_f32_16x16x32_bf16 v[110:113], v[142:145], v[190:193], v[110:113]
	v_mfma_f32_16x16x32_bf16 v[94:97], v[142:145], v[198:201], v[94:97]
	v_mfma_f32_16x16x32_bf16 v[90:93], v[150:153], v[198:201], v[90:93]
	v_mfma_f32_16x16x32_bf16 v[74:77], v[150:153], v[206:209], v[74:77]
	v_mfma_f32_16x16x32_bf16 v[78:81], v[142:145], v[206:209], v[78:81]
	v_mfma_f32_16x16x32_bf16 v[126:129], v[146:149], v[186:189], v[126:129]
	v_mfma_f32_16x16x32_bf16 v[122:125], v[154:157], v[186:189], v[122:125]
	v_mfma_f32_16x16x32_bf16 v[106:109], v[154:157], v[194:197], v[106:109]
	v_mfma_f32_16x16x32_bf16 v[110:113], v[146:149], v[194:197], v[110:113]
	v_mfma_f32_16x16x32_bf16 v[94:97], v[146:149], v[202:205], v[94:97]
	v_mfma_f32_16x16x32_bf16 v[90:93], v[154:157], v[202:205], v[90:93]
	v_mfma_f32_16x16x32_bf16 v[74:77], v[154:157], v[210:213], v[74:77]
	v_mfma_f32_16x16x32_bf16 v[78:81], v[146:149], v[210:213], v[78:81]
	s_setprio 0
	s_setprio 1
	v_mfma_f32_16x16x32_bf16 v[118:121], v[158:161], v[182:185], v[118:121]
	v_mfma_f32_16x16x32_bf16 v[114:117], v[174:177], v[182:185], v[114:117]
	v_mfma_f32_16x16x32_bf16 v[98:101], v[174:177], v[190:193], v[98:101]
	v_mfma_f32_16x16x32_bf16 v[102:105], v[158:161], v[190:193], v[102:105]
	v_mfma_f32_16x16x32_bf16 v[86:89], v[158:161], v[198:201], v[86:89]
	v_mfma_f32_16x16x32_bf16 v[82:85], v[174:177], v[198:201], v[82:85]
	v_mfma_f32_16x16x32_bf16 v[66:69], v[174:177], v[206:209], v[66:69]
	v_mfma_f32_16x16x32_bf16 v[70:73], v[158:161], v[206:209], v[70:73]
	v_mfma_f32_16x16x32_bf16 v[118:121], v[170:173], v[186:189], v[118:121]
	v_mfma_f32_16x16x32_bf16 v[114:117], v[178:181], v[186:189], v[114:117]
	v_mfma_f32_16x16x32_bf16 v[98:101], v[178:181], v[194:197], v[98:101]
	v_mfma_f32_16x16x32_bf16 v[102:105], v[170:173], v[194:197], v[102:105]
	v_mfma_f32_16x16x32_bf16 v[86:89], v[170:173], v[202:205], v[86:89]
	v_mfma_f32_16x16x32_bf16 v[82:85], v[178:181], v[202:205], v[82:85]
	v_mfma_f32_16x16x32_bf16 v[66:69], v[178:181], v[210:213], v[66:69]
	v_mfma_f32_16x16x32_bf16 v[70:73], v[170:173], v[210:213], v[70:73]
	s_setprio 0
	s_barrier
	s_mov_b32 m0, s63
	v_lshl_add_u64 v[162:163], s[60:61], 0, v[134:135]
	ds_read_b128 v[182:185], v168 offset:16384
	ds_read_b128 v[186:189], v168 offset:17408
	ds_read_b128 v[190:193], v168 offset:18432
	ds_read_b128 v[194:197], v168 offset:19456
	ds_read_b128 v[198:201], v168 offset:20480
	ds_read_b128 v[202:205], v168 offset:21504
	ds_read_b128 v[206:209], v168 offset:22528
	ds_read_b128 v[210:213], v168 offset:23552
	global_load_lds_dwordx4 v[162:163], off
	v_lshl_add_u64 v[214:215], s[60:61], 0, v[130:131]
	s_mov_b32 m0, s74
	v_lshl_add_u64 v[216:217], s[66:67], 0, v[134:135]
	global_load_lds_dwordx4 v[214:215], off
	s_mov_b32 m0, s62
	v_lshl_add_u64 v[218:219], s[58:59], 0, v[132:133]
	global_load_lds_dwordx4 v[216:217], off
	v_lshl_add_u64 v[216:217], s[66:67], 0, v[130:131]
	s_mov_b32 m0, s75
	s_nop 0
	global_load_lds_dwordx4 v[216:217], off
	v_lshl_add_u64 v[216:217], s[58:59], 0, v[136:137]
	s_mov_b32 m0, s72
	s_nop 0
	global_load_lds_dwordx4 v[216:217], off
	s_mov_b32 m0, s73
	s_nop 0
	global_load_lds_dwordx4 v[218:219], off
	s_waitcnt vmcnt(8)
	s_waitcnt lgkmcnt(0)
	s_barrier
; #define PG8_STAGE(bufoff, gbase, voff) do { _Pragma("unroll") for (int _i = 0; _i < 2; ++_i) \
;         __builtin_amdgcn_global_load_lds((const unsigned*)((const char*)(gbase) + (voff)[_i]), (LAS unsigned*)(lds + (bufoff) + ldsw + _i * 8192), 16, 0, 0); } while (0)
; #define PG8_LDA(dst, b, h) do { _Pragma("unroll") for (int m = 0; m < 4; ++m) _Pragma("unroll") for (int k = 0; k < 2; ++k) dst[m][k] = *(const LAS bf16x8*)(lds + PG8_SA(b, h) + aoff + m * 2048 + k * 1024); } while (0)
; #define PG8_LDB(dst, b, h) do { _Pragma("unroll") for (int n = 0; n < 2; ++n) _Pragma("unroll") for (int k = 0; k < 2; ++k) dst[n][k] = *(const LAS bf16x8*)(lds + PG8_SB(b, h) + boff + n * 2048 + k * 1024); } while (0)
; #define PG8_MMA(ai, bj, At, Bt) do { __builtin_amdgcn_s_setprio(1); _Pragma("unroll") for (int m = 0; m < 4; ++m) _Pragma("unroll") for (int n = 0; n < 2; ++n) _Pragma("unroll") for (int k = 0; k < 2; ++k) \
;         acc[ai][bj][m][n] = __builtin_amdgcn_mfma_f32_16x16x32_bf16(Bt[n][k], At[m][k], acc[ai][bj][m][n], 0, 0, 0); __builtin_amdgcn_s_setprio(0); } while (0)
; #define PG8_WAIT_V(n) asm volatile("s_waitcnt vmcnt(" #n ")" ::: "memory")
; #define PG8_WAIT_L(n) asm volatile("s_waitcnt lgkmcnt(" #n ")" ::: "memory")
; #define PG8_BAR __builtin_amdgcn_s_barrier()
; #define PG8_SCHED __builtin_amdgcn_sched_barrier(0)
; template <class Epi>
; __device__ __forceinline__ void gemm_phase(LAS unsigned char* lds, const Gemm g, int G, int c, const Epi& E) {
;     ...
;             PG8_WAIT_V(8); PG8_WAIT_L(0); PG8_BAR; PG8_MMA(1, 0, At, B0); PG8_MMA(1, 1, At, B1); PG8_BAR; PG8_SCHED;
;             PG8_LDB(B0, 1, 0); PG8_LDB(B1, 1, 1); PG8_SCHED; PG8_LDA(At, 1, 0); PG8_STAGE(PG8_SA(0, 1), a2 + hstepA, voffA);
;             PG8_WAIT_V(8); PG8_WAIT_L(0); PG8_BAR; PG8_MMA(0, 0, At, B0); PG8_MMA(0, 1, At, B1); PG8_BAR; PG8_SCHED;
	s_setprio 1
	s_waitcnt lgkmcnt(0)
	v_mfma_f32_16x16x32_bf16 v[62:65], v[142:145], v[182:185], v[62:65]
	v_mfma_f32_16x16x32_bf16 v[58:61], v[150:153], v[182:185], v[58:61]
	v_mfma_f32_16x16x32_bf16 v[42:45], v[150:153], v[190:193], v[42:45]
	v_mfma_f32_16x16x32_bf16 v[46:49], v[142:145], v[190:193], v[46:49]
	v_mfma_f32_16x16x32_bf16 v[30:33], v[142:145], v[198:201], v[30:33]
	v_mfma_f32_16x16x32_bf16 v[26:29], v[150:153], v[198:201], v[26:29]
	v_mfma_f32_16x16x32_bf16 v[10:13], v[150:153], v[206:209], v[10:13]
	v_mfma_f32_16x16x32_bf16 v[14:17], v[142:145], v[206:209], v[14:17]
	v_mfma_f32_16x16x32_bf16 v[62:65], v[146:149], v[186:189], v[62:65]
	v_mfma_f32_16x16x32_bf16 v[58:61], v[154:157], v[186:189], v[58:61]
	v_mfma_f32_16x16x32_bf16 v[42:45], v[154:157], v[194:197], v[42:45]
	v_mfma_f32_16x16x32_bf16 v[46:49], v[146:149], v[194:197], v[46:49]
	v_mfma_f32_16x16x32_bf16 v[30:33], v[146:149], v[202:205], v[30:33]
	v_mfma_f32_16x16x32_bf16 v[26:29], v[154:157], v[202:205], v[26:29]
	v_mfma_f32_16x16x32_bf16 v[10:13], v[154:157], v[210:213], v[10:13]
	v_mfma_f32_16x16x32_bf16 v[14:17], v[146:149], v[210:213], v[14:17]
	s_setprio 0
	s_setprio 1
	v_mfma_f32_16x16x32_bf16 v[54:57], v[158:161], v[182:185], v[54:57]
	v_mfma_f32_16x16x32_bf16 v[50:53], v[174:177], v[182:185], v[50:53]
	v_mfma_f32_16x16x32_bf16 v[34:37], v[174:177], v[190:193], v[34:37]
	v_mfma_f32_16x16x32_bf16 v[38:41], v[158:161], v[190:193], v[38:41]
	v_mfma_f32_16x16x32_bf16 v[22:25], v[158:161], v[198:201], v[22:25]
	v_mfma_f32_16x16x32_bf16 v[18:21], v[174:177], v[198:201], v[18:21]
	v_mfma_f32_16x16x32_bf16 v[2:5], v[174:177], v[206:209], v[2:5]
	v_mfma_f32_16x16x32_bf16 v[6:9], v[158:161], v[206:209], v[6:9]
	v_mfma_f32_16x16x32_bf16 v[54:57], v[170:173], v[186:189], v[54:57]
	v_mfma_f32_16x16x32_bf16 v[50:53], v[178:181], v[186:189], v[50:53]
	v_mfma_f32_16x16x32_bf16 v[34:37], v[178:181], v[194:197], v[34:37]
	v_mfma_f32_16x16x32_bf16 v[38:41], v[170:173], v[194:197], v[38:41]
	v_mfma_f32_16x16x32_bf16 v[22:25], v[170:173], v[202:205], v[22:25]
	v_mfma_f32_16x16x32_bf16 v[18:21], v[178:181], v[202:205], v[18:21]
	v_mfma_f32_16x16x32_bf16 v[2:5], v[178:181], v[210:213], v[2:5]
	v_mfma_f32_16x16x32_bf16 v[6:9], v[170:173], v[210:213], v[6:9]
	s_setprio 0
	s_barrier
	v_add_u32_e32 v154, s97, v165
	v_add_u32_e32 v178, s33, v165
	ds_read_b128 v[142:145], v154
	ds_read_b128 v[146:149], v154 offset:1024
	ds_read_b128 v[150:153], v154 offset:2048
	ds_read_b128 v[154:157], v154 offset:3072
	ds_read_b128 v[158:161], v178
	ds_read_b128 v[170:173], v178 offset:1024
	ds_read_b128 v[174:177], v178 offset:2048
	ds_read_b128 v[178:181], v178 offset:3072
	s_mov_b32 m0, s78
	v_lshl_add_u64 v[220:221], s[56:57], 0, v[136:137]
	ds_read_b128 v[182:185], v168 offset:32768
	ds_read_b128 v[186:189], v168 offset:33792
	ds_read_b128 v[190:193], v168 offset:34816
	ds_read_b128 v[194:197], v168 offset:35840
	ds_read_b128 v[198:201], v168 offset:36864
	ds_read_b128 v[202:205], v168 offset:37888
	ds_read_b128 v[206:209], v168 offset:38912
	ds_read_b128 v[210:213], v168 offset:39936
	global_load_lds_dwordx4 v[220:221], off
	v_lshl_add_u64 v[220:221], s[56:57], 0, v[132:133]
	s_mov_b32 m0, s81
	s_nop 0
	global_load_lds_dwordx4 v[220:221], off
	s_waitcnt vmcnt(8)
	s_waitcnt lgkmcnt(0)
	s_barrier
	s_setprio 1
	s_waitcnt lgkmcnt(0)
	v_mfma_f32_16x16x32_bf16 v[126:129], v[142:145], v[182:185], v[126:129]
	v_mfma_f32_16x16x32_bf16 v[122:125], v[150:153], v[182:185], v[122:125]
	v_mfma_f32_16x16x32_bf16 v[106:109], v[150:153], v[190:193], v[106:109]
	v_mfma_f32_16x16x32_bf16 v[110:113], v[142:145], v[190:193], v[110:113]
	v_mfma_f32_16x16x32_bf16 v[94:97], v[142:145], v[198:201], v[94:97]
	v_mfma_f32_16x16x32_bf16 v[90:93], v[150:153], v[198:201], v[90:93]
	v_mfma_f32_16x16x32_bf16 v[74:77], v[150:153], v[206:209], v[74:77]
	v_mfma_f32_16x16x32_bf16 v[78:81], v[142:145], v[206:209], v[78:81]
	v_mfma_f32_16x16x32_bf16 v[126:129], v[146:149], v[186:189], v[126:129]
	v_mfma_f32_16x16x32_bf16 v[122:125], v[154:157], v[186:189], v[122:125]
	v_mfma_f32_16x16x32_bf16 v[106:109], v[154:157], v[194:197], v[106:109]
	v_mfma_f32_16x16x32_bf16 v[110:113], v[146:149], v[194:197], v[110:113]
	v_mfma_f32_16x16x32_bf16 v[94:97], v[146:149], v[202:205], v[94:97]
	v_mfma_f32_16x16x32_bf16 v[90:93], v[154:157], v[202:205], v[90:93]
	v_mfma_f32_16x16x32_bf16 v[74:77], v[154:157], v[210:213], v[74:77]
	v_mfma_f32_16x16x32_bf16 v[78:81], v[146:149], v[210:213], v[78:81]
	s_setprio 0
	s_setprio 1
	v_mfma_f32_16x16x32_bf16 v[118:121], v[158:161], v[182:185], v[118:121]
	v_mfma_f32_16x16x32_bf16 v[114:117], v[174:177], v[182:185], v[114:117]
	v_mfma_f32_16x16x32_bf16 v[98:101], v[174:177], v[190:193], v[98:101]
	v_mfma_f32_16x16x32_bf16 v[102:105], v[158:161], v[190:193], v[102:105]
	v_mfma_f32_16x16x32_bf16 v[86:89], v[158:161], v[198:201], v[86:89]
	v_mfma_f32_16x16x32_bf16 v[82:85], v[174:177], v[198:201], v[82:85]
	v_mfma_f32_16x16x32_bf16 v[66:69], v[174:177], v[206:209], v[66:69]
	v_mfma_f32_16x16x32_bf16 v[70:73], v[158:161], v[206:209], v[70:73]
	v_mfma_f32_16x16x32_bf16 v[118:121], v[170:173], v[186:189], v[118:121]
	v_mfma_f32_16x16x32_bf16 v[114:117], v[178:181], v[186:189], v[114:117]
	v_mfma_f32_16x16x32_bf16 v[98:101], v[178:181], v[194:197], v[98:101]
	v_mfma_f32_16x16x32_bf16 v[102:105], v[170:173], v[194:197], v[102:105]
	v_mfma_f32_16x16x32_bf16 v[86:89], v[170:173], v[202:205], v[86:89]
	v_mfma_f32_16x16x32_bf16 v[82:85], v[178:181], v[202:205], v[82:85]
	v_mfma_f32_16x16x32_bf16 v[66:69], v[178:181], v[210:213], v[66:69]
	v_mfma_f32_16x16x32_bf16 v[70:73], v[170:173], v[210:213], v[70:73]
	s_setprio 0
	s_barrier
; #define PG8_STAGE(bufoff, gbase, voff) do { _Pragma("unroll") for (int _i = 0; _i < 2; ++_i) \
;         __builtin_amdgcn_global_load_lds((const unsigned*)((const char*)(gbase) + (voff)[_i]), (LAS unsigned*)(lds + (bufoff) + ldsw + _i * 8192), 16, 0, 0); } while (0)
; #define PG8_LDA(dst, b, h) do { _Pragma("unroll") for (int m = 0; m < 4; ++m) _Pragma("unroll") for (int k = 0; k < 2; ++k) dst[m][k] = *(const LAS bf16x8*)(lds + PG8_SA(b, h) + aoff + m * 2048 + k * 1024); } while (0)
; #define PG8_MMA(ai, bj, At, Bt) do { __builtin_amdgcn_s_setprio(1); _Pragma("unroll") for (int m = 0; m < 4; ++m) _Pragma("unroll") for (int n = 0; n < 2; ++n) _Pragma("unroll") for (int k = 0; k < 2; ++k) \
;         acc[ai][bj][m][n] = __builtin_amdgcn_mfma_f32_16x16x32_bf16(Bt[n][k], At[m][k], acc[ai][bj][m][n], 0, 0, 0); __builtin_amdgcn_s_setprio(0); } while (0)
; #define PG8_WAIT_V(n) asm volatile("s_waitcnt vmcnt(" #n ")" ::: "memory")
; #define PG8_WAIT_L(n) asm volatile("s_waitcnt lgkmcnt(" #n ")" ::: "memory")
; #define PG8_BAR __builtin_amdgcn_s_barrier()
; #define PG8_SCHED __builtin_amdgcn_sched_barrier(0)
; template <class Epi>
; __device__ __forceinline__ void gemm_phase(LAS unsigned char* lds, const Gemm g, int G, int c, const Epi& E) {
;     ...
;             PG8_LDA(At, 1, 1); PG8_STAGE(PG8_SB(1, 0), b3, voffB); PG8_STAGE(PG8_SB(1, 1), b3 + hstepB, voffB); PG8_STAGE(PG8_SA(1, 0), a3, voffA);
;             PG8_WAIT_V(8); PG8_WAIT_L(0); PG8_BAR; PG8_MMA(1, 0, At, B0); PG8_MMA(1, 1, At, B1); PG8_BAR; PG8_SCHED;
;         }
;         if (wr == 0) PG8_BAR;
	s_mov_b32 m0, s96
	v_lshl_add_u64 v[162:163], v[162:163], 0, s[18:19]
	ds_read_b128 v[182:185], v168 offset:49152
	ds_read_b128 v[186:189], v168 offset:50176
	ds_read_b128 v[190:193], v168 offset:51200
	ds_read_b128 v[194:197], v168 offset:52224
	ds_read_b128 v[198:201], v168 offset:53248
	ds_read_b128 v[202:205], v168 offset:54272
	ds_read_b128 v[206:209], v168 offset:55296
	ds_read_b128 v[210:213], v168 offset:56320
	global_load_lds_dwordx4 v[162:163], off
	v_lshl_add_u64 v[162:163], v[214:215], 0, s[18:19]
	s_mov_b32 m0, s39
	s_nop 0
	global_load_lds_dwordx4 v[162:163], off
	v_lshl_add_u64 v[162:163], s[54:55], 0, v[134:135]
	s_mov_b32 m0, s95
	s_nop 0
	global_load_lds_dwordx4 v[162:163], off
	v_lshl_add_u64 v[162:163], s[54:55], 0, v[130:131]
	s_mov_b32 m0, s38
	s_nop 0
	global_load_lds_dwordx4 v[162:163], off
	v_lshl_add_u64 v[162:163], v[216:217], 0, s[18:19]
	s_mov_b32 m0, s84
	s_nop 0
	global_load_lds_dwordx4 v[162:163], off
	v_lshl_add_u64 v[162:163], v[218:219], 0, s[18:19]
	s_mov_b32 m0, s85
	s_nop 0
	global_load_lds_dwordx4 v[162:163], off
	s_waitcnt vmcnt(8)
	s_waitcnt lgkmcnt(0)
	s_barrier
	s_setprio 1
	s_waitcnt lgkmcnt(0)
	v_mfma_f32_16x16x32_bf16 v[62:65], v[142:145], v[182:185], v[62:65]
	v_mfma_f32_16x16x32_bf16 v[58:61], v[150:153], v[182:185], v[58:61]
	v_mfma_f32_16x16x32_bf16 v[42:45], v[150:153], v[190:193], v[42:45]
	v_mfma_f32_16x16x32_bf16 v[46:49], v[142:145], v[190:193], v[46:49]
	v_mfma_f32_16x16x32_bf16 v[30:33], v[142:145], v[198:201], v[30:33]
	v_mfma_f32_16x16x32_bf16 v[26:29], v[150:153], v[198:201], v[26:29]
	v_mfma_f32_16x16x32_bf16 v[10:13], v[150:153], v[206:209], v[10:13]
	v_mfma_f32_16x16x32_bf16 v[14:17], v[142:145], v[206:209], v[14:17]
	v_mfma_f32_16x16x32_bf16 v[62:65], v[146:149], v[186:189], v[62:65]
	v_mfma_f32_16x16x32_bf16 v[58:61], v[154:157], v[186:189], v[58:61]
	v_mfma_f32_16x16x32_bf16 v[42:45], v[154:157], v[194:197], v[42:45]
	v_mfma_f32_16x16x32_bf16 v[46:49], v[146:149], v[194:197], v[46:49]
	v_mfma_f32_16x16x32_bf16 v[30:33], v[146:149], v[202:205], v[30:33]
	v_mfma_f32_16x16x32_bf16 v[26:29], v[154:157], v[202:205], v[26:29]
	v_mfma_f32_16x16x32_bf16 v[10:13], v[154:157], v[210:213], v[10:13]
	v_mfma_f32_16x16x32_bf16 v[14:17], v[146:149], v[210:213], v[14:17]
	s_setprio 0
	s_setprio 1
	v_mfma_f32_16x16x32_bf16 v[54:57], v[158:161], v[182:185], v[54:57]
	v_mfma_f32_16x16x32_bf16 v[50:53], v[174:177], v[182:185], v[50:53]
	v_mfma_f32_16x16x32_bf16 v[34:37], v[174:177], v[190:193], v[34:37]
	v_mfma_f32_16x16x32_bf16 v[38:41], v[158:161], v[190:193], v[38:41]
	v_mfma_f32_16x16x32_bf16 v[22:25], v[158:161], v[198:201], v[22:25]
	v_mfma_f32_16x16x32_bf16 v[18:21], v[174:177], v[198:201], v[18:21]
	v_mfma_f32_16x16x32_bf16 v[2:5], v[174:177], v[206:209], v[2:5]
	v_mfma_f32_16x16x32_bf16 v[6:9], v[158:161], v[206:209], v[6:9]
	v_mfma_f32_16x16x32_bf16 v[54:57], v[170:173], v[186:189], v[54:57]
	v_mfma_f32_16x16x32_bf16 v[50:53], v[178:181], v[186:189], v[50:53]
	v_mfma_f32_16x16x32_bf16 v[34:37], v[178:181], v[194:197], v[34:37]
	v_mfma_f32_16x16x32_bf16 v[38:41], v[170:173], v[194:197], v[38:41]
	v_mfma_f32_16x16x32_bf16 v[22:25], v[170:173], v[202:205], v[22:25]
	v_mfma_f32_16x16x32_bf16 v[18:21], v[178:181], v[202:205], v[18:21]
	v_mfma_f32_16x16x32_bf16 v[2:5], v[178:181], v[210:213], v[2:5]
	v_mfma_f32_16x16x32_bf16 v[6:9], v[170:173], v[210:213], v[6:9]
	s_setprio 0
	s_barrier
	s_movk_i32 s38, 0x100
	s_andn2_b64 vcc, exec, s[4:5]
	s_mov_b64 s[54:55], -1
	s_mov_b64 s[4:5], 0
	s_cbranch_vccz .LBB0_594
	s_and_b64 vcc, exec, s[20:21]
	s_cbranch_vccz .LBB0_597
	s_barrier

; #define PG8_STAGE(bufoff, gbase, voff) do { _Pragma("unroll") for (int _i = 0; _i < 2; ++_i) \
;         __builtin_amdgcn_global_load_lds((const unsigned*)((const char*)(gbase) + (voff)[_i]), (LAS unsigned*)(lds + (bufoff) + ldsw + _i * 8192), 16, 0, 0); } while (0)
; #define PG8_LDA(dst, b, h) do { _Pragma("unroll") for (int m = 0; m < 4; ++m) _Pragma("unroll") for (int k = 0; k < 2; ++k) dst[m][k] = *(const LAS bf16x8*)(lds + PG8_SA(b, h) + aoff + m * 2048 + k * 1024); } while (0)
; #define PG8_LDB(dst, b, h) do { _Pragma("unroll") for (int n = 0; n < 2; ++n) _Pragma("unroll") for (int k = 0; k < 2; ++k) dst[n][k] = *(const LAS bf16x8*)(lds + PG8_SB(b, h) + boff + n * 2048 + k * 1024); } while (0)
; #define PG8_MMA(ai, bj, At, Bt) do { __builtin_amdgcn_s_setprio(1); _Pragma("unroll") for (int m = 0; m < 4; ++m) _Pragma("unroll") for (int n = 0; n < 2; ++n) _Pragma("unroll") for (int k = 0; k < 2; ++k) \
;         acc[ai][bj][m][n] = __builtin_amdgcn_mfma_f32_16x16x32_bf16(Bt[n][k], At[m][k], acc[ai][bj][m][n], 0, 0, 0); __builtin_amdgcn_s_setprio(0); } while (0)
; #define PG8_WAIT_V(n) asm volatile("s_waitcnt vmcnt(" #n ")" ::: "memory")
; #define PG8_WAIT_L(n) asm volatile("s_waitcnt lgkmcnt(" #n ")" ::: "memory")
; #define PG8_BAR __builtin_amdgcn_s_barrier()
; #define PG8_SCHED __builtin_amdgcn_sched_barrier(0)
; template <class Epi>
; __device__ __forceinline__ void gemm_phase(LAS unsigned char* lds, const Gemm g, int G, int c, const Epi& E) {
;     ...
;             const bool last = (t == nt - 2);
;             const char* a1 = cA + (size_t)(t + 1) * kstep;
;             const char* a2 = last ? nA : cA + (size_t)(t + 2) * kstep; const char* b2 = last ? nB : cB + (size_t)(t + 2) * kstep;
;             const char* a3 = a2 + kstep; const char* b3 = b2 + kstep;
;             PG8_LDB(B0, 0, 0); PG8_LDB(B1, 0, 1); PG8_SCHED; PG8_LDA(At, 0, 0); PG8_STAGE(PG8_SA(1, 1), a1 + hstepA, voffA);
;             PG8_WAIT_V(8); PG8_WAIT_L(0); PG8_BAR; PG8_MMA(0, 0, At, B0); PG8_MMA(0, 1, At, B1); PG8_BAR; PG8_SCHED;
;             PG8_LDA(At, 0, 1); PG8_STAGE(PG8_SB(0, 0), b2, voffB); PG8_STAGE(PG8_SB(0, 1), b2 + hstepB, voffB); PG8_STAGE(PG8_SA(0, 0), a2, voffA);
.LBB0_765:
	ds_read_b128 v[146:149], v152
	ds_read_b128 v[156:159], v152 offset:1024
	ds_read_b128 v[160:163], v152 offset:2048
	ds_read_b128 v[164:167], v152 offset:3072
	ds_read_b128 v[168:171], v153
	ds_read_b128 v[172:175], v153 offset:1024
	ds_read_b128 v[176:179], v153 offset:2048
	ds_read_b128 v[180:183], v153 offset:3072
	s_add_u32 s33, s44, 0xfff00080
	s_addc_u32 s46, s45, -1
	s_cmp_eq_u32 s83, 60
	s_cselect_b32 s53, s15, s46
	s_cselect_b32 s52, s78, s33
	s_cselect_b32 s47, s11, s82
	s_cselect_b32 s46, s13, s81
	v_lshl_add_u64 v[216:217], s[44:45], 0, v[138:139]
	s_add_i32 m0, s17, 0xc000
	ds_read_b128 v[184:187], v154
	ds_read_b128 v[188:191], v154 offset:1024
	ds_read_b128 v[192:195], v154 offset:2048
	ds_read_b128 v[196:199], v154 offset:3072
	ds_read_b128 v[200:203], v154 offset:4096
	ds_read_b128 v[204:207], v154 offset:5120
	ds_read_b128 v[208:211], v154 offset:6144
	ds_read_b128 v[212:215], v154 offset:7168
	global_load_lds_dwordx4 v[216:217], off
	v_lshl_add_u64 v[216:217], s[44:45], 0, v[140:141]
	s_add_i32 m0, s17, 0xe000
	s_nop 0
	global_load_lds_dwordx4 v[216:217], off
	s_waitcnt vmcnt(8)
	s_waitcnt lgkmcnt(0)
	s_barrier
	s_setprio 1
	s_waitcnt lgkmcnt(0)
	v_mfma_f32_16x16x32_bf16 v[126:129], v[146:149], v[184:187], v[126:129]
	v_mfma_f32_16x16x32_bf16 v[122:125], v[160:163], v[184:187], v[122:125]
	v_mfma_f32_16x16x32_bf16 v[110:113], v[160:163], v[192:195], v[110:113]
	v_mfma_f32_16x16x32_bf16 v[118:121], v[146:149], v[192:195], v[118:121]
	v_mfma_f32_16x16x32_bf16 v[102:105], v[146:149], v[200:203], v[102:105]
	v_mfma_f32_16x16x32_bf16 v[94:97], v[160:163], v[200:203], v[94:97]
	v_mfma_f32_16x16x32_bf16 v[78:81], v[160:163], v[208:211], v[78:81]
	v_mfma_f32_16x16x32_bf16 v[86:89], v[146:149], v[208:211], v[86:89]
	v_mfma_f32_16x16x32_bf16 v[126:129], v[156:159], v[188:191], v[126:129]
	v_mfma_f32_16x16x32_bf16 v[122:125], v[164:167], v[188:191], v[122:125]
	v_mfma_f32_16x16x32_bf16 v[110:113], v[164:167], v[196:199], v[110:113]
	v_mfma_f32_16x16x32_bf16 v[118:121], v[156:159], v[196:199], v[118:121]
	v_mfma_f32_16x16x32_bf16 v[102:105], v[156:159], v[204:207], v[102:105]
	v_mfma_f32_16x16x32_bf16 v[94:97], v[164:167], v[204:207], v[94:97]
	v_mfma_f32_16x16x32_bf16 v[78:81], v[164:167], v[212:215], v[78:81]
	v_mfma_f32_16x16x32_bf16 v[86:89], v[156:159], v[212:215], v[86:89]
	s_setprio 0
	s_setprio 1
	v_mfma_f32_16x16x32_bf16 v[114:117], v[168:171], v[184:187], v[114:117]
	v_mfma_f32_16x16x32_bf16 v[106:109], v[176:179], v[184:187], v[106:109]
	v_mfma_f32_16x16x32_bf16 v[90:93], v[176:179], v[192:195], v[90:93]
	v_mfma_f32_16x16x32_bf16 v[98:101], v[168:171], v[192:195], v[98:101]
	v_mfma_f32_16x16x32_bf16 v[82:85], v[168:171], v[200:203], v[82:85]
	v_mfma_f32_16x16x32_bf16 v[74:77], v[176:179], v[200:203], v[74:77]
	v_mfma_f32_16x16x32_bf16 v[66:69], v[176:179], v[208:211], v[66:69]
	v_mfma_f32_16x16x32_bf16 v[70:73], v[168:171], v[208:211], v[70:73]
	v_mfma_f32_16x16x32_bf16 v[114:117], v[172:175], v[188:191], v[114:117]
	v_mfma_f32_16x16x32_bf16 v[106:109], v[180:183], v[188:191], v[106:109]
	v_mfma_f32_16x16x32_bf16 v[90:93], v[180:183], v[196:199], v[90:93]
	v_mfma_f32_16x16x32_bf16 v[98:101], v[172:175], v[196:199], v[98:101]
	v_mfma_f32_16x16x32_bf16 v[82:85], v[172:175], v[204:207], v[82:85]
	v_mfma_f32_16x16x32_bf16 v[74:77], v[180:183], v[204:207], v[74:77]
	v_mfma_f32_16x16x32_bf16 v[66:69], v[180:183], v[212:215], v[66:69]
	v_mfma_f32_16x16x32_bf16 v[70:73], v[172:175], v[212:215], v[70:73]
	s_setprio 0
	s_barrier
	s_add_i32 s33, s72, s61
	v_lshl_add_u64 v[216:217], s[46:47], 0, v[134:135]
	s_mov_b32 m0, s33
	ds_read_b128 v[184:187], v154 offset:16384
	ds_read_b128 v[188:191], v154 offset:17408
	ds_read_b128 v[192:195], v154 offset:18432
	ds_read_b128 v[196:199], v154 offset:19456
	ds_read_b128 v[200:203], v154 offset:20480
	ds_read_b128 v[204:207], v154 offset:21504
	ds_read_b128 v[208:211], v154 offset:22528
	ds_read_b128 v[212:215], v154 offset:23552
	global_load_lds_dwordx4 v[216:217], off
	s_add_i32 m0, s33, 0x2000
	s_add_u32 s62, s46, 0x100000
	v_lshl_add_u64 v[218:219], s[46:47], 0, v[130:131]
	s_addc_u32 s63, s47, 0
	s_add_i32 s33, s73, s61
	global_load_lds_dwordx4 v[218:219], off
	v_lshl_add_u64 v[220:221], s[62:63], 0, v[134:135]
	s_mov_b32 m0, s33
	v_lshl_add_u64 v[224:225], s[52:53], 0, v[132:133]
	global_load_lds_dwordx4 v[220:221], off
	v_lshl_add_u64 v[220:221], s[62:63], 0, v[130:131]
	s_add_i32 m0, s33, 0x2000
	s_nop 0
	global_load_lds_dwordx4 v[220:221], off
	v_lshl_add_u64 v[220:221], s[52:53], 0, v[136:137]
	s_mov_b32 m0, s17
	s_nop 0
	global_load_lds_dwordx4 v[220:221], off
	s_mov_b32 m0, s39
	s_nop 0
	global_load_lds_dwordx4 v[224:225], off
	s_waitcnt vmcnt(8)
	s_waitcnt lgkmcnt(0)
	s_barrier
; #define PG8_STAGE(bufoff, gbase, voff) do { _Pragma("unroll") for (int _i = 0; _i < 2; ++_i) \
;         __builtin_amdgcn_global_load_lds((const unsigned*)((const char*)(gbase) + (voff)[_i]), (LAS unsigned*)(lds + (bufoff) + ldsw + _i * 8192), 16, 0, 0); } while (0)
; #define PG8_LDA(dst, b, h) do { _Pragma("unroll") for (int m = 0; m < 4; ++m) _Pragma("unroll") for (int k = 0; k < 2; ++k) dst[m][k] = *(const LAS bf16x8*)(lds + PG8_SA(b, h) + aoff + m * 2048 + k * 1024); } while (0)
; #define PG8_LDB(dst, b, h) do { _Pragma("unroll") for (int n = 0; n < 2; ++n) _Pragma("unroll") for (int k = 0; k < 2; ++k) dst[n][k] = *(const LAS bf16x8*)(lds + PG8_SB(b, h) + boff + n * 2048 + k * 1024); } while (0)
; #define PG8_MMA(ai, bj, At, Bt) do { __builtin_amdgcn_s_setprio(1); _Pragma("unroll") for (int m = 0; m < 4; ++m) _Pragma("unroll") for (int n = 0; n < 2; ++n) _Pragma("unroll") for (int k = 0; k < 2; ++k) \
;         acc[ai][bj][m][n] = __builtin_amdgcn_mfma_f32_16x16x32_bf16(Bt[n][k], At[m][k], acc[ai][bj][m][n], 0, 0, 0); __builtin_amdgcn_s_setprio(0); } while (0)
; #define PG8_WAIT_V(n) asm volatile("s_waitcnt vmcnt(" #n ")" ::: "memory")
; #define PG8_WAIT_L(n) asm volatile("s_waitcnt lgkmcnt(" #n ")" ::: "memory")
; #define PG8_BAR __builtin_amdgcn_s_barrier()
; #define PG8_SCHED __builtin_amdgcn_sched_barrier(0)
; template <class Epi>
; __device__ __forceinline__ void gemm_phase(LAS unsigned char* lds, const Gemm g, int G, int c, const Epi& E) {
;     ...
;             PG8_WAIT_V(8); PG8_WAIT_L(0); PG8_BAR; PG8_MMA(1, 0, At, B0); PG8_MMA(1, 1, At, B1); PG8_BAR; PG8_SCHED;
;             PG8_LDB(B0, 1, 0); PG8_LDB(B1, 1, 1); PG8_SCHED; PG8_LDA(At, 1, 0); PG8_STAGE(PG8_SA(0, 1), a2 + hstepA, voffA);
;             PG8_WAIT_V(8); PG8_WAIT_L(0); PG8_BAR; PG8_MMA(0, 0, At, B0); PG8_MMA(0, 1, At, B1); PG8_BAR; PG8_SCHED;
	s_setprio 1
	s_waitcnt lgkmcnt(0)
	v_mfma_f32_16x16x32_bf16 v[62:65], v[146:149], v[184:187], v[62:65]
	v_mfma_f32_16x16x32_bf16 v[58:61], v[160:163], v[184:187], v[58:61]
	v_mfma_f32_16x16x32_bf16 v[46:49], v[160:163], v[192:195], v[46:49]
	v_mfma_f32_16x16x32_bf16 v[54:57], v[146:149], v[192:195], v[54:57]
	v_mfma_f32_16x16x32_bf16 v[38:41], v[146:149], v[200:203], v[38:41]
	v_mfma_f32_16x16x32_bf16 v[30:33], v[160:163], v[200:203], v[30:33]
	v_mfma_f32_16x16x32_bf16 v[14:17], v[160:163], v[208:211], v[14:17]
	v_mfma_f32_16x16x32_bf16 v[22:25], v[146:149], v[208:211], v[22:25]
	v_mfma_f32_16x16x32_bf16 v[62:65], v[156:159], v[188:191], v[62:65]
	v_mfma_f32_16x16x32_bf16 v[58:61], v[164:167], v[188:191], v[58:61]
	v_mfma_f32_16x16x32_bf16 v[46:49], v[164:167], v[196:199], v[46:49]
	v_mfma_f32_16x16x32_bf16 v[54:57], v[156:159], v[196:199], v[54:57]
	v_mfma_f32_16x16x32_bf16 v[38:41], v[156:159], v[204:207], v[38:41]
	v_mfma_f32_16x16x32_bf16 v[30:33], v[164:167], v[204:207], v[30:33]
	v_mfma_f32_16x16x32_bf16 v[14:17], v[164:167], v[212:215], v[14:17]
	v_mfma_f32_16x16x32_bf16 v[22:25], v[156:159], v[212:215], v[22:25]
	s_setprio 0
	s_setprio 1
	v_mfma_f32_16x16x32_bf16 v[50:53], v[168:171], v[184:187], v[50:53]
	v_mfma_f32_16x16x32_bf16 v[42:45], v[176:179], v[184:187], v[42:45]
	v_mfma_f32_16x16x32_bf16 v[26:29], v[176:179], v[192:195], v[26:29]
	v_mfma_f32_16x16x32_bf16 v[34:37], v[168:171], v[192:195], v[34:37]
	v_mfma_f32_16x16x32_bf16 v[18:21], v[168:171], v[200:203], v[18:21]
	v_mfma_f32_16x16x32_bf16 v[10:13], v[176:179], v[200:203], v[10:13]
	v_mfma_f32_16x16x32_bf16 v[2:5], v[176:179], v[208:211], v[2:5]
	v_mfma_f32_16x16x32_bf16 v[6:9], v[168:171], v[208:211], v[6:9]
	v_mfma_f32_16x16x32_bf16 v[50:53], v[172:175], v[188:191], v[50:53]
	v_mfma_f32_16x16x32_bf16 v[42:45], v[180:183], v[188:191], v[42:45]
	v_mfma_f32_16x16x32_bf16 v[26:29], v[180:183], v[196:199], v[26:29]
	v_mfma_f32_16x16x32_bf16 v[34:37], v[172:175], v[196:199], v[34:37]
	v_mfma_f32_16x16x32_bf16 v[18:21], v[172:175], v[204:207], v[18:21]
	v_mfma_f32_16x16x32_bf16 v[10:13], v[180:183], v[204:207], v[10:13]
	v_mfma_f32_16x16x32_bf16 v[2:5], v[180:183], v[212:215], v[2:5]
	v_mfma_f32_16x16x32_bf16 v[6:9], v[172:175], v[212:215], v[6:9]
	s_setprio 0
	s_barrier
	s_add_i32 s33, 0, 0x18000
	v_add_u32_e32 v155, s33, v151
	s_add_i32 s62, 0, 0x1c000
	ds_read_b128 v[146:149], v155
	ds_read_b128 v[156:159], v155 offset:1024
	ds_read_b128 v[160:163], v155 offset:2048
	ds_read_b128 v[164:167], v155 offset:3072
	v_add_u32_e32 v155, s62, v151
	ds_read_b128 v[168:171], v155
	ds_read_b128 v[172:175], v155 offset:1024
	ds_read_b128 v[176:179], v155 offset:2048
	ds_read_b128 v[180:183], v155 offset:3072
	s_add_u32 s52, s52, 0x100000
	s_addc_u32 s53, s53, 0
	s_mov_b32 m0, s43
	v_lshl_add_u64 v[226:227], s[52:53], 0, v[136:137]
	ds_read_b128 v[184:187], v154 offset:32768
	ds_read_b128 v[188:191], v154 offset:33792
	ds_read_b128 v[192:195], v154 offset:34816
	ds_read_b128 v[196:199], v154 offset:35840
	ds_read_b128 v[200:203], v154 offset:36864
	ds_read_b128 v[204:207], v154 offset:37888
	ds_read_b128 v[208:211], v154 offset:38912
	ds_read_b128 v[212:215], v154 offset:39936
	global_load_lds_dwordx4 v[226:227], off
	v_lshl_add_u64 v[226:227], s[52:53], 0, v[132:133]
	s_mov_b32 m0, s66
	s_nop 0
	global_load_lds_dwordx4 v[226:227], off
	s_waitcnt vmcnt(8)
	s_waitcnt lgkmcnt(0)
	s_barrier
	s_setprio 1
	s_waitcnt lgkmcnt(0)
	v_mfma_f32_16x16x32_bf16 v[126:129], v[146:149], v[184:187], v[126:129]
	v_mfma_f32_16x16x32_bf16 v[122:125], v[160:163], v[184:187], v[122:125]
	v_mfma_f32_16x16x32_bf16 v[110:113], v[160:163], v[192:195], v[110:113]
	v_mfma_f32_16x16x32_bf16 v[118:121], v[146:149], v[192:195], v[118:121]
	v_mfma_f32_16x16x32_bf16 v[102:105], v[146:149], v[200:203], v[102:105]
	v_mfma_f32_16x16x32_bf16 v[94:97], v[160:163], v[200:203], v[94:97]
	v_mfma_f32_16x16x32_bf16 v[78:81], v[160:163], v[208:211], v[78:81]
	v_mfma_f32_16x16x32_bf16 v[86:89], v[146:149], v[208:211], v[86:89]
	v_mfma_f32_16x16x32_bf16 v[126:129], v[156:159], v[188:191], v[126:129]
	v_mfma_f32_16x16x32_bf16 v[122:125], v[164:167], v[188:191], v[122:125]
	v_mfma_f32_16x16x32_bf16 v[110:113], v[164:167], v[196:199], v[110:113]
	v_mfma_f32_16x16x32_bf16 v[118:121], v[156:159], v[196:199], v[118:121]
	v_mfma_f32_16x16x32_bf16 v[102:105], v[156:159], v[204:207], v[102:105]
	v_mfma_f32_16x16x32_bf16 v[94:97], v[164:167], v[204:207], v[94:97]
	v_mfma_f32_16x16x32_bf16 v[78:81], v[164:167], v[212:215], v[78:81]
	v_mfma_f32_16x16x32_bf16 v[86:89], v[156:159], v[212:215], v[86:89]
	s_setprio 0
	s_setprio 1
	v_mfma_f32_16x16x32_bf16 v[114:117], v[168:171], v[184:187], v[114:117]
	v_mfma_f32_16x16x32_bf16 v[106:109], v[176:179], v[184:187], v[106:109]
	v_mfma_f32_16x16x32_bf16 v[90:93], v[176:179], v[192:195], v[90:93]
	v_mfma_f32_16x16x32_bf16 v[98:101], v[168:171], v[192:195], v[98:101]
	v_mfma_f32_16x16x32_bf16 v[82:85], v[168:171], v[200:203], v[82:85]
	v_mfma_f32_16x16x32_bf16 v[74:77], v[176:179], v[200:203], v[74:77]
	v_mfma_f32_16x16x32_bf16 v[66:69], v[176:179], v[208:211], v[66:69]
	v_mfma_f32_16x16x32_bf16 v[70:73], v[168:171], v[208:211], v[70:73]
	v_mfma_f32_16x16x32_bf16 v[114:117], v[172:175], v[188:191], v[114:117]
	v_mfma_f32_16x16x32_bf16 v[106:109], v[180:183], v[188:191], v[106:109]
	v_mfma_f32_16x16x32_bf16 v[90:93], v[180:183], v[196:199], v[90:93]
	v_mfma_f32_16x16x32_bf16 v[98:101], v[172:175], v[196:199], v[98:101]
	v_mfma_f32_16x16x32_bf16 v[82:85], v[172:175], v[204:207], v[82:85]
	v_mfma_f32_16x16x32_bf16 v[74:77], v[180:183], v[204:207], v[74:77]
	v_mfma_f32_16x16x32_bf16 v[66:69], v[180:183], v[212:215], v[66:69]
	v_mfma_f32_16x16x32_bf16 v[70:73], v[172:175], v[212:215], v[70:73]
	s_setprio 0
	s_barrier
; #define PG8_STAGE(bufoff, gbase, voff) do { _Pragma("unroll") for (int _i = 0; _i < 2; ++_i) \
;         __builtin_amdgcn_global_load_lds((const unsigned*)((const char*)(gbase) + (voff)[_i]), (LAS unsigned*)(lds + (bufoff) + ldsw + _i * 8192), 16, 0, 0); } while (0)
; #define PG8_LDA(dst, b, h) do { _Pragma("unroll") for (int m = 0; m < 4; ++m) _Pragma("unroll") for (int k = 0; k < 2; ++k) dst[m][k] = *(const LAS bf16x8*)(lds + PG8_SA(b, h) + aoff + m * 2048 + k * 1024); } while (0)
; #define PG8_MMA(ai, bj, At, Bt) do { __builtin_amdgcn_s_setprio(1); _Pragma("unroll") for (int m = 0; m < 4; ++m) _Pragma("unroll") for (int n = 0; n < 2; ++n) _Pragma("unroll") for (int k = 0; k < 2; ++k) \
;         acc[ai][bj][m][n] = __builtin_amdgcn_mfma_f32_16x16x32_bf16(Bt[n][k], At[m][k], acc[ai][bj][m][n], 0, 0, 0); __builtin_amdgcn_s_setprio(0); } while (0)
; #define PG8_WAIT_V(n) asm volatile("s_waitcnt vmcnt(" #n ")" ::: "memory")
; #define PG8_WAIT_L(n) asm volatile("s_waitcnt lgkmcnt(" #n ")" ::: "memory")
; #define PG8_BAR __builtin_amdgcn_s_barrier()
; #define PG8_SCHED __builtin_amdgcn_sched_barrier(0)
; template <class Epi>
; __device__ __forceinline__ void gemm_phase(LAS unsigned char* lds, const Gemm g, int G, int c, const Epi& E) {
;     ...
;             PG8_LDA(At, 1, 1); PG8_STAGE(PG8_SB(1, 0), b3, voffB); PG8_STAGE(PG8_SB(1, 1), b3 + hstepB, voffB); PG8_STAGE(PG8_SA(1, 0), a3, voffA);
;             PG8_WAIT_V(8); PG8_WAIT_L(0); PG8_BAR; PG8_MMA(1, 0, At, B0); PG8_MMA(1, 1, At, B1); PG8_BAR; PG8_SCHED;
;         }
;         if (wr == 0) PG8_BAR;
	s_add_i32 s33, s33, s61
	v_lshl_add_u64 v[216:217], v[216:217], 0, s[6:7]
	s_mov_b32 m0, s33
	ds_read_b128 v[184:187], v154 offset:49152
	ds_read_b128 v[188:191], v154 offset:50176
	ds_read_b128 v[192:195], v154 offset:51200
	ds_read_b128 v[196:199], v154 offset:52224
	ds_read_b128 v[200:203], v154 offset:53248
	ds_read_b128 v[204:207], v154 offset:54272
	ds_read_b128 v[208:211], v154 offset:55296
	ds_read_b128 v[212:215], v154 offset:56320
	global_load_lds_dwordx4 v[216:217], off
	s_add_i32 m0, s33, 0x2000
	s_add_u32 s46, s46, 0x100080
	v_lshl_add_u64 v[216:217], v[218:219], 0, s[6:7]
	s_addc_u32 s47, s47, 0
	s_add_i32 s33, s62, s61
	global_load_lds_dwordx4 v[216:217], off
	v_lshl_add_u64 v[216:217], s[46:47], 0, v[134:135]
	s_mov_b32 m0, s33
	s_nop 0
	global_load_lds_dwordx4 v[216:217], off
	v_lshl_add_u64 v[216:217], s[46:47], 0, v[130:131]
	s_add_i32 m0, s33, 0x2000
	s_nop 0
	global_load_lds_dwordx4 v[216:217], off
	v_lshl_add_u64 v[216:217], v[220:221], 0, s[6:7]
	s_mov_b32 m0, s70
	s_nop 0
	global_load_lds_dwordx4 v[216:217], off
	v_lshl_add_u64 v[216:217], v[224:225], 0, s[6:7]
	s_mov_b32 m0, s71
	s_nop 0
	global_load_lds_dwordx4 v[216:217], off
	s_waitcnt vmcnt(8)
	s_waitcnt lgkmcnt(0)
	s_barrier
	s_setprio 1
	s_waitcnt lgkmcnt(0)
	v_mfma_f32_16x16x32_bf16 v[62:65], v[146:149], v[184:187], v[62:65]
	v_mfma_f32_16x16x32_bf16 v[58:61], v[160:163], v[184:187], v[58:61]
	v_mfma_f32_16x16x32_bf16 v[46:49], v[160:163], v[192:195], v[46:49]
	v_mfma_f32_16x16x32_bf16 v[54:57], v[146:149], v[192:195], v[54:57]
	v_mfma_f32_16x16x32_bf16 v[38:41], v[146:149], v[200:203], v[38:41]
	v_mfma_f32_16x16x32_bf16 v[30:33], v[160:163], v[200:203], v[30:33]
	v_mfma_f32_16x16x32_bf16 v[14:17], v[160:163], v[208:211], v[14:17]
	v_mfma_f32_16x16x32_bf16 v[22:25], v[146:149], v[208:211], v[22:25]
	v_mfma_f32_16x16x32_bf16 v[62:65], v[156:159], v[188:191], v[62:65]
	v_mfma_f32_16x16x32_bf16 v[58:61], v[164:167], v[188:191], v[58:61]
	v_mfma_f32_16x16x32_bf16 v[46:49], v[164:167], v[196:199], v[46:49]
	v_mfma_f32_16x16x32_bf16 v[54:57], v[156:159], v[196:199], v[54:57]
	v_mfma_f32_16x16x32_bf16 v[38:41], v[156:159], v[204:207], v[38:41]
	v_mfma_f32_16x16x32_bf16 v[30:33], v[164:167], v[204:207], v[30:33]
	v_mfma_f32_16x16x32_bf16 v[14:17], v[164:167], v[212:215], v[14:17]
	v_mfma_f32_16x16x32_bf16 v[22:25], v[156:159], v[212:215], v[22:25]
	s_setprio 0
	s_setprio 1
	v_mfma_f32_16x16x32_bf16 v[50:53], v[168:171], v[184:187], v[50:53]
	v_mfma_f32_16x16x32_bf16 v[42:45], v[176:179], v[184:187], v[42:45]
	v_mfma_f32_16x16x32_bf16 v[26:29], v[176:179], v[192:195], v[26:29]
	v_mfma_f32_16x16x32_bf16 v[34:37], v[168:171], v[192:195], v[34:37]
	v_mfma_f32_16x16x32_bf16 v[18:21], v[168:171], v[200:203], v[18:21]
	v_mfma_f32_16x16x32_bf16 v[10:13], v[176:179], v[200:203], v[10:13]
	v_mfma_f32_16x16x32_bf16 v[2:5], v[176:179], v[208:211], v[2:5]
	v_mfma_f32_16x16x32_bf16 v[6:9], v[168:171], v[208:211], v[6:9]
	v_mfma_f32_16x16x32_bf16 v[50:53], v[172:175], v[188:191], v[50:53]
	v_mfma_f32_16x16x32_bf16 v[42:45], v[180:183], v[188:191], v[42:45]
	v_mfma_f32_16x16x32_bf16 v[26:29], v[180:183], v[196:199], v[26:29]
	v_mfma_f32_16x16x32_bf16 v[34:37], v[172:175], v[196:199], v[34:37]
	v_mfma_f32_16x16x32_bf16 v[18:21], v[172:175], v[204:207], v[18:21]
	v_mfma_f32_16x16x32_bf16 v[10:13], v[180:183], v[204:207], v[10:13]
	v_mfma_f32_16x16x32_bf16 v[2:5], v[180:183], v[212:215], v[2:5]
	v_mfma_f32_16x16x32_bf16 v[6:9], v[172:175], v[212:215], v[6:9]
	s_setprio 0
	s_barrier
	s_add_i32 s83, s83, 2
	s_add_u32 s44, s44, 0x100
	s_addc_u32 s45, s45, 0
	s_add_u32 s81, s81, 0x100
	s_addc_u32 s82, s82, 0
	s_cmp_gt_u32 s83, 61
	s_cbranch_scc0 .LBB0_765
	s_and_b64 vcc, exec, s[8:9]
	s_cbranch_vccz .LBB0_768
	s_barrier

; #define PG8_STAGE(bufoff, gbase, voff) do { _Pragma("unroll") for (int _i = 0; _i < 2; ++_i) \
;         __builtin_amdgcn_global_load_lds((const unsigned*)((const char*)(gbase) + (voff)[_i]), (LAS unsigned*)(lds + (bufoff) + ldsw + _i * 8192), 16, 0, 0); } while (0)
; #define PG8_LDA(dst, b, h) do { _Pragma("unroll") for (int m = 0; m < 4; ++m) _Pragma("unroll") for (int k = 0; k < 2; ++k) dst[m][k] = *(const LAS bf16x8*)(lds + PG8_SA(b, h) + aoff + m * 2048 + k * 1024); } while (0)
; #define PG8_LDB(dst, b, h) do { _Pragma("unroll") for (int n = 0; n < 2; ++n) _Pragma("unroll") for (int k = 0; k < 2; ++k) dst[n][k] = *(const LAS bf16x8*)(lds + PG8_SB(b, h) + boff + n * 2048 + k * 1024); } while (0)
; #define PG8_MMA(ai, bj, At, Bt) do { __builtin_amdgcn_s_setprio(1); _Pragma("unroll") for (int m = 0; m < 4; ++m) _Pragma("unroll") for (int n = 0; n < 2; ++n) _Pragma("unroll") for (int k = 0; k < 2; ++k) \
;         acc[ai][bj][m][n] = __builtin_amdgcn_mfma_f32_16x16x32_bf16(Bt[n][k], At[m][k], acc[ai][bj][m][n], 0, 0, 0); __builtin_amdgcn_s_setprio(0); } while (0)
; #define PG8_WAIT_V(n) asm volatile("s_waitcnt vmcnt(" #n ")" ::: "memory")
; #define PG8_WAIT_L(n) asm volatile("s_waitcnt lgkmcnt(" #n ")" ::: "memory")
; #define PG8_BAR __builtin_amdgcn_s_barrier()
; #define PG8_SCHED __builtin_amdgcn_sched_barrier(0)
; template <class Epi>
; __device__ __forceinline__ void gemm_phase(LAS unsigned char* lds, const Gemm g, int G, int c, const Epi& E) {
;     ...
;             const bool last = (t == nt - 2);
;             const char* a1 = cA + (size_t)(t + 1) * kstep;
;             const char* a2 = last ? nA : cA + (size_t)(t + 2) * kstep; const char* b2 = last ? nB : cB + (size_t)(t + 2) * kstep;
;             const char* a3 = a2 + kstep; const char* b3 = b2 + kstep;
;             PG8_LDB(B0, 0, 0); PG8_LDB(B1, 0, 1); PG8_SCHED; PG8_LDA(At, 0, 0); PG8_STAGE(PG8_SA(1, 1), a1 + hstepA, voffA);
;             PG8_WAIT_V(8); PG8_WAIT_L(0); PG8_BAR; PG8_MMA(0, 0, At, B0); PG8_MMA(0, 1, At, B1); PG8_BAR; PG8_SCHED;
;             PG8_LDA(At, 0, 1); PG8_STAGE(PG8_SB(0, 0), b2, voffB); PG8_STAGE(PG8_SB(0, 1), b2 + hstepB, voffB); PG8_STAGE(PG8_SA(0, 0), a2, voffA);
.LBB0_781:
	ds_read_b128 v[150:153], v146
	ds_read_b128 v[154:157], v146 offset:1024
	ds_read_b128 v[158:161], v146 offset:2048
	ds_read_b128 v[162:165], v146 offset:3072
	ds_read_b128 v[166:169], v147
	ds_read_b128 v[170:173], v147 offset:1024
	ds_read_b128 v[174:177], v147 offset:2048
	ds_read_b128 v[178:181], v147 offset:3072
	s_add_u32 s52, s46, 0x100
	s_addc_u32 s53, s47, 0
	s_add_u32 s33, s90, s46
	s_addc_u32 s55, s91, s47
	s_cmp_eq_u32 s92, 4
	s_cselect_b32 s56, 0, s52
	s_cselect_b32 s57, 0, s53
	s_cselect_b32 s54, s89, s33
	s_cselect_b32 s55, s25, s55
	s_add_u32 s56, s2, s56
	s_addc_u32 s57, s3, s57
	s_mov_b32 m0, s83
	v_lshl_add_u64 v[142:143], v[138:139], 0, s[46:47]
	ds_read_b128 v[182:185], v148
	ds_read_b128 v[186:189], v148 offset:1024
	ds_read_b128 v[190:193], v148 offset:2048
	ds_read_b128 v[194:197], v148 offset:3072
	ds_read_b128 v[198:201], v148 offset:4096
	ds_read_b128 v[202:205], v148 offset:5120
	ds_read_b128 v[206:209], v148 offset:6144
	ds_read_b128 v[210:213], v148 offset:7168
	global_load_lds_dwordx4 v[142:143], off
	v_lshl_add_u64 v[142:143], v[140:141], 0, s[46:47]
	s_mov_b32 m0, s84
	s_nop 0
	global_load_lds_dwordx4 v[142:143], off
	s_waitcnt vmcnt(8)
	s_waitcnt lgkmcnt(0)
	s_barrier
	s_setprio 1
	s_waitcnt lgkmcnt(0)
	v_mfma_f32_16x16x32_bf16 v[126:129], v[150:153], v[182:185], v[126:129]
	v_mfma_f32_16x16x32_bf16 v[122:125], v[158:161], v[182:185], v[122:125]
	v_mfma_f32_16x16x32_bf16 v[110:113], v[158:161], v[190:193], v[110:113]
	v_mfma_f32_16x16x32_bf16 v[118:121], v[150:153], v[190:193], v[118:121]
	v_mfma_f32_16x16x32_bf16 v[102:105], v[150:153], v[198:201], v[102:105]
	v_mfma_f32_16x16x32_bf16 v[94:97], v[158:161], v[198:201], v[94:97]
	v_mfma_f32_16x16x32_bf16 v[78:81], v[158:161], v[206:209], v[78:81]
	v_mfma_f32_16x16x32_bf16 v[86:89], v[150:153], v[206:209], v[86:89]
	v_mfma_f32_16x16x32_bf16 v[126:129], v[154:157], v[186:189], v[126:129]
	v_mfma_f32_16x16x32_bf16 v[122:125], v[162:165], v[186:189], v[122:125]
	v_mfma_f32_16x16x32_bf16 v[110:113], v[162:165], v[194:197], v[110:113]
	v_mfma_f32_16x16x32_bf16 v[118:121], v[154:157], v[194:197], v[118:121]
	v_mfma_f32_16x16x32_bf16 v[102:105], v[154:157], v[202:205], v[102:105]
	v_mfma_f32_16x16x32_bf16 v[94:97], v[162:165], v[202:205], v[94:97]
	v_mfma_f32_16x16x32_bf16 v[78:81], v[162:165], v[210:213], v[78:81]
	v_mfma_f32_16x16x32_bf16 v[86:89], v[154:157], v[210:213], v[86:89]
	s_setprio 0
	s_setprio 1
	v_mfma_f32_16x16x32_bf16 v[114:117], v[166:169], v[182:185], v[114:117]
	v_mfma_f32_16x16x32_bf16 v[106:109], v[174:177], v[182:185], v[106:109]
	v_mfma_f32_16x16x32_bf16 v[90:93], v[174:177], v[190:193], v[90:93]
	v_mfma_f32_16x16x32_bf16 v[98:101], v[166:169], v[190:193], v[98:101]
	v_mfma_f32_16x16x32_bf16 v[82:85], v[166:169], v[198:201], v[82:85]
	v_mfma_f32_16x16x32_bf16 v[74:77], v[174:177], v[198:201], v[74:77]
	v_mfma_f32_16x16x32_bf16 v[66:69], v[174:177], v[206:209], v[66:69]
	v_mfma_f32_16x16x32_bf16 v[70:73], v[166:169], v[206:209], v[70:73]
	v_mfma_f32_16x16x32_bf16 v[114:117], v[170:173], v[186:189], v[114:117]
	v_mfma_f32_16x16x32_bf16 v[106:109], v[178:181], v[186:189], v[106:109]
	v_mfma_f32_16x16x32_bf16 v[90:93], v[178:181], v[194:197], v[90:93]
	v_mfma_f32_16x16x32_bf16 v[98:101], v[170:173], v[194:197], v[98:101]
	v_mfma_f32_16x16x32_bf16 v[82:85], v[170:173], v[202:205], v[82:85]
	v_mfma_f32_16x16x32_bf16 v[74:77], v[178:181], v[202:205], v[74:77]
	v_mfma_f32_16x16x32_bf16 v[66:69], v[178:181], v[210:213], v[66:69]
	v_mfma_f32_16x16x32_bf16 v[70:73], v[170:173], v[210:213], v[70:73]
	s_setprio 0
	s_barrier
	s_mov_b32 m0, s85
	v_lshl_add_u64 v[142:143], s[54:55], 0, v[134:135]
	s_add_u32 s46, s54, 0x20000
	ds_read_b128 v[182:185], v148 offset:16384
	ds_read_b128 v[186:189], v148 offset:17408
	ds_read_b128 v[190:193], v148 offset:18432
	ds_read_b128 v[194:197], v148 offset:19456
	ds_read_b128 v[198:201], v148 offset:20480
	ds_read_b128 v[202:205], v148 offset:21504
	ds_read_b128 v[206:209], v148 offset:22528
	ds_read_b128 v[210:213], v148 offset:23552
	global_load_lds_dwordx4 v[142:143], off
	v_lshl_add_u64 v[214:215], s[54:55], 0, v[130:131]
	s_mov_b32 m0, s86
	s_addc_u32 s47, s55, 0
	global_load_lds_dwordx4 v[214:215], off
	v_lshl_add_u64 v[216:217], s[46:47], 0, v[134:135]
	s_mov_b32 m0, s87
	v_lshl_add_u64 v[218:219], s[56:57], 0, v[132:133]
	global_load_lds_dwordx4 v[216:217], off
	v_lshl_add_u64 v[216:217], s[46:47], 0, v[130:131]
	s_mov_b32 m0, s88
	s_nop 0
	global_load_lds_dwordx4 v[216:217], off
	v_lshl_add_u64 v[216:217], s[56:57], 0, v[136:137]
	s_mov_b32 m0, s45
	s_nop 0
	global_load_lds_dwordx4 v[216:217], off
	s_mov_b32 m0, s61
	s_nop 0
	global_load_lds_dwordx4 v[218:219], off
	s_waitcnt vmcnt(8)
	s_waitcnt lgkmcnt(0)
	s_barrier
; #define PG8_STAGE(bufoff, gbase, voff) do { _Pragma("unroll") for (int _i = 0; _i < 2; ++_i) \
;         __builtin_amdgcn_global_load_lds((const unsigned*)((const char*)(gbase) + (voff)[_i]), (LAS unsigned*)(lds + (bufoff) + ldsw + _i * 8192), 16, 0, 0); } while (0)
; #define PG8_LDA(dst, b, h) do { _Pragma("unroll") for (int m = 0; m < 4; ++m) _Pragma("unroll") for (int k = 0; k < 2; ++k) dst[m][k] = *(const LAS bf16x8*)(lds + PG8_SA(b, h) + aoff + m * 2048 + k * 1024); } while (0)
; #define PG8_LDB(dst, b, h) do { _Pragma("unroll") for (int n = 0; n < 2; ++n) _Pragma("unroll") for (int k = 0; k < 2; ++k) dst[n][k] = *(const LAS bf16x8*)(lds + PG8_SB(b, h) + boff + n * 2048 + k * 1024); } while (0)
; #define PG8_MMA(ai, bj, At, Bt) do { __builtin_amdgcn_s_setprio(1); _Pragma("unroll") for (int m = 0; m < 4; ++m) _Pragma("unroll") for (int n = 0; n < 2; ++n) _Pragma("unroll") for (int k = 0; k < 2; ++k) \
;         acc[ai][bj][m][n] = __builtin_amdgcn_mfma_f32_16x16x32_bf16(Bt[n][k], At[m][k], acc[ai][bj][m][n], 0, 0, 0); __builtin_amdgcn_s_setprio(0); } while (0)
; #define PG8_WAIT_V(n) asm volatile("s_waitcnt vmcnt(" #n ")" ::: "memory")
; #define PG8_WAIT_L(n) asm volatile("s_waitcnt lgkmcnt(" #n ")" ::: "memory")
; #define PG8_BAR __builtin_amdgcn_s_barrier()
; #define PG8_SCHED __builtin_amdgcn_sched_barrier(0)
; template <class Epi>
; __device__ __forceinline__ void gemm_phase(LAS unsigned char* lds, const Gemm g, int G, int c, const Epi& E) {
;     ...
;             PG8_WAIT_V(8); PG8_WAIT_L(0); PG8_BAR; PG8_MMA(1, 0, At, B0); PG8_MMA(1, 1, At, B1); PG8_BAR; PG8_SCHED;
;             PG8_LDB(B0, 1, 0); PG8_LDB(B1, 1, 1); PG8_SCHED; PG8_LDA(At, 1, 0); PG8_STAGE(PG8_SA(0, 1), a2 + hstepA, voffA);
;             PG8_WAIT_V(8); PG8_WAIT_L(0); PG8_BAR; PG8_MMA(0, 0, At, B0); PG8_MMA(0, 1, At, B1); PG8_BAR; PG8_SCHED;
	s_setprio 1
	s_waitcnt lgkmcnt(0)
	v_mfma_f32_16x16x32_bf16 v[62:65], v[150:153], v[182:185], v[62:65]
	v_mfma_f32_16x16x32_bf16 v[58:61], v[158:161], v[182:185], v[58:61]
	v_mfma_f32_16x16x32_bf16 v[46:49], v[158:161], v[190:193], v[46:49]
	v_mfma_f32_16x16x32_bf16 v[54:57], v[150:153], v[190:193], v[54:57]
	v_mfma_f32_16x16x32_bf16 v[38:41], v[150:153], v[198:201], v[38:41]
	v_mfma_f32_16x16x32_bf16 v[30:33], v[158:161], v[198:201], v[30:33]
	v_mfma_f32_16x16x32_bf16 v[14:17], v[158:161], v[206:209], v[14:17]
	v_mfma_f32_16x16x32_bf16 v[22:25], v[150:153], v[206:209], v[22:25]
	v_mfma_f32_16x16x32_bf16 v[62:65], v[154:157], v[186:189], v[62:65]
	v_mfma_f32_16x16x32_bf16 v[58:61], v[162:165], v[186:189], v[58:61]
	v_mfma_f32_16x16x32_bf16 v[46:49], v[162:165], v[194:197], v[46:49]
	v_mfma_f32_16x16x32_bf16 v[54:57], v[154:157], v[194:197], v[54:57]
	v_mfma_f32_16x16x32_bf16 v[38:41], v[154:157], v[202:205], v[38:41]
	v_mfma_f32_16x16x32_bf16 v[30:33], v[162:165], v[202:205], v[30:33]
	v_mfma_f32_16x16x32_bf16 v[14:17], v[162:165], v[210:213], v[14:17]
	v_mfma_f32_16x16x32_bf16 v[22:25], v[154:157], v[210:213], v[22:25]
	s_setprio 0
	s_setprio 1
	v_mfma_f32_16x16x32_bf16 v[50:53], v[166:169], v[182:185], v[50:53]
	v_mfma_f32_16x16x32_bf16 v[42:45], v[174:177], v[182:185], v[42:45]
	v_mfma_f32_16x16x32_bf16 v[26:29], v[174:177], v[190:193], v[26:29]
	v_mfma_f32_16x16x32_bf16 v[34:37], v[166:169], v[190:193], v[34:37]
	v_mfma_f32_16x16x32_bf16 v[18:21], v[166:169], v[198:201], v[18:21]
	v_mfma_f32_16x16x32_bf16 v[10:13], v[174:177], v[198:201], v[10:13]
	v_mfma_f32_16x16x32_bf16 v[2:5], v[174:177], v[206:209], v[2:5]
	v_mfma_f32_16x16x32_bf16 v[6:9], v[166:169], v[206:209], v[6:9]
	v_mfma_f32_16x16x32_bf16 v[50:53], v[170:173], v[186:189], v[50:53]
	v_mfma_f32_16x16x32_bf16 v[42:45], v[178:181], v[186:189], v[42:45]
	v_mfma_f32_16x16x32_bf16 v[26:29], v[178:181], v[194:197], v[26:29]
	v_mfma_f32_16x16x32_bf16 v[34:37], v[170:173], v[194:197], v[34:37]
	v_mfma_f32_16x16x32_bf16 v[18:21], v[170:173], v[202:205], v[18:21]
	v_mfma_f32_16x16x32_bf16 v[10:13], v[178:181], v[202:205], v[10:13]
	v_mfma_f32_16x16x32_bf16 v[2:5], v[178:181], v[210:213], v[2:5]
	v_mfma_f32_16x16x32_bf16 v[6:9], v[170:173], v[210:213], v[6:9]
	s_setprio 0
	s_barrier
	s_add_i32 s33, 0, 0x18000
	v_add_u32_e32 v149, s33, v145
	s_add_i32 s62, 0, 0x1c000
	ds_read_b128 v[150:153], v149
	ds_read_b128 v[154:157], v149 offset:1024
	ds_read_b128 v[158:161], v149 offset:2048
	ds_read_b128 v[162:165], v149 offset:3072
	v_add_u32_e32 v149, s62, v145
	ds_read_b128 v[166:169], v149
	ds_read_b128 v[170:173], v149 offset:1024
	ds_read_b128 v[174:177], v149 offset:2048
	ds_read_b128 v[178:181], v149 offset:3072
	s_add_u32 s46, s56, 0x20000
	s_addc_u32 s47, s57, 0
	s_mov_b32 m0, s66
	v_lshl_add_u64 v[220:221], s[46:47], 0, v[136:137]
	ds_read_b128 v[182:185], v148 offset:32768
	ds_read_b128 v[186:189], v148 offset:33792
	ds_read_b128 v[190:193], v148 offset:34816
	ds_read_b128 v[194:197], v148 offset:35840
	ds_read_b128 v[198:201], v148 offset:36864
	ds_read_b128 v[202:205], v148 offset:37888
	ds_read_b128 v[206:209], v148 offset:38912
	ds_read_b128 v[210:213], v148 offset:39936
	global_load_lds_dwordx4 v[220:221], off
	v_lshl_add_u64 v[220:221], s[46:47], 0, v[132:133]
	s_mov_b32 m0, s67
	s_nop 0
	global_load_lds_dwordx4 v[220:221], off
	s_waitcnt vmcnt(8)
	s_waitcnt lgkmcnt(0)
	s_barrier
	s_setprio 1
	s_waitcnt lgkmcnt(0)
	v_mfma_f32_16x16x32_bf16 v[126:129], v[150:153], v[182:185], v[126:129]
	v_mfma_f32_16x16x32_bf16 v[122:125], v[158:161], v[182:185], v[122:125]
	v_mfma_f32_16x16x32_bf16 v[110:113], v[158:161], v[190:193], v[110:113]
	v_mfma_f32_16x16x32_bf16 v[118:121], v[150:153], v[190:193], v[118:121]
	v_mfma_f32_16x16x32_bf16 v[102:105], v[150:153], v[198:201], v[102:105]
	v_mfma_f32_16x16x32_bf16 v[94:97], v[158:161], v[198:201], v[94:97]
	v_mfma_f32_16x16x32_bf16 v[78:81], v[158:161], v[206:209], v[78:81]
	v_mfma_f32_16x16x32_bf16 v[86:89], v[150:153], v[206:209], v[86:89]
	v_mfma_f32_16x16x32_bf16 v[126:129], v[154:157], v[186:189], v[126:129]
	v_mfma_f32_16x16x32_bf16 v[122:125], v[162:165], v[186:189], v[122:125]
	v_mfma_f32_16x16x32_bf16 v[110:113], v[162:165], v[194:197], v[110:113]
	v_mfma_f32_16x16x32_bf16 v[118:121], v[154:157], v[194:197], v[118:121]
	v_mfma_f32_16x16x32_bf16 v[102:105], v[154:157], v[202:205], v[102:105]
	v_mfma_f32_16x16x32_bf16 v[94:97], v[162:165], v[202:205], v[94:97]
	v_mfma_f32_16x16x32_bf16 v[78:81], v[162:165], v[210:213], v[78:81]
	v_mfma_f32_16x16x32_bf16 v[86:89], v[154:157], v[210:213], v[86:89]
	s_setprio 0
	s_setprio 1
	v_mfma_f32_16x16x32_bf16 v[114:117], v[166:169], v[182:185], v[114:117]
	v_mfma_f32_16x16x32_bf16 v[106:109], v[174:177], v[182:185], v[106:109]
	v_mfma_f32_16x16x32_bf16 v[90:93], v[174:177], v[190:193], v[90:93]
	v_mfma_f32_16x16x32_bf16 v[98:101], v[166:169], v[190:193], v[98:101]
	v_mfma_f32_16x16x32_bf16 v[82:85], v[166:169], v[198:201], v[82:85]
	v_mfma_f32_16x16x32_bf16 v[74:77], v[174:177], v[198:201], v[74:77]
	v_mfma_f32_16x16x32_bf16 v[66:69], v[174:177], v[206:209], v[66:69]
	v_mfma_f32_16x16x32_bf16 v[70:73], v[166:169], v[206:209], v[70:73]
	v_mfma_f32_16x16x32_bf16 v[114:117], v[170:173], v[186:189], v[114:117]
	v_mfma_f32_16x16x32_bf16 v[106:109], v[178:181], v[186:189], v[106:109]
	v_mfma_f32_16x16x32_bf16 v[90:93], v[178:181], v[194:197], v[90:93]
	v_mfma_f32_16x16x32_bf16 v[98:101], v[170:173], v[194:197], v[98:101]
	v_mfma_f32_16x16x32_bf16 v[82:85], v[170:173], v[202:205], v[82:85]
	v_mfma_f32_16x16x32_bf16 v[74:77], v[178:181], v[202:205], v[74:77]
	v_mfma_f32_16x16x32_bf16 v[66:69], v[178:181], v[210:213], v[66:69]
	v_mfma_f32_16x16x32_bf16 v[70:73], v[170:173], v[210:213], v[70:73]
	s_setprio 0
	s_barrier
; #define PG8_STAGE(bufoff, gbase, voff) do { _Pragma("unroll") for (int _i = 0; _i < 2; ++_i) \
;         __builtin_amdgcn_global_load_lds((const unsigned*)((const char*)(gbase) + (voff)[_i]), (LAS unsigned*)(lds + (bufoff) + ldsw + _i * 8192), 16, 0, 0); } while (0)
; #define PG8_LDA(dst, b, h) do { _Pragma("unroll") for (int m = 0; m < 4; ++m) _Pragma("unroll") for (int k = 0; k < 2; ++k) dst[m][k] = *(const LAS bf16x8*)(lds + PG8_SA(b, h) + aoff + m * 2048 + k * 1024); } while (0)
; #define PG8_MMA(ai, bj, At, Bt) do { __builtin_amdgcn_s_setprio(1); _Pragma("unroll") for (int m = 0; m < 4; ++m) _Pragma("unroll") for (int n = 0; n < 2; ++n) _Pragma("unroll") for (int k = 0; k < 2; ++k) \
;         acc[ai][bj][m][n] = __builtin_amdgcn_mfma_f32_16x16x32_bf16(Bt[n][k], At[m][k], acc[ai][bj][m][n], 0, 0, 0); __builtin_amdgcn_s_setprio(0); } while (0)
; #define PG8_WAIT_V(n) asm volatile("s_waitcnt vmcnt(" #n ")" ::: "memory")
; #define PG8_WAIT_L(n) asm volatile("s_waitcnt lgkmcnt(" #n ")" ::: "memory")
; #define PG8_BAR __builtin_amdgcn_s_barrier()
; #define PG8_SCHED __builtin_amdgcn_sched_barrier(0)
; template <class Epi>
; __device__ __forceinline__ void gemm_phase(LAS unsigned char* lds, const Gemm g, int G, int c, const Epi& E) {
;     ...
;             PG8_LDA(At, 1, 1); PG8_STAGE(PG8_SB(1, 0), b3, voffB); PG8_STAGE(PG8_SB(1, 1), b3 + hstepB, voffB); PG8_STAGE(PG8_SA(1, 0), a3, voffA);
;             PG8_WAIT_V(8); PG8_WAIT_L(0); PG8_BAR; PG8_MMA(1, 0, At, B0); PG8_MMA(1, 1, At, B1); PG8_BAR; PG8_SCHED;
;         }
;         if (wr == 0) PG8_BAR;
	s_add_i32 s33, s33, s58
	v_lshl_add_u64 v[142:143], v[142:143], 0, s[6:7]
	s_mov_b32 m0, s33
	ds_read_b128 v[182:185], v148 offset:49152
	ds_read_b128 v[186:189], v148 offset:50176
	ds_read_b128 v[190:193], v148 offset:51200
	ds_read_b128 v[194:197], v148 offset:52224
	ds_read_b128 v[198:201], v148 offset:53248
	ds_read_b128 v[202:205], v148 offset:54272
	ds_read_b128 v[206:209], v148 offset:55296
	ds_read_b128 v[210:213], v148 offset:56320
	global_load_lds_dwordx4 v[142:143], off
	s_add_i32 m0, s33, 0x2000
	s_add_u32 s46, s54, 0x20080
	v_lshl_add_u64 v[142:143], v[214:215], 0, s[6:7]
	s_addc_u32 s47, s55, 0
	s_add_i32 s33, s62, s58
	global_load_lds_dwordx4 v[142:143], off
	v_lshl_add_u64 v[142:143], s[46:47], 0, v[134:135]
	s_mov_b32 m0, s33
	s_nop 0
	global_load_lds_dwordx4 v[142:143], off
	v_lshl_add_u64 v[142:143], s[46:47], 0, v[130:131]
	s_add_i32 m0, s33, 0x2000
	s_nop 0
	global_load_lds_dwordx4 v[142:143], off
	v_lshl_add_u64 v[142:143], v[216:217], 0, s[6:7]
	s_mov_b32 m0, s71
	s_nop 0
	global_load_lds_dwordx4 v[142:143], off
	v_lshl_add_u64 v[142:143], v[218:219], 0, s[6:7]
	s_mov_b32 m0, s72
	s_nop 0
	global_load_lds_dwordx4 v[142:143], off
	s_waitcnt vmcnt(8)
	s_waitcnt lgkmcnt(0)
	s_barrier
	s_setprio 1
	s_waitcnt lgkmcnt(0)
	v_mfma_f32_16x16x32_bf16 v[62:65], v[150:153], v[182:185], v[62:65]
	v_mfma_f32_16x16x32_bf16 v[58:61], v[158:161], v[182:185], v[58:61]
	v_mfma_f32_16x16x32_bf16 v[46:49], v[158:161], v[190:193], v[46:49]
	v_mfma_f32_16x16x32_bf16 v[54:57], v[150:153], v[190:193], v[54:57]
	v_mfma_f32_16x16x32_bf16 v[38:41], v[150:153], v[198:201], v[38:41]
	v_mfma_f32_16x16x32_bf16 v[30:33], v[158:161], v[198:201], v[30:33]
	v_mfma_f32_16x16x32_bf16 v[14:17], v[158:161], v[206:209], v[14:17]
	v_mfma_f32_16x16x32_bf16 v[22:25], v[150:153], v[206:209], v[22:25]
	v_mfma_f32_16x16x32_bf16 v[62:65], v[154:157], v[186:189], v[62:65]
	v_mfma_f32_16x16x32_bf16 v[58:61], v[162:165], v[186:189], v[58:61]
	v_mfma_f32_16x16x32_bf16 v[46:49], v[162:165], v[194:197], v[46:49]
	v_mfma_f32_16x16x32_bf16 v[54:57], v[154:157], v[194:197], v[54:57]
	v_mfma_f32_16x16x32_bf16 v[38:41], v[154:157], v[202:205], v[38:41]
	v_mfma_f32_16x16x32_bf16 v[30:33], v[162:165], v[202:205], v[30:33]
	v_mfma_f32_16x16x32_bf16 v[14:17], v[162:165], v[210:213], v[14:17]
	v_mfma_f32_16x16x32_bf16 v[22:25], v[154:157], v[210:213], v[22:25]
	s_setprio 0
	s_setprio 1
	v_mfma_f32_16x16x32_bf16 v[50:53], v[166:169], v[182:185], v[50:53]
	v_mfma_f32_16x16x32_bf16 v[42:45], v[174:177], v[182:185], v[42:45]
	v_mfma_f32_16x16x32_bf16 v[26:29], v[174:177], v[190:193], v[26:29]
	v_mfma_f32_16x16x32_bf16 v[34:37], v[166:169], v[190:193], v[34:37]
	v_mfma_f32_16x16x32_bf16 v[18:21], v[166:169], v[198:201], v[18:21]
	v_mfma_f32_16x16x32_bf16 v[10:13], v[174:177], v[198:201], v[10:13]
	v_mfma_f32_16x16x32_bf16 v[2:5], v[174:177], v[206:209], v[2:5]
	v_mfma_f32_16x16x32_bf16 v[6:9], v[166:169], v[206:209], v[6:9]
	v_mfma_f32_16x16x32_bf16 v[50:53], v[170:173], v[186:189], v[50:53]
	v_mfma_f32_16x16x32_bf16 v[42:45], v[178:181], v[186:189], v[42:45]
	v_mfma_f32_16x16x32_bf16 v[26:29], v[178:181], v[194:197], v[26:29]
	v_mfma_f32_16x16x32_bf16 v[34:37], v[170:173], v[194:197], v[34:37]
	v_mfma_f32_16x16x32_bf16 v[18:21], v[170:173], v[202:205], v[18:21]
	v_mfma_f32_16x16x32_bf16 v[10:13], v[178:181], v[202:205], v[10:13]
	v_mfma_f32_16x16x32_bf16 v[2:5], v[178:181], v[210:213], v[2:5]
	v_mfma_f32_16x16x32_bf16 v[6:9], v[170:173], v[210:213], v[6:9]
	s_setprio 0
	s_barrier
	s_add_i32 s92, s92, 2
	s_cmp_gt_u32 s92, 5
	s_mov_b64 s[46:47], s[52:53]
	s_cbranch_scc0 .LBB0_781
	s_and_b64 vcc, exec, s[8:9]
	s_cbranch_vccz .LBB0_784
	s_barrier

; #define PG8_STAGE(bufoff, gbase, voff) do { _Pragma("unroll") for (int _i = 0; _i < 2; ++_i) \
;         __builtin_amdgcn_global_load_lds((const unsigned*)((const char*)(gbase) + (voff)[_i]), (LAS unsigned*)(lds + (bufoff) + ldsw + _i * 8192), 16, 0, 0); } while (0)
; #define PG8_LDA(dst, b, h) do { _Pragma("unroll") for (int m = 0; m < 4; ++m) _Pragma("unroll") for (int k = 0; k < 2; ++k) dst[m][k] = *(const LAS bf16x8*)(lds + PG8_SA(b, h) + aoff + m * 2048 + k * 1024); } while (0)
; #define PG8_LDB(dst, b, h) do { _Pragma("unroll") for (int n = 0; n < 2; ++n) _Pragma("unroll") for (int k = 0; k < 2; ++k) dst[n][k] = *(const LAS bf16x8*)(lds + PG8_SB(b, h) + boff + n * 2048 + k * 1024); } while (0)
; #define PG8_MMA(ai, bj, At, Bt) do { __builtin_amdgcn_s_setprio(1); _Pragma("unroll") for (int m = 0; m < 4; ++m) _Pragma("unroll") for (int n = 0; n < 2; ++n) _Pragma("unroll") for (int k = 0; k < 2; ++k) \
;         acc[ai][bj][m][n] = __builtin_amdgcn_mfma_f32_16x16x32_bf16(Bt[n][k], At[m][k], acc[ai][bj][m][n], 0, 0, 0); __builtin_amdgcn_s_setprio(0); } while (0)
; #define PG8_WAIT_V(n) asm volatile("s_waitcnt vmcnt(" #n ")" ::: "memory")
; #define PG8_WAIT_L(n) asm volatile("s_waitcnt lgkmcnt(" #n ")" ::: "memory")
; #define PG8_BAR __builtin_amdgcn_s_barrier()
; #define PG8_SCHED __builtin_amdgcn_sched_barrier(0)
; template <class Epi>
; __device__ __forceinline__ void gemm_phase(LAS unsigned char* lds, const Gemm g, int G, int c, const Epi& E) {
;     ...
;             const bool last = (t == nt - 2);
;             const char* a1 = cA + (size_t)(t + 1) * kstep;
;             const char* a2 = last ? nA : cA + (size_t)(t + 2) * kstep; const char* b2 = last ? nB : cB + (size_t)(t + 2) * kstep;
;             const char* a3 = a2 + kstep; const char* b3 = b2 + kstep;
;             PG8_LDB(B0, 0, 0); PG8_LDB(B1, 0, 1); PG8_SCHED; PG8_LDA(At, 0, 0); PG8_STAGE(PG8_SA(1, 1), a1 + hstepA, voffA);
;             PG8_WAIT_V(8); PG8_WAIT_L(0); PG8_BAR; PG8_MMA(0, 0, At, B0); PG8_MMA(0, 1, At, B1); PG8_BAR; PG8_SCHED;
;             PG8_LDA(At, 0, 1); PG8_STAGE(PG8_SB(0, 0), b2, voffB); PG8_STAGE(PG8_SB(0, 1), b2 + hstepB, voffB); PG8_STAGE(PG8_SA(0, 0), a2, voffA);
.LBB0_903:
	ds_read_b128 v[130:133], v170
	ds_read_b128 v[134:137], v170 offset:1024
	ds_read_b128 v[138:141], v170 offset:2048
	ds_read_b128 v[142:145], v170 offset:3072
	ds_read_b128 v[162:165], v171
	ds_read_b128 v[174:177], v171 offset:1024
	ds_read_b128 v[178:181], v171 offset:2048
	ds_read_b128 v[182:185], v171 offset:3072
	s_add_u32 s33, s4, 0xfffc0080
	s_addc_u32 s42, s5, -1
	s_cmp_eq_u32 s46, 12
	s_cselect_b32 s45, s19, s42
	s_cselect_b32 s44, s18, s33
	s_cselect_b32 s43, s15, s39
	s_cselect_b32 s42, s17, s23
	v_lshl_add_u64 v[166:167], s[4:5], 0, v[154:155]
	s_add_i32 m0, s25, 0xc000
	ds_read_b128 v[186:189], v172
	ds_read_b128 v[190:193], v172 offset:1024
	ds_read_b128 v[194:197], v172 offset:2048
	ds_read_b128 v[198:201], v172 offset:3072
	ds_read_b128 v[202:205], v172 offset:4096
	ds_read_b128 v[206:209], v172 offset:5120
	ds_read_b128 v[210:213], v172 offset:6144
	ds_read_b128 v[214:217], v172 offset:7168
	global_load_lds_dwordx4 v[166:167], off
	v_lshl_add_u64 v[166:167], s[4:5], 0, v[156:157]
	s_add_i32 m0, s25, 0xe000
	s_nop 0
	global_load_lds_dwordx4 v[166:167], off
	s_waitcnt vmcnt(8)
	s_waitcnt lgkmcnt(0)
	s_barrier
	s_setprio 1
	s_waitcnt lgkmcnt(0)
	v_mfma_f32_16x16x32_bf16 v[126:129], v[130:133], v[186:189], v[126:129]
	v_mfma_f32_16x16x32_bf16 v[122:125], v[138:141], v[186:189], v[122:125]
	v_mfma_f32_16x16x32_bf16 v[106:109], v[138:141], v[194:197], v[106:109]
	v_mfma_f32_16x16x32_bf16 v[110:113], v[130:133], v[194:197], v[110:113]
	v_mfma_f32_16x16x32_bf16 v[94:97], v[130:133], v[202:205], v[94:97]
	v_mfma_f32_16x16x32_bf16 v[90:93], v[138:141], v[202:205], v[90:93]
	v_mfma_f32_16x16x32_bf16 v[74:77], v[138:141], v[210:213], v[74:77]
	v_mfma_f32_16x16x32_bf16 v[78:81], v[130:133], v[210:213], v[78:81]
	v_mfma_f32_16x16x32_bf16 v[126:129], v[134:137], v[190:193], v[126:129]
	v_mfma_f32_16x16x32_bf16 v[122:125], v[142:145], v[190:193], v[122:125]
	v_mfma_f32_16x16x32_bf16 v[106:109], v[142:145], v[198:201], v[106:109]
	v_mfma_f32_16x16x32_bf16 v[110:113], v[134:137], v[198:201], v[110:113]
	v_mfma_f32_16x16x32_bf16 v[94:97], v[134:137], v[206:209], v[94:97]
	v_mfma_f32_16x16x32_bf16 v[90:93], v[142:145], v[206:209], v[90:93]
	v_mfma_f32_16x16x32_bf16 v[74:77], v[142:145], v[214:217], v[74:77]
	v_mfma_f32_16x16x32_bf16 v[78:81], v[134:137], v[214:217], v[78:81]
	s_setprio 0
	s_setprio 1
	v_mfma_f32_16x16x32_bf16 v[118:121], v[162:165], v[186:189], v[118:121]
	v_mfma_f32_16x16x32_bf16 v[114:117], v[178:181], v[186:189], v[114:117]
	v_mfma_f32_16x16x32_bf16 v[98:101], v[178:181], v[194:197], v[98:101]
	v_mfma_f32_16x16x32_bf16 v[102:105], v[162:165], v[194:197], v[102:105]
	v_mfma_f32_16x16x32_bf16 v[86:89], v[162:165], v[202:205], v[86:89]
	v_mfma_f32_16x16x32_bf16 v[82:85], v[178:181], v[202:205], v[82:85]
	v_mfma_f32_16x16x32_bf16 v[66:69], v[178:181], v[210:213], v[66:69]
	v_mfma_f32_16x16x32_bf16 v[70:73], v[162:165], v[210:213], v[70:73]
	v_mfma_f32_16x16x32_bf16 v[118:121], v[174:177], v[190:193], v[118:121]
	v_mfma_f32_16x16x32_bf16 v[114:117], v[182:185], v[190:193], v[114:117]
	v_mfma_f32_16x16x32_bf16 v[98:101], v[182:185], v[198:201], v[98:101]
	v_mfma_f32_16x16x32_bf16 v[102:105], v[174:177], v[198:201], v[102:105]
	v_mfma_f32_16x16x32_bf16 v[86:89], v[174:177], v[206:209], v[86:89]
	v_mfma_f32_16x16x32_bf16 v[82:85], v[182:185], v[206:209], v[82:85]
	v_mfma_f32_16x16x32_bf16 v[66:69], v[182:185], v[214:217], v[66:69]
	v_mfma_f32_16x16x32_bf16 v[70:73], v[174:177], v[214:217], v[70:73]
	s_setprio 0
	s_barrier
	s_add_i32 s33, s72, s54
	v_lshl_add_u64 v[166:167], s[42:43], 0, v[150:151]
	s_mov_b32 m0, s33
	ds_read_b128 v[186:189], v172 offset:16384
	ds_read_b128 v[190:193], v172 offset:17408
	ds_read_b128 v[194:197], v172 offset:18432
	ds_read_b128 v[198:201], v172 offset:19456
	ds_read_b128 v[202:205], v172 offset:20480
	ds_read_b128 v[206:209], v172 offset:21504
	ds_read_b128 v[210:213], v172 offset:22528
	ds_read_b128 v[214:217], v172 offset:23552
	global_load_lds_dwordx4 v[166:167], off
	s_add_i32 m0, s33, 0x2000
	s_add_u32 s62, s42, 0x40000
	v_lshl_add_u64 v[218:219], s[42:43], 0, v[146:147]
	s_addc_u32 s63, s43, 0
	s_add_i32 s33, s73, s54
	global_load_lds_dwordx4 v[218:219], off
	v_lshl_add_u64 v[220:221], s[62:63], 0, v[150:151]
	s_mov_b32 m0, s33
	v_lshl_add_u64 v[222:223], s[44:45], 0, v[148:149]
	global_load_lds_dwordx4 v[220:221], off
	v_lshl_add_u64 v[220:221], s[62:63], 0, v[146:147]
	s_add_i32 m0, s33, 0x2000
	s_nop 0
	global_load_lds_dwordx4 v[220:221], off
	v_lshl_add_u64 v[220:221], s[44:45], 0, v[152:153]
	s_mov_b32 m0, s25
	s_nop 0
	global_load_lds_dwordx4 v[220:221], off
	s_mov_b32 m0, s57
	s_nop 0
	global_load_lds_dwordx4 v[222:223], off
	s_waitcnt vmcnt(8)
	s_waitcnt lgkmcnt(0)
	s_barrier
; #define PG8_STAGE(bufoff, gbase, voff) do { _Pragma("unroll") for (int _i = 0; _i < 2; ++_i) \
;         __builtin_amdgcn_global_load_lds((const unsigned*)((const char*)(gbase) + (voff)[_i]), (LAS unsigned*)(lds + (bufoff) + ldsw + _i * 8192), 16, 0, 0); } while (0)
; #define PG8_LDA(dst, b, h) do { _Pragma("unroll") for (int m = 0; m < 4; ++m) _Pragma("unroll") for (int k = 0; k < 2; ++k) dst[m][k] = *(const LAS bf16x8*)(lds + PG8_SA(b, h) + aoff + m * 2048 + k * 1024); } while (0)
; #define PG8_LDB(dst, b, h) do { _Pragma("unroll") for (int n = 0; n < 2; ++n) _Pragma("unroll") for (int k = 0; k < 2; ++k) dst[n][k] = *(const LAS bf16x8*)(lds + PG8_SB(b, h) + boff + n * 2048 + k * 1024); } while (0)
; #define PG8_MMA(ai, bj, At, Bt) do { __builtin_amdgcn_s_setprio(1); _Pragma("unroll") for (int m = 0; m < 4; ++m) _Pragma("unroll") for (int n = 0; n < 2; ++n) _Pragma("unroll") for (int k = 0; k < 2; ++k) \
;         acc[ai][bj][m][n] = __builtin_amdgcn_mfma_f32_16x16x32_bf16(Bt[n][k], At[m][k], acc[ai][bj][m][n], 0, 0, 0); __builtin_amdgcn_s_setprio(0); } while (0)
; #define PG8_WAIT_V(n) asm volatile("s_waitcnt vmcnt(" #n ")" ::: "memory")
; #define PG8_WAIT_L(n) asm volatile("s_waitcnt lgkmcnt(" #n ")" ::: "memory")
; #define PG8_BAR __builtin_amdgcn_s_barrier()
; #define PG8_SCHED __builtin_amdgcn_sched_barrier(0)
; template <class Epi>
; __device__ __forceinline__ void gemm_phase(LAS unsigned char* lds, const Gemm g, int G, int c, const Epi& E) {
;     ...
;             PG8_WAIT_V(8); PG8_WAIT_L(0); PG8_BAR; PG8_MMA(1, 0, At, B0); PG8_MMA(1, 1, At, B1); PG8_BAR; PG8_SCHED;
;             PG8_LDB(B0, 1, 0); PG8_LDB(B1, 1, 1); PG8_SCHED; PG8_LDA(At, 1, 0); PG8_STAGE(PG8_SA(0, 1), a2 + hstepA, voffA);
;             PG8_WAIT_V(8); PG8_WAIT_L(0); PG8_BAR; PG8_MMA(0, 0, At, B0); PG8_MMA(0, 1, At, B1); PG8_BAR; PG8_SCHED;
	s_setprio 1
	s_waitcnt lgkmcnt(0)
	v_mfma_f32_16x16x32_bf16 v[62:65], v[130:133], v[186:189], v[62:65]
	v_mfma_f32_16x16x32_bf16 v[58:61], v[138:141], v[186:189], v[58:61]
	v_mfma_f32_16x16x32_bf16 v[42:45], v[138:141], v[194:197], v[42:45]
	v_mfma_f32_16x16x32_bf16 v[46:49], v[130:133], v[194:197], v[46:49]
	v_mfma_f32_16x16x32_bf16 v[30:33], v[130:133], v[202:205], v[30:33]
	v_mfma_f32_16x16x32_bf16 v[26:29], v[138:141], v[202:205], v[26:29]
	v_mfma_f32_16x16x32_bf16 v[10:13], v[138:141], v[210:213], v[10:13]
	v_mfma_f32_16x16x32_bf16 v[14:17], v[130:133], v[210:213], v[14:17]
	v_mfma_f32_16x16x32_bf16 v[62:65], v[134:137], v[190:193], v[62:65]
	v_mfma_f32_16x16x32_bf16 v[58:61], v[142:145], v[190:193], v[58:61]
	v_mfma_f32_16x16x32_bf16 v[42:45], v[142:145], v[198:201], v[42:45]
	v_mfma_f32_16x16x32_bf16 v[46:49], v[134:137], v[198:201], v[46:49]
	v_mfma_f32_16x16x32_bf16 v[30:33], v[134:137], v[206:209], v[30:33]
	v_mfma_f32_16x16x32_bf16 v[26:29], v[142:145], v[206:209], v[26:29]
	v_mfma_f32_16x16x32_bf16 v[10:13], v[142:145], v[214:217], v[10:13]
	v_mfma_f32_16x16x32_bf16 v[14:17], v[134:137], v[214:217], v[14:17]
	s_setprio 0
	s_setprio 1
	v_mfma_f32_16x16x32_bf16 v[54:57], v[162:165], v[186:189], v[54:57]
	v_mfma_f32_16x16x32_bf16 v[50:53], v[178:181], v[186:189], v[50:53]
	v_mfma_f32_16x16x32_bf16 v[34:37], v[178:181], v[194:197], v[34:37]
	v_mfma_f32_16x16x32_bf16 v[38:41], v[162:165], v[194:197], v[38:41]
	v_mfma_f32_16x16x32_bf16 v[22:25], v[162:165], v[202:205], v[22:25]
	v_mfma_f32_16x16x32_bf16 v[18:21], v[178:181], v[202:205], v[18:21]
	v_mfma_f32_16x16x32_bf16 v[2:5], v[178:181], v[210:213], v[2:5]
	v_mfma_f32_16x16x32_bf16 v[6:9], v[162:165], v[210:213], v[6:9]
	v_mfma_f32_16x16x32_bf16 v[54:57], v[174:177], v[190:193], v[54:57]
	v_mfma_f32_16x16x32_bf16 v[50:53], v[182:185], v[190:193], v[50:53]
	v_mfma_f32_16x16x32_bf16 v[34:37], v[182:185], v[198:201], v[34:37]
	v_mfma_f32_16x16x32_bf16 v[38:41], v[174:177], v[198:201], v[38:41]
	v_mfma_f32_16x16x32_bf16 v[22:25], v[174:177], v[206:209], v[22:25]
	v_mfma_f32_16x16x32_bf16 v[18:21], v[182:185], v[206:209], v[18:21]
	v_mfma_f32_16x16x32_bf16 v[2:5], v[182:185], v[214:217], v[2:5]
	v_mfma_f32_16x16x32_bf16 v[6:9], v[174:177], v[214:217], v[6:9]
	s_setprio 0
	s_barrier
	s_add_i32 s33, 0, 0x18000
	s_add_i32 s47, 0, 0x1c000
	v_add_u32_e32 v142, s33, v169
	v_add_u32_e32 v173, s47, v169
	ds_read_b128 v[130:133], v142
	ds_read_b128 v[134:137], v142 offset:1024
	ds_read_b128 v[138:141], v142 offset:2048
	ds_read_b128 v[142:145], v142 offset:3072
	ds_read_b128 v[162:165], v173
	ds_read_b128 v[174:177], v173 offset:1024
	ds_read_b128 v[178:181], v173 offset:2048
	ds_read_b128 v[182:185], v173 offset:3072
	s_add_u32 s44, s44, 0x40000
	s_addc_u32 s45, s45, 0
	s_mov_b32 m0, s58
	v_lshl_add_u64 v[224:225], s[44:45], 0, v[152:153]
	ds_read_b128 v[186:189], v172 offset:32768
	ds_read_b128 v[190:193], v172 offset:33792
	ds_read_b128 v[194:197], v172 offset:34816
	ds_read_b128 v[198:201], v172 offset:35840
	ds_read_b128 v[202:205], v172 offset:36864
	ds_read_b128 v[206:209], v172 offset:37888
	ds_read_b128 v[210:213], v172 offset:38912
	ds_read_b128 v[214:217], v172 offset:39936
	global_load_lds_dwordx4 v[224:225], off
	v_lshl_add_u64 v[224:225], s[44:45], 0, v[148:149]
	s_mov_b32 m0, s59
	s_nop 0
	global_load_lds_dwordx4 v[224:225], off
	s_waitcnt vmcnt(8)
	s_waitcnt lgkmcnt(0)
	s_barrier
	s_setprio 1
	s_waitcnt lgkmcnt(0)
	v_mfma_f32_16x16x32_bf16 v[126:129], v[130:133], v[186:189], v[126:129]
	v_mfma_f32_16x16x32_bf16 v[122:125], v[138:141], v[186:189], v[122:125]
	v_mfma_f32_16x16x32_bf16 v[106:109], v[138:141], v[194:197], v[106:109]
	v_mfma_f32_16x16x32_bf16 v[110:113], v[130:133], v[194:197], v[110:113]
	v_mfma_f32_16x16x32_bf16 v[94:97], v[130:133], v[202:205], v[94:97]
	v_mfma_f32_16x16x32_bf16 v[90:93], v[138:141], v[202:205], v[90:93]
	v_mfma_f32_16x16x32_bf16 v[74:77], v[138:141], v[210:213], v[74:77]
	v_mfma_f32_16x16x32_bf16 v[78:81], v[130:133], v[210:213], v[78:81]
	v_mfma_f32_16x16x32_bf16 v[126:129], v[134:137], v[190:193], v[126:129]
	v_mfma_f32_16x16x32_bf16 v[122:125], v[142:145], v[190:193], v[122:125]
	v_mfma_f32_16x16x32_bf16 v[106:109], v[142:145], v[198:201], v[106:109]
	v_mfma_f32_16x16x32_bf16 v[110:113], v[134:137], v[198:201], v[110:113]
	v_mfma_f32_16x16x32_bf16 v[94:97], v[134:137], v[206:209], v[94:97]
	v_mfma_f32_16x16x32_bf16 v[90:93], v[142:145], v[206:209], v[90:93]
	v_mfma_f32_16x16x32_bf16 v[74:77], v[142:145], v[214:217], v[74:77]
	v_mfma_f32_16x16x32_bf16 v[78:81], v[134:137], v[214:217], v[78:81]
	s_setprio 0
	s_setprio 1
	v_mfma_f32_16x16x32_bf16 v[118:121], v[162:165], v[186:189], v[118:121]
	v_mfma_f32_16x16x32_bf16 v[114:117], v[178:181], v[186:189], v[114:117]
	v_mfma_f32_16x16x32_bf16 v[98:101], v[178:181], v[194:197], v[98:101]
	v_mfma_f32_16x16x32_bf16 v[102:105], v[162:165], v[194:197], v[102:105]
	v_mfma_f32_16x16x32_bf16 v[86:89], v[162:165], v[202:205], v[86:89]
	v_mfma_f32_16x16x32_bf16 v[82:85], v[178:181], v[202:205], v[82:85]
	v_mfma_f32_16x16x32_bf16 v[66:69], v[178:181], v[210:213], v[66:69]
	v_mfma_f32_16x16x32_bf16 v[70:73], v[162:165], v[210:213], v[70:73]
	v_mfma_f32_16x16x32_bf16 v[118:121], v[174:177], v[190:193], v[118:121]
	v_mfma_f32_16x16x32_bf16 v[114:117], v[182:185], v[190:193], v[114:117]
	v_mfma_f32_16x16x32_bf16 v[98:101], v[182:185], v[198:201], v[98:101]
	v_mfma_f32_16x16x32_bf16 v[102:105], v[174:177], v[198:201], v[102:105]
	v_mfma_f32_16x16x32_bf16 v[86:89], v[174:177], v[206:209], v[86:89]
	v_mfma_f32_16x16x32_bf16 v[82:85], v[182:185], v[206:209], v[82:85]
	v_mfma_f32_16x16x32_bf16 v[66:69], v[182:185], v[214:217], v[66:69]
	v_mfma_f32_16x16x32_bf16 v[70:73], v[174:177], v[214:217], v[70:73]
	s_setprio 0
	s_barrier
; #define PG8_STAGE(bufoff, gbase, voff) do { _Pragma("unroll") for (int _i = 0; _i < 2; ++_i) \
;         __builtin_amdgcn_global_load_lds((const unsigned*)((const char*)(gbase) + (voff)[_i]), (LAS unsigned*)(lds + (bufoff) + ldsw + _i * 8192), 16, 0, 0); } while (0)
; #define PG8_LDA(dst, b, h) do { _Pragma("unroll") for (int m = 0; m < 4; ++m) _Pragma("unroll") for (int k = 0; k < 2; ++k) dst[m][k] = *(const LAS bf16x8*)(lds + PG8_SA(b, h) + aoff + m * 2048 + k * 1024); } while (0)
; #define PG8_MMA(ai, bj, At, Bt) do { __builtin_amdgcn_s_setprio(1); _Pragma("unroll") for (int m = 0; m < 4; ++m) _Pragma("unroll") for (int n = 0; n < 2; ++n) _Pragma("unroll") for (int k = 0; k < 2; ++k) \
;         acc[ai][bj][m][n] = __builtin_amdgcn_mfma_f32_16x16x32_bf16(Bt[n][k], At[m][k], acc[ai][bj][m][n], 0, 0, 0); __builtin_amdgcn_s_setprio(0); } while (0)
; #define PG8_WAIT_V(n) asm volatile("s_waitcnt vmcnt(" #n ")" ::: "memory")
; #define PG8_WAIT_L(n) asm volatile("s_waitcnt lgkmcnt(" #n ")" ::: "memory")
; #define PG8_BAR __builtin_amdgcn_s_barrier()
; #define PG8_SCHED __builtin_amdgcn_sched_barrier(0)
; template <class Epi>
; __device__ __forceinline__ void gemm_phase(LAS unsigned char* lds, const Gemm g, int G, int c, const Epi& E) {
;     ...
;             PG8_LDA(At, 1, 1); PG8_STAGE(PG8_SB(1, 0), b3, voffB); PG8_STAGE(PG8_SB(1, 1), b3 + hstepB, voffB); PG8_STAGE(PG8_SA(1, 0), a3, voffA);
;             PG8_WAIT_V(8); PG8_WAIT_L(0); PG8_BAR; PG8_MMA(1, 0, At, B0); PG8_MMA(1, 1, At, B1); PG8_BAR; PG8_SCHED;
;         }
;         if (wr == 0) PG8_BAR;
	s_add_i32 s33, s33, s54
	v_lshl_add_u64 v[166:167], v[166:167], 0, s[10:11]
	s_mov_b32 m0, s33
	ds_read_b128 v[186:189], v172 offset:49152
	ds_read_b128 v[190:193], v172 offset:50176
	ds_read_b128 v[194:197], v172 offset:51200
	ds_read_b128 v[198:201], v172 offset:52224
	ds_read_b128 v[202:205], v172 offset:53248
	ds_read_b128 v[206:209], v172 offset:54272
	ds_read_b128 v[210:213], v172 offset:55296
	ds_read_b128 v[214:217], v172 offset:56320
	global_load_lds_dwordx4 v[166:167], off
	s_add_i32 m0, s33, 0x2000
	s_add_u32 s42, s42, 0x40080
	v_lshl_add_u64 v[166:167], v[218:219], 0, s[10:11]
	s_addc_u32 s43, s43, 0
	s_add_i32 s33, s47, s54
	global_load_lds_dwordx4 v[166:167], off
	v_lshl_add_u64 v[166:167], s[42:43], 0, v[150:151]
	s_mov_b32 m0, s33
	s_nop 0
	global_load_lds_dwordx4 v[166:167], off
	v_lshl_add_u64 v[166:167], s[42:43], 0, v[146:147]
	s_add_i32 m0, s33, 0x2000
	s_nop 0
	global_load_lds_dwordx4 v[166:167], off
	v_lshl_add_u64 v[166:167], v[220:221], 0, s[10:11]
	s_mov_b32 m0, s69
	s_nop 0
	global_load_lds_dwordx4 v[166:167], off
	v_lshl_add_u64 v[166:167], v[222:223], 0, s[10:11]
	s_mov_b32 m0, s70
	s_nop 0
	global_load_lds_dwordx4 v[166:167], off
	s_waitcnt vmcnt(8)
	s_waitcnt lgkmcnt(0)
	s_barrier
	s_setprio 1
	s_waitcnt lgkmcnt(0)
	v_mfma_f32_16x16x32_bf16 v[62:65], v[130:133], v[186:189], v[62:65]
	v_mfma_f32_16x16x32_bf16 v[58:61], v[138:141], v[186:189], v[58:61]
	v_mfma_f32_16x16x32_bf16 v[42:45], v[138:141], v[194:197], v[42:45]
	v_mfma_f32_16x16x32_bf16 v[46:49], v[130:133], v[194:197], v[46:49]
	v_mfma_f32_16x16x32_bf16 v[30:33], v[130:133], v[202:205], v[30:33]
	v_mfma_f32_16x16x32_bf16 v[26:29], v[138:141], v[202:205], v[26:29]
	v_mfma_f32_16x16x32_bf16 v[10:13], v[138:141], v[210:213], v[10:13]
	v_mfma_f32_16x16x32_bf16 v[14:17], v[130:133], v[210:213], v[14:17]
	v_mfma_f32_16x16x32_bf16 v[62:65], v[134:137], v[190:193], v[62:65]
	v_mfma_f32_16x16x32_bf16 v[58:61], v[142:145], v[190:193], v[58:61]
	v_mfma_f32_16x16x32_bf16 v[42:45], v[142:145], v[198:201], v[42:45]
	v_mfma_f32_16x16x32_bf16 v[46:49], v[134:137], v[198:201], v[46:49]
	v_mfma_f32_16x16x32_bf16 v[30:33], v[134:137], v[206:209], v[30:33]
	v_mfma_f32_16x16x32_bf16 v[26:29], v[142:145], v[206:209], v[26:29]
	v_mfma_f32_16x16x32_bf16 v[10:13], v[142:145], v[214:217], v[10:13]
	v_mfma_f32_16x16x32_bf16 v[14:17], v[134:137], v[214:217], v[14:17]
	s_setprio 0
	s_setprio 1
	v_mfma_f32_16x16x32_bf16 v[54:57], v[162:165], v[186:189], v[54:57]
	v_mfma_f32_16x16x32_bf16 v[50:53], v[178:181], v[186:189], v[50:53]
	v_mfma_f32_16x16x32_bf16 v[34:37], v[178:181], v[194:197], v[34:37]
	v_mfma_f32_16x16x32_bf16 v[38:41], v[162:165], v[194:197], v[38:41]
	v_mfma_f32_16x16x32_bf16 v[22:25], v[162:165], v[202:205], v[22:25]
	v_mfma_f32_16x16x32_bf16 v[18:21], v[178:181], v[202:205], v[18:21]
	v_mfma_f32_16x16x32_bf16 v[2:5], v[178:181], v[210:213], v[2:5]
	v_mfma_f32_16x16x32_bf16 v[6:9], v[162:165], v[210:213], v[6:9]
	v_mfma_f32_16x16x32_bf16 v[54:57], v[174:177], v[190:193], v[54:57]
	v_mfma_f32_16x16x32_bf16 v[50:53], v[182:185], v[190:193], v[50:53]
	v_mfma_f32_16x16x32_bf16 v[34:37], v[182:185], v[198:201], v[34:37]
	v_mfma_f32_16x16x32_bf16 v[38:41], v[174:177], v[198:201], v[38:41]
	v_mfma_f32_16x16x32_bf16 v[22:25], v[174:177], v[206:209], v[22:25]
	v_mfma_f32_16x16x32_bf16 v[18:21], v[182:185], v[206:209], v[18:21]
	v_mfma_f32_16x16x32_bf16 v[2:5], v[182:185], v[214:217], v[2:5]
	v_mfma_f32_16x16x32_bf16 v[6:9], v[174:177], v[214:217], v[6:9]
	s_setprio 0
	s_barrier
	s_add_i32 s46, s46, 2
	s_add_u32 s4, s4, 0x100
	s_addc_u32 s5, s5, 0
	s_add_u32 s23, s23, 0x100
	s_addc_u32 s39, s39, 0
	s_cmp_gt_u32 s46, 13
	s_cbranch_scc0 .LBB0_903
	s_and_b64 vcc, exec, s[12:13]
	s_cbranch_vccz .LBB0_906
	s_barrier

; #define PG8_STAGE(bufoff, gbase, voff) do { _Pragma("unroll") for (int _i = 0; _i < 2; ++_i) \
;         __builtin_amdgcn_global_load_lds((const unsigned*)((const char*)(gbase) + (voff)[_i]), (LAS unsigned*)(lds + (bufoff) + ldsw + _i * 8192), 16, 0, 0); } while (0)
; #define PG8_LDA(dst, b, h) do { _Pragma("unroll") for (int m = 0; m < 4; ++m) _Pragma("unroll") for (int k = 0; k < 2; ++k) dst[m][k] = *(const LAS bf16x8*)(lds + PG8_SA(b, h) + aoff + m * 2048 + k * 1024); } while (0)
; #define PG8_LDB(dst, b, h) do { _Pragma("unroll") for (int n = 0; n < 2; ++n) _Pragma("unroll") for (int k = 0; k < 2; ++k) dst[n][k] = *(const LAS bf16x8*)(lds + PG8_SB(b, h) + boff + n * 2048 + k * 1024); } while (0)
; #define PG8_MMA(ai, bj, At, Bt) do { __builtin_amdgcn_s_setprio(1); _Pragma("unroll") for (int m = 0; m < 4; ++m) _Pragma("unroll") for (int n = 0; n < 2; ++n) _Pragma("unroll") for (int k = 0; k < 2; ++k) \
;         acc[ai][bj][m][n] = __builtin_amdgcn_mfma_f32_16x16x32_bf16(Bt[n][k], At[m][k], acc[ai][bj][m][n], 0, 0, 0); __builtin_amdgcn_s_setprio(0); } while (0)
; #define PG8_WAIT_V(n) asm volatile("s_waitcnt vmcnt(" #n ")" ::: "memory")
; #define PG8_WAIT_L(n) asm volatile("s_waitcnt lgkmcnt(" #n ")" ::: "memory")
; #define PG8_BAR __builtin_amdgcn_s_barrier()
; #define PG8_SCHED __builtin_amdgcn_sched_barrier(0)
; template <class Epi>
; __device__ __forceinline__ void gemm_phase(LAS unsigned char* lds, const Gemm g, int G, int c, const Epi& E) {
;     ...
;             const bool last = (t == nt - 2);
;             const char* a1 = cA + (size_t)(t + 1) * kstep;
;             const char* a2 = last ? nA : cA + (size_t)(t + 2) * kstep; const char* b2 = last ? nB : cB + (size_t)(t + 2) * kstep;
;             const char* a3 = a2 + kstep; const char* b3 = b2 + kstep;
;             PG8_LDB(B0, 0, 0); PG8_LDB(B1, 0, 1); PG8_SCHED; PG8_LDA(At, 0, 0); PG8_STAGE(PG8_SA(1, 1), a1 + hstepA, voffA);
;             PG8_WAIT_V(8); PG8_WAIT_L(0); PG8_BAR; PG8_MMA(0, 0, At, B0); PG8_MMA(0, 1, At, B1); PG8_BAR; PG8_SCHED;
;             PG8_LDA(At, 0, 1); PG8_STAGE(PG8_SB(0, 0), b2, voffB); PG8_STAGE(PG8_SB(0, 1), b2 + hstepB, voffB); PG8_STAGE(PG8_SA(0, 0), a2, voffA);
.LBB0_1058:
	ds_read_b128 v[152:155], v148
	ds_read_b128 v[156:159], v148 offset:1024
	ds_read_b128 v[160:163], v148 offset:2048
	ds_read_b128 v[164:167], v148 offset:3072
	ds_read_b128 v[168:171], v149
	ds_read_b128 v[172:175], v149 offset:1024
	ds_read_b128 v[176:179], v149 offset:2048
	ds_read_b128 v[180:183], v149 offset:3072
	s_add_u32 s33, s4, 0xfffc0080
	s_addc_u32 s38, s5, -1
	s_cmp_eq_u32 s80, 12
	s_cselect_b32 s41, s21, s38
	s_cselect_b32 s40, s20, s33
	s_cselect_b32 s39, s17, s79
	s_cselect_b32 s38, s19, s78
	v_lshl_add_u64 v[216:217], s[4:5], 0, v[138:139]
	s_add_i32 m0, s25, 0xc000
	ds_read_b128 v[184:187], v150
	ds_read_b128 v[188:191], v150 offset:1024
	ds_read_b128 v[192:195], v150 offset:2048
	ds_read_b128 v[196:199], v150 offset:3072
	ds_read_b128 v[200:203], v150 offset:4096
	ds_read_b128 v[204:207], v150 offset:5120
	ds_read_b128 v[208:211], v150 offset:6144
	ds_read_b128 v[212:215], v150 offset:7168
	global_load_lds_dwordx4 v[216:217], off
	v_lshl_add_u64 v[216:217], s[4:5], 0, v[140:141]
	s_add_i32 m0, s25, 0xe000
	s_nop 0
	global_load_lds_dwordx4 v[216:217], off
	s_waitcnt vmcnt(8)
	s_waitcnt lgkmcnt(0)
	s_barrier
	s_setprio 1
	s_waitcnt lgkmcnt(0)
	v_mfma_f32_16x16x32_bf16 v[126:129], v[152:155], v[184:187], v[126:129]
	v_mfma_f32_16x16x32_bf16 v[122:125], v[160:163], v[184:187], v[122:125]
	v_mfma_f32_16x16x32_bf16 v[106:109], v[160:163], v[192:195], v[106:109]
	v_mfma_f32_16x16x32_bf16 v[110:113], v[152:155], v[192:195], v[110:113]
	v_mfma_f32_16x16x32_bf16 v[94:97], v[152:155], v[200:203], v[94:97]
	v_mfma_f32_16x16x32_bf16 v[90:93], v[160:163], v[200:203], v[90:93]
	v_mfma_f32_16x16x32_bf16 v[74:77], v[160:163], v[208:211], v[74:77]
	v_mfma_f32_16x16x32_bf16 v[78:81], v[152:155], v[208:211], v[78:81]
	v_mfma_f32_16x16x32_bf16 v[126:129], v[156:159], v[188:191], v[126:129]
	v_mfma_f32_16x16x32_bf16 v[122:125], v[164:167], v[188:191], v[122:125]
	v_mfma_f32_16x16x32_bf16 v[106:109], v[164:167], v[196:199], v[106:109]
	v_mfma_f32_16x16x32_bf16 v[110:113], v[156:159], v[196:199], v[110:113]
	v_mfma_f32_16x16x32_bf16 v[94:97], v[156:159], v[204:207], v[94:97]
	v_mfma_f32_16x16x32_bf16 v[90:93], v[164:167], v[204:207], v[90:93]
	v_mfma_f32_16x16x32_bf16 v[74:77], v[164:167], v[212:215], v[74:77]
	v_mfma_f32_16x16x32_bf16 v[78:81], v[156:159], v[212:215], v[78:81]
	s_setprio 0
	s_setprio 1
	v_mfma_f32_16x16x32_bf16 v[118:121], v[168:171], v[184:187], v[118:121]
	v_mfma_f32_16x16x32_bf16 v[114:117], v[176:179], v[184:187], v[114:117]
	v_mfma_f32_16x16x32_bf16 v[98:101], v[176:179], v[192:195], v[98:101]
	v_mfma_f32_16x16x32_bf16 v[102:105], v[168:171], v[192:195], v[102:105]
	v_mfma_f32_16x16x32_bf16 v[86:89], v[168:171], v[200:203], v[86:89]
	v_mfma_f32_16x16x32_bf16 v[82:85], v[176:179], v[200:203], v[82:85]
	v_mfma_f32_16x16x32_bf16 v[66:69], v[176:179], v[208:211], v[66:69]
	v_mfma_f32_16x16x32_bf16 v[70:73], v[168:171], v[208:211], v[70:73]
	v_mfma_f32_16x16x32_bf16 v[118:121], v[172:175], v[188:191], v[118:121]
	v_mfma_f32_16x16x32_bf16 v[114:117], v[180:183], v[188:191], v[114:117]
	v_mfma_f32_16x16x32_bf16 v[98:101], v[180:183], v[196:199], v[98:101]
	v_mfma_f32_16x16x32_bf16 v[102:105], v[172:175], v[196:199], v[102:105]
	v_mfma_f32_16x16x32_bf16 v[86:89], v[172:175], v[204:207], v[86:89]
	v_mfma_f32_16x16x32_bf16 v[82:85], v[180:183], v[204:207], v[82:85]
	v_mfma_f32_16x16x32_bf16 v[66:69], v[180:183], v[212:215], v[66:69]
	v_mfma_f32_16x16x32_bf16 v[70:73], v[172:175], v[212:215], v[70:73]
	s_setprio 0
	s_barrier
	s_add_i32 s33, s60, s46
	v_lshl_add_u64 v[216:217], s[38:39], 0, v[134:135]
	s_mov_b32 m0, s33
	ds_read_b128 v[184:187], v150 offset:16384
	ds_read_b128 v[188:191], v150 offset:17408
	ds_read_b128 v[192:195], v150 offset:18432
	ds_read_b128 v[196:199], v150 offset:19456
	ds_read_b128 v[200:203], v150 offset:20480
	ds_read_b128 v[204:207], v150 offset:21504
	ds_read_b128 v[208:211], v150 offset:22528
	ds_read_b128 v[212:215], v150 offset:23552
	global_load_lds_dwordx4 v[216:217], off
	s_add_i32 m0, s33, 0x2000
	s_add_u32 s62, s38, 0x40000
	v_lshl_add_u64 v[218:219], s[38:39], 0, v[130:131]
	s_addc_u32 s63, s39, 0
	s_add_i32 s33, s61, s46
	global_load_lds_dwordx4 v[218:219], off
	v_lshl_add_u64 v[220:221], s[62:63], 0, v[134:135]
	s_mov_b32 m0, s33
	v_lshl_add_u64 v[222:223], s[40:41], 0, v[132:133]
	global_load_lds_dwordx4 v[220:221], off
	v_lshl_add_u64 v[220:221], s[62:63], 0, v[130:131]
	s_add_i32 m0, s33, 0x2000
	s_nop 0
	global_load_lds_dwordx4 v[220:221], off
	v_lshl_add_u64 v[220:221], s[40:41], 0, v[136:137]
	s_mov_b32 m0, s25
	s_nop 0
	global_load_lds_dwordx4 v[220:221], off
	s_mov_b32 m0, s37
	s_nop 0
	global_load_lds_dwordx4 v[222:223], off
	s_waitcnt vmcnt(8)
	s_waitcnt lgkmcnt(0)
	s_barrier
; #define PG8_STAGE(bufoff, gbase, voff) do { _Pragma("unroll") for (int _i = 0; _i < 2; ++_i) \
;         __builtin_amdgcn_global_load_lds((const unsigned*)((const char*)(gbase) + (voff)[_i]), (LAS unsigned*)(lds + (bufoff) + ldsw + _i * 8192), 16, 0, 0); } while (0)
; #define PG8_LDA(dst, b, h) do { _Pragma("unroll") for (int m = 0; m < 4; ++m) _Pragma("unroll") for (int k = 0; k < 2; ++k) dst[m][k] = *(const LAS bf16x8*)(lds + PG8_SA(b, h) + aoff + m * 2048 + k * 1024); } while (0)
; #define PG8_LDB(dst, b, h) do { _Pragma("unroll") for (int n = 0; n < 2; ++n) _Pragma("unroll") for (int k = 0; k < 2; ++k) dst[n][k] = *(const LAS bf16x8*)(lds + PG8_SB(b, h) + boff + n * 2048 + k * 1024); } while (0)
; #define PG8_MMA(ai, bj, At, Bt) do { __builtin_amdgcn_s_setprio(1); _Pragma("unroll") for (int m = 0; m < 4; ++m) _Pragma("unroll") for (int n = 0; n < 2; ++n) _Pragma("unroll") for (int k = 0; k < 2; ++k) \
;         acc[ai][bj][m][n] = __builtin_amdgcn_mfma_f32_16x16x32_bf16(Bt[n][k], At[m][k], acc[ai][bj][m][n], 0, 0, 0); __builtin_amdgcn_s_setprio(0); } while (0)
; #define PG8_WAIT_V(n) asm volatile("s_waitcnt vmcnt(" #n ")" ::: "memory")
; #define PG8_WAIT_L(n) asm volatile("s_waitcnt lgkmcnt(" #n ")" ::: "memory")
; #define PG8_BAR __builtin_amdgcn_s_barrier()
; #define PG8_SCHED __builtin_amdgcn_sched_barrier(0)
; template <class Epi>
; __device__ __forceinline__ void gemm_phase(LAS unsigned char* lds, const Gemm g, int G, int c, const Epi& E) {
;     ...
;             PG8_WAIT_V(8); PG8_WAIT_L(0); PG8_BAR; PG8_MMA(1, 0, At, B0); PG8_MMA(1, 1, At, B1); PG8_BAR; PG8_SCHED;
;             PG8_LDB(B0, 1, 0); PG8_LDB(B1, 1, 1); PG8_SCHED; PG8_LDA(At, 1, 0); PG8_STAGE(PG8_SA(0, 1), a2 + hstepA, voffA);
;             PG8_WAIT_V(8); PG8_WAIT_L(0); PG8_BAR; PG8_MMA(0, 0, At, B0); PG8_MMA(0, 1, At, B1); PG8_BAR; PG8_SCHED;
	s_setprio 1
	s_waitcnt lgkmcnt(0)
	v_mfma_f32_16x16x32_bf16 v[62:65], v[152:155], v[184:187], v[62:65]
	v_mfma_f32_16x16x32_bf16 v[58:61], v[160:163], v[184:187], v[58:61]
	v_mfma_f32_16x16x32_bf16 v[42:45], v[160:163], v[192:195], v[42:45]
	v_mfma_f32_16x16x32_bf16 v[46:49], v[152:155], v[192:195], v[46:49]
	v_mfma_f32_16x16x32_bf16 v[30:33], v[152:155], v[200:203], v[30:33]
	v_mfma_f32_16x16x32_bf16 v[26:29], v[160:163], v[200:203], v[26:29]
	v_mfma_f32_16x16x32_bf16 v[10:13], v[160:163], v[208:211], v[10:13]
	v_mfma_f32_16x16x32_bf16 v[14:17], v[152:155], v[208:211], v[14:17]
	v_mfma_f32_16x16x32_bf16 v[62:65], v[156:159], v[188:191], v[62:65]
	v_mfma_f32_16x16x32_bf16 v[58:61], v[164:167], v[188:191], v[58:61]
	v_mfma_f32_16x16x32_bf16 v[42:45], v[164:167], v[196:199], v[42:45]
	v_mfma_f32_16x16x32_bf16 v[46:49], v[156:159], v[196:199], v[46:49]
	v_mfma_f32_16x16x32_bf16 v[30:33], v[156:159], v[204:207], v[30:33]
	v_mfma_f32_16x16x32_bf16 v[26:29], v[164:167], v[204:207], v[26:29]
	v_mfma_f32_16x16x32_bf16 v[10:13], v[164:167], v[212:215], v[10:13]
	v_mfma_f32_16x16x32_bf16 v[14:17], v[156:159], v[212:215], v[14:17]
	s_setprio 0
	s_setprio 1
	v_mfma_f32_16x16x32_bf16 v[54:57], v[168:171], v[184:187], v[54:57]
	v_mfma_f32_16x16x32_bf16 v[50:53], v[176:179], v[184:187], v[50:53]
	v_mfma_f32_16x16x32_bf16 v[34:37], v[176:179], v[192:195], v[34:37]
	v_mfma_f32_16x16x32_bf16 v[38:41], v[168:171], v[192:195], v[38:41]
	v_mfma_f32_16x16x32_bf16 v[22:25], v[168:171], v[200:203], v[22:25]
	v_mfma_f32_16x16x32_bf16 v[18:21], v[176:179], v[200:203], v[18:21]
	v_mfma_f32_16x16x32_bf16 v[2:5], v[176:179], v[208:211], v[2:5]
	v_mfma_f32_16x16x32_bf16 v[6:9], v[168:171], v[208:211], v[6:9]
	v_mfma_f32_16x16x32_bf16 v[54:57], v[172:175], v[188:191], v[54:57]
	v_mfma_f32_16x16x32_bf16 v[50:53], v[180:183], v[188:191], v[50:53]
	v_mfma_f32_16x16x32_bf16 v[34:37], v[180:183], v[196:199], v[34:37]
	v_mfma_f32_16x16x32_bf16 v[38:41], v[172:175], v[196:199], v[38:41]
	v_mfma_f32_16x16x32_bf16 v[22:25], v[172:175], v[204:207], v[22:25]
	v_mfma_f32_16x16x32_bf16 v[18:21], v[180:183], v[204:207], v[18:21]
	v_mfma_f32_16x16x32_bf16 v[2:5], v[180:183], v[212:215], v[2:5]
	v_mfma_f32_16x16x32_bf16 v[6:9], v[172:175], v[212:215], v[6:9]
	s_setprio 0
	s_barrier
	s_add_i32 s33, 0, 0x18000
	s_add_i32 s62, 0, 0x1c000
	v_add_u32_e32 v164, s33, v147
	v_add_u32_e32 v180, s62, v147
	ds_read_b128 v[152:155], v164
	ds_read_b128 v[156:159], v164 offset:1024
	ds_read_b128 v[160:163], v164 offset:2048
	ds_read_b128 v[164:167], v164 offset:3072
	ds_read_b128 v[168:171], v180
	ds_read_b128 v[172:175], v180 offset:1024
	ds_read_b128 v[176:179], v180 offset:2048
	ds_read_b128 v[180:183], v180 offset:3072
	s_add_u32 s40, s40, 0x40000
	s_addc_u32 s41, s41, 0
	s_mov_b32 m0, s47
	v_lshl_add_u64 v[224:225], s[40:41], 0, v[136:137]
	ds_read_b128 v[184:187], v150 offset:32768
	ds_read_b128 v[188:191], v150 offset:33792
	ds_read_b128 v[192:195], v150 offset:34816
	ds_read_b128 v[196:199], v150 offset:35840
	ds_read_b128 v[200:203], v150 offset:36864
	ds_read_b128 v[204:207], v150 offset:37888
	ds_read_b128 v[208:211], v150 offset:38912
	ds_read_b128 v[212:215], v150 offset:39936
	global_load_lds_dwordx4 v[224:225], off
	v_lshl_add_u64 v[224:225], s[40:41], 0, v[132:133]
	s_mov_b32 m0, s52
	s_nop 0
	global_load_lds_dwordx4 v[224:225], off
	s_waitcnt vmcnt(8)
	s_waitcnt lgkmcnt(0)
	s_barrier
	s_setprio 1
	s_waitcnt lgkmcnt(0)
	v_mfma_f32_16x16x32_bf16 v[126:129], v[152:155], v[184:187], v[126:129]
	v_mfma_f32_16x16x32_bf16 v[122:125], v[160:163], v[184:187], v[122:125]
	v_mfma_f32_16x16x32_bf16 v[106:109], v[160:163], v[192:195], v[106:109]
	v_mfma_f32_16x16x32_bf16 v[110:113], v[152:155], v[192:195], v[110:113]
	v_mfma_f32_16x16x32_bf16 v[94:97], v[152:155], v[200:203], v[94:97]
	v_mfma_f32_16x16x32_bf16 v[90:93], v[160:163], v[200:203], v[90:93]
	v_mfma_f32_16x16x32_bf16 v[74:77], v[160:163], v[208:211], v[74:77]
	v_mfma_f32_16x16x32_bf16 v[78:81], v[152:155], v[208:211], v[78:81]
	v_mfma_f32_16x16x32_bf16 v[126:129], v[156:159], v[188:191], v[126:129]
	v_mfma_f32_16x16x32_bf16 v[122:125], v[164:167], v[188:191], v[122:125]
	v_mfma_f32_16x16x32_bf16 v[106:109], v[164:167], v[196:199], v[106:109]
	v_mfma_f32_16x16x32_bf16 v[110:113], v[156:159], v[196:199], v[110:113]
	v_mfma_f32_16x16x32_bf16 v[94:97], v[156:159], v[204:207], v[94:97]
	v_mfma_f32_16x16x32_bf16 v[90:93], v[164:167], v[204:207], v[90:93]
	v_mfma_f32_16x16x32_bf16 v[74:77], v[164:167], v[212:215], v[74:77]
	v_mfma_f32_16x16x32_bf16 v[78:81], v[156:159], v[212:215], v[78:81]
	s_setprio 0
	s_setprio 1
	v_mfma_f32_16x16x32_bf16 v[118:121], v[168:171], v[184:187], v[118:121]
	v_mfma_f32_16x16x32_bf16 v[114:117], v[176:179], v[184:187], v[114:117]
	v_mfma_f32_16x16x32_bf16 v[98:101], v[176:179], v[192:195], v[98:101]
	v_mfma_f32_16x16x32_bf16 v[102:105], v[168:171], v[192:195], v[102:105]
	v_mfma_f32_16x16x32_bf16 v[86:89], v[168:171], v[200:203], v[86:89]
	v_mfma_f32_16x16x32_bf16 v[82:85], v[176:179], v[200:203], v[82:85]
	v_mfma_f32_16x16x32_bf16 v[66:69], v[176:179], v[208:211], v[66:69]
	v_mfma_f32_16x16x32_bf16 v[70:73], v[168:171], v[208:211], v[70:73]
	v_mfma_f32_16x16x32_bf16 v[118:121], v[172:175], v[188:191], v[118:121]
	v_mfma_f32_16x16x32_bf16 v[114:117], v[180:183], v[188:191], v[114:117]
	v_mfma_f32_16x16x32_bf16 v[98:101], v[180:183], v[196:199], v[98:101]
	v_mfma_f32_16x16x32_bf16 v[102:105], v[172:175], v[196:199], v[102:105]
	v_mfma_f32_16x16x32_bf16 v[86:89], v[172:175], v[204:207], v[86:89]
	v_mfma_f32_16x16x32_bf16 v[82:85], v[180:183], v[204:207], v[82:85]
	v_mfma_f32_16x16x32_bf16 v[66:69], v[180:183], v[212:215], v[66:69]
	v_mfma_f32_16x16x32_bf16 v[70:73], v[172:175], v[212:215], v[70:73]
	s_setprio 0
	s_barrier
; #define PG8_STAGE(bufoff, gbase, voff) do { _Pragma("unroll") for (int _i = 0; _i < 2; ++_i) \
;         __builtin_amdgcn_global_load_lds((const unsigned*)((const char*)(gbase) + (voff)[_i]), (LAS unsigned*)(lds + (bufoff) + ldsw + _i * 8192), 16, 0, 0); } while (0)
; #define PG8_LDA(dst, b, h) do { _Pragma("unroll") for (int m = 0; m < 4; ++m) _Pragma("unroll") for (int k = 0; k < 2; ++k) dst[m][k] = *(const LAS bf16x8*)(lds + PG8_SA(b, h) + aoff + m * 2048 + k * 1024); } while (0)
; #define PG8_MMA(ai, bj, At, Bt) do { __builtin_amdgcn_s_setprio(1); _Pragma("unroll") for (int m = 0; m < 4; ++m) _Pragma("unroll") for (int n = 0; n < 2; ++n) _Pragma("unroll") for (int k = 0; k < 2; ++k) \
;         acc[ai][bj][m][n] = __builtin_amdgcn_mfma_f32_16x16x32_bf16(Bt[n][k], At[m][k], acc[ai][bj][m][n], 0, 0, 0); __builtin_amdgcn_s_setprio(0); } while (0)
; #define PG8_WAIT_V(n) asm volatile("s_waitcnt vmcnt(" #n ")" ::: "memory")
; #define PG8_WAIT_L(n) asm volatile("s_waitcnt lgkmcnt(" #n ")" ::: "memory")
; #define PG8_BAR __builtin_amdgcn_s_barrier()
; #define PG8_SCHED __builtin_amdgcn_sched_barrier(0)
; template <class Epi>
; __device__ __forceinline__ void gemm_phase(LAS unsigned char* lds, const Gemm g, int G, int c, const Epi& E) {
;     ...
;             PG8_LDA(At, 1, 1); PG8_STAGE(PG8_SB(1, 0), b3, voffB); PG8_STAGE(PG8_SB(1, 1), b3 + hstepB, voffB); PG8_STAGE(PG8_SA(1, 0), a3, voffA);
;             PG8_WAIT_V(8); PG8_WAIT_L(0); PG8_BAR; PG8_MMA(1, 0, At, B0); PG8_MMA(1, 1, At, B1); PG8_BAR; PG8_SCHED;
;         }
;         if (wr == 0) PG8_BAR;
	s_add_i32 s33, s33, s46
	v_lshl_add_u64 v[216:217], v[216:217], 0, s[12:13]
	s_mov_b32 m0, s33
	ds_read_b128 v[184:187], v150 offset:49152
	ds_read_b128 v[188:191], v150 offset:50176
	ds_read_b128 v[192:195], v150 offset:51200
	ds_read_b128 v[196:199], v150 offset:52224
	ds_read_b128 v[200:203], v150 offset:53248
	ds_read_b128 v[204:207], v150 offset:54272
	ds_read_b128 v[208:211], v150 offset:55296
	ds_read_b128 v[212:215], v150 offset:56320
	global_load_lds_dwordx4 v[216:217], off
	s_add_i32 m0, s33, 0x2000
	s_add_u32 s38, s38, 0x40080
	v_lshl_add_u64 v[216:217], v[218:219], 0, s[12:13]
	s_addc_u32 s39, s39, 0
	s_add_i32 s33, s62, s46
	global_load_lds_dwordx4 v[216:217], off
	v_lshl_add_u64 v[216:217], s[38:39], 0, v[134:135]
	s_mov_b32 m0, s33
	s_nop 0
	global_load_lds_dwordx4 v[216:217], off
	v_lshl_add_u64 v[216:217], s[38:39], 0, v[130:131]
	s_add_i32 m0, s33, 0x2000
	s_nop 0
	global_load_lds_dwordx4 v[216:217], off
	v_lshl_add_u64 v[216:217], v[220:221], 0, s[12:13]
	s_mov_b32 m0, s57
	s_nop 0
	global_load_lds_dwordx4 v[216:217], off
	v_lshl_add_u64 v[216:217], v[222:223], 0, s[12:13]
	s_mov_b32 m0, s58
	s_nop 0
	global_load_lds_dwordx4 v[216:217], off
	s_waitcnt vmcnt(8)
	s_waitcnt lgkmcnt(0)
	s_barrier
	s_setprio 1
	s_waitcnt lgkmcnt(0)
	v_mfma_f32_16x16x32_bf16 v[62:65], v[152:155], v[184:187], v[62:65]
	v_mfma_f32_16x16x32_bf16 v[58:61], v[160:163], v[184:187], v[58:61]
	v_mfma_f32_16x16x32_bf16 v[42:45], v[160:163], v[192:195], v[42:45]
	v_mfma_f32_16x16x32_bf16 v[46:49], v[152:155], v[192:195], v[46:49]
	v_mfma_f32_16x16x32_bf16 v[30:33], v[152:155], v[200:203], v[30:33]
	v_mfma_f32_16x16x32_bf16 v[26:29], v[160:163], v[200:203], v[26:29]
	v_mfma_f32_16x16x32_bf16 v[10:13], v[160:163], v[208:211], v[10:13]
	v_mfma_f32_16x16x32_bf16 v[14:17], v[152:155], v[208:211], v[14:17]
	v_mfma_f32_16x16x32_bf16 v[62:65], v[156:159], v[188:191], v[62:65]
	v_mfma_f32_16x16x32_bf16 v[58:61], v[164:167], v[188:191], v[58:61]
	v_mfma_f32_16x16x32_bf16 v[42:45], v[164:167], v[196:199], v[42:45]
	v_mfma_f32_16x16x32_bf16 v[46:49], v[156:159], v[196:199], v[46:49]
	v_mfma_f32_16x16x32_bf16 v[30:33], v[156:159], v[204:207], v[30:33]
	v_mfma_f32_16x16x32_bf16 v[26:29], v[164:167], v[204:207], v[26:29]
	v_mfma_f32_16x16x32_bf16 v[10:13], v[164:167], v[212:215], v[10:13]
	v_mfma_f32_16x16x32_bf16 v[14:17], v[156:159], v[212:215], v[14:17]
	s_setprio 0
	s_setprio 1
	v_mfma_f32_16x16x32_bf16 v[54:57], v[168:171], v[184:187], v[54:57]
	v_mfma_f32_16x16x32_bf16 v[50:53], v[176:179], v[184:187], v[50:53]
	v_mfma_f32_16x16x32_bf16 v[34:37], v[176:179], v[192:195], v[34:37]
	v_mfma_f32_16x16x32_bf16 v[38:41], v[168:171], v[192:195], v[38:41]
	v_mfma_f32_16x16x32_bf16 v[22:25], v[168:171], v[200:203], v[22:25]
	v_mfma_f32_16x16x32_bf16 v[18:21], v[176:179], v[200:203], v[18:21]
	v_mfma_f32_16x16x32_bf16 v[2:5], v[176:179], v[208:211], v[2:5]
	v_mfma_f32_16x16x32_bf16 v[6:9], v[168:171], v[208:211], v[6:9]
	v_mfma_f32_16x16x32_bf16 v[54:57], v[172:175], v[188:191], v[54:57]
	v_mfma_f32_16x16x32_bf16 v[50:53], v[180:183], v[188:191], v[50:53]
	v_mfma_f32_16x16x32_bf16 v[34:37], v[180:183], v[196:199], v[34:37]
	v_mfma_f32_16x16x32_bf16 v[38:41], v[172:175], v[196:199], v[38:41]
	v_mfma_f32_16x16x32_bf16 v[22:25], v[172:175], v[204:207], v[22:25]
	v_mfma_f32_16x16x32_bf16 v[18:21], v[180:183], v[204:207], v[18:21]
	v_mfma_f32_16x16x32_bf16 v[2:5], v[180:183], v[212:215], v[2:5]
	v_mfma_f32_16x16x32_bf16 v[6:9], v[172:175], v[212:215], v[6:9]
	s_setprio 0
	s_barrier
	s_add_i32 s80, s80, 2
	s_add_u32 s4, s4, 0x100
	s_addc_u32 s5, s5, 0
	s_add_u32 s78, s78, 0x100
	s_addc_u32 s79, s79, 0
	s_cmp_gt_u32 s80, 13
	s_cbranch_scc0 .LBB0_1058
	s_and_b64 vcc, exec, s[14:15]
	s_cbranch_vccz .LBB0_1061
	s_barrier

; #define PG8_STAGE(bufoff, gbase, voff) do { _Pragma("unroll") for (int _i = 0; _i < 2; ++_i) \
;         __builtin_amdgcn_global_load_lds((const unsigned*)((const char*)(gbase) + (voff)[_i]), (LAS unsigned*)(lds + (bufoff) + ldsw + _i * 8192), 16, 0, 0); } while (0)
; #define PG8_LDA(dst, b, h) do { _Pragma("unroll") for (int m = 0; m < 4; ++m) _Pragma("unroll") for (int k = 0; k < 2; ++k) dst[m][k] = *(const LAS bf16x8*)(lds + PG8_SA(b, h) + aoff + m * 2048 + k * 1024); } while (0)
; #define PG8_LDB(dst, b, h) do { _Pragma("unroll") for (int n = 0; n < 2; ++n) _Pragma("unroll") for (int k = 0; k < 2; ++k) dst[n][k] = *(const LAS bf16x8*)(lds + PG8_SB(b, h) + boff + n * 2048 + k * 1024); } while (0)
; #define PG8_MMA(ai, bj, At, Bt) do { __builtin_amdgcn_s_setprio(1); _Pragma("unroll") for (int m = 0; m < 4; ++m) _Pragma("unroll") for (int n = 0; n < 2; ++n) _Pragma("unroll") for (int k = 0; k < 2; ++k) \
;         acc[ai][bj][m][n] = __builtin_amdgcn_mfma_f32_16x16x32_bf16(Bt[n][k], At[m][k], acc[ai][bj][m][n], 0, 0, 0); __builtin_amdgcn_s_setprio(0); } while (0)
; #define PG8_WAIT_V(n) asm volatile("s_waitcnt vmcnt(" #n ")" ::: "memory")
; #define PG8_WAIT_L(n) asm volatile("s_waitcnt lgkmcnt(" #n ")" ::: "memory")
; #define PG8_BAR __builtin_amdgcn_s_barrier()
; #define PG8_SCHED __builtin_amdgcn_sched_barrier(0)
; template <class Epi>
; __device__ __forceinline__ void gemm_phase(LAS unsigned char* lds, const Gemm g, int G, int c, const Epi& E) {
;     ...
;             const bool last = (t == nt - 2);
;             const char* a1 = cA + (size_t)(t + 1) * kstep;
;             const char* a2 = last ? nA : cA + (size_t)(t + 2) * kstep; const char* b2 = last ? nB : cB + (size_t)(t + 2) * kstep;
;             const char* a3 = a2 + kstep; const char* b3 = b2 + kstep;
;             PG8_LDB(B0, 0, 0); PG8_LDB(B1, 0, 1); PG8_SCHED; PG8_LDA(At, 0, 0); PG8_STAGE(PG8_SA(1, 1), a1 + hstepA, voffA);
;             PG8_WAIT_V(8); PG8_WAIT_L(0); PG8_BAR; PG8_MMA(0, 0, At, B0); PG8_MMA(0, 1, At, B1); PG8_BAR; PG8_SCHED;
;             PG8_LDA(At, 0, 1); PG8_STAGE(PG8_SB(0, 0), b2, voffB); PG8_STAGE(PG8_SB(0, 1), b2 + hstepB, voffB); PG8_STAGE(PG8_SA(0, 0), a2, voffA);
.LBB0_1143:
	ds_read_b128 v[122:125], v168
	ds_read_b128 v[126:129], v168 offset:1024
	ds_read_b128 v[130:133], v168 offset:2048
	ds_read_b128 v[134:137], v168 offset:3072
	ds_read_b128 v[162:165], v169
	ds_read_b128 v[172:175], v169 offset:1024
	ds_read_b128 v[176:179], v169 offset:2048
	ds_read_b128 v[180:183], v169 offset:3072
	s_add_u32 s18, s16, 0x100
	s_addc_u32 s19, s17, 0
	s_cmp_eq_u32 s68, 40
	s_cselect_b32 s23, s5, s19
	s_cselect_b32 s22, s4, s18
	s_cselect_b32 s21, s15, s67
	s_cselect_b32 s20, s14, s66
	v_lshl_add_u64 v[216:217], s[16:17], 0, v[154:155]
	s_add_i32 m0, s38, 0xc000
	ds_read_b128 v[184:187], v170
	ds_read_b128 v[188:191], v170 offset:1024
	ds_read_b128 v[192:195], v170 offset:2048
	ds_read_b128 v[196:199], v170 offset:3072
	ds_read_b128 v[200:203], v170 offset:4096
	ds_read_b128 v[204:207], v170 offset:5120
	ds_read_b128 v[208:211], v170 offset:6144
	ds_read_b128 v[212:215], v170 offset:7168
	global_load_lds_dwordx4 v[216:217], off
	v_lshl_add_u64 v[216:217], s[16:17], 0, v[156:157]
	s_add_i32 m0, s38, 0xe000
	s_nop 0
	global_load_lds_dwordx4 v[216:217], off
	s_waitcnt vmcnt(8)
	s_waitcnt lgkmcnt(0)
	s_barrier
	s_setprio 1
	s_waitcnt lgkmcnt(0)
	v_mfma_f32_16x16x32_bf16 v[142:145], v[122:125], v[184:187], v[142:145]
	v_mfma_f32_16x16x32_bf16 v[138:141], v[130:133], v[184:187], v[138:141]
	v_mfma_f32_16x16x32_bf16 v[106:109], v[130:133], v[192:195], v[106:109]
	v_mfma_f32_16x16x32_bf16 v[118:121], v[122:125], v[192:195], v[118:121]
	v_mfma_f32_16x16x32_bf16 v[102:105], v[122:125], v[200:203], v[102:105]
	v_mfma_f32_16x16x32_bf16 v[90:93], v[130:133], v[200:203], v[90:93]
	v_mfma_f32_16x16x32_bf16 v[74:77], v[130:133], v[208:211], v[74:77]
	v_mfma_f32_16x16x32_bf16 v[86:89], v[122:125], v[208:211], v[86:89]
	v_mfma_f32_16x16x32_bf16 v[142:145], v[126:129], v[188:191], v[142:145]
	v_mfma_f32_16x16x32_bf16 v[138:141], v[134:137], v[188:191], v[138:141]
	v_mfma_f32_16x16x32_bf16 v[106:109], v[134:137], v[196:199], v[106:109]
	v_mfma_f32_16x16x32_bf16 v[118:121], v[126:129], v[196:199], v[118:121]
	v_mfma_f32_16x16x32_bf16 v[102:105], v[126:129], v[204:207], v[102:105]
	v_mfma_f32_16x16x32_bf16 v[90:93], v[134:137], v[204:207], v[90:93]
	v_mfma_f32_16x16x32_bf16 v[74:77], v[134:137], v[212:215], v[74:77]
	v_mfma_f32_16x16x32_bf16 v[86:89], v[126:129], v[212:215], v[86:89]
	s_setprio 0
	s_setprio 1
	v_mfma_f32_16x16x32_bf16 v[114:117], v[162:165], v[184:187], v[114:117]
	v_mfma_f32_16x16x32_bf16 v[110:113], v[176:179], v[184:187], v[110:113]
	v_mfma_f32_16x16x32_bf16 v[94:97], v[176:179], v[192:195], v[94:97]
	v_mfma_f32_16x16x32_bf16 v[98:101], v[162:165], v[192:195], v[98:101]
	v_mfma_f32_16x16x32_bf16 v[82:85], v[162:165], v[200:203], v[82:85]
	v_mfma_f32_16x16x32_bf16 v[78:81], v[176:179], v[200:203], v[78:81]
	v_mfma_f32_16x16x32_bf16 v[66:69], v[176:179], v[208:211], v[66:69]
	v_mfma_f32_16x16x32_bf16 v[70:73], v[162:165], v[208:211], v[70:73]
	v_mfma_f32_16x16x32_bf16 v[114:117], v[172:175], v[188:191], v[114:117]
	v_mfma_f32_16x16x32_bf16 v[110:113], v[180:183], v[188:191], v[110:113]
	v_mfma_f32_16x16x32_bf16 v[94:97], v[180:183], v[196:199], v[94:97]
	v_mfma_f32_16x16x32_bf16 v[98:101], v[172:175], v[196:199], v[98:101]
	v_mfma_f32_16x16x32_bf16 v[82:85], v[172:175], v[204:207], v[82:85]
	v_mfma_f32_16x16x32_bf16 v[78:81], v[180:183], v[204:207], v[78:81]
	v_mfma_f32_16x16x32_bf16 v[66:69], v[180:183], v[212:215], v[66:69]
	v_mfma_f32_16x16x32_bf16 v[70:73], v[172:175], v[212:215], v[70:73]
	s_setprio 0
	s_barrier
	s_add_i32 s16, s54, s36
	v_lshl_add_u64 v[216:217], s[20:21], 0, v[150:151]
	s_mov_b32 m0, s16
	ds_read_b128 v[184:187], v170 offset:16384
	ds_read_b128 v[188:191], v170 offset:17408
	ds_read_b128 v[192:195], v170 offset:18432
	ds_read_b128 v[196:199], v170 offset:19456
	ds_read_b128 v[200:203], v170 offset:20480
	ds_read_b128 v[204:207], v170 offset:21504
	ds_read_b128 v[208:211], v170 offset:22528
	ds_read_b128 v[212:215], v170 offset:23552
	global_load_lds_dwordx4 v[216:217], off
	s_add_i32 m0, s16, 0x2000
	s_add_u32 s16, s20, 0xb0000
	v_lshl_add_u64 v[218:219], s[20:21], 0, v[146:147]
	s_addc_u32 s17, s21, 0
	s_add_i32 s33, s55, s36
	global_load_lds_dwordx4 v[218:219], off
	v_lshl_add_u64 v[220:221], s[16:17], 0, v[150:151]
	s_mov_b32 m0, s33
	v_lshl_add_u64 v[222:223], s[22:23], 0, v[148:149]
	global_load_lds_dwordx4 v[220:221], off
	v_lshl_add_u64 v[220:221], s[16:17], 0, v[146:147]
	s_add_i32 m0, s33, 0x2000
	s_nop 0
	global_load_lds_dwordx4 v[220:221], off
	v_lshl_add_u64 v[220:221], s[22:23], 0, v[152:153]
	s_mov_b32 m0, s38
	s_nop 0
	global_load_lds_dwordx4 v[220:221], off
	s_mov_b32 m0, s39
	s_nop 0
	global_load_lds_dwordx4 v[222:223], off
	s_waitcnt vmcnt(8)
	s_waitcnt lgkmcnt(0)
	s_barrier
; #define PG8_STAGE(bufoff, gbase, voff) do { _Pragma("unroll") for (int _i = 0; _i < 2; ++_i) \
;         __builtin_amdgcn_global_load_lds((const unsigned*)((const char*)(gbase) + (voff)[_i]), (LAS unsigned*)(lds + (bufoff) + ldsw + _i * 8192), 16, 0, 0); } while (0)
; #define PG8_LDA(dst, b, h) do { _Pragma("unroll") for (int m = 0; m < 4; ++m) _Pragma("unroll") for (int k = 0; k < 2; ++k) dst[m][k] = *(const LAS bf16x8*)(lds + PG8_SA(b, h) + aoff + m * 2048 + k * 1024); } while (0)
; #define PG8_LDB(dst, b, h) do { _Pragma("unroll") for (int n = 0; n < 2; ++n) _Pragma("unroll") for (int k = 0; k < 2; ++k) dst[n][k] = *(const LAS bf16x8*)(lds + PG8_SB(b, h) + boff + n * 2048 + k * 1024); } while (0)
; #define PG8_MMA(ai, bj, At, Bt) do { __builtin_amdgcn_s_setprio(1); _Pragma("unroll") for (int m = 0; m < 4; ++m) _Pragma("unroll") for (int n = 0; n < 2; ++n) _Pragma("unroll") for (int k = 0; k < 2; ++k) \
;         acc[ai][bj][m][n] = __builtin_amdgcn_mfma_f32_16x16x32_bf16(Bt[n][k], At[m][k], acc[ai][bj][m][n], 0, 0, 0); __builtin_amdgcn_s_setprio(0); } while (0)
; #define PG8_WAIT_V(n) asm volatile("s_waitcnt vmcnt(" #n ")" ::: "memory")
; #define PG8_WAIT_L(n) asm volatile("s_waitcnt lgkmcnt(" #n ")" ::: "memory")
; #define PG8_BAR __builtin_amdgcn_s_barrier()
; #define PG8_SCHED __builtin_amdgcn_sched_barrier(0)
; template <class Epi>
; __device__ __forceinline__ void gemm_phase(LAS unsigned char* lds, const Gemm g, int G, int c, const Epi& E) {
;     ...
;             PG8_WAIT_V(8); PG8_WAIT_L(0); PG8_BAR; PG8_MMA(1, 0, At, B0); PG8_MMA(1, 1, At, B1); PG8_BAR; PG8_SCHED;
;             PG8_LDB(B0, 1, 0); PG8_LDB(B1, 1, 1); PG8_SCHED; PG8_LDA(At, 1, 0); PG8_STAGE(PG8_SA(0, 1), a2 + hstepA, voffA);
;             PG8_WAIT_V(8); PG8_WAIT_L(0); PG8_BAR; PG8_MMA(0, 0, At, B0); PG8_MMA(0, 1, At, B1); PG8_BAR; PG8_SCHED;
	s_setprio 1
	s_waitcnt lgkmcnt(0)
	v_mfma_f32_16x16x32_bf16 v[62:65], v[122:125], v[184:187], v[62:65]
	v_mfma_f32_16x16x32_bf16 v[58:61], v[130:133], v[184:187], v[58:61]
	v_mfma_f32_16x16x32_bf16 v[42:45], v[130:133], v[192:195], v[42:45]
	v_mfma_f32_16x16x32_bf16 v[54:57], v[122:125], v[192:195], v[54:57]
	v_mfma_f32_16x16x32_bf16 v[38:41], v[122:125], v[200:203], v[38:41]
	v_mfma_f32_16x16x32_bf16 v[26:29], v[130:133], v[200:203], v[26:29]
	v_mfma_f32_16x16x32_bf16 v[10:13], v[130:133], v[208:211], v[10:13]
	v_mfma_f32_16x16x32_bf16 v[22:25], v[122:125], v[208:211], v[22:25]
	v_mfma_f32_16x16x32_bf16 v[62:65], v[126:129], v[188:191], v[62:65]
	v_mfma_f32_16x16x32_bf16 v[58:61], v[134:137], v[188:191], v[58:61]
	v_mfma_f32_16x16x32_bf16 v[42:45], v[134:137], v[196:199], v[42:45]
	v_mfma_f32_16x16x32_bf16 v[54:57], v[126:129], v[196:199], v[54:57]
	v_mfma_f32_16x16x32_bf16 v[38:41], v[126:129], v[204:207], v[38:41]
	v_mfma_f32_16x16x32_bf16 v[26:29], v[134:137], v[204:207], v[26:29]
	v_mfma_f32_16x16x32_bf16 v[10:13], v[134:137], v[212:215], v[10:13]
	v_mfma_f32_16x16x32_bf16 v[22:25], v[126:129], v[212:215], v[22:25]
	s_setprio 0
	s_setprio 1
	v_mfma_f32_16x16x32_bf16 v[50:53], v[162:165], v[184:187], v[50:53]
	v_mfma_f32_16x16x32_bf16 v[46:49], v[176:179], v[184:187], v[46:49]
	v_mfma_f32_16x16x32_bf16 v[30:33], v[176:179], v[192:195], v[30:33]
	v_mfma_f32_16x16x32_bf16 v[34:37], v[162:165], v[192:195], v[34:37]
	v_mfma_f32_16x16x32_bf16 v[18:21], v[162:165], v[200:203], v[18:21]
	v_mfma_f32_16x16x32_bf16 v[14:17], v[176:179], v[200:203], v[14:17]
	v_mfma_f32_16x16x32_bf16 v[2:5], v[176:179], v[208:211], v[2:5]
	v_mfma_f32_16x16x32_bf16 v[6:9], v[162:165], v[208:211], v[6:9]
	v_mfma_f32_16x16x32_bf16 v[50:53], v[172:175], v[188:191], v[50:53]
	v_mfma_f32_16x16x32_bf16 v[46:49], v[180:183], v[188:191], v[46:49]
	v_mfma_f32_16x16x32_bf16 v[30:33], v[180:183], v[196:199], v[30:33]
	v_mfma_f32_16x16x32_bf16 v[34:37], v[172:175], v[196:199], v[34:37]
	v_mfma_f32_16x16x32_bf16 v[18:21], v[172:175], v[204:207], v[18:21]
	v_mfma_f32_16x16x32_bf16 v[14:17], v[180:183], v[204:207], v[14:17]
	v_mfma_f32_16x16x32_bf16 v[2:5], v[180:183], v[212:215], v[2:5]
	v_mfma_f32_16x16x32_bf16 v[6:9], v[172:175], v[212:215], v[6:9]
	s_setprio 0
	s_barrier
	s_add_i32 s33, 0, 0x18000
	s_add_i32 s62, 0, 0x1c000
	v_add_u32_e32 v134, s33, v167
	v_add_u32_e32 v171, s62, v167
	ds_read_b128 v[122:125], v134
	ds_read_b128 v[126:129], v134 offset:1024
	ds_read_b128 v[130:133], v134 offset:2048
	ds_read_b128 v[134:137], v134 offset:3072
	ds_read_b128 v[162:165], v171
	ds_read_b128 v[172:175], v171 offset:1024
	ds_read_b128 v[176:179], v171 offset:2048
	ds_read_b128 v[180:183], v171 offset:3072
	s_add_u32 s16, s22, 0xb0000
	s_addc_u32 s17, s23, 0
	s_mov_b32 m0, s40
	v_lshl_add_u64 v[224:225], s[16:17], 0, v[152:153]
	ds_read_b128 v[184:187], v170 offset:32768
	ds_read_b128 v[188:191], v170 offset:33792
	ds_read_b128 v[192:195], v170 offset:34816
	ds_read_b128 v[196:199], v170 offset:35840
	ds_read_b128 v[200:203], v170 offset:36864
	ds_read_b128 v[204:207], v170 offset:37888
	ds_read_b128 v[208:211], v170 offset:38912
	ds_read_b128 v[212:215], v170 offset:39936
	global_load_lds_dwordx4 v[224:225], off
	v_lshl_add_u64 v[224:225], s[16:17], 0, v[148:149]
	s_mov_b32 m0, s41
	s_nop 0
	global_load_lds_dwordx4 v[224:225], off
	s_waitcnt vmcnt(8)
	s_waitcnt lgkmcnt(0)
	s_barrier
	s_setprio 1
	s_waitcnt lgkmcnt(0)
	v_mfma_f32_16x16x32_bf16 v[142:145], v[122:125], v[184:187], v[142:145]
	v_mfma_f32_16x16x32_bf16 v[138:141], v[130:133], v[184:187], v[138:141]
	v_mfma_f32_16x16x32_bf16 v[106:109], v[130:133], v[192:195], v[106:109]
	v_mfma_f32_16x16x32_bf16 v[118:121], v[122:125], v[192:195], v[118:121]
	v_mfma_f32_16x16x32_bf16 v[102:105], v[122:125], v[200:203], v[102:105]
	v_mfma_f32_16x16x32_bf16 v[90:93], v[130:133], v[200:203], v[90:93]
	v_mfma_f32_16x16x32_bf16 v[74:77], v[130:133], v[208:211], v[74:77]
	v_mfma_f32_16x16x32_bf16 v[86:89], v[122:125], v[208:211], v[86:89]
	v_mfma_f32_16x16x32_bf16 v[142:145], v[126:129], v[188:191], v[142:145]
	v_mfma_f32_16x16x32_bf16 v[138:141], v[134:137], v[188:191], v[138:141]
	v_mfma_f32_16x16x32_bf16 v[106:109], v[134:137], v[196:199], v[106:109]
	v_mfma_f32_16x16x32_bf16 v[118:121], v[126:129], v[196:199], v[118:121]
	v_mfma_f32_16x16x32_bf16 v[102:105], v[126:129], v[204:207], v[102:105]
	v_mfma_f32_16x16x32_bf16 v[90:93], v[134:137], v[204:207], v[90:93]
	v_mfma_f32_16x16x32_bf16 v[74:77], v[134:137], v[212:215], v[74:77]
	v_mfma_f32_16x16x32_bf16 v[86:89], v[126:129], v[212:215], v[86:89]
	s_setprio 0
	s_setprio 1
	v_mfma_f32_16x16x32_bf16 v[114:117], v[162:165], v[184:187], v[114:117]
	v_mfma_f32_16x16x32_bf16 v[110:113], v[176:179], v[184:187], v[110:113]
	v_mfma_f32_16x16x32_bf16 v[94:97], v[176:179], v[192:195], v[94:97]
	v_mfma_f32_16x16x32_bf16 v[98:101], v[162:165], v[192:195], v[98:101]
	v_mfma_f32_16x16x32_bf16 v[82:85], v[162:165], v[200:203], v[82:85]
	v_mfma_f32_16x16x32_bf16 v[78:81], v[176:179], v[200:203], v[78:81]
	v_mfma_f32_16x16x32_bf16 v[66:69], v[176:179], v[208:211], v[66:69]
	v_mfma_f32_16x16x32_bf16 v[70:73], v[162:165], v[208:211], v[70:73]
	v_mfma_f32_16x16x32_bf16 v[114:117], v[172:175], v[188:191], v[114:117]
	v_mfma_f32_16x16x32_bf16 v[110:113], v[180:183], v[188:191], v[110:113]
	v_mfma_f32_16x16x32_bf16 v[94:97], v[180:183], v[196:199], v[94:97]
	v_mfma_f32_16x16x32_bf16 v[98:101], v[172:175], v[196:199], v[98:101]
	v_mfma_f32_16x16x32_bf16 v[82:85], v[172:175], v[204:207], v[82:85]
	v_mfma_f32_16x16x32_bf16 v[78:81], v[180:183], v[204:207], v[78:81]
	v_mfma_f32_16x16x32_bf16 v[66:69], v[180:183], v[212:215], v[66:69]
	v_mfma_f32_16x16x32_bf16 v[70:73], v[172:175], v[212:215], v[70:73]
	s_setprio 0
	s_barrier
; #define PG8_STAGE(bufoff, gbase, voff) do { _Pragma("unroll") for (int _i = 0; _i < 2; ++_i) \
;         __builtin_amdgcn_global_load_lds((const unsigned*)((const char*)(gbase) + (voff)[_i]), (LAS unsigned*)(lds + (bufoff) + ldsw + _i * 8192), 16, 0, 0); } while (0)
; #define PG8_LDA(dst, b, h) do { _Pragma("unroll") for (int m = 0; m < 4; ++m) _Pragma("unroll") for (int k = 0; k < 2; ++k) dst[m][k] = *(const LAS bf16x8*)(lds + PG8_SA(b, h) + aoff + m * 2048 + k * 1024); } while (0)
; #define PG8_MMA(ai, bj, At, Bt) do { __builtin_amdgcn_s_setprio(1); _Pragma("unroll") for (int m = 0; m < 4; ++m) _Pragma("unroll") for (int n = 0; n < 2; ++n) _Pragma("unroll") for (int k = 0; k < 2; ++k) \
;         acc[ai][bj][m][n] = __builtin_amdgcn_mfma_f32_16x16x32_bf16(Bt[n][k], At[m][k], acc[ai][bj][m][n], 0, 0, 0); __builtin_amdgcn_s_setprio(0); } while (0)
; #define PG8_WAIT_V(n) asm volatile("s_waitcnt vmcnt(" #n ")" ::: "memory")
; #define PG8_WAIT_L(n) asm volatile("s_waitcnt lgkmcnt(" #n ")" ::: "memory")
; #define PG8_BAR __builtin_amdgcn_s_barrier()
; #define PG8_SCHED __builtin_amdgcn_sched_barrier(0)
; template <class Epi>
; __device__ __forceinline__ void gemm_phase(LAS unsigned char* lds, const Gemm g, int G, int c, const Epi& E) {
;     ...
;             PG8_LDA(At, 1, 1); PG8_STAGE(PG8_SB(1, 0), b3, voffB); PG8_STAGE(PG8_SB(1, 1), b3 + hstepB, voffB); PG8_STAGE(PG8_SA(1, 0), a3, voffA);
;             PG8_WAIT_V(8); PG8_WAIT_L(0); PG8_BAR; PG8_MMA(1, 0, At, B0); PG8_MMA(1, 1, At, B1); PG8_BAR; PG8_SCHED;
;         }
;         if (wr == 0) PG8_BAR;
	s_add_i32 s16, s33, s36
	v_lshl_add_u64 v[216:217], v[216:217], 0, s[10:11]
	s_mov_b32 m0, s16
	ds_read_b128 v[184:187], v170 offset:49152
	ds_read_b128 v[188:191], v170 offset:50176
	ds_read_b128 v[192:195], v170 offset:51200
	ds_read_b128 v[196:199], v170 offset:52224
	ds_read_b128 v[200:203], v170 offset:53248
	ds_read_b128 v[204:207], v170 offset:54272
	ds_read_b128 v[208:211], v170 offset:55296
	ds_read_b128 v[212:215], v170 offset:56320
	global_load_lds_dwordx4 v[216:217], off
	s_add_i32 m0, s16, 0x2000
	s_add_u32 s16, s20, 0xb0080
	v_lshl_add_u64 v[216:217], v[218:219], 0, s[10:11]
	s_addc_u32 s17, s21, 0
	s_add_i32 s20, s62, s36
	global_load_lds_dwordx4 v[216:217], off
	v_lshl_add_u64 v[216:217], s[16:17], 0, v[150:151]
	s_mov_b32 m0, s20
	s_nop 0
	global_load_lds_dwordx4 v[216:217], off
	v_lshl_add_u64 v[216:217], s[16:17], 0, v[146:147]
	s_add_i32 m0, s20, 0x2000
	s_nop 0
	global_load_lds_dwordx4 v[216:217], off
	v_lshl_add_u64 v[216:217], v[220:221], 0, s[10:11]
	s_mov_b32 m0, s47
	s_nop 0
	global_load_lds_dwordx4 v[216:217], off
	v_lshl_add_u64 v[216:217], v[222:223], 0, s[10:11]
	s_mov_b32 m0, s52
	s_nop 0
	global_load_lds_dwordx4 v[216:217], off
	s_waitcnt vmcnt(8)
	s_waitcnt lgkmcnt(0)
	s_barrier
	s_setprio 1
	s_waitcnt lgkmcnt(0)
	v_mfma_f32_16x16x32_bf16 v[62:65], v[122:125], v[184:187], v[62:65]
	v_mfma_f32_16x16x32_bf16 v[58:61], v[130:133], v[184:187], v[58:61]
	v_mfma_f32_16x16x32_bf16 v[42:45], v[130:133], v[192:195], v[42:45]
	v_mfma_f32_16x16x32_bf16 v[54:57], v[122:125], v[192:195], v[54:57]
	v_mfma_f32_16x16x32_bf16 v[38:41], v[122:125], v[200:203], v[38:41]
	v_mfma_f32_16x16x32_bf16 v[26:29], v[130:133], v[200:203], v[26:29]
	v_mfma_f32_16x16x32_bf16 v[10:13], v[130:133], v[208:211], v[10:13]
	v_mfma_f32_16x16x32_bf16 v[22:25], v[122:125], v[208:211], v[22:25]
	v_mfma_f32_16x16x32_bf16 v[62:65], v[126:129], v[188:191], v[62:65]
	v_mfma_f32_16x16x32_bf16 v[58:61], v[134:137], v[188:191], v[58:61]
	v_mfma_f32_16x16x32_bf16 v[42:45], v[134:137], v[196:199], v[42:45]
	v_mfma_f32_16x16x32_bf16 v[54:57], v[126:129], v[196:199], v[54:57]
	v_mfma_f32_16x16x32_bf16 v[38:41], v[126:129], v[204:207], v[38:41]
	v_mfma_f32_16x16x32_bf16 v[26:29], v[134:137], v[204:207], v[26:29]
	v_mfma_f32_16x16x32_bf16 v[10:13], v[134:137], v[212:215], v[10:13]
	v_mfma_f32_16x16x32_bf16 v[22:25], v[126:129], v[212:215], v[22:25]
	s_setprio 0
	s_setprio 1
	v_mfma_f32_16x16x32_bf16 v[50:53], v[162:165], v[184:187], v[50:53]
	v_mfma_f32_16x16x32_bf16 v[46:49], v[176:179], v[184:187], v[46:49]
	v_mfma_f32_16x16x32_bf16 v[30:33], v[176:179], v[192:195], v[30:33]
	v_mfma_f32_16x16x32_bf16 v[34:37], v[162:165], v[192:195], v[34:37]
	v_mfma_f32_16x16x32_bf16 v[18:21], v[162:165], v[200:203], v[18:21]
	v_mfma_f32_16x16x32_bf16 v[14:17], v[176:179], v[200:203], v[14:17]
	v_mfma_f32_16x16x32_bf16 v[2:5], v[176:179], v[208:211], v[2:5]
	v_mfma_f32_16x16x32_bf16 v[6:9], v[162:165], v[208:211], v[6:9]
	v_mfma_f32_16x16x32_bf16 v[50:53], v[172:175], v[188:191], v[50:53]
	v_mfma_f32_16x16x32_bf16 v[46:49], v[180:183], v[188:191], v[46:49]
	v_mfma_f32_16x16x32_bf16 v[30:33], v[180:183], v[196:199], v[30:33]
	v_mfma_f32_16x16x32_bf16 v[34:37], v[172:175], v[196:199], v[34:37]
	v_mfma_f32_16x16x32_bf16 v[18:21], v[172:175], v[204:207], v[18:21]
	v_mfma_f32_16x16x32_bf16 v[14:17], v[180:183], v[204:207], v[14:17]
	v_mfma_f32_16x16x32_bf16 v[2:5], v[180:183], v[212:215], v[2:5]
	v_mfma_f32_16x16x32_bf16 v[6:9], v[172:175], v[212:215], v[6:9]
	s_setprio 0
	s_barrier
	s_add_i32 s68, s68, 2
	s_add_u32 s66, s66, 0x100
	s_addc_u32 s67, s67, 0
	s_cmp_gt_u32 s68, 41
	s_mov_b64 s[16:17], s[18:19]
	s_cbranch_scc0 .LBB0_1143
	s_and_b64 vcc, exec, s[12:13]
	s_cbranch_vccz .LBB0_1146
	s_barrier

; #define PG8_STAGE(bufoff, gbase, voff) do { _Pragma("unroll") for (int _i = 0; _i < 2; ++_i) \
;         __builtin_amdgcn_global_load_lds((const unsigned*)((const char*)(gbase) + (voff)[_i]), (LAS unsigned*)(lds + (bufoff) + ldsw + _i * 8192), 16, 0, 0); } while (0)
; #define PG8_LDA(dst, b, h) do { _Pragma("unroll") for (int m = 0; m < 4; ++m) _Pragma("unroll") for (int k = 0; k < 2; ++k) dst[m][k] = *(const LAS bf16x8*)(lds + PG8_SA(b, h) + aoff + m * 2048 + k * 1024); } while (0)
; #define PG8_LDB(dst, b, h) do { _Pragma("unroll") for (int n = 0; n < 2; ++n) _Pragma("unroll") for (int k = 0; k < 2; ++k) dst[n][k] = *(const LAS bf16x8*)(lds + PG8_SB(b, h) + boff + n * 2048 + k * 1024); } while (0)
; #define PG8_MMA(ai, bj, At, Bt) do { __builtin_amdgcn_s_setprio(1); _Pragma("unroll") for (int m = 0; m < 4; ++m) _Pragma("unroll") for (int n = 0; n < 2; ++n) _Pragma("unroll") for (int k = 0; k < 2; ++k) \
;         acc[ai][bj][m][n] = __builtin_amdgcn_mfma_f32_16x16x32_bf16(Bt[n][k], At[m][k], acc[ai][bj][m][n], 0, 0, 0); __builtin_amdgcn_s_setprio(0); } while (0)
; #define PG8_WAIT_V(n) asm volatile("s_waitcnt vmcnt(" #n ")" ::: "memory")
; #define PG8_WAIT_L(n) asm volatile("s_waitcnt lgkmcnt(" #n ")" ::: "memory")
; #define PG8_BAR __builtin_amdgcn_s_barrier()
; #define PG8_SCHED __builtin_amdgcn_sched_barrier(0)
; template <class Epi>
; __device__ __forceinline__ void gemm_phase(LAS unsigned char* lds, const Gemm g, int G, int c, const Epi& E) {
;     ...
;             const bool last = (t == nt - 2);
;             const char* a1 = cA + (size_t)(t + 1) * kstep;
;             const char* a2 = last ? nA : cA + (size_t)(t + 2) * kstep; const char* b2 = last ? nB : cB + (size_t)(t + 2) * kstep;
;             const char* a3 = a2 + kstep; const char* b3 = b2 + kstep;
;             PG8_LDB(B0, 0, 0); PG8_LDB(B1, 0, 1); PG8_SCHED; PG8_LDA(At, 0, 0); PG8_STAGE(PG8_SA(1, 1), a1 + hstepA, voffA);
;             PG8_WAIT_V(8); PG8_WAIT_L(0); PG8_BAR; PG8_MMA(0, 0, At, B0); PG8_MMA(0, 1, At, B1); PG8_BAR; PG8_SCHED;
;             PG8_LDA(At, 0, 1); PG8_STAGE(PG8_SB(0, 0), b2, voffB); PG8_STAGE(PG8_SB(0, 1), b2 + hstepB, voffB); PG8_STAGE(PG8_SA(0, 0), a2, voffA);
.LBB0_1297:
	ds_read_b128 v[146:149], v152
	ds_read_b128 v[158:161], v152 offset:1024
	ds_read_b128 v[162:165], v152 offset:2048
	ds_read_b128 v[166:169], v152 offset:3072
	ds_read_b128 v[170:173], v153
	ds_read_b128 v[174:177], v153 offset:1024
	ds_read_b128 v[178:181], v153 offset:2048
	ds_read_b128 v[182:185], v153 offset:3072
	s_add_u32 s33, s4, 0xfffc0080
	s_addc_u32 s46, s5, -1
	s_cmp_eq_u32 s81, 12
	s_cselect_b32 s49, s43, s46
	s_cselect_b32 s48, s42, s33
	s_cselect_b32 s47, s7, s80
	s_cselect_b32 s46, s39, s41
	v_lshl_add_u64 v[218:219], s[4:5], 0, v[138:139]
	s_add_i32 m0, s11, 0xc000
	ds_read_b128 v[186:189], v154
	ds_read_b128 v[190:193], v154 offset:1024
	ds_read_b128 v[194:197], v154 offset:2048
	ds_read_b128 v[198:201], v154 offset:3072
	ds_read_b128 v[202:205], v154 offset:4096
	ds_read_b128 v[206:209], v154 offset:5120
	ds_read_b128 v[210:213], v154 offset:6144
	ds_read_b128 v[214:217], v154 offset:7168
	global_load_lds_dwordx4 v[218:219], off
	v_lshl_add_u64 v[218:219], s[4:5], 0, v[140:141]
	s_add_i32 m0, s11, 0xe000
	s_nop 0
	global_load_lds_dwordx4 v[218:219], off
	s_waitcnt vmcnt(8)
	s_waitcnt lgkmcnt(0)
	s_barrier
	s_setprio 1
	s_waitcnt lgkmcnt(0)
	v_mfma_f32_16x16x32_bf16 v[126:129], v[146:149], v[186:189], v[126:129]
	v_mfma_f32_16x16x32_bf16 v[122:125], v[162:165], v[186:189], v[122:125]
	v_mfma_f32_16x16x32_bf16 v[106:109], v[162:165], v[194:197], v[106:109]
	v_mfma_f32_16x16x32_bf16 v[110:113], v[146:149], v[194:197], v[110:113]
	v_mfma_f32_16x16x32_bf16 v[94:97], v[146:149], v[202:205], v[94:97]
	v_mfma_f32_16x16x32_bf16 v[90:93], v[162:165], v[202:205], v[90:93]
	v_mfma_f32_16x16x32_bf16 v[74:77], v[162:165], v[210:213], v[74:77]
	v_mfma_f32_16x16x32_bf16 v[78:81], v[146:149], v[210:213], v[78:81]
	v_mfma_f32_16x16x32_bf16 v[126:129], v[158:161], v[190:193], v[126:129]
	v_mfma_f32_16x16x32_bf16 v[122:125], v[166:169], v[190:193], v[122:125]
	v_mfma_f32_16x16x32_bf16 v[106:109], v[166:169], v[198:201], v[106:109]
	v_mfma_f32_16x16x32_bf16 v[110:113], v[158:161], v[198:201], v[110:113]
	v_mfma_f32_16x16x32_bf16 v[94:97], v[158:161], v[206:209], v[94:97]
	v_mfma_f32_16x16x32_bf16 v[90:93], v[166:169], v[206:209], v[90:93]
	v_mfma_f32_16x16x32_bf16 v[74:77], v[166:169], v[214:217], v[74:77]
	v_mfma_f32_16x16x32_bf16 v[78:81], v[158:161], v[214:217], v[78:81]
	s_setprio 0
	s_setprio 1
	v_mfma_f32_16x16x32_bf16 v[118:121], v[170:173], v[186:189], v[118:121]
	v_mfma_f32_16x16x32_bf16 v[114:117], v[178:181], v[186:189], v[114:117]
	v_mfma_f32_16x16x32_bf16 v[98:101], v[178:181], v[194:197], v[98:101]
	v_mfma_f32_16x16x32_bf16 v[102:105], v[170:173], v[194:197], v[102:105]
	v_mfma_f32_16x16x32_bf16 v[86:89], v[170:173], v[202:205], v[86:89]
	v_mfma_f32_16x16x32_bf16 v[82:85], v[178:181], v[202:205], v[82:85]
	v_mfma_f32_16x16x32_bf16 v[66:69], v[178:181], v[210:213], v[66:69]
	v_mfma_f32_16x16x32_bf16 v[70:73], v[170:173], v[210:213], v[70:73]
	v_mfma_f32_16x16x32_bf16 v[118:121], v[174:177], v[190:193], v[118:121]
	v_mfma_f32_16x16x32_bf16 v[114:117], v[182:185], v[190:193], v[114:117]
	v_mfma_f32_16x16x32_bf16 v[98:101], v[182:185], v[198:201], v[98:101]
	v_mfma_f32_16x16x32_bf16 v[102:105], v[174:177], v[198:201], v[102:105]
	v_mfma_f32_16x16x32_bf16 v[86:89], v[174:177], v[206:209], v[86:89]
	v_mfma_f32_16x16x32_bf16 v[82:85], v[182:185], v[206:209], v[82:85]
	v_mfma_f32_16x16x32_bf16 v[66:69], v[182:185], v[214:217], v[66:69]
	v_mfma_f32_16x16x32_bf16 v[70:73], v[174:177], v[214:217], v[70:73]
	s_setprio 0
	s_barrier
	s_add_i32 s33, s71, s56
	v_lshl_add_u64 v[218:219], s[46:47], 0, v[132:133]
	s_mov_b32 m0, s33
	ds_read_b128 v[186:189], v154 offset:16384
	ds_read_b128 v[190:193], v154 offset:17408
	ds_read_b128 v[194:197], v154 offset:18432
	ds_read_b128 v[198:201], v154 offset:19456
	ds_read_b128 v[202:205], v154 offset:20480
	ds_read_b128 v[206:209], v154 offset:21504
	ds_read_b128 v[210:213], v154 offset:22528
	ds_read_b128 v[214:217], v154 offset:23552
	global_load_lds_dwordx4 v[218:219], off
	s_add_i32 m0, s33, 0x2000
	s_add_u32 s62, s46, 0x40000
	v_lshl_add_u64 v[220:221], s[46:47], 0, v[136:137]
	s_addc_u32 s63, s47, 0
	s_add_i32 s33, s72, s56
	global_load_lds_dwordx4 v[220:221], off
	v_lshl_add_u64 v[222:223], s[62:63], 0, v[132:133]
	s_mov_b32 m0, s33
	v_lshl_add_u64 v[224:225], s[48:49], 0, v[134:135]
	global_load_lds_dwordx4 v[222:223], off
	v_lshl_add_u64 v[222:223], s[62:63], 0, v[136:137]
	s_add_i32 m0, s33, 0x2000
	s_nop 0
	global_load_lds_dwordx4 v[222:223], off
	v_lshl_add_u64 v[222:223], s[48:49], 0, v[130:131]
	s_mov_b32 m0, s11
	s_nop 0
	global_load_lds_dwordx4 v[222:223], off
	s_mov_b32 m0, s57
	s_nop 0
	global_load_lds_dwordx4 v[224:225], off
	s_waitcnt vmcnt(8)
	s_waitcnt lgkmcnt(0)
	s_barrier
; #define PG8_STAGE(bufoff, gbase, voff) do { _Pragma("unroll") for (int _i = 0; _i < 2; ++_i) \
;         __builtin_amdgcn_global_load_lds((const unsigned*)((const char*)(gbase) + (voff)[_i]), (LAS unsigned*)(lds + (bufoff) + ldsw + _i * 8192), 16, 0, 0); } while (0)
; #define PG8_LDA(dst, b, h) do { _Pragma("unroll") for (int m = 0; m < 4; ++m) _Pragma("unroll") for (int k = 0; k < 2; ++k) dst[m][k] = *(const LAS bf16x8*)(lds + PG8_SA(b, h) + aoff + m * 2048 + k * 1024); } while (0)
; #define PG8_LDB(dst, b, h) do { _Pragma("unroll") for (int n = 0; n < 2; ++n) _Pragma("unroll") for (int k = 0; k < 2; ++k) dst[n][k] = *(const LAS bf16x8*)(lds + PG8_SB(b, h) + boff + n * 2048 + k * 1024); } while (0)
; #define PG8_MMA(ai, bj, At, Bt) do { __builtin_amdgcn_s_setprio(1); _Pragma("unroll") for (int m = 0; m < 4; ++m) _Pragma("unroll") for (int n = 0; n < 2; ++n) _Pragma("unroll") for (int k = 0; k < 2; ++k) \
;         acc[ai][bj][m][n] = __builtin_amdgcn_mfma_f32_16x16x32_bf16(Bt[n][k], At[m][k], acc[ai][bj][m][n], 0, 0, 0); __builtin_amdgcn_s_setprio(0); } while (0)
; #define PG8_WAIT_V(n) asm volatile("s_waitcnt vmcnt(" #n ")" ::: "memory")
; #define PG8_WAIT_L(n) asm volatile("s_waitcnt lgkmcnt(" #n ")" ::: "memory")
; #define PG8_BAR __builtin_amdgcn_s_barrier()
; #define PG8_SCHED __builtin_amdgcn_sched_barrier(0)
; template <class Epi>
; __device__ __forceinline__ void gemm_phase(LAS unsigned char* lds, const Gemm g, int G, int c, const Epi& E) {
;     ...
;             PG8_WAIT_V(8); PG8_WAIT_L(0); PG8_BAR; PG8_MMA(1, 0, At, B0); PG8_MMA(1, 1, At, B1); PG8_BAR; PG8_SCHED;
;             PG8_LDB(B0, 1, 0); PG8_LDB(B1, 1, 1); PG8_SCHED; PG8_LDA(At, 1, 0); PG8_STAGE(PG8_SA(0, 1), a2 + hstepA, voffA);
;             PG8_WAIT_V(8); PG8_WAIT_L(0); PG8_BAR; PG8_MMA(0, 0, At, B0); PG8_MMA(0, 1, At, B1); PG8_BAR; PG8_SCHED;
;             PG8_LDA(At, 1, 1); PG8_STAGE(PG8_SB(1, 0), b3, voffB); PG8_STAGE(PG8_SB(1, 1), b3 + hstepB, voffB); PG8_STAGE(PG8_SA(1, 0), a3, voffA);
;             PG8_WAIT_V(8); PG8_WAIT_L(0); PG8_BAR; PG8_MMA(1, 0, At, B0); PG8_MMA(1, 1, At, B1); PG8_BAR; PG8_SCHED;
	s_setprio 1
	s_waitcnt lgkmcnt(0)
	v_mfma_f32_16x16x32_bf16 v[62:65], v[146:149], v[186:189], v[62:65]
	v_mfma_f32_16x16x32_bf16 v[58:61], v[162:165], v[186:189], v[58:61]
	v_mfma_f32_16x16x32_bf16 v[42:45], v[162:165], v[194:197], v[42:45]
	v_mfma_f32_16x16x32_bf16 v[46:49], v[146:149], v[194:197], v[46:49]
	v_mfma_f32_16x16x32_bf16 v[30:33], v[146:149], v[202:205], v[30:33]
	v_mfma_f32_16x16x32_bf16 v[26:29], v[162:165], v[202:205], v[26:29]
	v_mfma_f32_16x16x32_bf16 v[10:13], v[162:165], v[210:213], v[10:13]
	v_mfma_f32_16x16x32_bf16 v[14:17], v[146:149], v[210:213], v[14:17]
	v_mfma_f32_16x16x32_bf16 v[62:65], v[158:161], v[190:193], v[62:65]
	v_mfma_f32_16x16x32_bf16 v[58:61], v[166:169], v[190:193], v[58:61]
	v_mfma_f32_16x16x32_bf16 v[42:45], v[166:169], v[198:201], v[42:45]
	v_mfma_f32_16x16x32_bf16 v[46:49], v[158:161], v[198:201], v[46:49]
	v_mfma_f32_16x16x32_bf16 v[30:33], v[158:161], v[206:209], v[30:33]
	v_mfma_f32_16x16x32_bf16 v[26:29], v[166:169], v[206:209], v[26:29]
	v_mfma_f32_16x16x32_bf16 v[10:13], v[166:169], v[214:217], v[10:13]
	v_mfma_f32_16x16x32_bf16 v[14:17], v[158:161], v[214:217], v[14:17]
	s_setprio 0
	s_setprio 1
	v_mfma_f32_16x16x32_bf16 v[54:57], v[170:173], v[186:189], v[54:57]
	v_mfma_f32_16x16x32_bf16 v[50:53], v[178:181], v[186:189], v[50:53]
	v_mfma_f32_16x16x32_bf16 v[34:37], v[178:181], v[194:197], v[34:37]
	v_mfma_f32_16x16x32_bf16 v[38:41], v[170:173], v[194:197], v[38:41]
	v_mfma_f32_16x16x32_bf16 v[22:25], v[170:173], v[202:205], v[22:25]
	v_mfma_f32_16x16x32_bf16 v[18:21], v[178:181], v[202:205], v[18:21]
	v_mfma_f32_16x16x32_bf16 v[2:5], v[178:181], v[210:213], v[2:5]
	v_mfma_f32_16x16x32_bf16 v[6:9], v[170:173], v[210:213], v[6:9]
	v_mfma_f32_16x16x32_bf16 v[54:57], v[174:177], v[190:193], v[54:57]
	v_mfma_f32_16x16x32_bf16 v[50:53], v[182:185], v[190:193], v[50:53]
	v_mfma_f32_16x16x32_bf16 v[34:37], v[182:185], v[198:201], v[34:37]
	v_mfma_f32_16x16x32_bf16 v[38:41], v[174:177], v[198:201], v[38:41]
	v_mfma_f32_16x16x32_bf16 v[22:25], v[174:177], v[206:209], v[22:25]
	v_mfma_f32_16x16x32_bf16 v[18:21], v[182:185], v[206:209], v[18:21]
	v_mfma_f32_16x16x32_bf16 v[2:5], v[182:185], v[214:217], v[2:5]
	v_mfma_f32_16x16x32_bf16 v[6:9], v[174:177], v[214:217], v[6:9]
	s_setprio 0
	s_barrier
	s_add_i32 s33, 0, 0x18000
	v_add_u32_e32 v157, s33, v151
	s_add_i32 s62, 0, 0x1c000
	ds_read_b128 v[146:149], v157
	ds_read_b128 v[158:161], v157 offset:1024
	ds_read_b128 v[162:165], v157 offset:2048
	ds_read_b128 v[166:169], v157 offset:3072
	v_add_u32_e32 v157, s62, v151
	ds_read_b128 v[170:173], v157
	ds_read_b128 v[174:177], v157 offset:1024
	ds_read_b128 v[178:181], v157 offset:2048
	ds_read_b128 v[182:185], v157 offset:3072
	s_add_u32 s48, s48, 0x40000
	s_addc_u32 s49, s49, 0
	s_mov_b32 m0, s58
	v_lshl_add_u64 v[226:227], s[48:49], 0, v[130:131]
	ds_read_b128 v[186:189], v154 offset:32768
	ds_read_b128 v[190:193], v154 offset:33792
	ds_read_b128 v[194:197], v154 offset:34816
	ds_read_b128 v[198:201], v154 offset:35840
	ds_read_b128 v[202:205], v154 offset:36864
	ds_read_b128 v[206:209], v154 offset:37888
	ds_read_b128 v[210:213], v154 offset:38912
	ds_read_b128 v[214:217], v154 offset:39936
	global_load_lds_dwordx4 v[226:227], off
	v_lshl_add_u64 v[226:227], s[48:49], 0, v[134:135]
	s_mov_b32 m0, s59
	s_nop 0
	global_load_lds_dwordx4 v[226:227], off
	s_waitcnt vmcnt(8)
	s_waitcnt lgkmcnt(0)
	s_barrier
	s_setprio 1
	s_waitcnt lgkmcnt(0)
	v_mfma_f32_16x16x32_bf16 v[126:129], v[146:149], v[186:189], v[126:129]
	v_mfma_f32_16x16x32_bf16 v[122:125], v[162:165], v[186:189], v[122:125]
	v_mfma_f32_16x16x32_bf16 v[106:109], v[162:165], v[194:197], v[106:109]
	v_mfma_f32_16x16x32_bf16 v[110:113], v[146:149], v[194:197], v[110:113]
	v_mfma_f32_16x16x32_bf16 v[94:97], v[146:149], v[202:205], v[94:97]
	v_mfma_f32_16x16x32_bf16 v[90:93], v[162:165], v[202:205], v[90:93]
	v_mfma_f32_16x16x32_bf16 v[74:77], v[162:165], v[210:213], v[74:77]
	v_mfma_f32_16x16x32_bf16 v[78:81], v[146:149], v[210:213], v[78:81]
	v_mfma_f32_16x16x32_bf16 v[126:129], v[158:161], v[190:193], v[126:129]
	v_mfma_f32_16x16x32_bf16 v[122:125], v[166:169], v[190:193], v[122:125]
	v_mfma_f32_16x16x32_bf16 v[106:109], v[166:169], v[198:201], v[106:109]
	v_mfma_f32_16x16x32_bf16 v[110:113], v[158:161], v[198:201], v[110:113]
	v_mfma_f32_16x16x32_bf16 v[94:97], v[158:161], v[206:209], v[94:97]
	v_mfma_f32_16x16x32_bf16 v[90:93], v[166:169], v[206:209], v[90:93]
	v_mfma_f32_16x16x32_bf16 v[74:77], v[166:169], v[214:217], v[74:77]
	v_mfma_f32_16x16x32_bf16 v[78:81], v[158:161], v[214:217], v[78:81]
	s_setprio 0
	s_setprio 1
	v_mfma_f32_16x16x32_bf16 v[118:121], v[170:173], v[186:189], v[118:121]
	v_mfma_f32_16x16x32_bf16 v[114:117], v[178:181], v[186:189], v[114:117]
	v_mfma_f32_16x16x32_bf16 v[98:101], v[178:181], v[194:197], v[98:101]
	v_mfma_f32_16x16x32_bf16 v[102:105], v[170:173], v[194:197], v[102:105]
	v_mfma_f32_16x16x32_bf16 v[86:89], v[170:173], v[202:205], v[86:89]
	v_mfma_f32_16x16x32_bf16 v[82:85], v[178:181], v[202:205], v[82:85]
	v_mfma_f32_16x16x32_bf16 v[66:69], v[178:181], v[210:213], v[66:69]
	v_mfma_f32_16x16x32_bf16 v[70:73], v[170:173], v[210:213], v[70:73]
	v_mfma_f32_16x16x32_bf16 v[118:121], v[174:177], v[190:193], v[118:121]
	v_mfma_f32_16x16x32_bf16 v[114:117], v[182:185], v[190:193], v[114:117]
	v_mfma_f32_16x16x32_bf16 v[98:101], v[182:185], v[198:201], v[98:101]
	v_mfma_f32_16x16x32_bf16 v[102:105], v[174:177], v[198:201], v[102:105]
	v_mfma_f32_16x16x32_bf16 v[86:89], v[174:177], v[206:209], v[86:89]
	v_mfma_f32_16x16x32_bf16 v[82:85], v[182:185], v[206:209], v[82:85]
	v_mfma_f32_16x16x32_bf16 v[66:69], v[182:185], v[214:217], v[66:69]
	v_mfma_f32_16x16x32_bf16 v[70:73], v[174:177], v[214:217], v[70:73]
	s_setprio 0
	s_barrier
; #define PG8_STAGE(bufoff, gbase, voff) do { _Pragma("unroll") for (int _i = 0; _i < 2; ++_i) \
;         __builtin_amdgcn_global_load_lds((const unsigned*)((const char*)(gbase) + (voff)[_i]), (LAS unsigned*)(lds + (bufoff) + ldsw + _i * 8192), 16, 0, 0); } while (0)
; #define PG8_LDA(dst, b, h) do { _Pragma("unroll") for (int m = 0; m < 4; ++m) _Pragma("unroll") for (int k = 0; k < 2; ++k) dst[m][k] = *(const LAS bf16x8*)(lds + PG8_SA(b, h) + aoff + m * 2048 + k * 1024); } while (0)
; #define PG8_MMA(ai, bj, At, Bt) do { __builtin_amdgcn_s_setprio(1); _Pragma("unroll") for (int m = 0; m < 4; ++m) _Pragma("unroll") for (int n = 0; n < 2; ++n) _Pragma("unroll") for (int k = 0; k < 2; ++k) \
;         acc[ai][bj][m][n] = __builtin_amdgcn_mfma_f32_16x16x32_bf16(Bt[n][k], At[m][k], acc[ai][bj][m][n], 0, 0, 0); __builtin_amdgcn_s_setprio(0); } while (0)
; #define PG8_WAIT_V(n) asm volatile("s_waitcnt vmcnt(" #n ")" ::: "memory")
; #define PG8_WAIT_L(n) asm volatile("s_waitcnt lgkmcnt(" #n ")" ::: "memory")
; #define PG8_BAR __builtin_amdgcn_s_barrier()
; #define PG8_SCHED __builtin_amdgcn_sched_barrier(0)
; template <class Epi>
; __device__ __forceinline__ void gemm_phase(LAS unsigned char* lds, const Gemm g, int G, int c, const Epi& E) {
;     ...
;             PG8_LDA(At, 1, 1); PG8_STAGE(PG8_SB(1, 0), b3, voffB); PG8_STAGE(PG8_SB(1, 1), b3 + hstepB, voffB); PG8_STAGE(PG8_SA(1, 0), a3, voffA);
;             PG8_WAIT_V(8); PG8_WAIT_L(0); PG8_BAR; PG8_MMA(1, 0, At, B0); PG8_MMA(1, 1, At, B1); PG8_BAR; PG8_SCHED;
;         }
	s_add_i32 s33, s33, s56
	v_lshl_add_u64 v[218:219], v[218:219], 0, s[20:21]
	s_mov_b32 m0, s33
	ds_read_b128 v[186:189], v154 offset:49152
	ds_read_b128 v[190:193], v154 offset:50176
	ds_read_b128 v[194:197], v154 offset:51200
	ds_read_b128 v[198:201], v154 offset:52224
	ds_read_b128 v[202:205], v154 offset:53248
	ds_read_b128 v[206:209], v154 offset:54272
	ds_read_b128 v[210:213], v154 offset:55296
	ds_read_b128 v[214:217], v154 offset:56320
	global_load_lds_dwordx4 v[218:219], off
	s_add_i32 m0, s33, 0x2000
	s_add_u32 s46, s46, 0x40080
	v_lshl_add_u64 v[218:219], v[220:221], 0, s[20:21]
	s_addc_u32 s47, s47, 0
	s_add_i32 s33, s62, s56
	global_load_lds_dwordx4 v[218:219], off
	v_lshl_add_u64 v[218:219], s[46:47], 0, v[132:133]
	s_mov_b32 m0, s33
	s_nop 0
	global_load_lds_dwordx4 v[218:219], off
	v_lshl_add_u64 v[218:219], s[46:47], 0, v[136:137]
	s_add_i32 m0, s33, 0x2000
	s_nop 0
	global_load_lds_dwordx4 v[218:219], off
	v_lshl_add_u64 v[218:219], v[222:223], 0, s[20:21]
	s_mov_b32 m0, s67
	s_nop 0
	global_load_lds_dwordx4 v[218:219], off
	v_lshl_add_u64 v[218:219], v[224:225], 0, s[20:21]
	s_mov_b32 m0, s68
	s_nop 0
	global_load_lds_dwordx4 v[218:219], off
	s_waitcnt vmcnt(8)
	s_waitcnt lgkmcnt(0)
	s_barrier
	s_setprio 1
	s_waitcnt lgkmcnt(0)
	v_mfma_f32_16x16x32_bf16 v[62:65], v[146:149], v[186:189], v[62:65]
	v_mfma_f32_16x16x32_bf16 v[58:61], v[162:165], v[186:189], v[58:61]
	v_mfma_f32_16x16x32_bf16 v[42:45], v[162:165], v[194:197], v[42:45]
	v_mfma_f32_16x16x32_bf16 v[46:49], v[146:149], v[194:197], v[46:49]
	v_mfma_f32_16x16x32_bf16 v[30:33], v[146:149], v[202:205], v[30:33]
	v_mfma_f32_16x16x32_bf16 v[26:29], v[162:165], v[202:205], v[26:29]
	v_mfma_f32_16x16x32_bf16 v[10:13], v[162:165], v[210:213], v[10:13]
	v_mfma_f32_16x16x32_bf16 v[14:17], v[146:149], v[210:213], v[14:17]
	v_mfma_f32_16x16x32_bf16 v[62:65], v[158:161], v[190:193], v[62:65]
	v_mfma_f32_16x16x32_bf16 v[58:61], v[166:169], v[190:193], v[58:61]
	v_mfma_f32_16x16x32_bf16 v[42:45], v[166:169], v[198:201], v[42:45]
	v_mfma_f32_16x16x32_bf16 v[46:49], v[158:161], v[198:201], v[46:49]
	v_mfma_f32_16x16x32_bf16 v[30:33], v[158:161], v[206:209], v[30:33]
	v_mfma_f32_16x16x32_bf16 v[26:29], v[166:169], v[206:209], v[26:29]
	v_mfma_f32_16x16x32_bf16 v[10:13], v[166:169], v[214:217], v[10:13]
	v_mfma_f32_16x16x32_bf16 v[14:17], v[158:161], v[214:217], v[14:17]
	s_setprio 0
	s_setprio 1
	v_mfma_f32_16x16x32_bf16 v[54:57], v[170:173], v[186:189], v[54:57]
	v_mfma_f32_16x16x32_bf16 v[50:53], v[178:181], v[186:189], v[50:53]
	v_mfma_f32_16x16x32_bf16 v[34:37], v[178:181], v[194:197], v[34:37]
	v_mfma_f32_16x16x32_bf16 v[38:41], v[170:173], v[194:197], v[38:41]
	v_mfma_f32_16x16x32_bf16 v[22:25], v[170:173], v[202:205], v[22:25]
	v_mfma_f32_16x16x32_bf16 v[18:21], v[178:181], v[202:205], v[18:21]
	v_mfma_f32_16x16x32_bf16 v[2:5], v[178:181], v[210:213], v[2:5]
	v_mfma_f32_16x16x32_bf16 v[6:9], v[170:173], v[210:213], v[6:9]
	v_mfma_f32_16x16x32_bf16 v[54:57], v[174:177], v[190:193], v[54:57]
	v_mfma_f32_16x16x32_bf16 v[50:53], v[182:185], v[190:193], v[50:53]
	v_mfma_f32_16x16x32_bf16 v[34:37], v[182:185], v[198:201], v[34:37]
	v_mfma_f32_16x16x32_bf16 v[38:41], v[174:177], v[198:201], v[38:41]
	v_mfma_f32_16x16x32_bf16 v[22:25], v[174:177], v[206:209], v[22:25]
	v_mfma_f32_16x16x32_bf16 v[18:21], v[182:185], v[206:209], v[18:21]
	v_mfma_f32_16x16x32_bf16 v[2:5], v[182:185], v[214:217], v[2:5]
	v_mfma_f32_16x16x32_bf16 v[6:9], v[174:177], v[214:217], v[6:9]
	s_setprio 0
	s_barrier
	s_add_i32 s81, s81, 2
	s_add_u32 s4, s4, 0x100
	s_addc_u32 s5, s5, 0
	s_add_u32 s41, s41, 0x100
	s_addc_u32 s80, s80, 0
	s_cmp_gt_u32 s81, 13
	s_cbranch_scc0 .LBB0_1297
	s_and_b64 vcc, exec, s[22:23]
	s_cbranch_vccz .LBB0_1300
	s_barrier

; #define PG8_STAGE(bufoff, gbase, voff) do { _Pragma("unroll") for (int _i = 0; _i < 2; ++_i) \
;         __builtin_amdgcn_global_load_lds((const unsigned*)((const char*)(gbase) + (voff)[_i]), (LAS unsigned*)(lds + (bufoff) + ldsw + _i * 8192), 16, 0, 0); } while (0)
; #define PG8_LDA(dst, b, h) do { _Pragma("unroll") for (int m = 0; m < 4; ++m) _Pragma("unroll") for (int k = 0; k < 2; ++k) dst[m][k] = *(const LAS bf16x8*)(lds + PG8_SA(b, h) + aoff + m * 2048 + k * 1024); } while (0)
; #define PG8_LDB(dst, b, h) do { _Pragma("unroll") for (int n = 0; n < 2; ++n) _Pragma("unroll") for (int k = 0; k < 2; ++k) dst[n][k] = *(const LAS bf16x8*)(lds + PG8_SB(b, h) + boff + n * 2048 + k * 1024); } while (0)
; #define PG8_MMA(ai, bj, At, Bt) do { __builtin_amdgcn_s_setprio(1); _Pragma("unroll") for (int m = 0; m < 4; ++m) _Pragma("unroll") for (int n = 0; n < 2; ++n) _Pragma("unroll") for (int k = 0; k < 2; ++k) \
;         acc[ai][bj][m][n] = __builtin_amdgcn_mfma_f32_16x16x32_bf16(Bt[n][k], At[m][k], acc[ai][bj][m][n], 0, 0, 0); __builtin_amdgcn_s_setprio(0); } while (0)
; #define PG8_WAIT_V(n) asm volatile("s_waitcnt vmcnt(" #n ")" ::: "memory")
; #define PG8_WAIT_L(n) asm volatile("s_waitcnt lgkmcnt(" #n ")" ::: "memory")
; #define PG8_BAR __builtin_amdgcn_s_barrier()
; #define PG8_SCHED __builtin_amdgcn_sched_barrier(0)
; template <class Epi>
; __device__ __forceinline__ void gemm_phase(LAS unsigned char* lds, const Gemm g, int G, int c, const Epi& E) {
;     ...
;             const char* a1 = cA + (size_t)(t + 1) * kstep;
;             const char* a2 = last ? nA : cA + (size_t)(t + 2) * kstep; const char* b2 = last ? nB : cB + (size_t)(t + 2) * kstep;
;             const char* a3 = a2 + kstep; const char* b3 = b2 + kstep;
;             PG8_LDB(B0, 0, 0); PG8_LDB(B1, 0, 1); PG8_SCHED; PG8_LDA(At, 0, 0); PG8_STAGE(PG8_SA(1, 1), a1 + hstepA, voffA);
;             PG8_WAIT_V(8); PG8_WAIT_L(0); PG8_BAR; PG8_MMA(0, 0, At, B0); PG8_MMA(0, 1, At, B1); PG8_BAR; PG8_SCHED;
;             PG8_LDA(At, 0, 1); PG8_STAGE(PG8_SB(0, 0), b2, voffB); PG8_STAGE(PG8_SB(0, 1), b2 + hstepB, voffB); PG8_STAGE(PG8_SA(0, 0), a2, voffA);
.LBB0_1429:
	s_add_u32 s33, s18, s13
	s_addc_u32 s42, s19, 0
	s_add_u32 s38, s33, 0x100
	s_addc_u32 s39, s42, 0
	s_and_b64 s[24:25], s[22:23], exec
	s_cselect_b32 s39, s5, s39
	s_cselect_b32 s38, s4, s38
	s_add_u32 s13, s16, s13
	s_addc_u32 s24, s17, 0
	s_add_u32 s13, s13, 0x100
	s_addc_u32 s24, s24, 0
	s_and_b64 s[22:23], s[22:23], exec
	s_cselect_b32 s41, s15, s24
	s_cselect_b32 s40, s14, s13
	s_add_u32 s44, s33, 0xb0080
	ds_read_b128 v[142:145], v148
	ds_read_b128 v[152:155], v148 offset:1024
	ds_read_b128 v[156:159], v148 offset:2048
	ds_read_b128 v[160:163], v148 offset:3072
	ds_read_b128 v[164:167], v149
	ds_read_b128 v[168:171], v149 offset:1024
	ds_read_b128 v[172:175], v149 offset:2048
	ds_read_b128 v[176:179], v149 offset:3072
	s_addc_u32 s45, s42, 0
	s_add_i32 s65, s72, s48
	s_add_i32 m0, s49, 0xc000
	s_add_i32 s85, s49, 0xe000
	s_add_i32 s62, s65, 0x2000
	s_add_u32 s42, s40, 0xb0000
	s_addc_u32 s43, s41, 0
	s_add_i32 s64, s73, s48
	s_add_i32 s63, s64, 0x2000
	s_add_i32 s84, 0, 0x18000
	s_add_i32 s33, 0, 0x1c000
	s_add_u32 s24, s38, 0xb0000
	s_addc_u32 s25, s39, 0
	s_add_i32 s83, s84, s48
	s_add_i32 s13, s83, 0x2000
	s_add_u32 s22, s40, 0xb0080
	s_addc_u32 s23, s41, 0
	s_add_i32 s75, s33, s48
	s_add_i32 s74, s75, 0x2000
	v_lshl_add_u64 v[212:213], s[44:45], 0, v[136:137]
	ds_read_b128 v[180:183], v150
	ds_read_b128 v[184:187], v150 offset:1024
	ds_read_b128 v[188:191], v150 offset:2048
	ds_read_b128 v[192:195], v150 offset:3072
	ds_read_b128 v[196:199], v150 offset:4096
	ds_read_b128 v[200:203], v150 offset:5120
	ds_read_b128 v[204:207], v150 offset:6144
	ds_read_b128 v[208:211], v150 offset:7168
	global_load_lds_dwordx4 v[212:213], off
	v_lshl_add_u64 v[212:213], s[44:45], 0, v[132:133]
	s_mov_b32 m0, s85
	s_nop 0
	global_load_lds_dwordx4 v[212:213], off
	s_waitcnt vmcnt(8)
	s_waitcnt lgkmcnt(0)
	s_barrier
	s_setprio 1
	s_waitcnt lgkmcnt(0)
	v_mfma_f32_16x16x32_bf16 v[126:129], v[142:145], v[180:183], v[126:129]
	v_mfma_f32_16x16x32_bf16 v[122:125], v[156:159], v[180:183], v[122:125]
	v_mfma_f32_16x16x32_bf16 v[110:113], v[156:159], v[188:191], v[110:113]
	v_mfma_f32_16x16x32_bf16 v[118:121], v[142:145], v[188:191], v[118:121]
	v_mfma_f32_16x16x32_bf16 v[102:105], v[142:145], v[196:199], v[102:105]
	v_mfma_f32_16x16x32_bf16 v[94:97], v[156:159], v[196:199], v[94:97]
	v_mfma_f32_16x16x32_bf16 v[78:81], v[156:159], v[204:207], v[78:81]
	v_mfma_f32_16x16x32_bf16 v[86:89], v[142:145], v[204:207], v[86:89]
	v_mfma_f32_16x16x32_bf16 v[126:129], v[152:155], v[184:187], v[126:129]
	v_mfma_f32_16x16x32_bf16 v[122:125], v[160:163], v[184:187], v[122:125]
	v_mfma_f32_16x16x32_bf16 v[110:113], v[160:163], v[192:195], v[110:113]
	v_mfma_f32_16x16x32_bf16 v[118:121], v[152:155], v[192:195], v[118:121]
	v_mfma_f32_16x16x32_bf16 v[102:105], v[152:155], v[200:203], v[102:105]
	v_mfma_f32_16x16x32_bf16 v[94:97], v[160:163], v[200:203], v[94:97]
	v_mfma_f32_16x16x32_bf16 v[78:81], v[160:163], v[208:211], v[78:81]
	v_mfma_f32_16x16x32_bf16 v[86:89], v[152:155], v[208:211], v[86:89]
	s_setprio 0
	s_setprio 1
	v_mfma_f32_16x16x32_bf16 v[114:117], v[164:167], v[180:183], v[114:117]
	v_mfma_f32_16x16x32_bf16 v[106:109], v[172:175], v[180:183], v[106:109]
	v_mfma_f32_16x16x32_bf16 v[90:93], v[172:175], v[188:191], v[90:93]
	v_mfma_f32_16x16x32_bf16 v[98:101], v[164:167], v[188:191], v[98:101]
	v_mfma_f32_16x16x32_bf16 v[82:85], v[164:167], v[196:199], v[82:85]
	v_mfma_f32_16x16x32_bf16 v[74:77], v[172:175], v[196:199], v[74:77]
	v_mfma_f32_16x16x32_bf16 v[66:69], v[172:175], v[204:207], v[66:69]
	v_mfma_f32_16x16x32_bf16 v[70:73], v[164:167], v[204:207], v[70:73]
	v_mfma_f32_16x16x32_bf16 v[114:117], v[168:171], v[184:187], v[114:117]
	v_mfma_f32_16x16x32_bf16 v[106:109], v[176:179], v[184:187], v[106:109]
	v_mfma_f32_16x16x32_bf16 v[90:93], v[176:179], v[192:195], v[90:93]
	v_mfma_f32_16x16x32_bf16 v[98:101], v[168:171], v[192:195], v[98:101]
	v_mfma_f32_16x16x32_bf16 v[82:85], v[168:171], v[200:203], v[82:85]
	v_mfma_f32_16x16x32_bf16 v[74:77], v[176:179], v[200:203], v[74:77]
	v_mfma_f32_16x16x32_bf16 v[66:69], v[176:179], v[208:211], v[66:69]
	v_mfma_f32_16x16x32_bf16 v[70:73], v[168:171], v[208:211], v[70:73]
	s_setprio 0
	s_barrier
	s_mov_b32 m0, s65
	v_lshl_add_u64 v[212:213], s[40:41], 0, v[134:135]
	ds_read_b128 v[180:183], v150 offset:16384
	ds_read_b128 v[184:187], v150 offset:17408
	ds_read_b128 v[188:191], v150 offset:18432
	ds_read_b128 v[192:195], v150 offset:19456
	ds_read_b128 v[196:199], v150 offset:20480
	ds_read_b128 v[200:203], v150 offset:21504
	ds_read_b128 v[204:207], v150 offset:22528
	ds_read_b128 v[208:211], v150 offset:23552
	global_load_lds_dwordx4 v[212:213], off
	v_lshl_add_u64 v[214:215], s[40:41], 0, v[130:131]
	s_mov_b32 m0, s62
	v_lshl_add_u64 v[216:217], s[42:43], 0, v[134:135]
	global_load_lds_dwordx4 v[214:215], off
	s_mov_b32 m0, s64
	v_lshl_add_u64 v[218:219], s[38:39], 0, v[132:133]
	global_load_lds_dwordx4 v[216:217], off
	v_lshl_add_u64 v[216:217], s[42:43], 0, v[130:131]
	s_mov_b32 m0, s63
	s_nop 0
	global_load_lds_dwordx4 v[216:217], off
	v_lshl_add_u64 v[216:217], s[38:39], 0, v[136:137]
	s_mov_b32 m0, s49
	s_nop 0
	global_load_lds_dwordx4 v[216:217], off
	s_mov_b32 m0, s52
	s_nop 0
	global_load_lds_dwordx4 v[218:219], off
	s_waitcnt vmcnt(8)
	s_waitcnt lgkmcnt(0)
	s_barrier
; #define PG8_STAGE(bufoff, gbase, voff) do { _Pragma("unroll") for (int _i = 0; _i < 2; ++_i) \
;         __builtin_amdgcn_global_load_lds((const unsigned*)((const char*)(gbase) + (voff)[_i]), (LAS unsigned*)(lds + (bufoff) + ldsw + _i * 8192), 16, 0, 0); } while (0)
; #define PG8_LDA(dst, b, h) do { _Pragma("unroll") for (int m = 0; m < 4; ++m) _Pragma("unroll") for (int k = 0; k < 2; ++k) dst[m][k] = *(const LAS bf16x8*)(lds + PG8_SA(b, h) + aoff + m * 2048 + k * 1024); } while (0)
; #define PG8_LDB(dst, b, h) do { _Pragma("unroll") for (int n = 0; n < 2; ++n) _Pragma("unroll") for (int k = 0; k < 2; ++k) dst[n][k] = *(const LAS bf16x8*)(lds + PG8_SB(b, h) + boff + n * 2048 + k * 1024); } while (0)
; #define PG8_MMA(ai, bj, At, Bt) do { __builtin_amdgcn_s_setprio(1); _Pragma("unroll") for (int m = 0; m < 4; ++m) _Pragma("unroll") for (int n = 0; n < 2; ++n) _Pragma("unroll") for (int k = 0; k < 2; ++k) \
;         acc[ai][bj][m][n] = __builtin_amdgcn_mfma_f32_16x16x32_bf16(Bt[n][k], At[m][k], acc[ai][bj][m][n], 0, 0, 0); __builtin_amdgcn_s_setprio(0); } while (0)
; #define PG8_WAIT_V(n) asm volatile("s_waitcnt vmcnt(" #n ")" ::: "memory")
; #define PG8_WAIT_L(n) asm volatile("s_waitcnt lgkmcnt(" #n ")" ::: "memory")
; #define PG8_BAR __builtin_amdgcn_s_barrier()
; #define PG8_SCHED __builtin_amdgcn_sched_barrier(0)
; template <class Epi>
; __device__ __forceinline__ void gemm_phase(LAS unsigned char* lds, const Gemm g, int G, int c, const Epi& E) {
;     ...
;             PG8_WAIT_V(8); PG8_WAIT_L(0); PG8_BAR; PG8_MMA(1, 0, At, B0); PG8_MMA(1, 1, At, B1); PG8_BAR; PG8_SCHED;
;             PG8_LDB(B0, 1, 0); PG8_LDB(B1, 1, 1); PG8_SCHED; PG8_LDA(At, 1, 0); PG8_STAGE(PG8_SA(0, 1), a2 + hstepA, voffA);
;             PG8_WAIT_V(8); PG8_WAIT_L(0); PG8_BAR; PG8_MMA(0, 0, At, B0); PG8_MMA(0, 1, At, B1); PG8_BAR; PG8_SCHED;
;             PG8_LDA(At, 1, 1); PG8_STAGE(PG8_SB(1, 0), b3, voffB); PG8_STAGE(PG8_SB(1, 1), b3 + hstepB, voffB); PG8_STAGE(PG8_SA(1, 0), a3, voffA);
	s_setprio 1
	s_waitcnt lgkmcnt(0)
	v_mfma_f32_16x16x32_bf16 v[62:65], v[142:145], v[180:183], v[62:65]
	v_mfma_f32_16x16x32_bf16 v[58:61], v[156:159], v[180:183], v[58:61]
	v_mfma_f32_16x16x32_bf16 v[46:49], v[156:159], v[188:191], v[46:49]
	v_mfma_f32_16x16x32_bf16 v[54:57], v[142:145], v[188:191], v[54:57]
	v_mfma_f32_16x16x32_bf16 v[38:41], v[142:145], v[196:199], v[38:41]
	v_mfma_f32_16x16x32_bf16 v[30:33], v[156:159], v[196:199], v[30:33]
	v_mfma_f32_16x16x32_bf16 v[14:17], v[156:159], v[204:207], v[14:17]
	v_mfma_f32_16x16x32_bf16 v[22:25], v[142:145], v[204:207], v[22:25]
	v_mfma_f32_16x16x32_bf16 v[62:65], v[152:155], v[184:187], v[62:65]
	v_mfma_f32_16x16x32_bf16 v[58:61], v[160:163], v[184:187], v[58:61]
	v_mfma_f32_16x16x32_bf16 v[46:49], v[160:163], v[192:195], v[46:49]
	v_mfma_f32_16x16x32_bf16 v[54:57], v[152:155], v[192:195], v[54:57]
	v_mfma_f32_16x16x32_bf16 v[38:41], v[152:155], v[200:203], v[38:41]
	v_mfma_f32_16x16x32_bf16 v[30:33], v[160:163], v[200:203], v[30:33]
	v_mfma_f32_16x16x32_bf16 v[14:17], v[160:163], v[208:211], v[14:17]
	v_mfma_f32_16x16x32_bf16 v[22:25], v[152:155], v[208:211], v[22:25]
	s_setprio 0
	s_setprio 1
	v_mfma_f32_16x16x32_bf16 v[50:53], v[164:167], v[180:183], v[50:53]
	v_mfma_f32_16x16x32_bf16 v[42:45], v[172:175], v[180:183], v[42:45]
	v_mfma_f32_16x16x32_bf16 v[26:29], v[172:175], v[188:191], v[26:29]
	v_mfma_f32_16x16x32_bf16 v[34:37], v[164:167], v[188:191], v[34:37]
	v_mfma_f32_16x16x32_bf16 v[18:21], v[164:167], v[196:199], v[18:21]
	v_mfma_f32_16x16x32_bf16 v[10:13], v[172:175], v[196:199], v[10:13]
	v_mfma_f32_16x16x32_bf16 v[2:5], v[172:175], v[204:207], v[2:5]
	v_mfma_f32_16x16x32_bf16 v[6:9], v[164:167], v[204:207], v[6:9]
	v_mfma_f32_16x16x32_bf16 v[50:53], v[168:171], v[184:187], v[50:53]
	v_mfma_f32_16x16x32_bf16 v[42:45], v[176:179], v[184:187], v[42:45]
	v_mfma_f32_16x16x32_bf16 v[26:29], v[176:179], v[192:195], v[26:29]
	v_mfma_f32_16x16x32_bf16 v[34:37], v[168:171], v[192:195], v[34:37]
	v_mfma_f32_16x16x32_bf16 v[18:21], v[168:171], v[200:203], v[18:21]
	v_mfma_f32_16x16x32_bf16 v[10:13], v[176:179], v[200:203], v[10:13]
	v_mfma_f32_16x16x32_bf16 v[2:5], v[176:179], v[208:211], v[2:5]
	v_mfma_f32_16x16x32_bf16 v[6:9], v[168:171], v[208:211], v[6:9]
	s_setprio 0
	s_barrier
	v_add_u32_e32 v151, s84, v147
	ds_read_b128 v[142:145], v151
	ds_read_b128 v[152:155], v151 offset:1024
	ds_read_b128 v[156:159], v151 offset:2048
	ds_read_b128 v[160:163], v151 offset:3072
	v_add_u32_e32 v151, s33, v147
	ds_read_b128 v[164:167], v151
	ds_read_b128 v[168:171], v151 offset:1024
	ds_read_b128 v[172:175], v151 offset:2048
	ds_read_b128 v[176:179], v151 offset:3072
	s_mov_b32 m0, s53
	v_lshl_add_u64 v[220:221], s[24:25], 0, v[136:137]
	ds_read_b128 v[180:183], v150 offset:32768
	ds_read_b128 v[184:187], v150 offset:33792
	ds_read_b128 v[188:191], v150 offset:34816
	ds_read_b128 v[192:195], v150 offset:35840
	ds_read_b128 v[196:199], v150 offset:36864
	ds_read_b128 v[200:203], v150 offset:37888
	ds_read_b128 v[204:207], v150 offset:38912
	ds_read_b128 v[208:211], v150 offset:39936
	global_load_lds_dwordx4 v[220:221], off
	v_lshl_add_u64 v[220:221], s[24:25], 0, v[132:133]
	s_mov_b32 m0, s54
	s_nop 0
	global_load_lds_dwordx4 v[220:221], off
	s_waitcnt vmcnt(8)
	s_waitcnt lgkmcnt(0)
	s_barrier
	s_setprio 1
	s_waitcnt lgkmcnt(0)
	v_mfma_f32_16x16x32_bf16 v[126:129], v[142:145], v[180:183], v[126:129]
	v_mfma_f32_16x16x32_bf16 v[122:125], v[156:159], v[180:183], v[122:125]
	v_mfma_f32_16x16x32_bf16 v[110:113], v[156:159], v[188:191], v[110:113]
	v_mfma_f32_16x16x32_bf16 v[118:121], v[142:145], v[188:191], v[118:121]
	v_mfma_f32_16x16x32_bf16 v[102:105], v[142:145], v[196:199], v[102:105]
	v_mfma_f32_16x16x32_bf16 v[94:97], v[156:159], v[196:199], v[94:97]
	v_mfma_f32_16x16x32_bf16 v[78:81], v[156:159], v[204:207], v[78:81]
	v_mfma_f32_16x16x32_bf16 v[86:89], v[142:145], v[204:207], v[86:89]
	v_mfma_f32_16x16x32_bf16 v[126:129], v[152:155], v[184:187], v[126:129]
	v_mfma_f32_16x16x32_bf16 v[122:125], v[160:163], v[184:187], v[122:125]
	v_mfma_f32_16x16x32_bf16 v[110:113], v[160:163], v[192:195], v[110:113]
	v_mfma_f32_16x16x32_bf16 v[118:121], v[152:155], v[192:195], v[118:121]
	v_mfma_f32_16x16x32_bf16 v[102:105], v[152:155], v[200:203], v[102:105]
	v_mfma_f32_16x16x32_bf16 v[94:97], v[160:163], v[200:203], v[94:97]
	v_mfma_f32_16x16x32_bf16 v[78:81], v[160:163], v[208:211], v[78:81]
	v_mfma_f32_16x16x32_bf16 v[86:89], v[152:155], v[208:211], v[86:89]
	s_setprio 0
	s_setprio 1
	v_mfma_f32_16x16x32_bf16 v[114:117], v[164:167], v[180:183], v[114:117]
	v_mfma_f32_16x16x32_bf16 v[106:109], v[172:175], v[180:183], v[106:109]
	v_mfma_f32_16x16x32_bf16 v[90:93], v[172:175], v[188:191], v[90:93]
	v_mfma_f32_16x16x32_bf16 v[98:101], v[164:167], v[188:191], v[98:101]
	v_mfma_f32_16x16x32_bf16 v[82:85], v[164:167], v[196:199], v[82:85]
	v_mfma_f32_16x16x32_bf16 v[74:77], v[172:175], v[196:199], v[74:77]
	v_mfma_f32_16x16x32_bf16 v[66:69], v[172:175], v[204:207], v[66:69]
	v_mfma_f32_16x16x32_bf16 v[70:73], v[164:167], v[204:207], v[70:73]
	v_mfma_f32_16x16x32_bf16 v[114:117], v[168:171], v[184:187], v[114:117]
	v_mfma_f32_16x16x32_bf16 v[106:109], v[176:179], v[184:187], v[106:109]
	v_mfma_f32_16x16x32_bf16 v[90:93], v[176:179], v[192:195], v[90:93]
	v_mfma_f32_16x16x32_bf16 v[98:101], v[168:171], v[192:195], v[98:101]
	v_mfma_f32_16x16x32_bf16 v[82:85], v[168:171], v[200:203], v[82:85]
	v_mfma_f32_16x16x32_bf16 v[74:77], v[176:179], v[200:203], v[74:77]
	v_mfma_f32_16x16x32_bf16 v[66:69], v[176:179], v[208:211], v[66:69]
	v_mfma_f32_16x16x32_bf16 v[70:73], v[168:171], v[208:211], v[70:73]
	s_setprio 0
	s_barrier
; #define PG8_STAGE(bufoff, gbase, voff) do { _Pragma("unroll") for (int _i = 0; _i < 2; ++_i) \
;         __builtin_amdgcn_global_load_lds((const unsigned*)((const char*)(gbase) + (voff)[_i]), (LAS unsigned*)(lds + (bufoff) + ldsw + _i * 8192), 16, 0, 0); } while (0)
; #define PG8_LDA(dst, b, h) do { _Pragma("unroll") for (int m = 0; m < 4; ++m) _Pragma("unroll") for (int k = 0; k < 2; ++k) dst[m][k] = *(const LAS bf16x8*)(lds + PG8_SA(b, h) + aoff + m * 2048 + k * 1024); } while (0)
; #define PG8_MMA(ai, bj, At, Bt) do { __builtin_amdgcn_s_setprio(1); _Pragma("unroll") for (int m = 0; m < 4; ++m) _Pragma("unroll") for (int n = 0; n < 2; ++n) _Pragma("unroll") for (int k = 0; k < 2; ++k) \
;         acc[ai][bj][m][n] = __builtin_amdgcn_mfma_f32_16x16x32_bf16(Bt[n][k], At[m][k], acc[ai][bj][m][n], 0, 0, 0); __builtin_amdgcn_s_setprio(0); } while (0)
; #define PG8_WAIT_V(n) asm volatile("s_waitcnt vmcnt(" #n ")" ::: "memory")
; #define PG8_WAIT_L(n) asm volatile("s_waitcnt lgkmcnt(" #n ")" ::: "memory")
; #define PG8_BAR __builtin_amdgcn_s_barrier()
; #define PG8_SCHED __builtin_amdgcn_sched_barrier(0)
; template <class Epi>
; __device__ __forceinline__ void gemm_phase(LAS unsigned char* lds, const Gemm g, int G, int c, const Epi& E) {
;     ...
;             PG8_LDA(At, 1, 1); PG8_STAGE(PG8_SB(1, 0), b3, voffB); PG8_STAGE(PG8_SB(1, 1), b3 + hstepB, voffB); PG8_STAGE(PG8_SA(1, 0), a3, voffA);
;             PG8_WAIT_V(8); PG8_WAIT_L(0); PG8_BAR; PG8_MMA(1, 0, At, B0); PG8_MMA(1, 1, At, B1); PG8_BAR; PG8_SCHED;
;         }
	s_mov_b32 m0, s83
	v_lshl_add_u64 v[212:213], v[212:213], 0, s[8:9]
	ds_read_b128 v[180:183], v150 offset:49152
	ds_read_b128 v[184:187], v150 offset:50176
	ds_read_b128 v[188:191], v150 offset:51200
	ds_read_b128 v[192:195], v150 offset:52224
	ds_read_b128 v[196:199], v150 offset:53248
	ds_read_b128 v[200:203], v150 offset:54272
	ds_read_b128 v[204:207], v150 offset:55296
	ds_read_b128 v[208:211], v150 offset:56320
	global_load_lds_dwordx4 v[212:213], off
	v_lshl_add_u64 v[212:213], v[214:215], 0, s[8:9]
	s_mov_b32 m0, s13
	s_nop 0
	global_load_lds_dwordx4 v[212:213], off
	v_lshl_add_u64 v[212:213], s[22:23], 0, v[134:135]
	s_mov_b32 m0, s75
	s_nop 0
	global_load_lds_dwordx4 v[212:213], off
	v_lshl_add_u64 v[212:213], s[22:23], 0, v[130:131]
	s_mov_b32 m0, s74
	s_nop 0
	global_load_lds_dwordx4 v[212:213], off
	v_lshl_add_u64 v[212:213], v[216:217], 0, s[8:9]
	s_mov_b32 m0, s70
	s_nop 0
	global_load_lds_dwordx4 v[212:213], off
	v_lshl_add_u64 v[212:213], v[218:219], 0, s[8:9]
	s_mov_b32 m0, s71
	s_nop 0
	global_load_lds_dwordx4 v[212:213], off
	s_waitcnt vmcnt(8)
	s_waitcnt lgkmcnt(0)
	s_barrier
	s_setprio 1
	s_waitcnt lgkmcnt(0)
	v_mfma_f32_16x16x32_bf16 v[62:65], v[142:145], v[180:183], v[62:65]
	v_mfma_f32_16x16x32_bf16 v[58:61], v[156:159], v[180:183], v[58:61]
	v_mfma_f32_16x16x32_bf16 v[46:49], v[156:159], v[188:191], v[46:49]
	v_mfma_f32_16x16x32_bf16 v[54:57], v[142:145], v[188:191], v[54:57]
	v_mfma_f32_16x16x32_bf16 v[38:41], v[142:145], v[196:199], v[38:41]
	v_mfma_f32_16x16x32_bf16 v[30:33], v[156:159], v[196:199], v[30:33]
	v_mfma_f32_16x16x32_bf16 v[14:17], v[156:159], v[204:207], v[14:17]
	v_mfma_f32_16x16x32_bf16 v[22:25], v[142:145], v[204:207], v[22:25]
	v_mfma_f32_16x16x32_bf16 v[62:65], v[152:155], v[184:187], v[62:65]
	v_mfma_f32_16x16x32_bf16 v[58:61], v[160:163], v[184:187], v[58:61]
	v_mfma_f32_16x16x32_bf16 v[46:49], v[160:163], v[192:195], v[46:49]
	v_mfma_f32_16x16x32_bf16 v[54:57], v[152:155], v[192:195], v[54:57]
	v_mfma_f32_16x16x32_bf16 v[38:41], v[152:155], v[200:203], v[38:41]
	v_mfma_f32_16x16x32_bf16 v[30:33], v[160:163], v[200:203], v[30:33]
	v_mfma_f32_16x16x32_bf16 v[14:17], v[160:163], v[208:211], v[14:17]
	v_mfma_f32_16x16x32_bf16 v[22:25], v[152:155], v[208:211], v[22:25]
	s_setprio 0
	s_setprio 1
	v_mfma_f32_16x16x32_bf16 v[50:53], v[164:167], v[180:183], v[50:53]
	v_mfma_f32_16x16x32_bf16 v[42:45], v[172:175], v[180:183], v[42:45]
	v_mfma_f32_16x16x32_bf16 v[26:29], v[172:175], v[188:191], v[26:29]
	v_mfma_f32_16x16x32_bf16 v[34:37], v[164:167], v[188:191], v[34:37]
	v_mfma_f32_16x16x32_bf16 v[18:21], v[164:167], v[196:199], v[18:21]
	v_mfma_f32_16x16x32_bf16 v[10:13], v[172:175], v[196:199], v[10:13]
	v_mfma_f32_16x16x32_bf16 v[2:5], v[172:175], v[204:207], v[2:5]
	v_mfma_f32_16x16x32_bf16 v[6:9], v[164:167], v[204:207], v[6:9]
	v_mfma_f32_16x16x32_bf16 v[50:53], v[168:171], v[184:187], v[50:53]
	v_mfma_f32_16x16x32_bf16 v[42:45], v[176:179], v[184:187], v[42:45]
	v_mfma_f32_16x16x32_bf16 v[26:29], v[176:179], v[192:195], v[26:29]
	v_mfma_f32_16x16x32_bf16 v[34:37], v[168:171], v[192:195], v[34:37]
	v_mfma_f32_16x16x32_bf16 v[18:21], v[168:171], v[200:203], v[18:21]
	v_mfma_f32_16x16x32_bf16 v[10:13], v[176:179], v[200:203], v[10:13]
	v_mfma_f32_16x16x32_bf16 v[2:5], v[176:179], v[208:211], v[2:5]
	v_mfma_f32_16x16x32_bf16 v[6:9], v[168:171], v[208:211], v[6:9]
	s_setprio 0
	s_barrier
	s_movk_i32 s13, 0x100
	s_andn2_b64 vcc, exec, s[20:21]
	s_mov_b64 s[22:23], -1
	s_mov_b64 s[20:21], 0
	s_cbranch_vccz .LBB0_1429
	s_and_b64 vcc, exec, s[10:11]
	s_cbranch_vccz .LBB0_1432
	s_barrier

; #define PG8_STAGE(bufoff, gbase, voff) do { _Pragma("unroll") for (int _i = 0; _i < 2; ++_i) \
;         __builtin_amdgcn_global_load_lds((const unsigned*)((const char*)(gbase) + (voff)[_i]), (LAS unsigned*)(lds + (bufoff) + ldsw + _i * 8192), 16, 0, 0); } while (0)
; #define PG8_LDA(dst, b, h) do { _Pragma("unroll") for (int m = 0; m < 4; ++m) _Pragma("unroll") for (int k = 0; k < 2; ++k) dst[m][k] = *(const LAS bf16x8*)(lds + PG8_SA(b, h) + aoff + m * 2048 + k * 1024); } while (0)
; #define PG8_LDB(dst, b, h) do { _Pragma("unroll") for (int n = 0; n < 2; ++n) _Pragma("unroll") for (int k = 0; k < 2; ++k) dst[n][k] = *(const LAS bf16x8*)(lds + PG8_SB(b, h) + boff + n * 2048 + k * 1024); } while (0)
; #define PG8_MMA(ai, bj, At, Bt) do { __builtin_amdgcn_s_setprio(1); _Pragma("unroll") for (int m = 0; m < 4; ++m) _Pragma("unroll") for (int n = 0; n < 2; ++n) _Pragma("unroll") for (int k = 0; k < 2; ++k) \
;         acc[ai][bj][m][n] = __builtin_amdgcn_mfma_f32_16x16x32_bf16(Bt[n][k], At[m][k], acc[ai][bj][m][n], 0, 0, 0); __builtin_amdgcn_s_setprio(0); } while (0)
; #define PG8_WAIT_V(n) asm volatile("s_waitcnt vmcnt(" #n ")" ::: "memory")
; #define PG8_WAIT_L(n) asm volatile("s_waitcnt lgkmcnt(" #n ")" ::: "memory")
; #define PG8_BAR __builtin_amdgcn_s_barrier()
; #define PG8_SCHED __builtin_amdgcn_sched_barrier(0)
; template <class Epi>
; __device__ __forceinline__ void gemm_phase(LAS unsigned char* lds, const Gemm g, int G, int c, const Epi& E) {
;     ...
;             const char* a1 = cA + (size_t)(t + 1) * kstep;
;             const char* a2 = last ? nA : cA + (size_t)(t + 2) * kstep; const char* b2 = last ? nB : cB + (size_t)(t + 2) * kstep;
;             const char* a3 = a2 + kstep; const char* b3 = b2 + kstep;
;             PG8_LDB(B0, 0, 0); PG8_LDB(B1, 0, 1); PG8_SCHED; PG8_LDA(At, 0, 0); PG8_STAGE(PG8_SA(1, 1), a1 + hstepA, voffA);
;             PG8_WAIT_V(8); PG8_WAIT_L(0); PG8_BAR; PG8_MMA(0, 0, At, B0); PG8_MMA(0, 1, At, B1); PG8_BAR; PG8_SCHED;
;             PG8_LDA(At, 0, 1); PG8_STAGE(PG8_SB(0, 0), b2, voffB); PG8_STAGE(PG8_SB(0, 1), b2 + hstepB, voffB); PG8_STAGE(PG8_SA(0, 0), a2, voffA);
.LBB0_1451:
	s_add_u32 s33, s8, s44
	s_addc_u32 s45, s9, 0
	s_add_u32 s48, s33, 0x100
	s_addc_u32 s49, s45, 0
	s_and_b64 s[46:47], s[10:11], exec
	s_cselect_b32 s47, s41, s49
	s_cselect_b32 s46, s40, s48
	s_add_u32 s44, s6, s44
	s_addc_u32 s48, s7, 0
	s_add_u32 s44, s44, 0x100
	s_addc_u32 s48, s48, 0
	s_and_b64 s[10:11], s[10:11], exec
	s_cselect_b32 s49, s43, s48
	s_cselect_b32 s48, s42, s44
	s_add_u32 s54, s33, 0xb0080
	ds_read_b128 v[142:145], v160
	ds_read_b128 v[146:149], v160 offset:1024
	ds_read_b128 v[150:153], v160 offset:2048
	ds_read_b128 v[154:157], v160 offset:3072
	ds_read_b128 v[166:169], v161
	ds_read_b128 v[170:173], v161 offset:1024
	ds_read_b128 v[174:177], v161 offset:2048
	ds_read_b128 v[178:181], v161 offset:3072
	s_addc_u32 s55, s45, 0
	s_add_i32 s65, s82, s66
	s_add_i32 m0, s69, 0xc000
	s_add_i32 s74, s69, 0xe000
	s_add_i32 s62, s65, 0x2000
	s_add_u32 s52, s48, 0xb0000
	s_addc_u32 s53, s49, 0
	s_add_i32 s64, s83, s66
	s_add_i32 s63, s64, 0x2000
	s_add_i32 s97, 0, 0x18000
	s_add_i32 s33, 0, 0x1c000
	s_add_u32 s44, s46, 0xb0000
	s_addc_u32 s45, s47, 0
	s_add_i32 s96, s97, s66
	s_add_i32 s94, s96, 0x2000
	s_add_u32 s10, s48, 0xb0080
	s_addc_u32 s11, s49, 0
	s_add_i32 s95, s33, s66
	s_add_i32 s93, s95, 0x2000
	v_lshl_add_u64 v[214:215], s[54:55], 0, v[130:131]
	ds_read_b128 v[182:185], v162
	ds_read_b128 v[186:189], v162 offset:1024
	ds_read_b128 v[190:193], v162 offset:2048
	ds_read_b128 v[194:197], v162 offset:3072
	ds_read_b128 v[198:201], v162 offset:4096
	ds_read_b128 v[202:205], v162 offset:5120
	ds_read_b128 v[206:209], v162 offset:6144
	ds_read_b128 v[210:213], v162 offset:7168
	global_load_lds_dwordx4 v[214:215], off
	v_lshl_add_u64 v[214:215], s[54:55], 0, v[134:135]
	s_mov_b32 m0, s74
	s_nop 0
	global_load_lds_dwordx4 v[214:215], off
	s_waitcnt vmcnt(8)
	s_waitcnt lgkmcnt(0)
	s_barrier
	s_setprio 1
	s_waitcnt lgkmcnt(0)
	v_mfma_f32_16x16x32_bf16 v[126:129], v[142:145], v[182:185], v[126:129]
	v_mfma_f32_16x16x32_bf16 v[122:125], v[150:153], v[182:185], v[122:125]
	v_mfma_f32_16x16x32_bf16 v[106:109], v[150:153], v[190:193], v[106:109]
	v_mfma_f32_16x16x32_bf16 v[110:113], v[142:145], v[190:193], v[110:113]
	v_mfma_f32_16x16x32_bf16 v[94:97], v[142:145], v[198:201], v[94:97]
	v_mfma_f32_16x16x32_bf16 v[90:93], v[150:153], v[198:201], v[90:93]
	v_mfma_f32_16x16x32_bf16 v[74:77], v[150:153], v[206:209], v[74:77]
	v_mfma_f32_16x16x32_bf16 v[78:81], v[142:145], v[206:209], v[78:81]
	v_mfma_f32_16x16x32_bf16 v[126:129], v[146:149], v[186:189], v[126:129]
	v_mfma_f32_16x16x32_bf16 v[122:125], v[154:157], v[186:189], v[122:125]
	v_mfma_f32_16x16x32_bf16 v[106:109], v[154:157], v[194:197], v[106:109]
	v_mfma_f32_16x16x32_bf16 v[110:113], v[146:149], v[194:197], v[110:113]
	v_mfma_f32_16x16x32_bf16 v[94:97], v[146:149], v[202:205], v[94:97]
	v_mfma_f32_16x16x32_bf16 v[90:93], v[154:157], v[202:205], v[90:93]
	v_mfma_f32_16x16x32_bf16 v[74:77], v[154:157], v[210:213], v[74:77]
	v_mfma_f32_16x16x32_bf16 v[78:81], v[146:149], v[210:213], v[78:81]
	s_setprio 0
	s_setprio 1
	v_mfma_f32_16x16x32_bf16 v[118:121], v[166:169], v[182:185], v[118:121]
	v_mfma_f32_16x16x32_bf16 v[114:117], v[174:177], v[182:185], v[114:117]
	v_mfma_f32_16x16x32_bf16 v[98:101], v[174:177], v[190:193], v[98:101]
	v_mfma_f32_16x16x32_bf16 v[102:105], v[166:169], v[190:193], v[102:105]
	v_mfma_f32_16x16x32_bf16 v[86:89], v[166:169], v[198:201], v[86:89]
	v_mfma_f32_16x16x32_bf16 v[82:85], v[174:177], v[198:201], v[82:85]
	v_mfma_f32_16x16x32_bf16 v[66:69], v[174:177], v[206:209], v[66:69]
	v_mfma_f32_16x16x32_bf16 v[70:73], v[166:169], v[206:209], v[70:73]
	v_mfma_f32_16x16x32_bf16 v[118:121], v[170:173], v[186:189], v[118:121]
	v_mfma_f32_16x16x32_bf16 v[114:117], v[178:181], v[186:189], v[114:117]
	v_mfma_f32_16x16x32_bf16 v[98:101], v[178:181], v[194:197], v[98:101]
	v_mfma_f32_16x16x32_bf16 v[102:105], v[170:173], v[194:197], v[102:105]
	v_mfma_f32_16x16x32_bf16 v[86:89], v[170:173], v[202:205], v[86:89]
	v_mfma_f32_16x16x32_bf16 v[82:85], v[178:181], v[202:205], v[82:85]
	v_mfma_f32_16x16x32_bf16 v[66:69], v[178:181], v[210:213], v[66:69]
	v_mfma_f32_16x16x32_bf16 v[70:73], v[170:173], v[210:213], v[70:73]
	s_setprio 0
	s_barrier
	s_mov_b32 m0, s65
	v_lshl_add_u64 v[214:215], s[48:49], 0, v[132:133]
	ds_read_b128 v[182:185], v162 offset:16384
	ds_read_b128 v[186:189], v162 offset:17408
	ds_read_b128 v[190:193], v162 offset:18432
	ds_read_b128 v[194:197], v162 offset:19456
	ds_read_b128 v[198:201], v162 offset:20480
	ds_read_b128 v[202:205], v162 offset:21504
	ds_read_b128 v[206:209], v162 offset:22528
	ds_read_b128 v[210:213], v162 offset:23552
	global_load_lds_dwordx4 v[214:215], off
	v_lshl_add_u64 v[216:217], s[48:49], 0, v[136:137]
	s_mov_b32 m0, s62
	v_lshl_add_u64 v[218:219], s[52:53], 0, v[132:133]
	global_load_lds_dwordx4 v[216:217], off
	s_mov_b32 m0, s64
	v_lshl_add_u64 v[220:221], s[46:47], 0, v[134:135]
	global_load_lds_dwordx4 v[218:219], off
	v_lshl_add_u64 v[218:219], s[52:53], 0, v[136:137]
	s_mov_b32 m0, s63
	s_nop 0
	global_load_lds_dwordx4 v[218:219], off
	v_lshl_add_u64 v[218:219], s[46:47], 0, v[130:131]
	s_mov_b32 m0, s69
	s_nop 0
	global_load_lds_dwordx4 v[218:219], off
	s_mov_b32 m0, s70
	s_nop 0
	global_load_lds_dwordx4 v[220:221], off
	s_waitcnt vmcnt(8)
	s_waitcnt lgkmcnt(0)
	s_barrier
; #define PG8_STAGE(bufoff, gbase, voff) do { _Pragma("unroll") for (int _i = 0; _i < 2; ++_i) \
;         __builtin_amdgcn_global_load_lds((const unsigned*)((const char*)(gbase) + (voff)[_i]), (LAS unsigned*)(lds + (bufoff) + ldsw + _i * 8192), 16, 0, 0); } while (0)
; #define PG8_LDA(dst, b, h) do { _Pragma("unroll") for (int m = 0; m < 4; ++m) _Pragma("unroll") for (int k = 0; k < 2; ++k) dst[m][k] = *(const LAS bf16x8*)(lds + PG8_SA(b, h) + aoff + m * 2048 + k * 1024); } while (0)
; #define PG8_LDB(dst, b, h) do { _Pragma("unroll") for (int n = 0; n < 2; ++n) _Pragma("unroll") for (int k = 0; k < 2; ++k) dst[n][k] = *(const LAS bf16x8*)(lds + PG8_SB(b, h) + boff + n * 2048 + k * 1024); } while (0)
; #define PG8_MMA(ai, bj, At, Bt) do { __builtin_amdgcn_s_setprio(1); _Pragma("unroll") for (int m = 0; m < 4; ++m) _Pragma("unroll") for (int n = 0; n < 2; ++n) _Pragma("unroll") for (int k = 0; k < 2; ++k) \
;         acc[ai][bj][m][n] = __builtin_amdgcn_mfma_f32_16x16x32_bf16(Bt[n][k], At[m][k], acc[ai][bj][m][n], 0, 0, 0); __builtin_amdgcn_s_setprio(0); } while (0)
; #define PG8_WAIT_V(n) asm volatile("s_waitcnt vmcnt(" #n ")" ::: "memory")
; #define PG8_WAIT_L(n) asm volatile("s_waitcnt lgkmcnt(" #n ")" ::: "memory")
; #define PG8_BAR __builtin_amdgcn_s_barrier()
; #define PG8_SCHED __builtin_amdgcn_sched_barrier(0)
; template <class Epi>
; __device__ __forceinline__ void gemm_phase(LAS unsigned char* lds, const Gemm g, int G, int c, const Epi& E) {
;     ...
;             PG8_WAIT_V(8); PG8_WAIT_L(0); PG8_BAR; PG8_MMA(1, 0, At, B0); PG8_MMA(1, 1, At, B1); PG8_BAR; PG8_SCHED;
;             PG8_LDB(B0, 1, 0); PG8_LDB(B1, 1, 1); PG8_SCHED; PG8_LDA(At, 1, 0); PG8_STAGE(PG8_SA(0, 1), a2 + hstepA, voffA);
;             PG8_WAIT_V(8); PG8_WAIT_L(0); PG8_BAR; PG8_MMA(0, 0, At, B0); PG8_MMA(0, 1, At, B1); PG8_BAR; PG8_SCHED;
;             PG8_LDA(At, 1, 1); PG8_STAGE(PG8_SB(1, 0), b3, voffB); PG8_STAGE(PG8_SB(1, 1), b3 + hstepB, voffB); PG8_STAGE(PG8_SA(1, 0), a3, voffA);
	s_setprio 1
	s_waitcnt lgkmcnt(0)
	v_mfma_f32_16x16x32_bf16 v[62:65], v[142:145], v[182:185], v[62:65]
	v_mfma_f32_16x16x32_bf16 v[58:61], v[150:153], v[182:185], v[58:61]
	v_mfma_f32_16x16x32_bf16 v[42:45], v[150:153], v[190:193], v[42:45]
	v_mfma_f32_16x16x32_bf16 v[46:49], v[142:145], v[190:193], v[46:49]
	v_mfma_f32_16x16x32_bf16 v[30:33], v[142:145], v[198:201], v[30:33]
	v_mfma_f32_16x16x32_bf16 v[26:29], v[150:153], v[198:201], v[26:29]
	v_mfma_f32_16x16x32_bf16 v[10:13], v[150:153], v[206:209], v[10:13]
	v_mfma_f32_16x16x32_bf16 v[14:17], v[142:145], v[206:209], v[14:17]
	v_mfma_f32_16x16x32_bf16 v[62:65], v[146:149], v[186:189], v[62:65]
	v_mfma_f32_16x16x32_bf16 v[58:61], v[154:157], v[186:189], v[58:61]
	v_mfma_f32_16x16x32_bf16 v[42:45], v[154:157], v[194:197], v[42:45]
	v_mfma_f32_16x16x32_bf16 v[46:49], v[146:149], v[194:197], v[46:49]
	v_mfma_f32_16x16x32_bf16 v[30:33], v[146:149], v[202:205], v[30:33]
	v_mfma_f32_16x16x32_bf16 v[26:29], v[154:157], v[202:205], v[26:29]
	v_mfma_f32_16x16x32_bf16 v[10:13], v[154:157], v[210:213], v[10:13]
	v_mfma_f32_16x16x32_bf16 v[14:17], v[146:149], v[210:213], v[14:17]
	s_setprio 0
	s_setprio 1
	v_mfma_f32_16x16x32_bf16 v[54:57], v[166:169], v[182:185], v[54:57]
	v_mfma_f32_16x16x32_bf16 v[50:53], v[174:177], v[182:185], v[50:53]
	v_mfma_f32_16x16x32_bf16 v[34:37], v[174:177], v[190:193], v[34:37]
	v_mfma_f32_16x16x32_bf16 v[38:41], v[166:169], v[190:193], v[38:41]
	v_mfma_f32_16x16x32_bf16 v[22:25], v[166:169], v[198:201], v[22:25]
	v_mfma_f32_16x16x32_bf16 v[18:21], v[174:177], v[198:201], v[18:21]
	v_mfma_f32_16x16x32_bf16 v[2:5], v[174:177], v[206:209], v[2:5]
	v_mfma_f32_16x16x32_bf16 v[6:9], v[166:169], v[206:209], v[6:9]
	v_mfma_f32_16x16x32_bf16 v[54:57], v[170:173], v[186:189], v[54:57]
	v_mfma_f32_16x16x32_bf16 v[50:53], v[178:181], v[186:189], v[50:53]
	v_mfma_f32_16x16x32_bf16 v[34:37], v[178:181], v[194:197], v[34:37]
	v_mfma_f32_16x16x32_bf16 v[38:41], v[170:173], v[194:197], v[38:41]
	v_mfma_f32_16x16x32_bf16 v[22:25], v[170:173], v[202:205], v[22:25]
	v_mfma_f32_16x16x32_bf16 v[18:21], v[178:181], v[202:205], v[18:21]
	v_mfma_f32_16x16x32_bf16 v[2:5], v[178:181], v[210:213], v[2:5]
	v_mfma_f32_16x16x32_bf16 v[6:9], v[170:173], v[210:213], v[6:9]
	s_setprio 0
	s_barrier
	v_add_u32_e32 v154, s97, v159
	v_add_u32_e32 v178, s33, v159
	ds_read_b128 v[142:145], v154
	ds_read_b128 v[146:149], v154 offset:1024
	ds_read_b128 v[150:153], v154 offset:2048
	ds_read_b128 v[154:157], v154 offset:3072
	ds_read_b128 v[166:169], v178
	ds_read_b128 v[170:173], v178 offset:1024
	ds_read_b128 v[174:177], v178 offset:2048
	ds_read_b128 v[178:181], v178 offset:3072
	s_mov_b32 m0, s71
	v_lshl_add_u64 v[222:223], s[44:45], 0, v[130:131]
	ds_read_b128 v[182:185], v162 offset:32768
	ds_read_b128 v[186:189], v162 offset:33792
	ds_read_b128 v[190:193], v162 offset:34816
	ds_read_b128 v[194:197], v162 offset:35840
	ds_read_b128 v[198:201], v162 offset:36864
	ds_read_b128 v[202:205], v162 offset:37888
	ds_read_b128 v[206:209], v162 offset:38912
	ds_read_b128 v[210:213], v162 offset:39936
	global_load_lds_dwordx4 v[222:223], off
	v_lshl_add_u64 v[222:223], s[44:45], 0, v[134:135]
	s_mov_b32 m0, s72
	s_nop 0
	global_load_lds_dwordx4 v[222:223], off
	s_waitcnt vmcnt(8)
	s_waitcnt lgkmcnt(0)
	s_barrier
	s_setprio 1
	s_waitcnt lgkmcnt(0)
	v_mfma_f32_16x16x32_bf16 v[126:129], v[142:145], v[182:185], v[126:129]
	v_mfma_f32_16x16x32_bf16 v[122:125], v[150:153], v[182:185], v[122:125]
	v_mfma_f32_16x16x32_bf16 v[106:109], v[150:153], v[190:193], v[106:109]
	v_mfma_f32_16x16x32_bf16 v[110:113], v[142:145], v[190:193], v[110:113]
	v_mfma_f32_16x16x32_bf16 v[94:97], v[142:145], v[198:201], v[94:97]
	v_mfma_f32_16x16x32_bf16 v[90:93], v[150:153], v[198:201], v[90:93]
	v_mfma_f32_16x16x32_bf16 v[74:77], v[150:153], v[206:209], v[74:77]
	v_mfma_f32_16x16x32_bf16 v[78:81], v[142:145], v[206:209], v[78:81]
	v_mfma_f32_16x16x32_bf16 v[126:129], v[146:149], v[186:189], v[126:129]
	v_mfma_f32_16x16x32_bf16 v[122:125], v[154:157], v[186:189], v[122:125]
	v_mfma_f32_16x16x32_bf16 v[106:109], v[154:157], v[194:197], v[106:109]
	v_mfma_f32_16x16x32_bf16 v[110:113], v[146:149], v[194:197], v[110:113]
	v_mfma_f32_16x16x32_bf16 v[94:97], v[146:149], v[202:205], v[94:97]
	v_mfma_f32_16x16x32_bf16 v[90:93], v[154:157], v[202:205], v[90:93]
	v_mfma_f32_16x16x32_bf16 v[74:77], v[154:157], v[210:213], v[74:77]
	v_mfma_f32_16x16x32_bf16 v[78:81], v[146:149], v[210:213], v[78:81]
	s_setprio 0
	s_setprio 1
	v_mfma_f32_16x16x32_bf16 v[118:121], v[166:169], v[182:185], v[118:121]
	v_mfma_f32_16x16x32_bf16 v[114:117], v[174:177], v[182:185], v[114:117]
	v_mfma_f32_16x16x32_bf16 v[98:101], v[174:177], v[190:193], v[98:101]
	v_mfma_f32_16x16x32_bf16 v[102:105], v[166:169], v[190:193], v[102:105]
	v_mfma_f32_16x16x32_bf16 v[86:89], v[166:169], v[198:201], v[86:89]
	v_mfma_f32_16x16x32_bf16 v[82:85], v[174:177], v[198:201], v[82:85]
	v_mfma_f32_16x16x32_bf16 v[66:69], v[174:177], v[206:209], v[66:69]
	v_mfma_f32_16x16x32_bf16 v[70:73], v[166:169], v[206:209], v[70:73]
	v_mfma_f32_16x16x32_bf16 v[118:121], v[170:173], v[186:189], v[118:121]
	v_mfma_f32_16x16x32_bf16 v[114:117], v[178:181], v[186:189], v[114:117]
	v_mfma_f32_16x16x32_bf16 v[98:101], v[178:181], v[194:197], v[98:101]
	v_mfma_f32_16x16x32_bf16 v[102:105], v[170:173], v[194:197], v[102:105]
	v_mfma_f32_16x16x32_bf16 v[86:89], v[170:173], v[202:205], v[86:89]
	v_mfma_f32_16x16x32_bf16 v[82:85], v[178:181], v[202:205], v[82:85]
	v_mfma_f32_16x16x32_bf16 v[66:69], v[178:181], v[210:213], v[66:69]
	v_mfma_f32_16x16x32_bf16 v[70:73], v[170:173], v[210:213], v[70:73]
	s_setprio 0
	s_barrier
; #define PG8_STAGE(bufoff, gbase, voff) do { _Pragma("unroll") for (int _i = 0; _i < 2; ++_i) \
;         __builtin_amdgcn_global_load_lds((const unsigned*)((const char*)(gbase) + (voff)[_i]), (LAS unsigned*)(lds + (bufoff) + ldsw + _i * 8192), 16, 0, 0); } while (0)
; #define PG8_LDA(dst, b, h) do { _Pragma("unroll") for (int m = 0; m < 4; ++m) _Pragma("unroll") for (int k = 0; k < 2; ++k) dst[m][k] = *(const LAS bf16x8*)(lds + PG8_SA(b, h) + aoff + m * 2048 + k * 1024); } while (0)
; #define PG8_MMA(ai, bj, At, Bt) do { __builtin_amdgcn_s_setprio(1); _Pragma("unroll") for (int m = 0; m < 4; ++m) _Pragma("unroll") for (int n = 0; n < 2; ++n) _Pragma("unroll") for (int k = 0; k < 2; ++k) \
;         acc[ai][bj][m][n] = __builtin_amdgcn_mfma_f32_16x16x32_bf16(Bt[n][k], At[m][k], acc[ai][bj][m][n], 0, 0, 0); __builtin_amdgcn_s_setprio(0); } while (0)
; #define PG8_WAIT_V(n) asm volatile("s_waitcnt vmcnt(" #n ")" ::: "memory")
; #define PG8_WAIT_L(n) asm volatile("s_waitcnt lgkmcnt(" #n ")" ::: "memory")
; #define PG8_BAR __builtin_amdgcn_s_barrier()
; #define PG8_SCHED __builtin_amdgcn_sched_barrier(0)
; template <class Epi>
; __device__ __forceinline__ void gemm_phase(LAS unsigned char* lds, const Gemm g, int G, int c, const Epi& E) {
;     ...
;             PG8_LDA(At, 1, 1); PG8_STAGE(PG8_SB(1, 0), b3, voffB); PG8_STAGE(PG8_SB(1, 1), b3 + hstepB, voffB); PG8_STAGE(PG8_SA(1, 0), a3, voffA);
;             PG8_WAIT_V(8); PG8_WAIT_L(0); PG8_BAR; PG8_MMA(1, 0, At, B0); PG8_MMA(1, 1, At, B1); PG8_BAR; PG8_SCHED;
;         }
	s_mov_b32 m0, s96
	v_lshl_add_u64 v[214:215], v[214:215], 0, s[22:23]
	ds_read_b128 v[182:185], v162 offset:49152
	ds_read_b128 v[186:189], v162 offset:50176
	ds_read_b128 v[190:193], v162 offset:51200
	ds_read_b128 v[194:197], v162 offset:52224
	ds_read_b128 v[198:201], v162 offset:53248
	ds_read_b128 v[202:205], v162 offset:54272
	ds_read_b128 v[206:209], v162 offset:55296
	ds_read_b128 v[210:213], v162 offset:56320
	global_load_lds_dwordx4 v[214:215], off
	v_lshl_add_u64 v[214:215], v[216:217], 0, s[22:23]
	s_mov_b32 m0, s94
	s_nop 0
	global_load_lds_dwordx4 v[214:215], off
	v_lshl_add_u64 v[214:215], s[10:11], 0, v[132:133]
	s_mov_b32 m0, s95
	s_nop 0
	global_load_lds_dwordx4 v[214:215], off
	v_lshl_add_u64 v[214:215], s[10:11], 0, v[136:137]
	s_mov_b32 m0, s93
	s_nop 0
	global_load_lds_dwordx4 v[214:215], off
	v_lshl_add_u64 v[214:215], v[218:219], 0, s[22:23]
	s_mov_b32 m0, s80
	s_nop 0
	global_load_lds_dwordx4 v[214:215], off
	v_lshl_add_u64 v[214:215], v[220:221], 0, s[22:23]
	s_mov_b32 m0, s81
	s_nop 0
	global_load_lds_dwordx4 v[214:215], off
	s_waitcnt vmcnt(8)
	s_waitcnt lgkmcnt(0)
	s_barrier
	s_setprio 1
	s_waitcnt lgkmcnt(0)
	v_mfma_f32_16x16x32_bf16 v[62:65], v[142:145], v[182:185], v[62:65]
	v_mfma_f32_16x16x32_bf16 v[58:61], v[150:153], v[182:185], v[58:61]
	v_mfma_f32_16x16x32_bf16 v[42:45], v[150:153], v[190:193], v[42:45]
	v_mfma_f32_16x16x32_bf16 v[46:49], v[142:145], v[190:193], v[46:49]
	v_mfma_f32_16x16x32_bf16 v[30:33], v[142:145], v[198:201], v[30:33]
	v_mfma_f32_16x16x32_bf16 v[26:29], v[150:153], v[198:201], v[26:29]
	v_mfma_f32_16x16x32_bf16 v[10:13], v[150:153], v[206:209], v[10:13]
	v_mfma_f32_16x16x32_bf16 v[14:17], v[142:145], v[206:209], v[14:17]
	v_mfma_f32_16x16x32_bf16 v[62:65], v[146:149], v[186:189], v[62:65]
	v_mfma_f32_16x16x32_bf16 v[58:61], v[154:157], v[186:189], v[58:61]
	v_mfma_f32_16x16x32_bf16 v[42:45], v[154:157], v[194:197], v[42:45]
	v_mfma_f32_16x16x32_bf16 v[46:49], v[146:149], v[194:197], v[46:49]
	v_mfma_f32_16x16x32_bf16 v[30:33], v[146:149], v[202:205], v[30:33]
	v_mfma_f32_16x16x32_bf16 v[26:29], v[154:157], v[202:205], v[26:29]
	v_mfma_f32_16x16x32_bf16 v[10:13], v[154:157], v[210:213], v[10:13]
	v_mfma_f32_16x16x32_bf16 v[14:17], v[146:149], v[210:213], v[14:17]
	s_setprio 0
	s_setprio 1
	v_mfma_f32_16x16x32_bf16 v[54:57], v[166:169], v[182:185], v[54:57]
	v_mfma_f32_16x16x32_bf16 v[50:53], v[174:177], v[182:185], v[50:53]
	v_mfma_f32_16x16x32_bf16 v[34:37], v[174:177], v[190:193], v[34:37]
	v_mfma_f32_16x16x32_bf16 v[38:41], v[166:169], v[190:193], v[38:41]
	v_mfma_f32_16x16x32_bf16 v[22:25], v[166:169], v[198:201], v[22:25]
	v_mfma_f32_16x16x32_bf16 v[18:21], v[174:177], v[198:201], v[18:21]
	v_mfma_f32_16x16x32_bf16 v[2:5], v[174:177], v[206:209], v[2:5]
	v_mfma_f32_16x16x32_bf16 v[6:9], v[166:169], v[206:209], v[6:9]
	v_mfma_f32_16x16x32_bf16 v[54:57], v[170:173], v[186:189], v[54:57]
	v_mfma_f32_16x16x32_bf16 v[50:53], v[178:181], v[186:189], v[50:53]
	v_mfma_f32_16x16x32_bf16 v[34:37], v[178:181], v[194:197], v[34:37]
	v_mfma_f32_16x16x32_bf16 v[38:41], v[170:173], v[194:197], v[38:41]
	v_mfma_f32_16x16x32_bf16 v[22:25], v[170:173], v[202:205], v[22:25]
	v_mfma_f32_16x16x32_bf16 v[18:21], v[178:181], v[202:205], v[18:21]
	v_mfma_f32_16x16x32_bf16 v[2:5], v[178:181], v[210:213], v[2:5]
	v_mfma_f32_16x16x32_bf16 v[6:9], v[170:173], v[210:213], v[6:9]
	s_setprio 0
	s_barrier
	s_movk_i32 s44, 0x100
	s_andn2_b64 vcc, exec, s[4:5]
	s_mov_b64 s[10:11], -1
	s_mov_b64 s[4:5], 0
	s_cbranch_vccz .LBB0_1451
	s_and_b64 vcc, exec, s[24:25]
	s_cbranch_vccz .LBB0_1454
	s_barrier

; #define PG8_STAGE(bufoff, gbase, voff) do { _Pragma("unroll") for (int _i = 0; _i < 2; ++_i) \
;         __builtin_amdgcn_global_load_lds((const unsigned*)((const char*)(gbase) + (voff)[_i]), (LAS unsigned*)(lds + (bufoff) + ldsw + _i * 8192), 16, 0, 0); } while (0)
; #define PG8_LDA(dst, b, h) do { _Pragma("unroll") for (int m = 0; m < 4; ++m) _Pragma("unroll") for (int k = 0; k < 2; ++k) dst[m][k] = *(const LAS bf16x8*)(lds + PG8_SA(b, h) + aoff + m * 2048 + k * 1024); } while (0)
; #define PG8_LDB(dst, b, h) do { _Pragma("unroll") for (int n = 0; n < 2; ++n) _Pragma("unroll") for (int k = 0; k < 2; ++k) dst[n][k] = *(const LAS bf16x8*)(lds + PG8_SB(b, h) + boff + n * 2048 + k * 1024); } while (0)
; #define PG8_MMA(ai, bj, At, Bt) do { __builtin_amdgcn_s_setprio(1); _Pragma("unroll") for (int m = 0; m < 4; ++m) _Pragma("unroll") for (int n = 0; n < 2; ++n) _Pragma("unroll") for (int k = 0; k < 2; ++k) \
;         acc[ai][bj][m][n] = __builtin_amdgcn_mfma_f32_16x16x32_bf16(Bt[n][k], At[m][k], acc[ai][bj][m][n], 0, 0, 0); __builtin_amdgcn_s_setprio(0); } while (0)
; #define PG8_WAIT_V(n) asm volatile("s_waitcnt vmcnt(" #n ")" ::: "memory")
; #define PG8_WAIT_L(n) asm volatile("s_waitcnt lgkmcnt(" #n ")" ::: "memory")
; #define PG8_BAR __builtin_amdgcn_s_barrier()
; #define PG8_SCHED __builtin_amdgcn_sched_barrier(0)
; template <class Epi>
; __device__ __forceinline__ void gemm_phase(LAS unsigned char* lds, const Gemm g, int G, int c, const Epi& E) {
;     ...
;             const char* a1 = cA + (size_t)(t + 1) * kstep;
;             const char* a2 = last ? nA : cA + (size_t)(t + 2) * kstep; const char* b2 = last ? nB : cB + (size_t)(t + 2) * kstep;
;             const char* a3 = a2 + kstep; const char* b3 = b2 + kstep;
;             PG8_LDB(B0, 0, 0); PG8_LDB(B1, 0, 1); PG8_SCHED; PG8_LDA(At, 0, 0); PG8_STAGE(PG8_SA(1, 1), a1 + hstepA, voffA);
;             PG8_WAIT_V(8); PG8_WAIT_L(0); PG8_BAR; PG8_MMA(0, 0, At, B0); PG8_MMA(0, 1, At, B1); PG8_BAR; PG8_SCHED;
;             PG8_LDA(At, 0, 1); PG8_STAGE(PG8_SB(0, 0), b2, voffB); PG8_STAGE(PG8_SB(0, 1), b2 + hstepB, voffB); PG8_STAGE(PG8_SA(0, 0), a2, voffA);
.LBB0_1537:
	s_add_u32 s33, s8, s44
	s_addc_u32 s45, s9, 0
	s_add_u32 s48, s33, 0x100
	s_addc_u32 s49, s45, 0
	s_and_b64 s[46:47], s[10:11], exec
	s_cselect_b32 s47, s41, s49
	s_cselect_b32 s46, s40, s48
	s_add_u32 s44, s6, s44
	s_addc_u32 s48, s7, 0
	s_add_u32 s44, s44, 0x100
	s_addc_u32 s48, s48, 0
	s_and_b64 s[10:11], s[10:11], exec
	s_cselect_b32 s49, s43, s48
	s_cselect_b32 s48, s42, s44
	s_add_u32 s54, s33, 0xb0080
	ds_read_b128 v[130:133], v166
	ds_read_b128 v[134:137], v166 offset:1024
	ds_read_b128 v[150:153], v166 offset:2048
	ds_read_b128 v[154:157], v166 offset:3072
	ds_read_b128 v[158:161], v167
	ds_read_b128 v[172:175], v167 offset:1024
	ds_read_b128 v[176:179], v167 offset:2048
	ds_read_b128 v[180:183], v167 offset:3072
	s_addc_u32 s55, s45, 0
	s_add_i32 s63, s87, s70
	s_add_i32 m0, s73, 0xc000
	s_add_i32 s64, s73, 0xe000
	s_add_i32 s74, s63, 0x2000
	s_add_u32 s52, s48, 0xb0000
	s_addc_u32 s53, s49, 0
	s_add_i32 s62, s88, s70
	s_add_i32 s75, s62, 0x2000
	s_add_i32 s97, 0, 0x18000
	s_add_i32 s33, 0, 0x1c000
	s_add_u32 s44, s46, 0xb0000
	s_addc_u32 s45, s47, 0
	s_add_i32 s96, s97, s70
	s_add_i32 s94, s96, 0x2000
	s_add_u32 s10, s48, 0xb0080
	s_addc_u32 s11, s49, 0
	s_add_i32 s95, s33, s70
	s_add_i32 s93, s95, 0x2000
	v_lshl_add_u64 v[162:163], s[54:55], 0, v[138:139]
	ds_read_b128 v[184:187], v168
	ds_read_b128 v[188:191], v168 offset:1024
	ds_read_b128 v[192:195], v168 offset:2048
	ds_read_b128 v[196:199], v168 offset:3072
	ds_read_b128 v[200:203], v168 offset:4096
	ds_read_b128 v[204:207], v168 offset:5120
	ds_read_b128 v[208:211], v168 offset:6144
	ds_read_b128 v[212:215], v168 offset:7168
	global_load_lds_dwordx4 v[162:163], off
	v_lshl_add_u64 v[162:163], s[54:55], 0, v[142:143]
	s_mov_b32 m0, s64
	s_nop 0
	global_load_lds_dwordx4 v[162:163], off
	s_waitcnt vmcnt(8)
	s_waitcnt lgkmcnt(0)
	s_barrier
	s_setprio 1
	s_waitcnt lgkmcnt(0)
	v_mfma_f32_16x16x32_bf16 v[126:129], v[130:133], v[184:187], v[126:129]
	v_mfma_f32_16x16x32_bf16 v[122:125], v[150:153], v[184:187], v[122:125]
	v_mfma_f32_16x16x32_bf16 v[106:109], v[150:153], v[192:195], v[106:109]
	v_mfma_f32_16x16x32_bf16 v[110:113], v[130:133], v[192:195], v[110:113]
	v_mfma_f32_16x16x32_bf16 v[94:97], v[130:133], v[200:203], v[94:97]
	v_mfma_f32_16x16x32_bf16 v[90:93], v[150:153], v[200:203], v[90:93]
	v_mfma_f32_16x16x32_bf16 v[74:77], v[150:153], v[208:211], v[74:77]
	v_mfma_f32_16x16x32_bf16 v[78:81], v[130:133], v[208:211], v[78:81]
	v_mfma_f32_16x16x32_bf16 v[126:129], v[134:137], v[188:191], v[126:129]
	v_mfma_f32_16x16x32_bf16 v[122:125], v[154:157], v[188:191], v[122:125]
	v_mfma_f32_16x16x32_bf16 v[106:109], v[154:157], v[196:199], v[106:109]
	v_mfma_f32_16x16x32_bf16 v[110:113], v[134:137], v[196:199], v[110:113]
	v_mfma_f32_16x16x32_bf16 v[94:97], v[134:137], v[204:207], v[94:97]
	v_mfma_f32_16x16x32_bf16 v[90:93], v[154:157], v[204:207], v[90:93]
	v_mfma_f32_16x16x32_bf16 v[74:77], v[154:157], v[212:215], v[74:77]
	v_mfma_f32_16x16x32_bf16 v[78:81], v[134:137], v[212:215], v[78:81]
	s_setprio 0
	s_setprio 1
	v_mfma_f32_16x16x32_bf16 v[118:121], v[158:161], v[184:187], v[118:121]
	v_mfma_f32_16x16x32_bf16 v[114:117], v[176:179], v[184:187], v[114:117]
	v_mfma_f32_16x16x32_bf16 v[98:101], v[176:179], v[192:195], v[98:101]
	v_mfma_f32_16x16x32_bf16 v[102:105], v[158:161], v[192:195], v[102:105]
	v_mfma_f32_16x16x32_bf16 v[86:89], v[158:161], v[200:203], v[86:89]
	v_mfma_f32_16x16x32_bf16 v[82:85], v[176:179], v[200:203], v[82:85]
	v_mfma_f32_16x16x32_bf16 v[66:69], v[176:179], v[208:211], v[66:69]
	v_mfma_f32_16x16x32_bf16 v[70:73], v[158:161], v[208:211], v[70:73]
	v_mfma_f32_16x16x32_bf16 v[118:121], v[172:175], v[188:191], v[118:121]
	v_mfma_f32_16x16x32_bf16 v[114:117], v[180:183], v[188:191], v[114:117]
	v_mfma_f32_16x16x32_bf16 v[98:101], v[180:183], v[196:199], v[98:101]
	v_mfma_f32_16x16x32_bf16 v[102:105], v[172:175], v[196:199], v[102:105]
	v_mfma_f32_16x16x32_bf16 v[86:89], v[172:175], v[204:207], v[86:89]
	v_mfma_f32_16x16x32_bf16 v[82:85], v[180:183], v[204:207], v[82:85]
	v_mfma_f32_16x16x32_bf16 v[66:69], v[180:183], v[212:215], v[66:69]
	v_mfma_f32_16x16x32_bf16 v[70:73], v[172:175], v[212:215], v[70:73]
	s_setprio 0
	s_barrier
	s_mov_b32 m0, s63
	v_lshl_add_u64 v[162:163], s[48:49], 0, v[140:141]
	ds_read_b128 v[184:187], v168 offset:16384
	ds_read_b128 v[188:191], v168 offset:17408
	ds_read_b128 v[192:195], v168 offset:18432
	ds_read_b128 v[196:199], v168 offset:19456
	ds_read_b128 v[200:203], v168 offset:20480
	ds_read_b128 v[204:207], v168 offset:21504
	ds_read_b128 v[208:211], v168 offset:22528
	ds_read_b128 v[212:215], v168 offset:23552
	global_load_lds_dwordx4 v[162:163], off
	v_lshl_add_u64 v[216:217], s[48:49], 0, v[144:145]
	s_mov_b32 m0, s74
	v_lshl_add_u64 v[218:219], s[52:53], 0, v[140:141]
	global_load_lds_dwordx4 v[216:217], off
	s_mov_b32 m0, s62
	v_lshl_add_u64 v[220:221], s[46:47], 0, v[142:143]
	global_load_lds_dwordx4 v[218:219], off
	v_lshl_add_u64 v[218:219], s[52:53], 0, v[144:145]
	s_mov_b32 m0, s75
	s_nop 0
	global_load_lds_dwordx4 v[218:219], off
	v_lshl_add_u64 v[218:219], s[46:47], 0, v[138:139]
	s_mov_b32 m0, s73
	s_nop 0
	global_load_lds_dwordx4 v[218:219], off
	s_mov_b32 m0, s79
	s_nop 0
	global_load_lds_dwordx4 v[220:221], off
	s_waitcnt vmcnt(8)
	s_waitcnt lgkmcnt(0)
	s_barrier
; #define PG8_STAGE(bufoff, gbase, voff) do { _Pragma("unroll") for (int _i = 0; _i < 2; ++_i) \
;         __builtin_amdgcn_global_load_lds((const unsigned*)((const char*)(gbase) + (voff)[_i]), (LAS unsigned*)(lds + (bufoff) + ldsw + _i * 8192), 16, 0, 0); } while (0)
; #define PG8_LDA(dst, b, h) do { _Pragma("unroll") for (int m = 0; m < 4; ++m) _Pragma("unroll") for (int k = 0; k < 2; ++k) dst[m][k] = *(const LAS bf16x8*)(lds + PG8_SA(b, h) + aoff + m * 2048 + k * 1024); } while (0)
; #define PG8_LDB(dst, b, h) do { _Pragma("unroll") for (int n = 0; n < 2; ++n) _Pragma("unroll") for (int k = 0; k < 2; ++k) dst[n][k] = *(const LAS bf16x8*)(lds + PG8_SB(b, h) + boff + n * 2048 + k * 1024); } while (0)
; #define PG8_MMA(ai, bj, At, Bt) do { __builtin_amdgcn_s_setprio(1); _Pragma("unroll") for (int m = 0; m < 4; ++m) _Pragma("unroll") for (int n = 0; n < 2; ++n) _Pragma("unroll") for (int k = 0; k < 2; ++k) \
;         acc[ai][bj][m][n] = __builtin_amdgcn_mfma_f32_16x16x32_bf16(Bt[n][k], At[m][k], acc[ai][bj][m][n], 0, 0, 0); __builtin_amdgcn_s_setprio(0); } while (0)
; #define PG8_WAIT_V(n) asm volatile("s_waitcnt vmcnt(" #n ")" ::: "memory")
; #define PG8_WAIT_L(n) asm volatile("s_waitcnt lgkmcnt(" #n ")" ::: "memory")
; #define PG8_BAR __builtin_amdgcn_s_barrier()
; #define PG8_SCHED __builtin_amdgcn_sched_barrier(0)
; template <class Epi>
; __device__ __forceinline__ void gemm_phase(LAS unsigned char* lds, const Gemm g, int G, int c, const Epi& E) {
;     ...
;             PG8_WAIT_V(8); PG8_WAIT_L(0); PG8_BAR; PG8_MMA(1, 0, At, B0); PG8_MMA(1, 1, At, B1); PG8_BAR; PG8_SCHED;
;             PG8_LDB(B0, 1, 0); PG8_LDB(B1, 1, 1); PG8_SCHED; PG8_LDA(At, 1, 0); PG8_STAGE(PG8_SA(0, 1), a2 + hstepA, voffA);
;             PG8_WAIT_V(8); PG8_WAIT_L(0); PG8_BAR; PG8_MMA(0, 0, At, B0); PG8_MMA(0, 1, At, B1); PG8_BAR; PG8_SCHED;
;             PG8_LDA(At, 1, 1); PG8_STAGE(PG8_SB(1, 0), b3, voffB); PG8_STAGE(PG8_SB(1, 1), b3 + hstepB, voffB); PG8_STAGE(PG8_SA(1, 0), a3, voffA);
	s_setprio 1
	s_waitcnt lgkmcnt(0)
	v_mfma_f32_16x16x32_bf16 v[62:65], v[130:133], v[184:187], v[62:65]
	v_mfma_f32_16x16x32_bf16 v[58:61], v[150:153], v[184:187], v[58:61]
	v_mfma_f32_16x16x32_bf16 v[42:45], v[150:153], v[192:195], v[42:45]
	v_mfma_f32_16x16x32_bf16 v[46:49], v[130:133], v[192:195], v[46:49]
	v_mfma_f32_16x16x32_bf16 v[30:33], v[130:133], v[200:203], v[30:33]
	v_mfma_f32_16x16x32_bf16 v[26:29], v[150:153], v[200:203], v[26:29]
	v_mfma_f32_16x16x32_bf16 v[10:13], v[150:153], v[208:211], v[10:13]
	v_mfma_f32_16x16x32_bf16 v[14:17], v[130:133], v[208:211], v[14:17]
	v_mfma_f32_16x16x32_bf16 v[62:65], v[134:137], v[188:191], v[62:65]
	v_mfma_f32_16x16x32_bf16 v[58:61], v[154:157], v[188:191], v[58:61]
	v_mfma_f32_16x16x32_bf16 v[42:45], v[154:157], v[196:199], v[42:45]
	v_mfma_f32_16x16x32_bf16 v[46:49], v[134:137], v[196:199], v[46:49]
	v_mfma_f32_16x16x32_bf16 v[30:33], v[134:137], v[204:207], v[30:33]
	v_mfma_f32_16x16x32_bf16 v[26:29], v[154:157], v[204:207], v[26:29]
	v_mfma_f32_16x16x32_bf16 v[10:13], v[154:157], v[212:215], v[10:13]
	v_mfma_f32_16x16x32_bf16 v[14:17], v[134:137], v[212:215], v[14:17]
	s_setprio 0
	s_setprio 1
	v_mfma_f32_16x16x32_bf16 v[54:57], v[158:161], v[184:187], v[54:57]
	v_mfma_f32_16x16x32_bf16 v[50:53], v[176:179], v[184:187], v[50:53]
	v_mfma_f32_16x16x32_bf16 v[34:37], v[176:179], v[192:195], v[34:37]
	v_mfma_f32_16x16x32_bf16 v[38:41], v[158:161], v[192:195], v[38:41]
	v_mfma_f32_16x16x32_bf16 v[22:25], v[158:161], v[200:203], v[22:25]
	v_mfma_f32_16x16x32_bf16 v[18:21], v[176:179], v[200:203], v[18:21]
	v_mfma_f32_16x16x32_bf16 v[2:5], v[176:179], v[208:211], v[2:5]
	v_mfma_f32_16x16x32_bf16 v[6:9], v[158:161], v[208:211], v[6:9]
	v_mfma_f32_16x16x32_bf16 v[54:57], v[172:175], v[188:191], v[54:57]
	v_mfma_f32_16x16x32_bf16 v[50:53], v[180:183], v[188:191], v[50:53]
	v_mfma_f32_16x16x32_bf16 v[34:37], v[180:183], v[196:199], v[34:37]
	v_mfma_f32_16x16x32_bf16 v[38:41], v[172:175], v[196:199], v[38:41]
	v_mfma_f32_16x16x32_bf16 v[22:25], v[172:175], v[204:207], v[22:25]
	v_mfma_f32_16x16x32_bf16 v[18:21], v[180:183], v[204:207], v[18:21]
	v_mfma_f32_16x16x32_bf16 v[2:5], v[180:183], v[212:215], v[2:5]
	v_mfma_f32_16x16x32_bf16 v[6:9], v[172:175], v[212:215], v[6:9]
	s_setprio 0
	s_barrier
	v_add_u32_e32 v154, s97, v165
	v_add_u32_e32 v180, s33, v165
	ds_read_b128 v[130:133], v154
	ds_read_b128 v[134:137], v154 offset:1024
	ds_read_b128 v[150:153], v154 offset:2048
	ds_read_b128 v[154:157], v154 offset:3072
	ds_read_b128 v[158:161], v180
	ds_read_b128 v[172:175], v180 offset:1024
	ds_read_b128 v[176:179], v180 offset:2048
	ds_read_b128 v[180:183], v180 offset:3072
	s_mov_b32 m0, s80
	v_lshl_add_u64 v[222:223], s[44:45], 0, v[138:139]
	ds_read_b128 v[184:187], v168 offset:32768
	ds_read_b128 v[188:191], v168 offset:33792
	ds_read_b128 v[192:195], v168 offset:34816
	ds_read_b128 v[196:199], v168 offset:35840
	ds_read_b128 v[200:203], v168 offset:36864
	ds_read_b128 v[204:207], v168 offset:37888
	ds_read_b128 v[208:211], v168 offset:38912
	ds_read_b128 v[212:215], v168 offset:39936
	global_load_lds_dwordx4 v[222:223], off
	v_lshl_add_u64 v[222:223], s[44:45], 0, v[142:143]
	s_mov_b32 m0, s81
	s_nop 0
	global_load_lds_dwordx4 v[222:223], off
	s_waitcnt vmcnt(8)
	s_waitcnt lgkmcnt(0)
	s_barrier
	s_setprio 1
	s_waitcnt lgkmcnt(0)
	v_mfma_f32_16x16x32_bf16 v[126:129], v[130:133], v[184:187], v[126:129]
	v_mfma_f32_16x16x32_bf16 v[122:125], v[150:153], v[184:187], v[122:125]
	v_mfma_f32_16x16x32_bf16 v[106:109], v[150:153], v[192:195], v[106:109]
	v_mfma_f32_16x16x32_bf16 v[110:113], v[130:133], v[192:195], v[110:113]
	v_mfma_f32_16x16x32_bf16 v[94:97], v[130:133], v[200:203], v[94:97]
	v_mfma_f32_16x16x32_bf16 v[90:93], v[150:153], v[200:203], v[90:93]
	v_mfma_f32_16x16x32_bf16 v[74:77], v[150:153], v[208:211], v[74:77]
	v_mfma_f32_16x16x32_bf16 v[78:81], v[130:133], v[208:211], v[78:81]
	v_mfma_f32_16x16x32_bf16 v[126:129], v[134:137], v[188:191], v[126:129]
	v_mfma_f32_16x16x32_bf16 v[122:125], v[154:157], v[188:191], v[122:125]
	v_mfma_f32_16x16x32_bf16 v[106:109], v[154:157], v[196:199], v[106:109]
	v_mfma_f32_16x16x32_bf16 v[110:113], v[134:137], v[196:199], v[110:113]
	v_mfma_f32_16x16x32_bf16 v[94:97], v[134:137], v[204:207], v[94:97]
	v_mfma_f32_16x16x32_bf16 v[90:93], v[154:157], v[204:207], v[90:93]
	v_mfma_f32_16x16x32_bf16 v[74:77], v[154:157], v[212:215], v[74:77]
	v_mfma_f32_16x16x32_bf16 v[78:81], v[134:137], v[212:215], v[78:81]
	s_setprio 0
	s_setprio 1
	v_mfma_f32_16x16x32_bf16 v[118:121], v[158:161], v[184:187], v[118:121]
	v_mfma_f32_16x16x32_bf16 v[114:117], v[176:179], v[184:187], v[114:117]
	v_mfma_f32_16x16x32_bf16 v[98:101], v[176:179], v[192:195], v[98:101]
	v_mfma_f32_16x16x32_bf16 v[102:105], v[158:161], v[192:195], v[102:105]
	v_mfma_f32_16x16x32_bf16 v[86:89], v[158:161], v[200:203], v[86:89]
	v_mfma_f32_16x16x32_bf16 v[82:85], v[176:179], v[200:203], v[82:85]
	v_mfma_f32_16x16x32_bf16 v[66:69], v[176:179], v[208:211], v[66:69]
	v_mfma_f32_16x16x32_bf16 v[70:73], v[158:161], v[208:211], v[70:73]
	v_mfma_f32_16x16x32_bf16 v[118:121], v[172:175], v[188:191], v[118:121]
	v_mfma_f32_16x16x32_bf16 v[114:117], v[180:183], v[188:191], v[114:117]
	v_mfma_f32_16x16x32_bf16 v[98:101], v[180:183], v[196:199], v[98:101]
	v_mfma_f32_16x16x32_bf16 v[102:105], v[172:175], v[196:199], v[102:105]
	v_mfma_f32_16x16x32_bf16 v[86:89], v[172:175], v[204:207], v[86:89]
	v_mfma_f32_16x16x32_bf16 v[82:85], v[180:183], v[204:207], v[82:85]
	v_mfma_f32_16x16x32_bf16 v[66:69], v[180:183], v[212:215], v[66:69]
	v_mfma_f32_16x16x32_bf16 v[70:73], v[172:175], v[212:215], v[70:73]
	s_setprio 0
	s_barrier
; #define PG8_STAGE(bufoff, gbase, voff) do { _Pragma("unroll") for (int _i = 0; _i < 2; ++_i) \
;         __builtin_amdgcn_global_load_lds((const unsigned*)((const char*)(gbase) + (voff)[_i]), (LAS unsigned*)(lds + (bufoff) + ldsw + _i * 8192), 16, 0, 0); } while (0)
; #define PG8_LDA(dst, b, h) do { _Pragma("unroll") for (int m = 0; m < 4; ++m) _Pragma("unroll") for (int k = 0; k < 2; ++k) dst[m][k] = *(const LAS bf16x8*)(lds + PG8_SA(b, h) + aoff + m * 2048 + k * 1024); } while (0)
; #define PG8_MMA(ai, bj, At, Bt) do { __builtin_amdgcn_s_setprio(1); _Pragma("unroll") for (int m = 0; m < 4; ++m) _Pragma("unroll") for (int n = 0; n < 2; ++n) _Pragma("unroll") for (int k = 0; k < 2; ++k) \
;         acc[ai][bj][m][n] = __builtin_amdgcn_mfma_f32_16x16x32_bf16(Bt[n][k], At[m][k], acc[ai][bj][m][n], 0, 0, 0); __builtin_amdgcn_s_setprio(0); } while (0)
; #define PG8_WAIT_V(n) asm volatile("s_waitcnt vmcnt(" #n ")" ::: "memory")
; #define PG8_WAIT_L(n) asm volatile("s_waitcnt lgkmcnt(" #n ")" ::: "memory")
; #define PG8_BAR __builtin_amdgcn_s_barrier()
; #define PG8_SCHED __builtin_amdgcn_sched_barrier(0)
; template <class Epi>
; __device__ __forceinline__ void gemm_phase(LAS unsigned char* lds, const Gemm g, int G, int c, const Epi& E) {
;     ...
;             PG8_LDA(At, 1, 1); PG8_STAGE(PG8_SB(1, 0), b3, voffB); PG8_STAGE(PG8_SB(1, 1), b3 + hstepB, voffB); PG8_STAGE(PG8_SA(1, 0), a3, voffA);
;             PG8_WAIT_V(8); PG8_WAIT_L(0); PG8_BAR; PG8_MMA(1, 0, At, B0); PG8_MMA(1, 1, At, B1); PG8_BAR; PG8_SCHED;
;         }
	s_mov_b32 m0, s96
	v_lshl_add_u64 v[162:163], v[162:163], 0, s[22:23]
	ds_read_b128 v[184:187], v168 offset:49152
	ds_read_b128 v[188:191], v168 offset:50176
	ds_read_b128 v[192:195], v168 offset:51200
	ds_read_b128 v[196:199], v168 offset:52224
	ds_read_b128 v[200:203], v168 offset:53248
	ds_read_b128 v[204:207], v168 offset:54272
	ds_read_b128 v[208:211], v168 offset:55296
	ds_read_b128 v[212:215], v168 offset:56320
	global_load_lds_dwordx4 v[162:163], off
	v_lshl_add_u64 v[162:163], v[216:217], 0, s[22:23]
	s_mov_b32 m0, s94
	s_nop 0
	global_load_lds_dwordx4 v[162:163], off
	v_lshl_add_u64 v[162:163], s[10:11], 0, v[140:141]
	s_mov_b32 m0, s95
	s_nop 0
	global_load_lds_dwordx4 v[162:163], off
	v_lshl_add_u64 v[162:163], s[10:11], 0, v[144:145]
	s_mov_b32 m0, s93
	s_nop 0
	global_load_lds_dwordx4 v[162:163], off
	v_lshl_add_u64 v[162:163], v[218:219], 0, s[22:23]
	s_mov_b32 m0, s85
	s_nop 0
	global_load_lds_dwordx4 v[162:163], off
	v_lshl_add_u64 v[162:163], v[220:221], 0, s[22:23]
	s_mov_b32 m0, s86
	s_nop 0
	global_load_lds_dwordx4 v[162:163], off
	s_waitcnt vmcnt(8)
	s_waitcnt lgkmcnt(0)
	s_barrier
	s_setprio 1
	s_waitcnt lgkmcnt(0)
	v_mfma_f32_16x16x32_bf16 v[62:65], v[130:133], v[184:187], v[62:65]
	v_mfma_f32_16x16x32_bf16 v[58:61], v[150:153], v[184:187], v[58:61]
	v_mfma_f32_16x16x32_bf16 v[42:45], v[150:153], v[192:195], v[42:45]
	v_mfma_f32_16x16x32_bf16 v[46:49], v[130:133], v[192:195], v[46:49]
	v_mfma_f32_16x16x32_bf16 v[30:33], v[130:133], v[200:203], v[30:33]
	v_mfma_f32_16x16x32_bf16 v[26:29], v[150:153], v[200:203], v[26:29]
	v_mfma_f32_16x16x32_bf16 v[10:13], v[150:153], v[208:211], v[10:13]
	v_mfma_f32_16x16x32_bf16 v[14:17], v[130:133], v[208:211], v[14:17]
	v_mfma_f32_16x16x32_bf16 v[62:65], v[134:137], v[188:191], v[62:65]
	v_mfma_f32_16x16x32_bf16 v[58:61], v[154:157], v[188:191], v[58:61]
	v_mfma_f32_16x16x32_bf16 v[42:45], v[154:157], v[196:199], v[42:45]
	v_mfma_f32_16x16x32_bf16 v[46:49], v[134:137], v[196:199], v[46:49]
	v_mfma_f32_16x16x32_bf16 v[30:33], v[134:137], v[204:207], v[30:33]
	v_mfma_f32_16x16x32_bf16 v[26:29], v[154:157], v[204:207], v[26:29]
	v_mfma_f32_16x16x32_bf16 v[10:13], v[154:157], v[212:215], v[10:13]
	v_mfma_f32_16x16x32_bf16 v[14:17], v[134:137], v[212:215], v[14:17]
	s_setprio 0
	s_setprio 1
	v_mfma_f32_16x16x32_bf16 v[54:57], v[158:161], v[184:187], v[54:57]
	v_mfma_f32_16x16x32_bf16 v[50:53], v[176:179], v[184:187], v[50:53]
	v_mfma_f32_16x16x32_bf16 v[34:37], v[176:179], v[192:195], v[34:37]
	v_mfma_f32_16x16x32_bf16 v[38:41], v[158:161], v[192:195], v[38:41]
	v_mfma_f32_16x16x32_bf16 v[22:25], v[158:161], v[200:203], v[22:25]
	v_mfma_f32_16x16x32_bf16 v[18:21], v[176:179], v[200:203], v[18:21]
	v_mfma_f32_16x16x32_bf16 v[2:5], v[176:179], v[208:211], v[2:5]
	v_mfma_f32_16x16x32_bf16 v[6:9], v[158:161], v[208:211], v[6:9]
	v_mfma_f32_16x16x32_bf16 v[54:57], v[172:175], v[188:191], v[54:57]
	v_mfma_f32_16x16x32_bf16 v[50:53], v[180:183], v[188:191], v[50:53]
	v_mfma_f32_16x16x32_bf16 v[34:37], v[180:183], v[196:199], v[34:37]
	v_mfma_f32_16x16x32_bf16 v[38:41], v[172:175], v[196:199], v[38:41]
	v_mfma_f32_16x16x32_bf16 v[22:25], v[172:175], v[204:207], v[22:25]
	v_mfma_f32_16x16x32_bf16 v[18:21], v[180:183], v[204:207], v[18:21]
	v_mfma_f32_16x16x32_bf16 v[2:5], v[180:183], v[212:215], v[2:5]
	v_mfma_f32_16x16x32_bf16 v[6:9], v[172:175], v[212:215], v[6:9]
	s_setprio 0
	s_barrier
	s_movk_i32 s44, 0x100
	s_andn2_b64 vcc, exec, s[4:5]
	s_mov_b64 s[10:11], -1
	s_mov_b64 s[4:5], 0
	s_cbranch_vccz .LBB0_1537
	s_and_b64 vcc, exec, s[24:25]
	s_cbranch_vccz .LBB0_1540
	s_barrier

; #define PG8_STAGE(bufoff, gbase, voff) do { _Pragma("unroll") for (int _i = 0; _i < 2; ++_i) \
;         __builtin_amdgcn_global_load_lds((const unsigned*)((const char*)(gbase) + (voff)[_i]), (LAS unsigned*)(lds + (bufoff) + ldsw + _i * 8192), 16, 0, 0); } while (0)
; #define PG8_LDA(dst, b, h) do { _Pragma("unroll") for (int m = 0; m < 4; ++m) _Pragma("unroll") for (int k = 0; k < 2; ++k) dst[m][k] = *(const LAS bf16x8*)(lds + PG8_SA(b, h) + aoff + m * 2048 + k * 1024); } while (0)
; #define PG8_LDB(dst, b, h) do { _Pragma("unroll") for (int n = 0; n < 2; ++n) _Pragma("unroll") for (int k = 0; k < 2; ++k) dst[n][k] = *(const LAS bf16x8*)(lds + PG8_SB(b, h) + boff + n * 2048 + k * 1024); } while (0)
; #define PG8_MMA(ai, bj, At, Bt) do { __builtin_amdgcn_s_setprio(1); _Pragma("unroll") for (int m = 0; m < 4; ++m) _Pragma("unroll") for (int n = 0; n < 2; ++n) _Pragma("unroll") for (int k = 0; k < 2; ++k) \
;         acc[ai][bj][m][n] = __builtin_amdgcn_mfma_f32_16x16x32_bf16(Bt[n][k], At[m][k], acc[ai][bj][m][n], 0, 0, 0); __builtin_amdgcn_s_setprio(0); } while (0)
; #define PG8_WAIT_V(n) asm volatile("s_waitcnt vmcnt(" #n ")" ::: "memory")
; #define PG8_WAIT_L(n) asm volatile("s_waitcnt lgkmcnt(" #n ")" ::: "memory")
; #define PG8_BAR __builtin_amdgcn_s_barrier()
; #define PG8_SCHED __builtin_amdgcn_sched_barrier(0)
; template <class Epi>
; __device__ __forceinline__ void gemm_phase(LAS unsigned char* lds, const Gemm g, int G, int c, const Epi& E) {
;     ...
;             const char* a1 = cA + (size_t)(t + 1) * kstep;
;             const char* a2 = last ? nA : cA + (size_t)(t + 2) * kstep; const char* b2 = last ? nB : cB + (size_t)(t + 2) * kstep;
;             const char* a3 = a2 + kstep; const char* b3 = b2 + kstep;
;             PG8_LDB(B0, 0, 0); PG8_LDB(B1, 0, 1); PG8_SCHED; PG8_LDA(At, 0, 0); PG8_STAGE(PG8_SA(1, 1), a1 + hstepA, voffA);
;             PG8_WAIT_V(8); PG8_WAIT_L(0); PG8_BAR; PG8_MMA(0, 0, At, B0); PG8_MMA(0, 1, At, B1); PG8_BAR; PG8_SCHED;
;             PG8_LDA(At, 0, 1); PG8_STAGE(PG8_SB(0, 0), b2, voffB); PG8_STAGE(PG8_SB(0, 1), b2 + hstepB, voffB); PG8_STAGE(PG8_SA(0, 0), a2, voffA);
.LBB0_1653:
	s_add_u32 s33, s8, s48
	s_addc_u32 s49, s9, 0
	s_add_u32 s54, s33, 0x100
	s_addc_u32 s55, s49, 0
	s_and_b64 s[52:53], s[46:47], exec
	s_cselect_b32 s53, s41, s55
	s_cselect_b32 s52, s40, s54
	s_add_u32 s48, s6, s48
	s_addc_u32 s54, s7, 0
	s_add_u32 s48, s48, 0x100
	s_addc_u32 s54, s54, 0
	s_and_b64 s[46:47], s[46:47], exec
	s_cselect_b32 s55, s43, s54
	s_cselect_b32 s54, s42, s48
	s_add_u32 s58, s33, 0xb0080
	ds_read_b128 v[142:145], v166
	ds_read_b128 v[146:149], v166 offset:1024
	ds_read_b128 v[150:153], v166 offset:2048
	ds_read_b128 v[154:157], v166 offset:3072
	ds_read_b128 v[158:161], v167
	ds_read_b128 v[170:173], v167 offset:1024
	ds_read_b128 v[174:177], v167 offset:2048
	ds_read_b128 v[178:181], v167 offset:3072
	s_addc_u32 s59, s49, 0
	s_add_i32 s63, s80, s23
	s_add_i32 m0, s68, 0xc000
	s_add_i32 s64, s68, 0xe000
	s_add_i32 s74, s63, 0x2000
	s_add_u32 s56, s54, 0xb0000
	s_addc_u32 s57, s55, 0
	s_add_i32 s62, s81, s23
	s_add_i32 s75, s62, 0x2000
	s_add_i32 s93, 0, 0x18000
	s_add_i32 s33, 0, 0x1c000
	s_add_u32 s48, s52, 0xb0000
	s_addc_u32 s49, s53, 0
	s_add_i32 s92, s93, s23
	s_add_i32 s90, s92, 0x2000
	s_add_u32 s46, s54, 0xb0080
	s_addc_u32 s47, s55, 0
	s_add_i32 s91, s33, s23
	s_add_i32 s89, s91, 0x2000
	v_lshl_add_u64 v[162:163], s[58:59], 0, v[136:137]
	ds_read_b128 v[182:185], v168
	ds_read_b128 v[186:189], v168 offset:1024
	ds_read_b128 v[190:193], v168 offset:2048
	ds_read_b128 v[194:197], v168 offset:3072
	ds_read_b128 v[198:201], v168 offset:4096
	ds_read_b128 v[202:205], v168 offset:5120
	ds_read_b128 v[206:209], v168 offset:6144
	ds_read_b128 v[210:213], v168 offset:7168
	global_load_lds_dwordx4 v[162:163], off
	v_lshl_add_u64 v[162:163], s[58:59], 0, v[132:133]
	s_mov_b32 m0, s64
	s_nop 0
	global_load_lds_dwordx4 v[162:163], off
	s_waitcnt vmcnt(8)
	s_waitcnt lgkmcnt(0)
	s_barrier
	s_setprio 1
	s_waitcnt lgkmcnt(0)
	v_mfma_f32_16x16x32_bf16 v[126:129], v[142:145], v[182:185], v[126:129]
	v_mfma_f32_16x16x32_bf16 v[122:125], v[150:153], v[182:185], v[122:125]
	v_mfma_f32_16x16x32_bf16 v[106:109], v[150:153], v[190:193], v[106:109]
	v_mfma_f32_16x16x32_bf16 v[110:113], v[142:145], v[190:193], v[110:113]
	v_mfma_f32_16x16x32_bf16 v[94:97], v[142:145], v[198:201], v[94:97]
	v_mfma_f32_16x16x32_bf16 v[90:93], v[150:153], v[198:201], v[90:93]
	v_mfma_f32_16x16x32_bf16 v[74:77], v[150:153], v[206:209], v[74:77]
	v_mfma_f32_16x16x32_bf16 v[78:81], v[142:145], v[206:209], v[78:81]
	v_mfma_f32_16x16x32_bf16 v[126:129], v[146:149], v[186:189], v[126:129]
	v_mfma_f32_16x16x32_bf16 v[122:125], v[154:157], v[186:189], v[122:125]
	v_mfma_f32_16x16x32_bf16 v[106:109], v[154:157], v[194:197], v[106:109]
	v_mfma_f32_16x16x32_bf16 v[110:113], v[146:149], v[194:197], v[110:113]
	v_mfma_f32_16x16x32_bf16 v[94:97], v[146:149], v[202:205], v[94:97]
	v_mfma_f32_16x16x32_bf16 v[90:93], v[154:157], v[202:205], v[90:93]
	v_mfma_f32_16x16x32_bf16 v[74:77], v[154:157], v[210:213], v[74:77]
	v_mfma_f32_16x16x32_bf16 v[78:81], v[146:149], v[210:213], v[78:81]
	s_setprio 0
	s_setprio 1
	v_mfma_f32_16x16x32_bf16 v[118:121], v[158:161], v[182:185], v[118:121]
	v_mfma_f32_16x16x32_bf16 v[114:117], v[174:177], v[182:185], v[114:117]
	v_mfma_f32_16x16x32_bf16 v[98:101], v[174:177], v[190:193], v[98:101]
	v_mfma_f32_16x16x32_bf16 v[102:105], v[158:161], v[190:193], v[102:105]
	v_mfma_f32_16x16x32_bf16 v[86:89], v[158:161], v[198:201], v[86:89]
	v_mfma_f32_16x16x32_bf16 v[82:85], v[174:177], v[198:201], v[82:85]
	v_mfma_f32_16x16x32_bf16 v[66:69], v[174:177], v[206:209], v[66:69]
	v_mfma_f32_16x16x32_bf16 v[70:73], v[158:161], v[206:209], v[70:73]
	v_mfma_f32_16x16x32_bf16 v[118:121], v[170:173], v[186:189], v[118:121]
	v_mfma_f32_16x16x32_bf16 v[114:117], v[178:181], v[186:189], v[114:117]
	v_mfma_f32_16x16x32_bf16 v[98:101], v[178:181], v[194:197], v[98:101]
	v_mfma_f32_16x16x32_bf16 v[102:105], v[170:173], v[194:197], v[102:105]
	v_mfma_f32_16x16x32_bf16 v[86:89], v[170:173], v[202:205], v[86:89]
	v_mfma_f32_16x16x32_bf16 v[82:85], v[178:181], v[202:205], v[82:85]
	v_mfma_f32_16x16x32_bf16 v[66:69], v[178:181], v[210:213], v[66:69]
	v_mfma_f32_16x16x32_bf16 v[70:73], v[170:173], v[210:213], v[70:73]
	s_setprio 0
	s_barrier
	s_mov_b32 m0, s63
	v_lshl_add_u64 v[162:163], s[54:55], 0, v[134:135]
	ds_read_b128 v[182:185], v168 offset:16384
	ds_read_b128 v[186:189], v168 offset:17408
	ds_read_b128 v[190:193], v168 offset:18432
	ds_read_b128 v[194:197], v168 offset:19456
	ds_read_b128 v[198:201], v168 offset:20480
	ds_read_b128 v[202:205], v168 offset:21504
	ds_read_b128 v[206:209], v168 offset:22528
	ds_read_b128 v[210:213], v168 offset:23552
	global_load_lds_dwordx4 v[162:163], off
	v_lshl_add_u64 v[214:215], s[54:55], 0, v[130:131]
	s_mov_b32 m0, s74
	v_lshl_add_u64 v[216:217], s[56:57], 0, v[134:135]
	global_load_lds_dwordx4 v[214:215], off
	s_mov_b32 m0, s62
	v_lshl_add_u64 v[218:219], s[52:53], 0, v[132:133]
	global_load_lds_dwordx4 v[216:217], off
	v_lshl_add_u64 v[216:217], s[56:57], 0, v[130:131]
	s_mov_b32 m0, s75
	s_nop 0
	global_load_lds_dwordx4 v[216:217], off
	v_lshl_add_u64 v[216:217], s[52:53], 0, v[136:137]
	s_mov_b32 m0, s68
	s_nop 0
	global_load_lds_dwordx4 v[216:217], off
	s_mov_b32 m0, s69
	s_nop 0
	global_load_lds_dwordx4 v[218:219], off
	s_waitcnt vmcnt(8)
	s_waitcnt lgkmcnt(0)
	s_barrier
; #define PG8_STAGE(bufoff, gbase, voff) do { _Pragma("unroll") for (int _i = 0; _i < 2; ++_i) \
;         __builtin_amdgcn_global_load_lds((const unsigned*)((const char*)(gbase) + (voff)[_i]), (LAS unsigned*)(lds + (bufoff) + ldsw + _i * 8192), 16, 0, 0); } while (0)
; #define PG8_LDA(dst, b, h) do { _Pragma("unroll") for (int m = 0; m < 4; ++m) _Pragma("unroll") for (int k = 0; k < 2; ++k) dst[m][k] = *(const LAS bf16x8*)(lds + PG8_SA(b, h) + aoff + m * 2048 + k * 1024); } while (0)
; #define PG8_LDB(dst, b, h) do { _Pragma("unroll") for (int n = 0; n < 2; ++n) _Pragma("unroll") for (int k = 0; k < 2; ++k) dst[n][k] = *(const LAS bf16x8*)(lds + PG8_SB(b, h) + boff + n * 2048 + k * 1024); } while (0)
; #define PG8_MMA(ai, bj, At, Bt) do { __builtin_amdgcn_s_setprio(1); _Pragma("unroll") for (int m = 0; m < 4; ++m) _Pragma("unroll") for (int n = 0; n < 2; ++n) _Pragma("unroll") for (int k = 0; k < 2; ++k) \
;         acc[ai][bj][m][n] = __builtin_amdgcn_mfma_f32_16x16x32_bf16(Bt[n][k], At[m][k], acc[ai][bj][m][n], 0, 0, 0); __builtin_amdgcn_s_setprio(0); } while (0)
; #define PG8_WAIT_V(n) asm volatile("s_waitcnt vmcnt(" #n ")" ::: "memory")
; #define PG8_WAIT_L(n) asm volatile("s_waitcnt lgkmcnt(" #n ")" ::: "memory")
; #define PG8_BAR __builtin_amdgcn_s_barrier()
; #define PG8_SCHED __builtin_amdgcn_sched_barrier(0)
; template <class Epi>
; __device__ __forceinline__ void gemm_phase(LAS unsigned char* lds, const Gemm g, int G, int c, const Epi& E) {
;     ...
;             PG8_WAIT_V(8); PG8_WAIT_L(0); PG8_BAR; PG8_MMA(1, 0, At, B0); PG8_MMA(1, 1, At, B1); PG8_BAR; PG8_SCHED;
;             PG8_LDB(B0, 1, 0); PG8_LDB(B1, 1, 1); PG8_SCHED; PG8_LDA(At, 1, 0); PG8_STAGE(PG8_SA(0, 1), a2 + hstepA, voffA);
;             PG8_WAIT_V(8); PG8_WAIT_L(0); PG8_BAR; PG8_MMA(0, 0, At, B0); PG8_MMA(0, 1, At, B1); PG8_BAR; PG8_SCHED;
;             PG8_LDA(At, 1, 1); PG8_STAGE(PG8_SB(1, 0), b3, voffB); PG8_STAGE(PG8_SB(1, 1), b3 + hstepB, voffB); PG8_STAGE(PG8_SA(1, 0), a3, voffA);
	s_setprio 1
	s_waitcnt lgkmcnt(0)
	v_mfma_f32_16x16x32_bf16 v[62:65], v[142:145], v[182:185], v[62:65]
	v_mfma_f32_16x16x32_bf16 v[58:61], v[150:153], v[182:185], v[58:61]
	v_mfma_f32_16x16x32_bf16 v[42:45], v[150:153], v[190:193], v[42:45]
	v_mfma_f32_16x16x32_bf16 v[46:49], v[142:145], v[190:193], v[46:49]
	v_mfma_f32_16x16x32_bf16 v[30:33], v[142:145], v[198:201], v[30:33]
	v_mfma_f32_16x16x32_bf16 v[26:29], v[150:153], v[198:201], v[26:29]
	v_mfma_f32_16x16x32_bf16 v[10:13], v[150:153], v[206:209], v[10:13]
	v_mfma_f32_16x16x32_bf16 v[14:17], v[142:145], v[206:209], v[14:17]
	v_mfma_f32_16x16x32_bf16 v[62:65], v[146:149], v[186:189], v[62:65]
	v_mfma_f32_16x16x32_bf16 v[58:61], v[154:157], v[186:189], v[58:61]
	v_mfma_f32_16x16x32_bf16 v[42:45], v[154:157], v[194:197], v[42:45]
	v_mfma_f32_16x16x32_bf16 v[46:49], v[146:149], v[194:197], v[46:49]
	v_mfma_f32_16x16x32_bf16 v[30:33], v[146:149], v[202:205], v[30:33]
	v_mfma_f32_16x16x32_bf16 v[26:29], v[154:157], v[202:205], v[26:29]
	v_mfma_f32_16x16x32_bf16 v[10:13], v[154:157], v[210:213], v[10:13]
	v_mfma_f32_16x16x32_bf16 v[14:17], v[146:149], v[210:213], v[14:17]
	s_setprio 0
	s_setprio 1
	v_mfma_f32_16x16x32_bf16 v[54:57], v[158:161], v[182:185], v[54:57]
	v_mfma_f32_16x16x32_bf16 v[50:53], v[174:177], v[182:185], v[50:53]
	v_mfma_f32_16x16x32_bf16 v[34:37], v[174:177], v[190:193], v[34:37]
	v_mfma_f32_16x16x32_bf16 v[38:41], v[158:161], v[190:193], v[38:41]
	v_mfma_f32_16x16x32_bf16 v[22:25], v[158:161], v[198:201], v[22:25]
	v_mfma_f32_16x16x32_bf16 v[18:21], v[174:177], v[198:201], v[18:21]
	v_mfma_f32_16x16x32_bf16 v[2:5], v[174:177], v[206:209], v[2:5]
	v_mfma_f32_16x16x32_bf16 v[6:9], v[158:161], v[206:209], v[6:9]
	v_mfma_f32_16x16x32_bf16 v[54:57], v[170:173], v[186:189], v[54:57]
	v_mfma_f32_16x16x32_bf16 v[50:53], v[178:181], v[186:189], v[50:53]
	v_mfma_f32_16x16x32_bf16 v[34:37], v[178:181], v[194:197], v[34:37]
	v_mfma_f32_16x16x32_bf16 v[38:41], v[170:173], v[194:197], v[38:41]
	v_mfma_f32_16x16x32_bf16 v[22:25], v[170:173], v[202:205], v[22:25]
	v_mfma_f32_16x16x32_bf16 v[18:21], v[178:181], v[202:205], v[18:21]
	v_mfma_f32_16x16x32_bf16 v[2:5], v[178:181], v[210:213], v[2:5]
	v_mfma_f32_16x16x32_bf16 v[6:9], v[170:173], v[210:213], v[6:9]
	s_setprio 0
	s_barrier
	v_add_u32_e32 v154, s93, v165
	v_add_u32_e32 v178, s33, v165
	ds_read_b128 v[142:145], v154
	ds_read_b128 v[146:149], v154 offset:1024
	ds_read_b128 v[150:153], v154 offset:2048
	ds_read_b128 v[154:157], v154 offset:3072
	ds_read_b128 v[158:161], v178
	ds_read_b128 v[170:173], v178 offset:1024
	ds_read_b128 v[174:177], v178 offset:2048
	ds_read_b128 v[178:181], v178 offset:3072
	s_mov_b32 m0, s70
	v_lshl_add_u64 v[220:221], s[48:49], 0, v[136:137]
	ds_read_b128 v[182:185], v168 offset:32768
	ds_read_b128 v[186:189], v168 offset:33792
	ds_read_b128 v[190:193], v168 offset:34816
	ds_read_b128 v[194:197], v168 offset:35840
	ds_read_b128 v[198:201], v168 offset:36864
	ds_read_b128 v[202:205], v168 offset:37888
	ds_read_b128 v[206:209], v168 offset:38912
	ds_read_b128 v[210:213], v168 offset:39936
	global_load_lds_dwordx4 v[220:221], off
	v_lshl_add_u64 v[220:221], s[48:49], 0, v[132:133]
	s_mov_b32 m0, s71
	s_nop 0
	global_load_lds_dwordx4 v[220:221], off
	s_waitcnt vmcnt(8)
	s_waitcnt lgkmcnt(0)
	s_barrier
	s_setprio 1
	s_waitcnt lgkmcnt(0)
	v_mfma_f32_16x16x32_bf16 v[126:129], v[142:145], v[182:185], v[126:129]
	v_mfma_f32_16x16x32_bf16 v[122:125], v[150:153], v[182:185], v[122:125]
	v_mfma_f32_16x16x32_bf16 v[106:109], v[150:153], v[190:193], v[106:109]
	v_mfma_f32_16x16x32_bf16 v[110:113], v[142:145], v[190:193], v[110:113]
	v_mfma_f32_16x16x32_bf16 v[94:97], v[142:145], v[198:201], v[94:97]
	v_mfma_f32_16x16x32_bf16 v[90:93], v[150:153], v[198:201], v[90:93]
	v_mfma_f32_16x16x32_bf16 v[74:77], v[150:153], v[206:209], v[74:77]
	v_mfma_f32_16x16x32_bf16 v[78:81], v[142:145], v[206:209], v[78:81]
	v_mfma_f32_16x16x32_bf16 v[126:129], v[146:149], v[186:189], v[126:129]
	v_mfma_f32_16x16x32_bf16 v[122:125], v[154:157], v[186:189], v[122:125]
	v_mfma_f32_16x16x32_bf16 v[106:109], v[154:157], v[194:197], v[106:109]
	v_mfma_f32_16x16x32_bf16 v[110:113], v[146:149], v[194:197], v[110:113]
	v_mfma_f32_16x16x32_bf16 v[94:97], v[146:149], v[202:205], v[94:97]
	v_mfma_f32_16x16x32_bf16 v[90:93], v[154:157], v[202:205], v[90:93]
	v_mfma_f32_16x16x32_bf16 v[74:77], v[154:157], v[210:213], v[74:77]
	v_mfma_f32_16x16x32_bf16 v[78:81], v[146:149], v[210:213], v[78:81]
	s_setprio 0
	s_setprio 1
	v_mfma_f32_16x16x32_bf16 v[118:121], v[158:161], v[182:185], v[118:121]
	v_mfma_f32_16x16x32_bf16 v[114:117], v[174:177], v[182:185], v[114:117]
	v_mfma_f32_16x16x32_bf16 v[98:101], v[174:177], v[190:193], v[98:101]
	v_mfma_f32_16x16x32_bf16 v[102:105], v[158:161], v[190:193], v[102:105]
	v_mfma_f32_16x16x32_bf16 v[86:89], v[158:161], v[198:201], v[86:89]
	v_mfma_f32_16x16x32_bf16 v[82:85], v[174:177], v[198:201], v[82:85]
	v_mfma_f32_16x16x32_bf16 v[66:69], v[174:177], v[206:209], v[66:69]
	v_mfma_f32_16x16x32_bf16 v[70:73], v[158:161], v[206:209], v[70:73]
	v_mfma_f32_16x16x32_bf16 v[118:121], v[170:173], v[186:189], v[118:121]
	v_mfma_f32_16x16x32_bf16 v[114:117], v[178:181], v[186:189], v[114:117]
	v_mfma_f32_16x16x32_bf16 v[98:101], v[178:181], v[194:197], v[98:101]
	v_mfma_f32_16x16x32_bf16 v[102:105], v[170:173], v[194:197], v[102:105]
	v_mfma_f32_16x16x32_bf16 v[86:89], v[170:173], v[202:205], v[86:89]
	v_mfma_f32_16x16x32_bf16 v[82:85], v[178:181], v[202:205], v[82:85]
	v_mfma_f32_16x16x32_bf16 v[66:69], v[178:181], v[210:213], v[66:69]
	v_mfma_f32_16x16x32_bf16 v[70:73], v[170:173], v[210:213], v[70:73]
	s_setprio 0
	s_barrier
; #define PG8_STAGE(bufoff, gbase, voff) do { _Pragma("unroll") for (int _i = 0; _i < 2; ++_i) \
;         __builtin_amdgcn_global_load_lds((const unsigned*)((const char*)(gbase) + (voff)[_i]), (LAS unsigned*)(lds + (bufoff) + ldsw + _i * 8192), 16, 0, 0); } while (0)
; #define PG8_LDA(dst, b, h) do { _Pragma("unroll") for (int m = 0; m < 4; ++m) _Pragma("unroll") for (int k = 0; k < 2; ++k) dst[m][k] = *(const LAS bf16x8*)(lds + PG8_SA(b, h) + aoff + m * 2048 + k * 1024); } while (0)
; #define PG8_MMA(ai, bj, At, Bt) do { __builtin_amdgcn_s_setprio(1); _Pragma("unroll") for (int m = 0; m < 4; ++m) _Pragma("unroll") for (int n = 0; n < 2; ++n) _Pragma("unroll") for (int k = 0; k < 2; ++k) \
;         acc[ai][bj][m][n] = __builtin_amdgcn_mfma_f32_16x16x32_bf16(Bt[n][k], At[m][k], acc[ai][bj][m][n], 0, 0, 0); __builtin_amdgcn_s_setprio(0); } while (0)
; #define PG8_WAIT_V(n) asm volatile("s_waitcnt vmcnt(" #n ")" ::: "memory")
; #define PG8_WAIT_L(n) asm volatile("s_waitcnt lgkmcnt(" #n ")" ::: "memory")
; #define PG8_BAR __builtin_amdgcn_s_barrier()
; #define PG8_SCHED __builtin_amdgcn_sched_barrier(0)
; template <class Epi>
; __device__ __forceinline__ void gemm_phase(LAS unsigned char* lds, const Gemm g, int G, int c, const Epi& E) {
;     ...
;             PG8_LDA(At, 1, 1); PG8_STAGE(PG8_SB(1, 0), b3, voffB); PG8_STAGE(PG8_SB(1, 1), b3 + hstepB, voffB); PG8_STAGE(PG8_SA(1, 0), a3, voffA);
;             PG8_WAIT_V(8); PG8_WAIT_L(0); PG8_BAR; PG8_MMA(1, 0, At, B0); PG8_MMA(1, 1, At, B1); PG8_BAR; PG8_SCHED;
;         }
	s_mov_b32 m0, s92
	v_lshl_add_u64 v[162:163], v[162:163], 0, s[18:19]
	ds_read_b128 v[182:185], v168 offset:49152
	ds_read_b128 v[186:189], v168 offset:50176
	ds_read_b128 v[190:193], v168 offset:51200
	ds_read_b128 v[194:197], v168 offset:52224
	ds_read_b128 v[198:201], v168 offset:53248
	ds_read_b128 v[202:205], v168 offset:54272
	ds_read_b128 v[206:209], v168 offset:55296
	ds_read_b128 v[210:213], v168 offset:56320
	global_load_lds_dwordx4 v[162:163], off
	v_lshl_add_u64 v[162:163], v[214:215], 0, s[18:19]
	s_mov_b32 m0, s90
	s_nop 0
	global_load_lds_dwordx4 v[162:163], off
	v_lshl_add_u64 v[162:163], s[46:47], 0, v[134:135]
	s_mov_b32 m0, s91
	s_nop 0
	global_load_lds_dwordx4 v[162:163], off
	v_lshl_add_u64 v[162:163], s[46:47], 0, v[130:131]
	s_mov_b32 m0, s89
	s_nop 0
	global_load_lds_dwordx4 v[162:163], off
	v_lshl_add_u64 v[162:163], v[216:217], 0, s[18:19]
	s_mov_b32 m0, s78
	s_nop 0
	global_load_lds_dwordx4 v[162:163], off
	v_lshl_add_u64 v[162:163], v[218:219], 0, s[18:19]
	s_mov_b32 m0, s79
	s_nop 0
	global_load_lds_dwordx4 v[162:163], off
	s_waitcnt vmcnt(8)
	s_waitcnt lgkmcnt(0)
	s_barrier
	s_setprio 1
	s_waitcnt lgkmcnt(0)
	v_mfma_f32_16x16x32_bf16 v[62:65], v[142:145], v[182:185], v[62:65]
	v_mfma_f32_16x16x32_bf16 v[58:61], v[150:153], v[182:185], v[58:61]
	v_mfma_f32_16x16x32_bf16 v[42:45], v[150:153], v[190:193], v[42:45]
	v_mfma_f32_16x16x32_bf16 v[46:49], v[142:145], v[190:193], v[46:49]
	v_mfma_f32_16x16x32_bf16 v[30:33], v[142:145], v[198:201], v[30:33]
	v_mfma_f32_16x16x32_bf16 v[26:29], v[150:153], v[198:201], v[26:29]
	v_mfma_f32_16x16x32_bf16 v[10:13], v[150:153], v[206:209], v[10:13]
	v_mfma_f32_16x16x32_bf16 v[14:17], v[142:145], v[206:209], v[14:17]
	v_mfma_f32_16x16x32_bf16 v[62:65], v[146:149], v[186:189], v[62:65]
	v_mfma_f32_16x16x32_bf16 v[58:61], v[154:157], v[186:189], v[58:61]
	v_mfma_f32_16x16x32_bf16 v[42:45], v[154:157], v[194:197], v[42:45]
	v_mfma_f32_16x16x32_bf16 v[46:49], v[146:149], v[194:197], v[46:49]
	v_mfma_f32_16x16x32_bf16 v[30:33], v[146:149], v[202:205], v[30:33]
	v_mfma_f32_16x16x32_bf16 v[26:29], v[154:157], v[202:205], v[26:29]
	v_mfma_f32_16x16x32_bf16 v[10:13], v[154:157], v[210:213], v[10:13]
	v_mfma_f32_16x16x32_bf16 v[14:17], v[146:149], v[210:213], v[14:17]
	s_setprio 0
	s_setprio 1
	v_mfma_f32_16x16x32_bf16 v[54:57], v[158:161], v[182:185], v[54:57]
	v_mfma_f32_16x16x32_bf16 v[50:53], v[174:177], v[182:185], v[50:53]
	v_mfma_f32_16x16x32_bf16 v[34:37], v[174:177], v[190:193], v[34:37]
	v_mfma_f32_16x16x32_bf16 v[38:41], v[158:161], v[190:193], v[38:41]
	v_mfma_f32_16x16x32_bf16 v[22:25], v[158:161], v[198:201], v[22:25]
	v_mfma_f32_16x16x32_bf16 v[18:21], v[174:177], v[198:201], v[18:21]
	v_mfma_f32_16x16x32_bf16 v[2:5], v[174:177], v[206:209], v[2:5]
	v_mfma_f32_16x16x32_bf16 v[6:9], v[158:161], v[206:209], v[6:9]
	v_mfma_f32_16x16x32_bf16 v[54:57], v[170:173], v[186:189], v[54:57]
	v_mfma_f32_16x16x32_bf16 v[50:53], v[178:181], v[186:189], v[50:53]
	v_mfma_f32_16x16x32_bf16 v[34:37], v[178:181], v[194:197], v[34:37]
	v_mfma_f32_16x16x32_bf16 v[38:41], v[170:173], v[194:197], v[38:41]
	v_mfma_f32_16x16x32_bf16 v[22:25], v[170:173], v[202:205], v[22:25]
	v_mfma_f32_16x16x32_bf16 v[18:21], v[178:181], v[202:205], v[18:21]
	v_mfma_f32_16x16x32_bf16 v[2:5], v[178:181], v[210:213], v[2:5]
	v_mfma_f32_16x16x32_bf16 v[6:9], v[170:173], v[210:213], v[6:9]
	s_setprio 0
	s_barrier
	s_movk_i32 s48, 0x100
	s_andn2_b64 vcc, exec, s[4:5]
	s_mov_b64 s[46:47], -1
	s_mov_b64 s[4:5], 0
	s_cbranch_vccz .LBB0_1653
	s_and_b64 vcc, exec, s[20:21]
	s_cbranch_vccz .LBB0_1656
	s_barrier

; #define PG8_STAGE(bufoff, gbase, voff) do { _Pragma("unroll") for (int _i = 0; _i < 2; ++_i) \
;         __builtin_amdgcn_global_load_lds((const unsigned*)((const char*)(gbase) + (voff)[_i]), (LAS unsigned*)(lds + (bufoff) + ldsw + _i * 8192), 16, 0, 0); } while (0)
; #define PG8_LDA(dst, b, h) do { _Pragma("unroll") for (int m = 0; m < 4; ++m) _Pragma("unroll") for (int k = 0; k < 2; ++k) dst[m][k] = *(const LAS bf16x8*)(lds + PG8_SA(b, h) + aoff + m * 2048 + k * 1024); } while (0)
; #define PG8_LDB(dst, b, h) do { _Pragma("unroll") for (int n = 0; n < 2; ++n) _Pragma("unroll") for (int k = 0; k < 2; ++k) dst[n][k] = *(const LAS bf16x8*)(lds + PG8_SB(b, h) + boff + n * 2048 + k * 1024); } while (0)
; #define PG8_MMA(ai, bj, At, Bt) do { __builtin_amdgcn_s_setprio(1); _Pragma("unroll") for (int m = 0; m < 4; ++m) _Pragma("unroll") for (int n = 0; n < 2; ++n) _Pragma("unroll") for (int k = 0; k < 2; ++k) \
;         acc[ai][bj][m][n] = __builtin_amdgcn_mfma_f32_16x16x32_bf16(Bt[n][k], At[m][k], acc[ai][bj][m][n], 0, 0, 0); __builtin_amdgcn_s_setprio(0); } while (0)
; #define PG8_WAIT_V(n) asm volatile("s_waitcnt vmcnt(" #n ")" ::: "memory")
; #define PG8_WAIT_L(n) asm volatile("s_waitcnt lgkmcnt(" #n ")" ::: "memory")
; #define PG8_BAR __builtin_amdgcn_s_barrier()
; #define PG8_SCHED __builtin_amdgcn_sched_barrier(0)
; template <class Epi>
; __device__ __forceinline__ void gemm_phase(LAS unsigned char* lds, const Gemm g, int G, int c, const Epi& E) {
;     ...
;             const bool last = (t == nt - 2);
;             const char* a1 = cA + (size_t)(t + 1) * kstep;
;             const char* a2 = last ? nA : cA + (size_t)(t + 2) * kstep; const char* b2 = last ? nB : cB + (size_t)(t + 2) * kstep;
;             const char* a3 = a2 + kstep; const char* b3 = b2 + kstep;
;             PG8_LDB(B0, 0, 0); PG8_LDB(B1, 0, 1); PG8_SCHED; PG8_LDA(At, 0, 0); PG8_STAGE(PG8_SA(1, 1), a1 + hstepA, voffA);
;             PG8_WAIT_V(8); PG8_WAIT_L(0); PG8_BAR; PG8_MMA(0, 0, At, B0); PG8_MMA(0, 1, At, B1); PG8_BAR; PG8_SCHED;
;             PG8_LDA(At, 0, 1); PG8_STAGE(PG8_SB(0, 0), b2, voffB); PG8_STAGE(PG8_SB(0, 1), b2 + hstepB, voffB); PG8_STAGE(PG8_SA(0, 0), a2, voffA);
.LBB0_1825:
	ds_read_b128 v[146:149], v152
	ds_read_b128 v[156:159], v152 offset:1024
	ds_read_b128 v[160:163], v152 offset:2048
	ds_read_b128 v[164:167], v152 offset:3072
	ds_read_b128 v[168:171], v153
	ds_read_b128 v[172:175], v153 offset:1024
	ds_read_b128 v[176:179], v153 offset:2048
	ds_read_b128 v[180:183], v153 offset:3072
	s_add_u32 s33, s40, 0xfff00080
	s_addc_u32 s42, s41, -1
	s_cmp_eq_u32 s68, 60
	s_cselect_b32 s45, s15, s42
	s_cselect_b32 s44, s63, s33
	s_cselect_b32 s43, s11, s67
	s_cselect_b32 s42, s13, s66
	v_lshl_add_u64 v[216:217], s[40:41], 0, v[138:139]
	s_add_i32 m0, s17, 0xc000
	ds_read_b128 v[184:187], v154
	ds_read_b128 v[188:191], v154 offset:1024
	ds_read_b128 v[192:195], v154 offset:2048
	ds_read_b128 v[196:199], v154 offset:3072
	ds_read_b128 v[200:203], v154 offset:4096
	ds_read_b128 v[204:207], v154 offset:5120
	ds_read_b128 v[208:211], v154 offset:6144
	ds_read_b128 v[212:215], v154 offset:7168
	global_load_lds_dwordx4 v[216:217], off
	v_lshl_add_u64 v[216:217], s[40:41], 0, v[140:141]
	s_add_i32 m0, s17, 0xe000
	s_nop 0
	global_load_lds_dwordx4 v[216:217], off
	s_waitcnt vmcnt(8)
	s_waitcnt lgkmcnt(0)
	s_barrier
	s_setprio 1
	s_waitcnt lgkmcnt(0)
	v_mfma_f32_16x16x32_bf16 v[126:129], v[146:149], v[184:187], v[126:129]
	v_mfma_f32_16x16x32_bf16 v[122:125], v[160:163], v[184:187], v[122:125]
	v_mfma_f32_16x16x32_bf16 v[110:113], v[160:163], v[192:195], v[110:113]
	v_mfma_f32_16x16x32_bf16 v[118:121], v[146:149], v[192:195], v[118:121]
	v_mfma_f32_16x16x32_bf16 v[102:105], v[146:149], v[200:203], v[102:105]
	v_mfma_f32_16x16x32_bf16 v[94:97], v[160:163], v[200:203], v[94:97]
	v_mfma_f32_16x16x32_bf16 v[78:81], v[160:163], v[208:211], v[78:81]
	v_mfma_f32_16x16x32_bf16 v[86:89], v[146:149], v[208:211], v[86:89]
	v_mfma_f32_16x16x32_bf16 v[126:129], v[156:159], v[188:191], v[126:129]
	v_mfma_f32_16x16x32_bf16 v[122:125], v[164:167], v[188:191], v[122:125]
	v_mfma_f32_16x16x32_bf16 v[110:113], v[164:167], v[196:199], v[110:113]
	v_mfma_f32_16x16x32_bf16 v[118:121], v[156:159], v[196:199], v[118:121]
	v_mfma_f32_16x16x32_bf16 v[102:105], v[156:159], v[204:207], v[102:105]
	v_mfma_f32_16x16x32_bf16 v[94:97], v[164:167], v[204:207], v[94:97]
	v_mfma_f32_16x16x32_bf16 v[78:81], v[164:167], v[212:215], v[78:81]
	v_mfma_f32_16x16x32_bf16 v[86:89], v[156:159], v[212:215], v[86:89]
	s_setprio 0
	s_setprio 1
	v_mfma_f32_16x16x32_bf16 v[114:117], v[168:171], v[184:187], v[114:117]
	v_mfma_f32_16x16x32_bf16 v[106:109], v[176:179], v[184:187], v[106:109]
	v_mfma_f32_16x16x32_bf16 v[90:93], v[176:179], v[192:195], v[90:93]
	v_mfma_f32_16x16x32_bf16 v[98:101], v[168:171], v[192:195], v[98:101]
	v_mfma_f32_16x16x32_bf16 v[82:85], v[168:171], v[200:203], v[82:85]
	v_mfma_f32_16x16x32_bf16 v[74:77], v[176:179], v[200:203], v[74:77]
	v_mfma_f32_16x16x32_bf16 v[66:69], v[176:179], v[208:211], v[66:69]
	v_mfma_f32_16x16x32_bf16 v[70:73], v[168:171], v[208:211], v[70:73]
	v_mfma_f32_16x16x32_bf16 v[114:117], v[172:175], v[188:191], v[114:117]
	v_mfma_f32_16x16x32_bf16 v[106:109], v[180:183], v[188:191], v[106:109]
	v_mfma_f32_16x16x32_bf16 v[90:93], v[180:183], v[196:199], v[90:93]
	v_mfma_f32_16x16x32_bf16 v[98:101], v[172:175], v[196:199], v[98:101]
	v_mfma_f32_16x16x32_bf16 v[82:85], v[172:175], v[204:207], v[82:85]
	v_mfma_f32_16x16x32_bf16 v[74:77], v[180:183], v[204:207], v[74:77]
	v_mfma_f32_16x16x32_bf16 v[66:69], v[180:183], v[212:215], v[66:69]
	v_mfma_f32_16x16x32_bf16 v[70:73], v[172:175], v[212:215], v[70:73]
	s_setprio 0
	s_barrier
	s_add_i32 s33, s61, s52
	v_lshl_add_u64 v[216:217], s[42:43], 0, v[134:135]
	s_mov_b32 m0, s33
	ds_read_b128 v[184:187], v154 offset:16384
	ds_read_b128 v[188:191], v154 offset:17408
	ds_read_b128 v[192:195], v154 offset:18432
	ds_read_b128 v[196:199], v154 offset:19456
	ds_read_b128 v[200:203], v154 offset:20480
	ds_read_b128 v[204:207], v154 offset:21504
	ds_read_b128 v[208:211], v154 offset:22528
	ds_read_b128 v[212:215], v154 offset:23552
	global_load_lds_dwordx4 v[216:217], off
	s_add_i32 m0, s33, 0x2000
	s_add_u32 s64, s42, 0x100000
	v_lshl_add_u64 v[218:219], s[42:43], 0, v[130:131]
	s_addc_u32 s65, s43, 0
	s_add_i32 s33, s62, s52
	global_load_lds_dwordx4 v[218:219], off
	v_lshl_add_u64 v[220:221], s[64:65], 0, v[134:135]
	s_mov_b32 m0, s33
	v_lshl_add_u64 v[222:223], s[44:45], 0, v[132:133]
	global_load_lds_dwordx4 v[220:221], off
	v_lshl_add_u64 v[220:221], s[64:65], 0, v[130:131]
	s_add_i32 m0, s33, 0x2000
	s_nop 0
	global_load_lds_dwordx4 v[220:221], off
	v_lshl_add_u64 v[220:221], s[44:45], 0, v[136:137]
	s_mov_b32 m0, s17
	s_nop 0
	global_load_lds_dwordx4 v[220:221], off
	s_mov_b32 m0, s37
	s_nop 0
	global_load_lds_dwordx4 v[222:223], off
	s_waitcnt vmcnt(8)
	s_waitcnt lgkmcnt(0)
	s_barrier
; #define PG8_STAGE(bufoff, gbase, voff) do { _Pragma("unroll") for (int _i = 0; _i < 2; ++_i) \
;         __builtin_amdgcn_global_load_lds((const unsigned*)((const char*)(gbase) + (voff)[_i]), (LAS unsigned*)(lds + (bufoff) + ldsw + _i * 8192), 16, 0, 0); } while (0)
; #define PG8_LDA(dst, b, h) do { _Pragma("unroll") for (int m = 0; m < 4; ++m) _Pragma("unroll") for (int k = 0; k < 2; ++k) dst[m][k] = *(const LAS bf16x8*)(lds + PG8_SA(b, h) + aoff + m * 2048 + k * 1024); } while (0)
; #define PG8_LDB(dst, b, h) do { _Pragma("unroll") for (int n = 0; n < 2; ++n) _Pragma("unroll") for (int k = 0; k < 2; ++k) dst[n][k] = *(const LAS bf16x8*)(lds + PG8_SB(b, h) + boff + n * 2048 + k * 1024); } while (0)
; #define PG8_MMA(ai, bj, At, Bt) do { __builtin_amdgcn_s_setprio(1); _Pragma("unroll") for (int m = 0; m < 4; ++m) _Pragma("unroll") for (int n = 0; n < 2; ++n) _Pragma("unroll") for (int k = 0; k < 2; ++k) \
;         acc[ai][bj][m][n] = __builtin_amdgcn_mfma_f32_16x16x32_bf16(Bt[n][k], At[m][k], acc[ai][bj][m][n], 0, 0, 0); __builtin_amdgcn_s_setprio(0); } while (0)
; #define PG8_WAIT_V(n) asm volatile("s_waitcnt vmcnt(" #n ")" ::: "memory")
; #define PG8_WAIT_L(n) asm volatile("s_waitcnt lgkmcnt(" #n ")" ::: "memory")
; #define PG8_BAR __builtin_amdgcn_s_barrier()
; #define PG8_SCHED __builtin_amdgcn_sched_barrier(0)
; template <class Epi>
; __device__ __forceinline__ void gemm_phase(LAS unsigned char* lds, const Gemm g, int G, int c, const Epi& E) {
;     ...
;             PG8_WAIT_V(8); PG8_WAIT_L(0); PG8_BAR; PG8_MMA(1, 0, At, B0); PG8_MMA(1, 1, At, B1); PG8_BAR; PG8_SCHED;
;             PG8_LDB(B0, 1, 0); PG8_LDB(B1, 1, 1); PG8_SCHED; PG8_LDA(At, 1, 0); PG8_STAGE(PG8_SA(0, 1), a2 + hstepA, voffA);
;             PG8_WAIT_V(8); PG8_WAIT_L(0); PG8_BAR; PG8_MMA(0, 0, At, B0); PG8_MMA(0, 1, At, B1); PG8_BAR; PG8_SCHED;
;             PG8_LDA(At, 1, 1); PG8_STAGE(PG8_SB(1, 0), b3, voffB); PG8_STAGE(PG8_SB(1, 1), b3 + hstepB, voffB); PG8_STAGE(PG8_SA(1, 0), a3, voffA);
	s_setprio 1
	s_waitcnt lgkmcnt(0)
	v_mfma_f32_16x16x32_bf16 v[62:65], v[146:149], v[184:187], v[62:65]
	v_mfma_f32_16x16x32_bf16 v[58:61], v[160:163], v[184:187], v[58:61]
	v_mfma_f32_16x16x32_bf16 v[46:49], v[160:163], v[192:195], v[46:49]
	v_mfma_f32_16x16x32_bf16 v[54:57], v[146:149], v[192:195], v[54:57]
	v_mfma_f32_16x16x32_bf16 v[38:41], v[146:149], v[200:203], v[38:41]
	v_mfma_f32_16x16x32_bf16 v[30:33], v[160:163], v[200:203], v[30:33]
	v_mfma_f32_16x16x32_bf16 v[14:17], v[160:163], v[208:211], v[14:17]
	v_mfma_f32_16x16x32_bf16 v[22:25], v[146:149], v[208:211], v[22:25]
	v_mfma_f32_16x16x32_bf16 v[62:65], v[156:159], v[188:191], v[62:65]
	v_mfma_f32_16x16x32_bf16 v[58:61], v[164:167], v[188:191], v[58:61]
	v_mfma_f32_16x16x32_bf16 v[46:49], v[164:167], v[196:199], v[46:49]
	v_mfma_f32_16x16x32_bf16 v[54:57], v[156:159], v[196:199], v[54:57]
	v_mfma_f32_16x16x32_bf16 v[38:41], v[156:159], v[204:207], v[38:41]
	v_mfma_f32_16x16x32_bf16 v[30:33], v[164:167], v[204:207], v[30:33]
	v_mfma_f32_16x16x32_bf16 v[14:17], v[164:167], v[212:215], v[14:17]
	v_mfma_f32_16x16x32_bf16 v[22:25], v[156:159], v[212:215], v[22:25]
	s_setprio 0
	s_setprio 1
	v_mfma_f32_16x16x32_bf16 v[50:53], v[168:171], v[184:187], v[50:53]
	v_mfma_f32_16x16x32_bf16 v[42:45], v[176:179], v[184:187], v[42:45]
	v_mfma_f32_16x16x32_bf16 v[26:29], v[176:179], v[192:195], v[26:29]
	v_mfma_f32_16x16x32_bf16 v[34:37], v[168:171], v[192:195], v[34:37]
	v_mfma_f32_16x16x32_bf16 v[18:21], v[168:171], v[200:203], v[18:21]
	v_mfma_f32_16x16x32_bf16 v[10:13], v[176:179], v[200:203], v[10:13]
	v_mfma_f32_16x16x32_bf16 v[2:5], v[176:179], v[208:211], v[2:5]
	v_mfma_f32_16x16x32_bf16 v[6:9], v[168:171], v[208:211], v[6:9]
	v_mfma_f32_16x16x32_bf16 v[50:53], v[172:175], v[188:191], v[50:53]
	v_mfma_f32_16x16x32_bf16 v[42:45], v[180:183], v[188:191], v[42:45]
	v_mfma_f32_16x16x32_bf16 v[26:29], v[180:183], v[196:199], v[26:29]
	v_mfma_f32_16x16x32_bf16 v[34:37], v[172:175], v[196:199], v[34:37]
	v_mfma_f32_16x16x32_bf16 v[18:21], v[172:175], v[204:207], v[18:21]
	v_mfma_f32_16x16x32_bf16 v[10:13], v[180:183], v[204:207], v[10:13]
	v_mfma_f32_16x16x32_bf16 v[2:5], v[180:183], v[212:215], v[2:5]
	v_mfma_f32_16x16x32_bf16 v[6:9], v[172:175], v[212:215], v[6:9]
	s_setprio 0
	s_barrier
	s_add_i32 s33, 0, 0x18000
	v_add_u32_e32 v155, s33, v151
	s_add_i32 s64, 0, 0x1c000
	ds_read_b128 v[146:149], v155
	ds_read_b128 v[156:159], v155 offset:1024
	ds_read_b128 v[160:163], v155 offset:2048
	ds_read_b128 v[164:167], v155 offset:3072
	v_add_u32_e32 v155, s64, v151
	ds_read_b128 v[168:171], v155
	ds_read_b128 v[172:175], v155 offset:1024
	ds_read_b128 v[176:179], v155 offset:2048
	ds_read_b128 v[180:183], v155 offset:3072
	s_add_u32 s44, s44, 0x100000
	s_addc_u32 s45, s45, 0
	s_mov_b32 m0, s39
	v_lshl_add_u64 v[226:227], s[44:45], 0, v[136:137]
	ds_read_b128 v[184:187], v154 offset:32768
	ds_read_b128 v[188:191], v154 offset:33792
	ds_read_b128 v[192:195], v154 offset:34816
	ds_read_b128 v[196:199], v154 offset:35840
	ds_read_b128 v[200:203], v154 offset:36864
	ds_read_b128 v[204:207], v154 offset:37888
	ds_read_b128 v[208:211], v154 offset:38912
	ds_read_b128 v[212:215], v154 offset:39936
	global_load_lds_dwordx4 v[226:227], off
	v_lshl_add_u64 v[226:227], s[44:45], 0, v[132:133]
	s_mov_b32 m0, s53
	s_nop 0
	global_load_lds_dwordx4 v[226:227], off
	s_waitcnt vmcnt(8)
	s_waitcnt lgkmcnt(0)
	s_barrier
	s_setprio 1
	s_waitcnt lgkmcnt(0)
	v_mfma_f32_16x16x32_bf16 v[126:129], v[146:149], v[184:187], v[126:129]
	v_mfma_f32_16x16x32_bf16 v[122:125], v[160:163], v[184:187], v[122:125]
	v_mfma_f32_16x16x32_bf16 v[110:113], v[160:163], v[192:195], v[110:113]
	v_mfma_f32_16x16x32_bf16 v[118:121], v[146:149], v[192:195], v[118:121]
	v_mfma_f32_16x16x32_bf16 v[102:105], v[146:149], v[200:203], v[102:105]
	v_mfma_f32_16x16x32_bf16 v[94:97], v[160:163], v[200:203], v[94:97]
	v_mfma_f32_16x16x32_bf16 v[78:81], v[160:163], v[208:211], v[78:81]
	v_mfma_f32_16x16x32_bf16 v[86:89], v[146:149], v[208:211], v[86:89]
	v_mfma_f32_16x16x32_bf16 v[126:129], v[156:159], v[188:191], v[126:129]
	v_mfma_f32_16x16x32_bf16 v[122:125], v[164:167], v[188:191], v[122:125]
	v_mfma_f32_16x16x32_bf16 v[110:113], v[164:167], v[196:199], v[110:113]
	v_mfma_f32_16x16x32_bf16 v[118:121], v[156:159], v[196:199], v[118:121]
	v_mfma_f32_16x16x32_bf16 v[102:105], v[156:159], v[204:207], v[102:105]
	v_mfma_f32_16x16x32_bf16 v[94:97], v[164:167], v[204:207], v[94:97]
	v_mfma_f32_16x16x32_bf16 v[78:81], v[164:167], v[212:215], v[78:81]
	v_mfma_f32_16x16x32_bf16 v[86:89], v[156:159], v[212:215], v[86:89]
	s_setprio 0
	s_setprio 1
	v_mfma_f32_16x16x32_bf16 v[114:117], v[168:171], v[184:187], v[114:117]
	v_mfma_f32_16x16x32_bf16 v[106:109], v[176:179], v[184:187], v[106:109]
	v_mfma_f32_16x16x32_bf16 v[90:93], v[176:179], v[192:195], v[90:93]
	v_mfma_f32_16x16x32_bf16 v[98:101], v[168:171], v[192:195], v[98:101]
	v_mfma_f32_16x16x32_bf16 v[82:85], v[168:171], v[200:203], v[82:85]
	v_mfma_f32_16x16x32_bf16 v[74:77], v[176:179], v[200:203], v[74:77]
	v_mfma_f32_16x16x32_bf16 v[66:69], v[176:179], v[208:211], v[66:69]
	v_mfma_f32_16x16x32_bf16 v[70:73], v[168:171], v[208:211], v[70:73]
	v_mfma_f32_16x16x32_bf16 v[114:117], v[172:175], v[188:191], v[114:117]
	v_mfma_f32_16x16x32_bf16 v[106:109], v[180:183], v[188:191], v[106:109]
	v_mfma_f32_16x16x32_bf16 v[90:93], v[180:183], v[196:199], v[90:93]
	v_mfma_f32_16x16x32_bf16 v[98:101], v[172:175], v[196:199], v[98:101]
	v_mfma_f32_16x16x32_bf16 v[82:85], v[172:175], v[204:207], v[82:85]
	v_mfma_f32_16x16x32_bf16 v[74:77], v[180:183], v[204:207], v[74:77]
	v_mfma_f32_16x16x32_bf16 v[66:69], v[180:183], v[212:215], v[66:69]
	v_mfma_f32_16x16x32_bf16 v[70:73], v[172:175], v[212:215], v[70:73]
	s_setprio 0
	s_barrier
; #define PG8_STAGE(bufoff, gbase, voff) do { _Pragma("unroll") for (int _i = 0; _i < 2; ++_i) \
;         __builtin_amdgcn_global_load_lds((const unsigned*)((const char*)(gbase) + (voff)[_i]), (LAS unsigned*)(lds + (bufoff) + ldsw + _i * 8192), 16, 0, 0); } while (0)
; #define PG8_LDA(dst, b, h) do { _Pragma("unroll") for (int m = 0; m < 4; ++m) _Pragma("unroll") for (int k = 0; k < 2; ++k) dst[m][k] = *(const LAS bf16x8*)(lds + PG8_SA(b, h) + aoff + m * 2048 + k * 1024); } while (0)
; #define PG8_MMA(ai, bj, At, Bt) do { __builtin_amdgcn_s_setprio(1); _Pragma("unroll") for (int m = 0; m < 4; ++m) _Pragma("unroll") for (int n = 0; n < 2; ++n) _Pragma("unroll") for (int k = 0; k < 2; ++k) \
;         acc[ai][bj][m][n] = __builtin_amdgcn_mfma_f32_16x16x32_bf16(Bt[n][k], At[m][k], acc[ai][bj][m][n], 0, 0, 0); __builtin_amdgcn_s_setprio(0); } while (0)
; #define PG8_WAIT_V(n) asm volatile("s_waitcnt vmcnt(" #n ")" ::: "memory")
; #define PG8_WAIT_L(n) asm volatile("s_waitcnt lgkmcnt(" #n ")" ::: "memory")
; #define PG8_BAR __builtin_amdgcn_s_barrier()
; #define PG8_SCHED __builtin_amdgcn_sched_barrier(0)
; template <class Epi>
; __device__ __forceinline__ void gemm_phase(LAS unsigned char* lds, const Gemm g, int G, int c, const Epi& E) {
;     ...
;             PG8_LDA(At, 1, 1); PG8_STAGE(PG8_SB(1, 0), b3, voffB); PG8_STAGE(PG8_SB(1, 1), b3 + hstepB, voffB); PG8_STAGE(PG8_SA(1, 0), a3, voffA);
;             PG8_WAIT_V(8); PG8_WAIT_L(0); PG8_BAR; PG8_MMA(1, 0, At, B0); PG8_MMA(1, 1, At, B1); PG8_BAR; PG8_SCHED;
;         }
	s_add_i32 s33, s33, s52
	v_lshl_add_u64 v[216:217], v[216:217], 0, s[6:7]
	s_mov_b32 m0, s33
	ds_read_b128 v[184:187], v154 offset:49152
	ds_read_b128 v[188:191], v154 offset:50176
	ds_read_b128 v[192:195], v154 offset:51200
	ds_read_b128 v[196:199], v154 offset:52224
	ds_read_b128 v[200:203], v154 offset:53248
	ds_read_b128 v[204:207], v154 offset:54272
	ds_read_b128 v[208:211], v154 offset:55296
	ds_read_b128 v[212:215], v154 offset:56320
	global_load_lds_dwordx4 v[216:217], off
	s_add_i32 m0, s33, 0x2000
	s_add_u32 s42, s42, 0x100080
	v_lshl_add_u64 v[216:217], v[218:219], 0, s[6:7]
	s_addc_u32 s43, s43, 0
	s_add_i32 s33, s64, s52
	global_load_lds_dwordx4 v[216:217], off
	v_lshl_add_u64 v[216:217], s[42:43], 0, v[134:135]
	s_mov_b32 m0, s33
	s_nop 0
	global_load_lds_dwordx4 v[216:217], off
	v_lshl_add_u64 v[216:217], s[42:43], 0, v[130:131]
	s_add_i32 m0, s33, 0x2000
	s_nop 0
	global_load_lds_dwordx4 v[216:217], off
	v_lshl_add_u64 v[216:217], v[220:221], 0, s[6:7]
	s_mov_b32 m0, s59
	s_nop 0
	global_load_lds_dwordx4 v[216:217], off
	v_lshl_add_u64 v[216:217], v[222:223], 0, s[6:7]
	s_mov_b32 m0, s60
	s_nop 0
	global_load_lds_dwordx4 v[216:217], off
	s_waitcnt vmcnt(8)
	s_waitcnt lgkmcnt(0)
	s_barrier
	s_setprio 1
	s_waitcnt lgkmcnt(0)
	v_mfma_f32_16x16x32_bf16 v[62:65], v[146:149], v[184:187], v[62:65]
	v_mfma_f32_16x16x32_bf16 v[58:61], v[160:163], v[184:187], v[58:61]
	v_mfma_f32_16x16x32_bf16 v[46:49], v[160:163], v[192:195], v[46:49]
	v_mfma_f32_16x16x32_bf16 v[54:57], v[146:149], v[192:195], v[54:57]
	v_mfma_f32_16x16x32_bf16 v[38:41], v[146:149], v[200:203], v[38:41]
	v_mfma_f32_16x16x32_bf16 v[30:33], v[160:163], v[200:203], v[30:33]
	v_mfma_f32_16x16x32_bf16 v[14:17], v[160:163], v[208:211], v[14:17]
	v_mfma_f32_16x16x32_bf16 v[22:25], v[146:149], v[208:211], v[22:25]
	v_mfma_f32_16x16x32_bf16 v[62:65], v[156:159], v[188:191], v[62:65]
	v_mfma_f32_16x16x32_bf16 v[58:61], v[164:167], v[188:191], v[58:61]
	v_mfma_f32_16x16x32_bf16 v[46:49], v[164:167], v[196:199], v[46:49]
	v_mfma_f32_16x16x32_bf16 v[54:57], v[156:159], v[196:199], v[54:57]
	v_mfma_f32_16x16x32_bf16 v[38:41], v[156:159], v[204:207], v[38:41]
	v_mfma_f32_16x16x32_bf16 v[30:33], v[164:167], v[204:207], v[30:33]
	v_mfma_f32_16x16x32_bf16 v[14:17], v[164:167], v[212:215], v[14:17]
	v_mfma_f32_16x16x32_bf16 v[22:25], v[156:159], v[212:215], v[22:25]
	s_setprio 0
	s_setprio 1
	v_mfma_f32_16x16x32_bf16 v[50:53], v[168:171], v[184:187], v[50:53]
	v_mfma_f32_16x16x32_bf16 v[42:45], v[176:179], v[184:187], v[42:45]
	v_mfma_f32_16x16x32_bf16 v[26:29], v[176:179], v[192:195], v[26:29]
	v_mfma_f32_16x16x32_bf16 v[34:37], v[168:171], v[192:195], v[34:37]
	v_mfma_f32_16x16x32_bf16 v[18:21], v[168:171], v[200:203], v[18:21]
	v_mfma_f32_16x16x32_bf16 v[10:13], v[176:179], v[200:203], v[10:13]
	v_mfma_f32_16x16x32_bf16 v[2:5], v[176:179], v[208:211], v[2:5]
	v_mfma_f32_16x16x32_bf16 v[6:9], v[168:171], v[208:211], v[6:9]
	v_mfma_f32_16x16x32_bf16 v[50:53], v[172:175], v[188:191], v[50:53]
	v_mfma_f32_16x16x32_bf16 v[42:45], v[180:183], v[188:191], v[42:45]
	v_mfma_f32_16x16x32_bf16 v[26:29], v[180:183], v[196:199], v[26:29]
	v_mfma_f32_16x16x32_bf16 v[34:37], v[172:175], v[196:199], v[34:37]
	v_mfma_f32_16x16x32_bf16 v[18:21], v[172:175], v[204:207], v[18:21]
	v_mfma_f32_16x16x32_bf16 v[10:13], v[180:183], v[204:207], v[10:13]
	v_mfma_f32_16x16x32_bf16 v[2:5], v[180:183], v[212:215], v[2:5]
	v_mfma_f32_16x16x32_bf16 v[6:9], v[172:175], v[212:215], v[6:9]
	s_setprio 0
	s_barrier
	s_add_i32 s68, s68, 2
	s_add_u32 s40, s40, 0x100
	s_addc_u32 s41, s41, 0
	s_add_u32 s66, s66, 0x100
	s_addc_u32 s67, s67, 0
	s_cmp_gt_u32 s68, 61
	s_cbranch_scc0 .LBB0_1825
	s_and_b64 vcc, exec, s[8:9]
	s_cbranch_vccz .LBB0_1828
	s_barrier

; #define PG8_STAGE(bufoff, gbase, voff) do { _Pragma("unroll") for (int _i = 0; _i < 2; ++_i) \
;         __builtin_amdgcn_global_load_lds((const unsigned*)((const char*)(gbase) + (voff)[_i]), (LAS unsigned*)(lds + (bufoff) + ldsw + _i * 8192), 16, 0, 0); } while (0)
; #define PG8_LDA(dst, b, h) do { _Pragma("unroll") for (int m = 0; m < 4; ++m) _Pragma("unroll") for (int k = 0; k < 2; ++k) dst[m][k] = *(const LAS bf16x8*)(lds + PG8_SA(b, h) + aoff + m * 2048 + k * 1024); } while (0)
; #define PG8_LDB(dst, b, h) do { _Pragma("unroll") for (int n = 0; n < 2; ++n) _Pragma("unroll") for (int k = 0; k < 2; ++k) dst[n][k] = *(const LAS bf16x8*)(lds + PG8_SB(b, h) + boff + n * 2048 + k * 1024); } while (0)
; #define PG8_MMA(ai, bj, At, Bt) do { __builtin_amdgcn_s_setprio(1); _Pragma("unroll") for (int m = 0; m < 4; ++m) _Pragma("unroll") for (int n = 0; n < 2; ++n) _Pragma("unroll") for (int k = 0; k < 2; ++k) \
;         acc[ai][bj][m][n] = __builtin_amdgcn_mfma_f32_16x16x32_bf16(Bt[n][k], At[m][k], acc[ai][bj][m][n], 0, 0, 0); __builtin_amdgcn_s_setprio(0); } while (0)
; #define PG8_WAIT_V(n) asm volatile("s_waitcnt vmcnt(" #n ")" ::: "memory")
; #define PG8_WAIT_L(n) asm volatile("s_waitcnt lgkmcnt(" #n ")" ::: "memory")
; #define PG8_BAR __builtin_amdgcn_s_barrier()
; #define PG8_SCHED __builtin_amdgcn_sched_barrier(0)
; template <class Epi>
; __device__ __forceinline__ void gemm_phase(LAS unsigned char* lds, const Gemm g, int G, int c, const Epi& E) {
;     ...
;             const bool last = (t == nt - 2);
;             const char* a1 = cA + (size_t)(t + 1) * kstep;
;             const char* a2 = last ? nA : cA + (size_t)(t + 2) * kstep; const char* b2 = last ? nB : cB + (size_t)(t + 2) * kstep;
;             const char* a3 = a2 + kstep; const char* b3 = b2 + kstep;
;             PG8_LDB(B0, 0, 0); PG8_LDB(B1, 0, 1); PG8_SCHED; PG8_LDA(At, 0, 0); PG8_STAGE(PG8_SA(1, 1), a1 + hstepA, voffA);
;             PG8_WAIT_V(8); PG8_WAIT_L(0); PG8_BAR; PG8_MMA(0, 0, At, B0); PG8_MMA(0, 1, At, B1); PG8_BAR; PG8_SCHED;
;             PG8_LDA(At, 0, 1); PG8_STAGE(PG8_SB(0, 0), b2, voffB); PG8_STAGE(PG8_SB(0, 1), b2 + hstepB, voffB); PG8_STAGE(PG8_SA(0, 0), a2, voffA);
.LBB0_1931:
	ds_read_b128 v[122:125], v168
	ds_read_b128 v[126:129], v168 offset:1024
	ds_read_b128 v[130:133], v168 offset:2048
	ds_read_b128 v[134:137], v168 offset:3072
	ds_read_b128 v[162:165], v169
	ds_read_b128 v[172:175], v169 offset:1024
	ds_read_b128 v[176:179], v169 offset:2048
	ds_read_b128 v[180:183], v169 offset:3072
	s_add_u32 s33, s4, 0xfffc0080
	s_addc_u32 s36, s5, -1
	s_cmp_eq_u32 s62, 12
	s_cselect_b32 s39, s19, s36
	s_cselect_b32 s38, s18, s33
	s_cselect_b32 s37, s15, s61
	s_cselect_b32 s36, s17, s60
	v_lshl_add_u64 v[216:217], s[4:5], 0, v[154:155]
	s_add_i32 m0, s23, 0xc000
	ds_read_b128 v[184:187], v170
	ds_read_b128 v[188:191], v170 offset:1024
	ds_read_b128 v[192:195], v170 offset:2048
	ds_read_b128 v[196:199], v170 offset:3072
	ds_read_b128 v[200:203], v170 offset:4096
	ds_read_b128 v[204:207], v170 offset:5120
	ds_read_b128 v[208:211], v170 offset:6144
	ds_read_b128 v[212:215], v170 offset:7168
	global_load_lds_dwordx4 v[216:217], off
	v_lshl_add_u64 v[216:217], s[4:5], 0, v[156:157]
	s_add_i32 m0, s23, 0xe000
	s_nop 0
	global_load_lds_dwordx4 v[216:217], off
	s_waitcnt vmcnt(8)
	s_waitcnt lgkmcnt(0)
	s_barrier
	s_setprio 1
	s_waitcnt lgkmcnt(0)
	v_mfma_f32_16x16x32_bf16 v[142:145], v[122:125], v[184:187], v[142:145]
	v_mfma_f32_16x16x32_bf16 v[138:141], v[130:133], v[184:187], v[138:141]
	v_mfma_f32_16x16x32_bf16 v[106:109], v[130:133], v[192:195], v[106:109]
	v_mfma_f32_16x16x32_bf16 v[118:121], v[122:125], v[192:195], v[118:121]
	v_mfma_f32_16x16x32_bf16 v[102:105], v[122:125], v[200:203], v[102:105]
	v_mfma_f32_16x16x32_bf16 v[90:93], v[130:133], v[200:203], v[90:93]
	v_mfma_f32_16x16x32_bf16 v[74:77], v[130:133], v[208:211], v[74:77]
	v_mfma_f32_16x16x32_bf16 v[86:89], v[122:125], v[208:211], v[86:89]
	v_mfma_f32_16x16x32_bf16 v[142:145], v[126:129], v[188:191], v[142:145]
	v_mfma_f32_16x16x32_bf16 v[138:141], v[134:137], v[188:191], v[138:141]
	v_mfma_f32_16x16x32_bf16 v[106:109], v[134:137], v[196:199], v[106:109]
	v_mfma_f32_16x16x32_bf16 v[118:121], v[126:129], v[196:199], v[118:121]
	v_mfma_f32_16x16x32_bf16 v[102:105], v[126:129], v[204:207], v[102:105]
	v_mfma_f32_16x16x32_bf16 v[90:93], v[134:137], v[204:207], v[90:93]
	v_mfma_f32_16x16x32_bf16 v[74:77], v[134:137], v[212:215], v[74:77]
	v_mfma_f32_16x16x32_bf16 v[86:89], v[126:129], v[212:215], v[86:89]
	s_setprio 0
	s_setprio 1
	v_mfma_f32_16x16x32_bf16 v[114:117], v[162:165], v[184:187], v[114:117]
	v_mfma_f32_16x16x32_bf16 v[110:113], v[176:179], v[184:187], v[110:113]
	v_mfma_f32_16x16x32_bf16 v[94:97], v[176:179], v[192:195], v[94:97]
	v_mfma_f32_16x16x32_bf16 v[98:101], v[162:165], v[192:195], v[98:101]
	v_mfma_f32_16x16x32_bf16 v[82:85], v[162:165], v[200:203], v[82:85]
	v_mfma_f32_16x16x32_bf16 v[78:81], v[176:179], v[200:203], v[78:81]
	v_mfma_f32_16x16x32_bf16 v[66:69], v[176:179], v[208:211], v[66:69]
	v_mfma_f32_16x16x32_bf16 v[70:73], v[162:165], v[208:211], v[70:73]
	v_mfma_f32_16x16x32_bf16 v[114:117], v[172:175], v[188:191], v[114:117]
	v_mfma_f32_16x16x32_bf16 v[110:113], v[180:183], v[188:191], v[110:113]
	v_mfma_f32_16x16x32_bf16 v[94:97], v[180:183], v[196:199], v[94:97]
	v_mfma_f32_16x16x32_bf16 v[98:101], v[172:175], v[196:199], v[98:101]
	v_mfma_f32_16x16x32_bf16 v[82:85], v[172:175], v[204:207], v[82:85]
	v_mfma_f32_16x16x32_bf16 v[78:81], v[180:183], v[204:207], v[78:81]
	v_mfma_f32_16x16x32_bf16 v[66:69], v[180:183], v[212:215], v[66:69]
	v_mfma_f32_16x16x32_bf16 v[70:73], v[172:175], v[212:215], v[70:73]
	s_setprio 0
	s_barrier
	s_add_i32 s33, s56, s42
	v_lshl_add_u64 v[216:217], s[36:37], 0, v[150:151]
	s_mov_b32 m0, s33
	ds_read_b128 v[184:187], v170 offset:16384
	ds_read_b128 v[188:191], v170 offset:17408
	ds_read_b128 v[192:195], v170 offset:18432
	ds_read_b128 v[196:199], v170 offset:19456
	ds_read_b128 v[200:203], v170 offset:20480
	ds_read_b128 v[204:207], v170 offset:21504
	ds_read_b128 v[208:211], v170 offset:22528
	ds_read_b128 v[212:215], v170 offset:23552
	global_load_lds_dwordx4 v[216:217], off
	s_add_i32 m0, s33, 0x2000
	s_add_u32 s64, s36, 0x40000
	v_lshl_add_u64 v[218:219], s[36:37], 0, v[146:147]
	s_addc_u32 s65, s37, 0
	s_add_i32 s33, s57, s42
	global_load_lds_dwordx4 v[218:219], off
	v_lshl_add_u64 v[220:221], s[64:65], 0, v[150:151]
	s_mov_b32 m0, s33
	v_lshl_add_u64 v[222:223], s[38:39], 0, v[148:149]
	global_load_lds_dwordx4 v[220:221], off
	v_lshl_add_u64 v[220:221], s[64:65], 0, v[146:147]
	s_add_i32 m0, s33, 0x2000
	s_nop 0
	global_load_lds_dwordx4 v[220:221], off
	v_lshl_add_u64 v[220:221], s[38:39], 0, v[152:153]
	s_mov_b32 m0, s23
	s_nop 0
	global_load_lds_dwordx4 v[220:221], off
	s_mov_b32 m0, s25
	s_nop 0
	global_load_lds_dwordx4 v[222:223], off
	s_waitcnt vmcnt(8)
	s_waitcnt lgkmcnt(0)
	s_barrier
; #define PG8_STAGE(bufoff, gbase, voff) do { _Pragma("unroll") for (int _i = 0; _i < 2; ++_i) \
;         __builtin_amdgcn_global_load_lds((const unsigned*)((const char*)(gbase) + (voff)[_i]), (LAS unsigned*)(lds + (bufoff) + ldsw + _i * 8192), 16, 0, 0); } while (0)
; #define PG8_LDA(dst, b, h) do { _Pragma("unroll") for (int m = 0; m < 4; ++m) _Pragma("unroll") for (int k = 0; k < 2; ++k) dst[m][k] = *(const LAS bf16x8*)(lds + PG8_SA(b, h) + aoff + m * 2048 + k * 1024); } while (0)
; #define PG8_LDB(dst, b, h) do { _Pragma("unroll") for (int n = 0; n < 2; ++n) _Pragma("unroll") for (int k = 0; k < 2; ++k) dst[n][k] = *(const LAS bf16x8*)(lds + PG8_SB(b, h) + boff + n * 2048 + k * 1024); } while (0)
; #define PG8_MMA(ai, bj, At, Bt) do { __builtin_amdgcn_s_setprio(1); _Pragma("unroll") for (int m = 0; m < 4; ++m) _Pragma("unroll") for (int n = 0; n < 2; ++n) _Pragma("unroll") for (int k = 0; k < 2; ++k) \
;         acc[ai][bj][m][n] = __builtin_amdgcn_mfma_f32_16x16x32_bf16(Bt[n][k], At[m][k], acc[ai][bj][m][n], 0, 0, 0); __builtin_amdgcn_s_setprio(0); } while (0)
; #define PG8_WAIT_V(n) asm volatile("s_waitcnt vmcnt(" #n ")" ::: "memory")
; #define PG8_WAIT_L(n) asm volatile("s_waitcnt lgkmcnt(" #n ")" ::: "memory")
; #define PG8_BAR __builtin_amdgcn_s_barrier()
; #define PG8_SCHED __builtin_amdgcn_sched_barrier(0)
; template <class Epi>
; __device__ __forceinline__ void gemm_phase(LAS unsigned char* lds, const Gemm g, int G, int c, const Epi& E) {
;     ...
;             PG8_WAIT_V(8); PG8_WAIT_L(0); PG8_BAR; PG8_MMA(1, 0, At, B0); PG8_MMA(1, 1, At, B1); PG8_BAR; PG8_SCHED;
;             PG8_LDB(B0, 1, 0); PG8_LDB(B1, 1, 1); PG8_SCHED; PG8_LDA(At, 1, 0); PG8_STAGE(PG8_SA(0, 1), a2 + hstepA, voffA);
;             PG8_WAIT_V(8); PG8_WAIT_L(0); PG8_BAR; PG8_MMA(0, 0, At, B0); PG8_MMA(0, 1, At, B1); PG8_BAR; PG8_SCHED;
;             PG8_LDA(At, 1, 1); PG8_STAGE(PG8_SB(1, 0), b3, voffB); PG8_STAGE(PG8_SB(1, 1), b3 + hstepB, voffB); PG8_STAGE(PG8_SA(1, 0), a3, voffA);
	s_setprio 1
	s_waitcnt lgkmcnt(0)
	v_mfma_f32_16x16x32_bf16 v[62:65], v[122:125], v[184:187], v[62:65]
	v_mfma_f32_16x16x32_bf16 v[58:61], v[130:133], v[184:187], v[58:61]
	v_mfma_f32_16x16x32_bf16 v[42:45], v[130:133], v[192:195], v[42:45]
	v_mfma_f32_16x16x32_bf16 v[54:57], v[122:125], v[192:195], v[54:57]
	v_mfma_f32_16x16x32_bf16 v[38:41], v[122:125], v[200:203], v[38:41]
	v_mfma_f32_16x16x32_bf16 v[26:29], v[130:133], v[200:203], v[26:29]
	v_mfma_f32_16x16x32_bf16 v[10:13], v[130:133], v[208:211], v[10:13]
	v_mfma_f32_16x16x32_bf16 v[22:25], v[122:125], v[208:211], v[22:25]
	v_mfma_f32_16x16x32_bf16 v[62:65], v[126:129], v[188:191], v[62:65]
	v_mfma_f32_16x16x32_bf16 v[58:61], v[134:137], v[188:191], v[58:61]
	v_mfma_f32_16x16x32_bf16 v[42:45], v[134:137], v[196:199], v[42:45]
	v_mfma_f32_16x16x32_bf16 v[54:57], v[126:129], v[196:199], v[54:57]
	v_mfma_f32_16x16x32_bf16 v[38:41], v[126:129], v[204:207], v[38:41]
	v_mfma_f32_16x16x32_bf16 v[26:29], v[134:137], v[204:207], v[26:29]
	v_mfma_f32_16x16x32_bf16 v[10:13], v[134:137], v[212:215], v[10:13]
	v_mfma_f32_16x16x32_bf16 v[22:25], v[126:129], v[212:215], v[22:25]
	s_setprio 0
	s_setprio 1
	v_mfma_f32_16x16x32_bf16 v[50:53], v[162:165], v[184:187], v[50:53]
	v_mfma_f32_16x16x32_bf16 v[46:49], v[176:179], v[184:187], v[46:49]
	v_mfma_f32_16x16x32_bf16 v[30:33], v[176:179], v[192:195], v[30:33]
	v_mfma_f32_16x16x32_bf16 v[34:37], v[162:165], v[192:195], v[34:37]
	v_mfma_f32_16x16x32_bf16 v[18:21], v[162:165], v[200:203], v[18:21]
	v_mfma_f32_16x16x32_bf16 v[14:17], v[176:179], v[200:203], v[14:17]
	v_mfma_f32_16x16x32_bf16 v[2:5], v[176:179], v[208:211], v[2:5]
	v_mfma_f32_16x16x32_bf16 v[6:9], v[162:165], v[208:211], v[6:9]
	v_mfma_f32_16x16x32_bf16 v[50:53], v[172:175], v[188:191], v[50:53]
	v_mfma_f32_16x16x32_bf16 v[46:49], v[180:183], v[188:191], v[46:49]
	v_mfma_f32_16x16x32_bf16 v[30:33], v[180:183], v[196:199], v[30:33]
	v_mfma_f32_16x16x32_bf16 v[34:37], v[172:175], v[196:199], v[34:37]
	v_mfma_f32_16x16x32_bf16 v[18:21], v[172:175], v[204:207], v[18:21]
	v_mfma_f32_16x16x32_bf16 v[14:17], v[180:183], v[204:207], v[14:17]
	v_mfma_f32_16x16x32_bf16 v[2:5], v[180:183], v[212:215], v[2:5]
	v_mfma_f32_16x16x32_bf16 v[6:9], v[172:175], v[212:215], v[6:9]
	s_setprio 0
	s_barrier
	s_add_i32 s33, 0, 0x18000
	s_add_i32 s63, 0, 0x1c000
	v_add_u32_e32 v134, s33, v167
	v_add_u32_e32 v171, s63, v167
	ds_read_b128 v[122:125], v134
	ds_read_b128 v[126:129], v134 offset:1024
	ds_read_b128 v[130:133], v134 offset:2048
	ds_read_b128 v[134:137], v134 offset:3072
	ds_read_b128 v[162:165], v171
	ds_read_b128 v[172:175], v171 offset:1024
	ds_read_b128 v[176:179], v171 offset:2048
	ds_read_b128 v[180:183], v171 offset:3072
	s_add_u32 s38, s38, 0x40000
	s_addc_u32 s39, s39, 0
	s_mov_b32 m0, s44
	v_lshl_add_u64 v[224:225], s[38:39], 0, v[152:153]
	ds_read_b128 v[184:187], v170 offset:32768
	ds_read_b128 v[188:191], v170 offset:33792
	ds_read_b128 v[192:195], v170 offset:34816
	ds_read_b128 v[196:199], v170 offset:35840
	ds_read_b128 v[200:203], v170 offset:36864
	ds_read_b128 v[204:207], v170 offset:37888
	ds_read_b128 v[208:211], v170 offset:38912
	ds_read_b128 v[212:215], v170 offset:39936
	global_load_lds_dwordx4 v[224:225], off
	v_lshl_add_u64 v[224:225], s[38:39], 0, v[148:149]
	s_mov_b32 m0, s45
	s_nop 0
	global_load_lds_dwordx4 v[224:225], off
	s_waitcnt vmcnt(8)
	s_waitcnt lgkmcnt(0)
	s_barrier
	s_setprio 1
	s_waitcnt lgkmcnt(0)
	v_mfma_f32_16x16x32_bf16 v[142:145], v[122:125], v[184:187], v[142:145]
	v_mfma_f32_16x16x32_bf16 v[138:141], v[130:133], v[184:187], v[138:141]
	v_mfma_f32_16x16x32_bf16 v[106:109], v[130:133], v[192:195], v[106:109]
	v_mfma_f32_16x16x32_bf16 v[118:121], v[122:125], v[192:195], v[118:121]
	v_mfma_f32_16x16x32_bf16 v[102:105], v[122:125], v[200:203], v[102:105]
	v_mfma_f32_16x16x32_bf16 v[90:93], v[130:133], v[200:203], v[90:93]
	v_mfma_f32_16x16x32_bf16 v[74:77], v[130:133], v[208:211], v[74:77]
	v_mfma_f32_16x16x32_bf16 v[86:89], v[122:125], v[208:211], v[86:89]
	v_mfma_f32_16x16x32_bf16 v[142:145], v[126:129], v[188:191], v[142:145]
	v_mfma_f32_16x16x32_bf16 v[138:141], v[134:137], v[188:191], v[138:141]
	v_mfma_f32_16x16x32_bf16 v[106:109], v[134:137], v[196:199], v[106:109]
	v_mfma_f32_16x16x32_bf16 v[118:121], v[126:129], v[196:199], v[118:121]
	v_mfma_f32_16x16x32_bf16 v[102:105], v[126:129], v[204:207], v[102:105]
	v_mfma_f32_16x16x32_bf16 v[90:93], v[134:137], v[204:207], v[90:93]
	v_mfma_f32_16x16x32_bf16 v[74:77], v[134:137], v[212:215], v[74:77]
	v_mfma_f32_16x16x32_bf16 v[86:89], v[126:129], v[212:215], v[86:89]
	s_setprio 0
	s_setprio 1
	v_mfma_f32_16x16x32_bf16 v[114:117], v[162:165], v[184:187], v[114:117]
	v_mfma_f32_16x16x32_bf16 v[110:113], v[176:179], v[184:187], v[110:113]
	v_mfma_f32_16x16x32_bf16 v[94:97], v[176:179], v[192:195], v[94:97]
	v_mfma_f32_16x16x32_bf16 v[98:101], v[162:165], v[192:195], v[98:101]
	v_mfma_f32_16x16x32_bf16 v[82:85], v[162:165], v[200:203], v[82:85]
	v_mfma_f32_16x16x32_bf16 v[78:81], v[176:179], v[200:203], v[78:81]
	v_mfma_f32_16x16x32_bf16 v[66:69], v[176:179], v[208:211], v[66:69]
	v_mfma_f32_16x16x32_bf16 v[70:73], v[162:165], v[208:211], v[70:73]
	v_mfma_f32_16x16x32_bf16 v[114:117], v[172:175], v[188:191], v[114:117]
	v_mfma_f32_16x16x32_bf16 v[110:113], v[180:183], v[188:191], v[110:113]
	v_mfma_f32_16x16x32_bf16 v[94:97], v[180:183], v[196:199], v[94:97]
	v_mfma_f32_16x16x32_bf16 v[98:101], v[172:175], v[196:199], v[98:101]
	v_mfma_f32_16x16x32_bf16 v[82:85], v[172:175], v[204:207], v[82:85]
	v_mfma_f32_16x16x32_bf16 v[78:81], v[180:183], v[204:207], v[78:81]
	v_mfma_f32_16x16x32_bf16 v[66:69], v[180:183], v[212:215], v[66:69]
	v_mfma_f32_16x16x32_bf16 v[70:73], v[172:175], v[212:215], v[70:73]
	s_setprio 0
	s_barrier
; #define PG8_STAGE(bufoff, gbase, voff) do { _Pragma("unroll") for (int _i = 0; _i < 2; ++_i) \
;         __builtin_amdgcn_global_load_lds((const unsigned*)((const char*)(gbase) + (voff)[_i]), (LAS unsigned*)(lds + (bufoff) + ldsw + _i * 8192), 16, 0, 0); } while (0)
; #define PG8_LDA(dst, b, h) do { _Pragma("unroll") for (int m = 0; m < 4; ++m) _Pragma("unroll") for (int k = 0; k < 2; ++k) dst[m][k] = *(const LAS bf16x8*)(lds + PG8_SA(b, h) + aoff + m * 2048 + k * 1024); } while (0)
; #define PG8_MMA(ai, bj, At, Bt) do { __builtin_amdgcn_s_setprio(1); _Pragma("unroll") for (int m = 0; m < 4; ++m) _Pragma("unroll") for (int n = 0; n < 2; ++n) _Pragma("unroll") for (int k = 0; k < 2; ++k) \
;         acc[ai][bj][m][n] = __builtin_amdgcn_mfma_f32_16x16x32_bf16(Bt[n][k], At[m][k], acc[ai][bj][m][n], 0, 0, 0); __builtin_amdgcn_s_setprio(0); } while (0)
; #define PG8_WAIT_V(n) asm volatile("s_waitcnt vmcnt(" #n ")" ::: "memory")
; #define PG8_WAIT_L(n) asm volatile("s_waitcnt lgkmcnt(" #n ")" ::: "memory")
; #define PG8_BAR __builtin_amdgcn_s_barrier()
; #define PG8_SCHED __builtin_amdgcn_sched_barrier(0)
; template <class Epi>
; __device__ __forceinline__ void gemm_phase(LAS unsigned char* lds, const Gemm g, int G, int c, const Epi& E) {
;     ...
;             PG8_LDA(At, 1, 1); PG8_STAGE(PG8_SB(1, 0), b3, voffB); PG8_STAGE(PG8_SB(1, 1), b3 + hstepB, voffB); PG8_STAGE(PG8_SA(1, 0), a3, voffA);
;             PG8_WAIT_V(8); PG8_WAIT_L(0); PG8_BAR; PG8_MMA(1, 0, At, B0); PG8_MMA(1, 1, At, B1); PG8_BAR; PG8_SCHED;
;         }
	s_add_i32 s33, s33, s42
	v_lshl_add_u64 v[216:217], v[216:217], 0, s[10:11]
	s_mov_b32 m0, s33
	ds_read_b128 v[184:187], v170 offset:49152
	ds_read_b128 v[188:191], v170 offset:50176
	ds_read_b128 v[192:195], v170 offset:51200
	ds_read_b128 v[196:199], v170 offset:52224
	ds_read_b128 v[200:203], v170 offset:53248
	ds_read_b128 v[204:207], v170 offset:54272
	ds_read_b128 v[208:211], v170 offset:55296
	ds_read_b128 v[212:215], v170 offset:56320
	global_load_lds_dwordx4 v[216:217], off
	s_add_i32 m0, s33, 0x2000
	s_add_u32 s36, s36, 0x40080
	v_lshl_add_u64 v[216:217], v[218:219], 0, s[10:11]
	s_addc_u32 s37, s37, 0
	s_add_i32 s33, s63, s42
	global_load_lds_dwordx4 v[216:217], off
	v_lshl_add_u64 v[216:217], s[36:37], 0, v[150:151]
	s_mov_b32 m0, s33
	s_nop 0
	global_load_lds_dwordx4 v[216:217], off
	v_lshl_add_u64 v[216:217], s[36:37], 0, v[146:147]
	s_add_i32 m0, s33, 0x2000
	s_nop 0
	global_load_lds_dwordx4 v[216:217], off
	v_lshl_add_u64 v[216:217], v[220:221], 0, s[10:11]
	s_mov_b32 m0, s53
	s_nop 0
	global_load_lds_dwordx4 v[216:217], off
	v_lshl_add_u64 v[216:217], v[222:223], 0, s[10:11]
	s_mov_b32 m0, s54
	s_nop 0
	global_load_lds_dwordx4 v[216:217], off
	s_waitcnt vmcnt(8)
	s_waitcnt lgkmcnt(0)
	s_barrier
	s_setprio 1
	s_waitcnt lgkmcnt(0)
	v_mfma_f32_16x16x32_bf16 v[62:65], v[122:125], v[184:187], v[62:65]
	v_mfma_f32_16x16x32_bf16 v[58:61], v[130:133], v[184:187], v[58:61]
	v_mfma_f32_16x16x32_bf16 v[42:45], v[130:133], v[192:195], v[42:45]
	v_mfma_f32_16x16x32_bf16 v[54:57], v[122:125], v[192:195], v[54:57]
	v_mfma_f32_16x16x32_bf16 v[38:41], v[122:125], v[200:203], v[38:41]
	v_mfma_f32_16x16x32_bf16 v[26:29], v[130:133], v[200:203], v[26:29]
	v_mfma_f32_16x16x32_bf16 v[10:13], v[130:133], v[208:211], v[10:13]
	v_mfma_f32_16x16x32_bf16 v[22:25], v[122:125], v[208:211], v[22:25]
	v_mfma_f32_16x16x32_bf16 v[62:65], v[126:129], v[188:191], v[62:65]
	v_mfma_f32_16x16x32_bf16 v[58:61], v[134:137], v[188:191], v[58:61]
	v_mfma_f32_16x16x32_bf16 v[42:45], v[134:137], v[196:199], v[42:45]
	v_mfma_f32_16x16x32_bf16 v[54:57], v[126:129], v[196:199], v[54:57]
	v_mfma_f32_16x16x32_bf16 v[38:41], v[126:129], v[204:207], v[38:41]
	v_mfma_f32_16x16x32_bf16 v[26:29], v[134:137], v[204:207], v[26:29]
	v_mfma_f32_16x16x32_bf16 v[10:13], v[134:137], v[212:215], v[10:13]
	v_mfma_f32_16x16x32_bf16 v[22:25], v[126:129], v[212:215], v[22:25]
	s_setprio 0
	s_setprio 1
	v_mfma_f32_16x16x32_bf16 v[50:53], v[162:165], v[184:187], v[50:53]
	v_mfma_f32_16x16x32_bf16 v[46:49], v[176:179], v[184:187], v[46:49]
	v_mfma_f32_16x16x32_bf16 v[30:33], v[176:179], v[192:195], v[30:33]
	v_mfma_f32_16x16x32_bf16 v[34:37], v[162:165], v[192:195], v[34:37]
	v_mfma_f32_16x16x32_bf16 v[18:21], v[162:165], v[200:203], v[18:21]
	v_mfma_f32_16x16x32_bf16 v[14:17], v[176:179], v[200:203], v[14:17]
	v_mfma_f32_16x16x32_bf16 v[2:5], v[176:179], v[208:211], v[2:5]
	v_mfma_f32_16x16x32_bf16 v[6:9], v[162:165], v[208:211], v[6:9]
	v_mfma_f32_16x16x32_bf16 v[50:53], v[172:175], v[188:191], v[50:53]
	v_mfma_f32_16x16x32_bf16 v[46:49], v[180:183], v[188:191], v[46:49]
	v_mfma_f32_16x16x32_bf16 v[30:33], v[180:183], v[196:199], v[30:33]
	v_mfma_f32_16x16x32_bf16 v[34:37], v[172:175], v[196:199], v[34:37]
	v_mfma_f32_16x16x32_bf16 v[18:21], v[172:175], v[204:207], v[18:21]
	v_mfma_f32_16x16x32_bf16 v[14:17], v[180:183], v[204:207], v[14:17]
	v_mfma_f32_16x16x32_bf16 v[2:5], v[180:183], v[212:215], v[2:5]
	v_mfma_f32_16x16x32_bf16 v[6:9], v[172:175], v[212:215], v[6:9]
	s_setprio 0
	s_barrier
	s_add_i32 s62, s62, 2
	s_add_u32 s4, s4, 0x100
	s_addc_u32 s5, s5, 0
	s_add_u32 s60, s60, 0x100
	s_addc_u32 s61, s61, 0
	s_cmp_gt_u32 s62, 13
	s_cbranch_scc0 .LBB0_1931
	s_and_b64 vcc, exec, s[12:13]
	s_cbranch_vccz .LBB0_1934
	s_barrier

; #define PG8_STAGE(bufoff, gbase, voff) do { _Pragma("unroll") for (int _i = 0; _i < 2; ++_i) \
;         __builtin_amdgcn_global_load_lds((const unsigned*)((const char*)(gbase) + (voff)[_i]), (LAS unsigned*)(lds + (bufoff) + ldsw + _i * 8192), 16, 0, 0); } while (0)
; #define PG8_LDA(dst, b, h) do { _Pragma("unroll") for (int m = 0; m < 4; ++m) _Pragma("unroll") for (int k = 0; k < 2; ++k) dst[m][k] = *(const LAS bf16x8*)(lds + PG8_SA(b, h) + aoff + m * 2048 + k * 1024); } while (0)
; #define PG8_LDB(dst, b, h) do { _Pragma("unroll") for (int n = 0; n < 2; ++n) _Pragma("unroll") for (int k = 0; k < 2; ++k) dst[n][k] = *(const LAS bf16x8*)(lds + PG8_SB(b, h) + boff + n * 2048 + k * 1024); } while (0)
; #define PG8_MMA(ai, bj, At, Bt) do { __builtin_amdgcn_s_setprio(1); _Pragma("unroll") for (int m = 0; m < 4; ++m) _Pragma("unroll") for (int n = 0; n < 2; ++n) _Pragma("unroll") for (int k = 0; k < 2; ++k) \
;         acc[ai][bj][m][n] = __builtin_amdgcn_mfma_f32_16x16x32_bf16(Bt[n][k], At[m][k], acc[ai][bj][m][n], 0, 0, 0); __builtin_amdgcn_s_setprio(0); } while (0)
; #define PG8_WAIT_V(n) asm volatile("s_waitcnt vmcnt(" #n ")" ::: "memory")
; #define PG8_WAIT_L(n) asm volatile("s_waitcnt lgkmcnt(" #n ")" ::: "memory")
; #define PG8_BAR __builtin_amdgcn_s_barrier()
; #define PG8_SCHED __builtin_amdgcn_sched_barrier(0)
; template <class Epi>
; __device__ __forceinline__ void gemm_phase(LAS unsigned char* lds, const Gemm g, int G, int c, const Epi& E) {
;     ...
;             const bool last = (t == nt - 2);
;             const char* a1 = cA + (size_t)(t + 1) * kstep;
;             const char* a2 = last ? nA : cA + (size_t)(t + 2) * kstep; const char* b2 = last ? nB : cB + (size_t)(t + 2) * kstep;
;             const char* a3 = a2 + kstep; const char* b3 = b2 + kstep;
;             PG8_LDB(B0, 0, 0); PG8_LDB(B1, 0, 1); PG8_SCHED; PG8_LDA(At, 0, 0); PG8_STAGE(PG8_SA(1, 1), a1 + hstepA, voffA);
;             PG8_WAIT_V(8); PG8_WAIT_L(0); PG8_BAR; PG8_MMA(0, 0, At, B0); PG8_MMA(0, 1, At, B1); PG8_BAR; PG8_SCHED;
;             PG8_LDA(At, 0, 1); PG8_STAGE(PG8_SB(0, 0), b2, voffB); PG8_STAGE(PG8_SB(0, 1), b2 + hstepB, voffB); PG8_STAGE(PG8_SA(0, 0), a2, voffA);
;             PG8_WAIT_V(8); PG8_WAIT_L(0); PG8_BAR; PG8_MMA(1, 0, At, B0); PG8_MMA(1, 1, At, B1); PG8_BAR; PG8_SCHED;
.LBB0_2084:
	ds_read_b128 v[152:155], v148
	ds_read_b128 v[156:159], v148 offset:1024
	ds_read_b128 v[160:163], v148 offset:2048
	ds_read_b128 v[164:167], v148 offset:3072
	ds_read_b128 v[168:171], v149
	ds_read_b128 v[172:175], v149 offset:1024
	ds_read_b128 v[176:179], v149 offset:2048
	ds_read_b128 v[180:183], v149 offset:3072
	s_add_u32 s33, s4, 0xfffc0080
	s_addc_u32 s38, s5, -1
	s_cmp_eq_u32 s68, 12
	s_cselect_b32 s41, s21, s38
	s_cselect_b32 s40, s20, s33
	s_cselect_b32 s39, s17, s67
	s_cselect_b32 s38, s19, s66
	v_lshl_add_u64 v[216:217], s[4:5], 0, v[138:139]
	s_add_i32 m0, s25, 0xc000
	ds_read_b128 v[184:187], v150
	ds_read_b128 v[188:191], v150 offset:1024
	ds_read_b128 v[192:195], v150 offset:2048
	ds_read_b128 v[196:199], v150 offset:3072
	ds_read_b128 v[200:203], v150 offset:4096
	ds_read_b128 v[204:207], v150 offset:5120
	ds_read_b128 v[208:211], v150 offset:6144
	ds_read_b128 v[212:215], v150 offset:7168
	global_load_lds_dwordx4 v[216:217], off
	v_lshl_add_u64 v[216:217], s[4:5], 0, v[140:141]
	s_add_i32 m0, s25, 0xe000
	s_nop 0
	global_load_lds_dwordx4 v[216:217], off
	s_waitcnt vmcnt(8)
	s_waitcnt lgkmcnt(0)
	s_barrier
	s_setprio 1
	s_waitcnt lgkmcnt(0)
	v_mfma_f32_16x16x32_bf16 v[126:129], v[152:155], v[184:187], v[126:129]
	v_mfma_f32_16x16x32_bf16 v[122:125], v[160:163], v[184:187], v[122:125]
	v_mfma_f32_16x16x32_bf16 v[106:109], v[160:163], v[192:195], v[106:109]
	v_mfma_f32_16x16x32_bf16 v[110:113], v[152:155], v[192:195], v[110:113]
	v_mfma_f32_16x16x32_bf16 v[94:97], v[152:155], v[200:203], v[94:97]
	v_mfma_f32_16x16x32_bf16 v[90:93], v[160:163], v[200:203], v[90:93]
	v_mfma_f32_16x16x32_bf16 v[74:77], v[160:163], v[208:211], v[74:77]
	v_mfma_f32_16x16x32_bf16 v[78:81], v[152:155], v[208:211], v[78:81]
	v_mfma_f32_16x16x32_bf16 v[126:129], v[156:159], v[188:191], v[126:129]
	v_mfma_f32_16x16x32_bf16 v[122:125], v[164:167], v[188:191], v[122:125]
	v_mfma_f32_16x16x32_bf16 v[106:109], v[164:167], v[196:199], v[106:109]
	v_mfma_f32_16x16x32_bf16 v[110:113], v[156:159], v[196:199], v[110:113]
	v_mfma_f32_16x16x32_bf16 v[94:97], v[156:159], v[204:207], v[94:97]
	v_mfma_f32_16x16x32_bf16 v[90:93], v[164:167], v[204:207], v[90:93]
	v_mfma_f32_16x16x32_bf16 v[74:77], v[164:167], v[212:215], v[74:77]
	v_mfma_f32_16x16x32_bf16 v[78:81], v[156:159], v[212:215], v[78:81]
	s_setprio 0
	s_setprio 1
	v_mfma_f32_16x16x32_bf16 v[118:121], v[168:171], v[184:187], v[118:121]
	v_mfma_f32_16x16x32_bf16 v[114:117], v[176:179], v[184:187], v[114:117]
	v_mfma_f32_16x16x32_bf16 v[98:101], v[176:179], v[192:195], v[98:101]
	v_mfma_f32_16x16x32_bf16 v[102:105], v[168:171], v[192:195], v[102:105]
	v_mfma_f32_16x16x32_bf16 v[86:89], v[168:171], v[200:203], v[86:89]
	v_mfma_f32_16x16x32_bf16 v[82:85], v[176:179], v[200:203], v[82:85]
	v_mfma_f32_16x16x32_bf16 v[66:69], v[176:179], v[208:211], v[66:69]
	v_mfma_f32_16x16x32_bf16 v[70:73], v[168:171], v[208:211], v[70:73]
	v_mfma_f32_16x16x32_bf16 v[118:121], v[172:175], v[188:191], v[118:121]
	v_mfma_f32_16x16x32_bf16 v[114:117], v[180:183], v[188:191], v[114:117]
	v_mfma_f32_16x16x32_bf16 v[98:101], v[180:183], v[196:199], v[98:101]
	v_mfma_f32_16x16x32_bf16 v[102:105], v[172:175], v[196:199], v[102:105]
	v_mfma_f32_16x16x32_bf16 v[86:89], v[172:175], v[204:207], v[86:89]
	v_mfma_f32_16x16x32_bf16 v[82:85], v[180:183], v[204:207], v[82:85]
	v_mfma_f32_16x16x32_bf16 v[66:69], v[180:183], v[212:215], v[66:69]
	v_mfma_f32_16x16x32_bf16 v[70:73], v[172:175], v[212:215], v[70:73]
	s_setprio 0
	s_barrier
	s_add_i32 s33, s56, s46
	v_lshl_add_u64 v[216:217], s[38:39], 0, v[134:135]
	s_mov_b32 m0, s33
	ds_read_b128 v[184:187], v150 offset:16384
	ds_read_b128 v[188:191], v150 offset:17408
	ds_read_b128 v[192:195], v150 offset:18432
	ds_read_b128 v[196:199], v150 offset:19456
	ds_read_b128 v[200:203], v150 offset:20480
	ds_read_b128 v[204:207], v150 offset:21504
	ds_read_b128 v[208:211], v150 offset:22528
	ds_read_b128 v[212:215], v150 offset:23552
	global_load_lds_dwordx4 v[216:217], off
	s_add_i32 m0, s33, 0x2000
	s_add_u32 s70, s38, 0x40000
	v_lshl_add_u64 v[218:219], s[38:39], 0, v[130:131]
	s_addc_u32 s71, s39, 0
	s_add_i32 s33, s57, s46
	global_load_lds_dwordx4 v[218:219], off
	v_lshl_add_u64 v[220:221], s[70:71], 0, v[134:135]
	s_mov_b32 m0, s33
	v_lshl_add_u64 v[222:223], s[40:41], 0, v[132:133]
	global_load_lds_dwordx4 v[220:221], off
	v_lshl_add_u64 v[220:221], s[70:71], 0, v[130:131]
	s_add_i32 m0, s33, 0x2000
	s_nop 0
	global_load_lds_dwordx4 v[220:221], off
	v_lshl_add_u64 v[220:221], s[40:41], 0, v[136:137]
	s_mov_b32 m0, s25
	s_nop 0
	global_load_lds_dwordx4 v[220:221], off
	s_mov_b32 m0, s37
	s_nop 0
	global_load_lds_dwordx4 v[222:223], off
	s_waitcnt vmcnt(8)
	s_waitcnt lgkmcnt(0)
	s_barrier
; #define PG8_STAGE(bufoff, gbase, voff) do { _Pragma("unroll") for (int _i = 0; _i < 2; ++_i) \
;         __builtin_amdgcn_global_load_lds((const unsigned*)((const char*)(gbase) + (voff)[_i]), (LAS unsigned*)(lds + (bufoff) + ldsw + _i * 8192), 16, 0, 0); } while (0)
; #define PG8_LDA(dst, b, h) do { _Pragma("unroll") for (int m = 0; m < 4; ++m) _Pragma("unroll") for (int k = 0; k < 2; ++k) dst[m][k] = *(const LAS bf16x8*)(lds + PG8_SA(b, h) + aoff + m * 2048 + k * 1024); } while (0)
; #define PG8_LDB(dst, b, h) do { _Pragma("unroll") for (int n = 0; n < 2; ++n) _Pragma("unroll") for (int k = 0; k < 2; ++k) dst[n][k] = *(const LAS bf16x8*)(lds + PG8_SB(b, h) + boff + n * 2048 + k * 1024); } while (0)
; #define PG8_MMA(ai, bj, At, Bt) do { __builtin_amdgcn_s_setprio(1); _Pragma("unroll") for (int m = 0; m < 4; ++m) _Pragma("unroll") for (int n = 0; n < 2; ++n) _Pragma("unroll") for (int k = 0; k < 2; ++k) \
;         acc[ai][bj][m][n] = __builtin_amdgcn_mfma_f32_16x16x32_bf16(Bt[n][k], At[m][k], acc[ai][bj][m][n], 0, 0, 0); __builtin_amdgcn_s_setprio(0); } while (0)
; #define PG8_WAIT_V(n) asm volatile("s_waitcnt vmcnt(" #n ")" ::: "memory")
; #define PG8_WAIT_L(n) asm volatile("s_waitcnt lgkmcnt(" #n ")" ::: "memory")
; #define PG8_BAR __builtin_amdgcn_s_barrier()
; #define PG8_SCHED __builtin_amdgcn_sched_barrier(0)
; template <class Epi>
; __device__ __forceinline__ void gemm_phase(LAS unsigned char* lds, const Gemm g, int G, int c, const Epi& E) {
;     ...
;             PG8_WAIT_V(8); PG8_WAIT_L(0); PG8_BAR; PG8_MMA(1, 0, At, B0); PG8_MMA(1, 1, At, B1); PG8_BAR; PG8_SCHED;
;             PG8_LDB(B0, 1, 0); PG8_LDB(B1, 1, 1); PG8_SCHED; PG8_LDA(At, 1, 0); PG8_STAGE(PG8_SA(0, 1), a2 + hstepA, voffA);
;             PG8_WAIT_V(8); PG8_WAIT_L(0); PG8_BAR; PG8_MMA(0, 0, At, B0); PG8_MMA(0, 1, At, B1); PG8_BAR; PG8_SCHED;
	s_setprio 1
	s_waitcnt lgkmcnt(0)
	v_mfma_f32_16x16x32_bf16 v[62:65], v[152:155], v[184:187], v[62:65]
	v_mfma_f32_16x16x32_bf16 v[58:61], v[160:163], v[184:187], v[58:61]
	v_mfma_f32_16x16x32_bf16 v[42:45], v[160:163], v[192:195], v[42:45]
	v_mfma_f32_16x16x32_bf16 v[46:49], v[152:155], v[192:195], v[46:49]
	v_mfma_f32_16x16x32_bf16 v[30:33], v[152:155], v[200:203], v[30:33]
	v_mfma_f32_16x16x32_bf16 v[26:29], v[160:163], v[200:203], v[26:29]
	v_mfma_f32_16x16x32_bf16 v[10:13], v[160:163], v[208:211], v[10:13]
	v_mfma_f32_16x16x32_bf16 v[14:17], v[152:155], v[208:211], v[14:17]
	v_mfma_f32_16x16x32_bf16 v[62:65], v[156:159], v[188:191], v[62:65]
	v_mfma_f32_16x16x32_bf16 v[58:61], v[164:167], v[188:191], v[58:61]
	v_mfma_f32_16x16x32_bf16 v[42:45], v[164:167], v[196:199], v[42:45]
	v_mfma_f32_16x16x32_bf16 v[46:49], v[156:159], v[196:199], v[46:49]
	v_mfma_f32_16x16x32_bf16 v[30:33], v[156:159], v[204:207], v[30:33]
	v_mfma_f32_16x16x32_bf16 v[26:29], v[164:167], v[204:207], v[26:29]
	v_mfma_f32_16x16x32_bf16 v[10:13], v[164:167], v[212:215], v[10:13]
	v_mfma_f32_16x16x32_bf16 v[14:17], v[156:159], v[212:215], v[14:17]
	s_setprio 0
	s_setprio 1
	v_mfma_f32_16x16x32_bf16 v[54:57], v[168:171], v[184:187], v[54:57]
	v_mfma_f32_16x16x32_bf16 v[50:53], v[176:179], v[184:187], v[50:53]
	v_mfma_f32_16x16x32_bf16 v[34:37], v[176:179], v[192:195], v[34:37]
	v_mfma_f32_16x16x32_bf16 v[38:41], v[168:171], v[192:195], v[38:41]
	v_mfma_f32_16x16x32_bf16 v[22:25], v[168:171], v[200:203], v[22:25]
	v_mfma_f32_16x16x32_bf16 v[18:21], v[176:179], v[200:203], v[18:21]
	v_mfma_f32_16x16x32_bf16 v[2:5], v[176:179], v[208:211], v[2:5]
	v_mfma_f32_16x16x32_bf16 v[6:9], v[168:171], v[208:211], v[6:9]
	v_mfma_f32_16x16x32_bf16 v[54:57], v[172:175], v[188:191], v[54:57]
	v_mfma_f32_16x16x32_bf16 v[50:53], v[180:183], v[188:191], v[50:53]
	v_mfma_f32_16x16x32_bf16 v[34:37], v[180:183], v[196:199], v[34:37]
	v_mfma_f32_16x16x32_bf16 v[38:41], v[172:175], v[196:199], v[38:41]
	v_mfma_f32_16x16x32_bf16 v[22:25], v[172:175], v[204:207], v[22:25]
	v_mfma_f32_16x16x32_bf16 v[18:21], v[180:183], v[204:207], v[18:21]
	v_mfma_f32_16x16x32_bf16 v[2:5], v[180:183], v[212:215], v[2:5]
	v_mfma_f32_16x16x32_bf16 v[6:9], v[172:175], v[212:215], v[6:9]
	s_setprio 0
	s_barrier
	s_add_i32 s33, 0, 0x18000
	s_add_i32 s69, 0, 0x1c000
	v_add_u32_e32 v164, s33, v147
	v_add_u32_e32 v180, s69, v147
	ds_read_b128 v[152:155], v164
	ds_read_b128 v[156:159], v164 offset:1024
	ds_read_b128 v[160:163], v164 offset:2048
	ds_read_b128 v[164:167], v164 offset:3072
	ds_read_b128 v[168:171], v180
	ds_read_b128 v[172:175], v180 offset:1024
	ds_read_b128 v[176:179], v180 offset:2048
	ds_read_b128 v[180:183], v180 offset:3072
	s_add_u32 s40, s40, 0x40000
	s_addc_u32 s41, s41, 0
	s_mov_b32 m0, s47
	v_lshl_add_u64 v[224:225], s[40:41], 0, v[136:137]
	ds_read_b128 v[184:187], v150 offset:32768
	ds_read_b128 v[188:191], v150 offset:33792
	ds_read_b128 v[192:195], v150 offset:34816
	ds_read_b128 v[196:199], v150 offset:35840
	ds_read_b128 v[200:203], v150 offset:36864
	ds_read_b128 v[204:207], v150 offset:37888
	ds_read_b128 v[208:211], v150 offset:38912
	ds_read_b128 v[212:215], v150 offset:39936
	global_load_lds_dwordx4 v[224:225], off
	v_lshl_add_u64 v[224:225], s[40:41], 0, v[132:133]
	s_mov_b32 m0, s48
	s_nop 0
	global_load_lds_dwordx4 v[224:225], off
	s_waitcnt vmcnt(8)
	s_waitcnt lgkmcnt(0)
	s_barrier
	s_setprio 1
	s_waitcnt lgkmcnt(0)
	v_mfma_f32_16x16x32_bf16 v[126:129], v[152:155], v[184:187], v[126:129]
	v_mfma_f32_16x16x32_bf16 v[122:125], v[160:163], v[184:187], v[122:125]
	v_mfma_f32_16x16x32_bf16 v[106:109], v[160:163], v[192:195], v[106:109]
	v_mfma_f32_16x16x32_bf16 v[110:113], v[152:155], v[192:195], v[110:113]
	v_mfma_f32_16x16x32_bf16 v[94:97], v[152:155], v[200:203], v[94:97]
	v_mfma_f32_16x16x32_bf16 v[90:93], v[160:163], v[200:203], v[90:93]
	v_mfma_f32_16x16x32_bf16 v[74:77], v[160:163], v[208:211], v[74:77]
	v_mfma_f32_16x16x32_bf16 v[78:81], v[152:155], v[208:211], v[78:81]
	v_mfma_f32_16x16x32_bf16 v[126:129], v[156:159], v[188:191], v[126:129]
	v_mfma_f32_16x16x32_bf16 v[122:125], v[164:167], v[188:191], v[122:125]
	v_mfma_f32_16x16x32_bf16 v[106:109], v[164:167], v[196:199], v[106:109]
	v_mfma_f32_16x16x32_bf16 v[110:113], v[156:159], v[196:199], v[110:113]
	v_mfma_f32_16x16x32_bf16 v[94:97], v[156:159], v[204:207], v[94:97]
	v_mfma_f32_16x16x32_bf16 v[90:93], v[164:167], v[204:207], v[90:93]
	v_mfma_f32_16x16x32_bf16 v[74:77], v[164:167], v[212:215], v[74:77]
	v_mfma_f32_16x16x32_bf16 v[78:81], v[156:159], v[212:215], v[78:81]
	s_setprio 0
	s_setprio 1
	v_mfma_f32_16x16x32_bf16 v[118:121], v[168:171], v[184:187], v[118:121]
	v_mfma_f32_16x16x32_bf16 v[114:117], v[176:179], v[184:187], v[114:117]
	v_mfma_f32_16x16x32_bf16 v[98:101], v[176:179], v[192:195], v[98:101]
	v_mfma_f32_16x16x32_bf16 v[102:105], v[168:171], v[192:195], v[102:105]
	v_mfma_f32_16x16x32_bf16 v[86:89], v[168:171], v[200:203], v[86:89]
	v_mfma_f32_16x16x32_bf16 v[82:85], v[176:179], v[200:203], v[82:85]
	v_mfma_f32_16x16x32_bf16 v[66:69], v[176:179], v[208:211], v[66:69]
	v_mfma_f32_16x16x32_bf16 v[70:73], v[168:171], v[208:211], v[70:73]
	v_mfma_f32_16x16x32_bf16 v[118:121], v[172:175], v[188:191], v[118:121]
	v_mfma_f32_16x16x32_bf16 v[114:117], v[180:183], v[188:191], v[114:117]
	v_mfma_f32_16x16x32_bf16 v[98:101], v[180:183], v[196:199], v[98:101]
	v_mfma_f32_16x16x32_bf16 v[102:105], v[172:175], v[196:199], v[102:105]
	v_mfma_f32_16x16x32_bf16 v[86:89], v[172:175], v[204:207], v[86:89]
	v_mfma_f32_16x16x32_bf16 v[82:85], v[180:183], v[204:207], v[82:85]
	v_mfma_f32_16x16x32_bf16 v[66:69], v[180:183], v[212:215], v[66:69]
	v_mfma_f32_16x16x32_bf16 v[70:73], v[172:175], v[212:215], v[70:73]
	s_setprio 0
	s_barrier
; #define PG8_STAGE(bufoff, gbase, voff) do { _Pragma("unroll") for (int _i = 0; _i < 2; ++_i) \
;         __builtin_amdgcn_global_load_lds((const unsigned*)((const char*)(gbase) + (voff)[_i]), (LAS unsigned*)(lds + (bufoff) + ldsw + _i * 8192), 16, 0, 0); } while (0)
; #define PG8_LDA(dst, b, h) do { _Pragma("unroll") for (int m = 0; m < 4; ++m) _Pragma("unroll") for (int k = 0; k < 2; ++k) dst[m][k] = *(const LAS bf16x8*)(lds + PG8_SA(b, h) + aoff + m * 2048 + k * 1024); } while (0)
; #define PG8_MMA(ai, bj, At, Bt) do { __builtin_amdgcn_s_setprio(1); _Pragma("unroll") for (int m = 0; m < 4; ++m) _Pragma("unroll") for (int n = 0; n < 2; ++n) _Pragma("unroll") for (int k = 0; k < 2; ++k) \
;         acc[ai][bj][m][n] = __builtin_amdgcn_mfma_f32_16x16x32_bf16(Bt[n][k], At[m][k], acc[ai][bj][m][n], 0, 0, 0); __builtin_amdgcn_s_setprio(0); } while (0)
; #define PG8_WAIT_V(n) asm volatile("s_waitcnt vmcnt(" #n ")" ::: "memory")
; #define PG8_WAIT_L(n) asm volatile("s_waitcnt lgkmcnt(" #n ")" ::: "memory")
; #define PG8_BAR __builtin_amdgcn_s_barrier()
; #define PG8_SCHED __builtin_amdgcn_sched_barrier(0)
; template <class Epi>
; __device__ __forceinline__ void gemm_phase(LAS unsigned char* lds, const Gemm g, int G, int c, const Epi& E) {
;     ...
;             PG8_LDA(At, 1, 1); PG8_STAGE(PG8_SB(1, 0), b3, voffB); PG8_STAGE(PG8_SB(1, 1), b3 + hstepB, voffB); PG8_STAGE(PG8_SA(1, 0), a3, voffA);
;             PG8_WAIT_V(8); PG8_WAIT_L(0); PG8_BAR; PG8_MMA(1, 0, At, B0); PG8_MMA(1, 1, At, B1); PG8_BAR; PG8_SCHED;
;         }
	s_add_i32 s33, s33, s46
	v_lshl_add_u64 v[216:217], v[216:217], 0, s[12:13]
	s_mov_b32 m0, s33
	ds_read_b128 v[184:187], v150 offset:49152
	ds_read_b128 v[188:191], v150 offset:50176
	ds_read_b128 v[192:195], v150 offset:51200
	ds_read_b128 v[196:199], v150 offset:52224
	ds_read_b128 v[200:203], v150 offset:53248
	ds_read_b128 v[204:207], v150 offset:54272
	ds_read_b128 v[208:211], v150 offset:55296
	ds_read_b128 v[212:215], v150 offset:56320
	global_load_lds_dwordx4 v[216:217], off
	s_add_i32 m0, s33, 0x2000
	s_add_u32 s38, s38, 0x40080
	v_lshl_add_u64 v[216:217], v[218:219], 0, s[12:13]
	s_addc_u32 s39, s39, 0
	s_add_i32 s33, s69, s46
	global_load_lds_dwordx4 v[216:217], off
	v_lshl_add_u64 v[216:217], s[38:39], 0, v[134:135]
	s_mov_b32 m0, s33
	s_nop 0
	global_load_lds_dwordx4 v[216:217], off
	v_lshl_add_u64 v[216:217], s[38:39], 0, v[130:131]
	s_add_i32 m0, s33, 0x2000
	s_nop 0
	global_load_lds_dwordx4 v[216:217], off
	v_lshl_add_u64 v[216:217], v[220:221], 0, s[12:13]
	s_mov_b32 m0, s53
	s_nop 0
	global_load_lds_dwordx4 v[216:217], off
	v_lshl_add_u64 v[216:217], v[222:223], 0, s[12:13]
	s_mov_b32 m0, s54
	s_nop 0
	global_load_lds_dwordx4 v[216:217], off
	s_waitcnt vmcnt(8)
	s_waitcnt lgkmcnt(0)
	s_barrier
	s_setprio 1
	s_waitcnt lgkmcnt(0)
	v_mfma_f32_16x16x32_bf16 v[62:65], v[152:155], v[184:187], v[62:65]
	v_mfma_f32_16x16x32_bf16 v[58:61], v[160:163], v[184:187], v[58:61]
	v_mfma_f32_16x16x32_bf16 v[42:45], v[160:163], v[192:195], v[42:45]
	v_mfma_f32_16x16x32_bf16 v[46:49], v[152:155], v[192:195], v[46:49]
	v_mfma_f32_16x16x32_bf16 v[30:33], v[152:155], v[200:203], v[30:33]
	v_mfma_f32_16x16x32_bf16 v[26:29], v[160:163], v[200:203], v[26:29]
	v_mfma_f32_16x16x32_bf16 v[10:13], v[160:163], v[208:211], v[10:13]
	v_mfma_f32_16x16x32_bf16 v[14:17], v[152:155], v[208:211], v[14:17]
	v_mfma_f32_16x16x32_bf16 v[62:65], v[156:159], v[188:191], v[62:65]
	v_mfma_f32_16x16x32_bf16 v[58:61], v[164:167], v[188:191], v[58:61]
	v_mfma_f32_16x16x32_bf16 v[42:45], v[164:167], v[196:199], v[42:45]
	v_mfma_f32_16x16x32_bf16 v[46:49], v[156:159], v[196:199], v[46:49]
	v_mfma_f32_16x16x32_bf16 v[30:33], v[156:159], v[204:207], v[30:33]
	v_mfma_f32_16x16x32_bf16 v[26:29], v[164:167], v[204:207], v[26:29]
	v_mfma_f32_16x16x32_bf16 v[10:13], v[164:167], v[212:215], v[10:13]
	v_mfma_f32_16x16x32_bf16 v[14:17], v[156:159], v[212:215], v[14:17]
	s_setprio 0
	s_setprio 1
	v_mfma_f32_16x16x32_bf16 v[54:57], v[168:171], v[184:187], v[54:57]
	v_mfma_f32_16x16x32_bf16 v[50:53], v[176:179], v[184:187], v[50:53]
	v_mfma_f32_16x16x32_bf16 v[34:37], v[176:179], v[192:195], v[34:37]
	v_mfma_f32_16x16x32_bf16 v[38:41], v[168:171], v[192:195], v[38:41]
	v_mfma_f32_16x16x32_bf16 v[22:25], v[168:171], v[200:203], v[22:25]
	v_mfma_f32_16x16x32_bf16 v[18:21], v[176:179], v[200:203], v[18:21]
	v_mfma_f32_16x16x32_bf16 v[2:5], v[176:179], v[208:211], v[2:5]
	v_mfma_f32_16x16x32_bf16 v[6:9], v[168:171], v[208:211], v[6:9]
	v_mfma_f32_16x16x32_bf16 v[54:57], v[172:175], v[188:191], v[54:57]
	v_mfma_f32_16x16x32_bf16 v[50:53], v[180:183], v[188:191], v[50:53]
	v_mfma_f32_16x16x32_bf16 v[34:37], v[180:183], v[196:199], v[34:37]
	v_mfma_f32_16x16x32_bf16 v[38:41], v[172:175], v[196:199], v[38:41]
	v_mfma_f32_16x16x32_bf16 v[22:25], v[172:175], v[204:207], v[22:25]
	v_mfma_f32_16x16x32_bf16 v[18:21], v[180:183], v[204:207], v[18:21]
	v_mfma_f32_16x16x32_bf16 v[2:5], v[180:183], v[212:215], v[2:5]
	v_mfma_f32_16x16x32_bf16 v[6:9], v[172:175], v[212:215], v[6:9]
	s_setprio 0
	s_barrier
	s_add_i32 s68, s68, 2
	s_add_u32 s4, s4, 0x100
	s_addc_u32 s5, s5, 0
	s_add_u32 s66, s66, 0x100
	s_addc_u32 s67, s67, 0
	s_cmp_gt_u32 s68, 13
	s_cbranch_scc0 .LBB0_2084
	s_and_b64 vcc, exec, s[14:15]
	s_cbranch_vccz .LBB0_2087
	s_barrier

; #define PG8_STAGE(bufoff, gbase, voff) do { _Pragma("unroll") for (int _i = 0; _i < 2; ++_i) \
;         __builtin_amdgcn_global_load_lds((const unsigned*)((const char*)(gbase) + (voff)[_i]), (LAS unsigned*)(lds + (bufoff) + ldsw + _i * 8192), 16, 0, 0); } while (0)
; #define PG8_LDA(dst, b, h) do { _Pragma("unroll") for (int m = 0; m < 4; ++m) _Pragma("unroll") for (int k = 0; k < 2; ++k) dst[m][k] = *(const LAS bf16x8*)(lds + PG8_SA(b, h) + aoff + m * 2048 + k * 1024); } while (0)
; #define PG8_LDB(dst, b, h) do { _Pragma("unroll") for (int n = 0; n < 2; ++n) _Pragma("unroll") for (int k = 0; k < 2; ++k) dst[n][k] = *(const LAS bf16x8*)(lds + PG8_SB(b, h) + boff + n * 2048 + k * 1024); } while (0)
; #define PG8_MMA(ai, bj, At, Bt) do { __builtin_amdgcn_s_setprio(1); _Pragma("unroll") for (int m = 0; m < 4; ++m) _Pragma("unroll") for (int n = 0; n < 2; ++n) _Pragma("unroll") for (int k = 0; k < 2; ++k) \
;         acc[ai][bj][m][n] = __builtin_amdgcn_mfma_f32_16x16x32_bf16(Bt[n][k], At[m][k], acc[ai][bj][m][n], 0, 0, 0); __builtin_amdgcn_s_setprio(0); } while (0)
; #define PG8_WAIT_V(n) asm volatile("s_waitcnt vmcnt(" #n ")" ::: "memory")
; #define PG8_WAIT_L(n) asm volatile("s_waitcnt lgkmcnt(" #n ")" ::: "memory")
; #define PG8_BAR __builtin_amdgcn_s_barrier()
; #define PG8_SCHED __builtin_amdgcn_sched_barrier(0)
; template <class Epi>
; __device__ __forceinline__ void gemm_phase(LAS unsigned char* lds, const Gemm g, int G, int c, const Epi& E) {
;     ...
;             const bool last = (t == nt - 2);
;             const char* a1 = cA + (size_t)(t + 1) * kstep;
;             const char* a2 = last ? nA : cA + (size_t)(t + 2) * kstep; const char* b2 = last ? nB : cB + (size_t)(t + 2) * kstep;
;             const char* a3 = a2 + kstep; const char* b3 = b2 + kstep;
;             PG8_LDB(B0, 0, 0); PG8_LDB(B1, 0, 1); PG8_SCHED; PG8_LDA(At, 0, 0); PG8_STAGE(PG8_SA(1, 1), a1 + hstepA, voffA);
;             PG8_WAIT_V(8); PG8_WAIT_L(0); PG8_BAR; PG8_MMA(0, 0, At, B0); PG8_MMA(0, 1, At, B1); PG8_BAR; PG8_SCHED;
;             PG8_LDA(At, 0, 1); PG8_STAGE(PG8_SB(0, 0), b2, voffB); PG8_STAGE(PG8_SB(0, 1), b2 + hstepB, voffB); PG8_STAGE(PG8_SA(0, 0), a2, voffA);
;             PG8_WAIT_V(8); PG8_WAIT_L(0); PG8_BAR; PG8_MMA(1, 0, At, B0); PG8_MMA(1, 1, At, B1); PG8_BAR; PG8_SCHED;
.LBB0_2169:
	ds_read_b128 v[106:109], v168
	ds_read_b128 v[110:113], v168 offset:1024
	ds_read_b128 v[114:117], v168 offset:2048
	ds_read_b128 v[118:121], v168 offset:3072
	ds_read_b128 v[162:165], v169
	ds_read_b128 v[172:175], v169 offset:1024
	ds_read_b128 v[176:179], v169 offset:2048
	ds_read_b128 v[180:183], v169 offset:3072
	s_add_u32 s20, s18, 0x100
	s_addc_u32 s21, s19, 0
	s_cmp_eq_u32 s62, 40
	s_cselect_b32 s25, s5, s21
	s_cselect_b32 s24, s4, s20
	s_cselect_b32 s23, s17, s61
	s_cselect_b32 s22, s16, s60
	v_lshl_add_u64 v[216:217], s[18:19], 0, v[154:155]
	s_add_i32 m0, s40, 0xc000
	ds_read_b128 v[184:187], v170
	ds_read_b128 v[188:191], v170 offset:1024
	ds_read_b128 v[192:195], v170 offset:2048
	ds_read_b128 v[196:199], v170 offset:3072
	ds_read_b128 v[200:203], v170 offset:4096
	ds_read_b128 v[204:207], v170 offset:5120
	ds_read_b128 v[208:211], v170 offset:6144
	ds_read_b128 v[212:215], v170 offset:7168
	global_load_lds_dwordx4 v[216:217], off
	v_lshl_add_u64 v[216:217], s[18:19], 0, v[156:157]
	s_add_i32 m0, s40, 0xe000
	s_nop 0
	global_load_lds_dwordx4 v[216:217], off
	s_waitcnt vmcnt(8)
	s_waitcnt lgkmcnt(0)
	s_barrier
	s_setprio 1
	s_waitcnt lgkmcnt(0)
	v_mfma_f32_16x16x32_bf16 v[142:145], v[106:109], v[184:187], v[142:145]
	v_mfma_f32_16x16x32_bf16 v[138:141], v[114:117], v[184:187], v[138:141]
	v_mfma_f32_16x16x32_bf16 v[122:125], v[114:117], v[192:195], v[122:125]
	v_mfma_f32_16x16x32_bf16 v[126:129], v[106:109], v[192:195], v[126:129]
	v_mfma_f32_16x16x32_bf16 v[94:97], v[106:109], v[200:203], v[94:97]
	v_mfma_f32_16x16x32_bf16 v[90:93], v[114:117], v[200:203], v[90:93]
	v_mfma_f32_16x16x32_bf16 v[74:77], v[114:117], v[208:211], v[74:77]
	v_mfma_f32_16x16x32_bf16 v[78:81], v[106:109], v[208:211], v[78:81]
	v_mfma_f32_16x16x32_bf16 v[142:145], v[110:113], v[188:191], v[142:145]
	v_mfma_f32_16x16x32_bf16 v[138:141], v[118:121], v[188:191], v[138:141]
	v_mfma_f32_16x16x32_bf16 v[122:125], v[118:121], v[196:199], v[122:125]
	v_mfma_f32_16x16x32_bf16 v[126:129], v[110:113], v[196:199], v[126:129]
	v_mfma_f32_16x16x32_bf16 v[94:97], v[110:113], v[204:207], v[94:97]
	v_mfma_f32_16x16x32_bf16 v[90:93], v[118:121], v[204:207], v[90:93]
	v_mfma_f32_16x16x32_bf16 v[74:77], v[118:121], v[212:215], v[74:77]
	v_mfma_f32_16x16x32_bf16 v[78:81], v[110:113], v[212:215], v[78:81]
	s_setprio 0
	s_setprio 1
	v_mfma_f32_16x16x32_bf16 v[134:137], v[162:165], v[184:187], v[134:137]
	v_mfma_f32_16x16x32_bf16 v[130:133], v[176:179], v[184:187], v[130:133]
	v_mfma_f32_16x16x32_bf16 v[98:101], v[176:179], v[192:195], v[98:101]
	v_mfma_f32_16x16x32_bf16 v[102:105], v[162:165], v[192:195], v[102:105]
	v_mfma_f32_16x16x32_bf16 v[86:89], v[162:165], v[200:203], v[86:89]
	v_mfma_f32_16x16x32_bf16 v[82:85], v[176:179], v[200:203], v[82:85]
	v_mfma_f32_16x16x32_bf16 v[66:69], v[176:179], v[208:211], v[66:69]
	v_mfma_f32_16x16x32_bf16 v[70:73], v[162:165], v[208:211], v[70:73]
	v_mfma_f32_16x16x32_bf16 v[134:137], v[172:175], v[188:191], v[134:137]
	v_mfma_f32_16x16x32_bf16 v[130:133], v[180:183], v[188:191], v[130:133]
	v_mfma_f32_16x16x32_bf16 v[98:101], v[180:183], v[196:199], v[98:101]
	v_mfma_f32_16x16x32_bf16 v[102:105], v[172:175], v[196:199], v[102:105]
	v_mfma_f32_16x16x32_bf16 v[86:89], v[172:175], v[204:207], v[86:89]
	v_mfma_f32_16x16x32_bf16 v[82:85], v[180:183], v[204:207], v[82:85]
	v_mfma_f32_16x16x32_bf16 v[66:69], v[180:183], v[212:215], v[66:69]
	v_mfma_f32_16x16x32_bf16 v[70:73], v[172:175], v[212:215], v[70:73]
	s_setprio 0
	s_barrier
	s_add_i32 s18, s52, s38
	v_lshl_add_u64 v[216:217], s[22:23], 0, v[150:151]
	s_mov_b32 m0, s18
	ds_read_b128 v[184:187], v170 offset:16384
	ds_read_b128 v[188:191], v170 offset:17408
	ds_read_b128 v[192:195], v170 offset:18432
	ds_read_b128 v[196:199], v170 offset:19456
	ds_read_b128 v[200:203], v170 offset:20480
	ds_read_b128 v[204:207], v170 offset:21504
	ds_read_b128 v[208:211], v170 offset:22528
	ds_read_b128 v[212:215], v170 offset:23552
	global_load_lds_dwordx4 v[216:217], off
	s_add_i32 m0, s18, 0x2000
	s_add_u32 s18, s22, 0xb0000
	v_lshl_add_u64 v[218:219], s[22:23], 0, v[146:147]
	s_addc_u32 s19, s23, 0
	s_add_i32 s33, s53, s38
	global_load_lds_dwordx4 v[218:219], off
	v_lshl_add_u64 v[220:221], s[18:19], 0, v[150:151]
	s_mov_b32 m0, s33
	v_lshl_add_u64 v[222:223], s[24:25], 0, v[148:149]
	global_load_lds_dwordx4 v[220:221], off
	v_lshl_add_u64 v[220:221], s[18:19], 0, v[146:147]
	s_add_i32 m0, s33, 0x2000
	s_nop 0
	global_load_lds_dwordx4 v[220:221], off
	v_lshl_add_u64 v[220:221], s[24:25], 0, v[152:153]
	s_mov_b32 m0, s40
	s_nop 0
	global_load_lds_dwordx4 v[220:221], off
	s_mov_b32 m0, s41
	s_nop 0
	global_load_lds_dwordx4 v[222:223], off
	s_waitcnt vmcnt(8)
	s_waitcnt lgkmcnt(0)
	s_barrier
; #define PG8_STAGE(bufoff, gbase, voff) do { _Pragma("unroll") for (int _i = 0; _i < 2; ++_i) \
;         __builtin_amdgcn_global_load_lds((const unsigned*)((const char*)(gbase) + (voff)[_i]), (LAS unsigned*)(lds + (bufoff) + ldsw + _i * 8192), 16, 0, 0); } while (0)
; #define PG8_LDA(dst, b, h) do { _Pragma("unroll") for (int m = 0; m < 4; ++m) _Pragma("unroll") for (int k = 0; k < 2; ++k) dst[m][k] = *(const LAS bf16x8*)(lds + PG8_SA(b, h) + aoff + m * 2048 + k * 1024); } while (0)
; #define PG8_LDB(dst, b, h) do { _Pragma("unroll") for (int n = 0; n < 2; ++n) _Pragma("unroll") for (int k = 0; k < 2; ++k) dst[n][k] = *(const LAS bf16x8*)(lds + PG8_SB(b, h) + boff + n * 2048 + k * 1024); } while (0)
; #define PG8_MMA(ai, bj, At, Bt) do { __builtin_amdgcn_s_setprio(1); _Pragma("unroll") for (int m = 0; m < 4; ++m) _Pragma("unroll") for (int n = 0; n < 2; ++n) _Pragma("unroll") for (int k = 0; k < 2; ++k) \
;         acc[ai][bj][m][n] = __builtin_amdgcn_mfma_f32_16x16x32_bf16(Bt[n][k], At[m][k], acc[ai][bj][m][n], 0, 0, 0); __builtin_amdgcn_s_setprio(0); } while (0)
; #define PG8_WAIT_V(n) asm volatile("s_waitcnt vmcnt(" #n ")" ::: "memory")
; #define PG8_WAIT_L(n) asm volatile("s_waitcnt lgkmcnt(" #n ")" ::: "memory")
; #define PG8_BAR __builtin_amdgcn_s_barrier()
; #define PG8_SCHED __builtin_amdgcn_sched_barrier(0)
; template <class Epi>
; __device__ __forceinline__ void gemm_phase(LAS unsigned char* lds, const Gemm g, int G, int c, const Epi& E) {
;     ...
;             PG8_WAIT_V(8); PG8_WAIT_L(0); PG8_BAR; PG8_MMA(1, 0, At, B0); PG8_MMA(1, 1, At, B1); PG8_BAR; PG8_SCHED;
;             PG8_LDB(B0, 1, 0); PG8_LDB(B1, 1, 1); PG8_SCHED; PG8_LDA(At, 1, 0); PG8_STAGE(PG8_SA(0, 1), a2 + hstepA, voffA);
;             PG8_WAIT_V(8); PG8_WAIT_L(0); PG8_BAR; PG8_MMA(0, 0, At, B0); PG8_MMA(0, 1, At, B1); PG8_BAR; PG8_SCHED;
	s_setprio 1
	s_waitcnt lgkmcnt(0)
	v_mfma_f32_16x16x32_bf16 v[62:65], v[106:109], v[184:187], v[62:65]
	v_mfma_f32_16x16x32_bf16 v[58:61], v[114:117], v[184:187], v[58:61]
	v_mfma_f32_16x16x32_bf16 v[42:45], v[114:117], v[192:195], v[42:45]
	v_mfma_f32_16x16x32_bf16 v[46:49], v[106:109], v[192:195], v[46:49]
	v_mfma_f32_16x16x32_bf16 v[30:33], v[106:109], v[200:203], v[30:33]
	v_mfma_f32_16x16x32_bf16 v[26:29], v[114:117], v[200:203], v[26:29]
	v_mfma_f32_16x16x32_bf16 v[10:13], v[114:117], v[208:211], v[10:13]
	v_mfma_f32_16x16x32_bf16 v[14:17], v[106:109], v[208:211], v[14:17]
	v_mfma_f32_16x16x32_bf16 v[62:65], v[110:113], v[188:191], v[62:65]
	v_mfma_f32_16x16x32_bf16 v[58:61], v[118:121], v[188:191], v[58:61]
	v_mfma_f32_16x16x32_bf16 v[42:45], v[118:121], v[196:199], v[42:45]
	v_mfma_f32_16x16x32_bf16 v[46:49], v[110:113], v[196:199], v[46:49]
	v_mfma_f32_16x16x32_bf16 v[30:33], v[110:113], v[204:207], v[30:33]
	v_mfma_f32_16x16x32_bf16 v[26:29], v[118:121], v[204:207], v[26:29]
	v_mfma_f32_16x16x32_bf16 v[10:13], v[118:121], v[212:215], v[10:13]
	v_mfma_f32_16x16x32_bf16 v[14:17], v[110:113], v[212:215], v[14:17]
	s_setprio 0
	s_setprio 1
	v_mfma_f32_16x16x32_bf16 v[54:57], v[162:165], v[184:187], v[54:57]
	v_mfma_f32_16x16x32_bf16 v[50:53], v[176:179], v[184:187], v[50:53]
	v_mfma_f32_16x16x32_bf16 v[34:37], v[176:179], v[192:195], v[34:37]
	v_mfma_f32_16x16x32_bf16 v[38:41], v[162:165], v[192:195], v[38:41]
	v_mfma_f32_16x16x32_bf16 v[22:25], v[162:165], v[200:203], v[22:25]
	v_mfma_f32_16x16x32_bf16 v[18:21], v[176:179], v[200:203], v[18:21]
	v_mfma_f32_16x16x32_bf16 v[2:5], v[176:179], v[208:211], v[2:5]
	v_mfma_f32_16x16x32_bf16 v[6:9], v[162:165], v[208:211], v[6:9]
	v_mfma_f32_16x16x32_bf16 v[54:57], v[172:175], v[188:191], v[54:57]
	v_mfma_f32_16x16x32_bf16 v[50:53], v[180:183], v[188:191], v[50:53]
	v_mfma_f32_16x16x32_bf16 v[34:37], v[180:183], v[196:199], v[34:37]
	v_mfma_f32_16x16x32_bf16 v[38:41], v[172:175], v[196:199], v[38:41]
	v_mfma_f32_16x16x32_bf16 v[22:25], v[172:175], v[204:207], v[22:25]
	v_mfma_f32_16x16x32_bf16 v[18:21], v[180:183], v[204:207], v[18:21]
	v_mfma_f32_16x16x32_bf16 v[2:5], v[180:183], v[212:215], v[2:5]
	v_mfma_f32_16x16x32_bf16 v[6:9], v[172:175], v[212:215], v[6:9]
	s_setprio 0
	s_barrier
	s_add_i32 s33, 0, 0x18000
	s_add_i32 s63, 0, 0x1c000
	v_add_u32_e32 v118, s33, v167
	v_add_u32_e32 v171, s63, v167
	ds_read_b128 v[106:109], v118
	ds_read_b128 v[110:113], v118 offset:1024
	ds_read_b128 v[114:117], v118 offset:2048
	ds_read_b128 v[118:121], v118 offset:3072
	ds_read_b128 v[162:165], v171
	ds_read_b128 v[172:175], v171 offset:1024
	ds_read_b128 v[176:179], v171 offset:2048
	ds_read_b128 v[180:183], v171 offset:3072
	s_add_u32 s18, s24, 0xb0000
	s_addc_u32 s19, s25, 0
	s_mov_b32 m0, s42
	v_lshl_add_u64 v[224:225], s[18:19], 0, v[152:153]
	ds_read_b128 v[184:187], v170 offset:32768
	ds_read_b128 v[188:191], v170 offset:33792
	ds_read_b128 v[192:195], v170 offset:34816
	ds_read_b128 v[196:199], v170 offset:35840
	ds_read_b128 v[200:203], v170 offset:36864
	ds_read_b128 v[204:207], v170 offset:37888
	ds_read_b128 v[208:211], v170 offset:38912
	ds_read_b128 v[212:215], v170 offset:39936
	global_load_lds_dwordx4 v[224:225], off
	v_lshl_add_u64 v[224:225], s[18:19], 0, v[148:149]
	s_mov_b32 m0, s43
	s_nop 0
	global_load_lds_dwordx4 v[224:225], off
	s_waitcnt vmcnt(8)
	s_waitcnt lgkmcnt(0)
	s_barrier
	s_setprio 1
	s_waitcnt lgkmcnt(0)
	v_mfma_f32_16x16x32_bf16 v[142:145], v[106:109], v[184:187], v[142:145]
	v_mfma_f32_16x16x32_bf16 v[138:141], v[114:117], v[184:187], v[138:141]
	v_mfma_f32_16x16x32_bf16 v[122:125], v[114:117], v[192:195], v[122:125]
	v_mfma_f32_16x16x32_bf16 v[126:129], v[106:109], v[192:195], v[126:129]
	v_mfma_f32_16x16x32_bf16 v[94:97], v[106:109], v[200:203], v[94:97]
	v_mfma_f32_16x16x32_bf16 v[90:93], v[114:117], v[200:203], v[90:93]
	v_mfma_f32_16x16x32_bf16 v[74:77], v[114:117], v[208:211], v[74:77]
	v_mfma_f32_16x16x32_bf16 v[78:81], v[106:109], v[208:211], v[78:81]
	v_mfma_f32_16x16x32_bf16 v[142:145], v[110:113], v[188:191], v[142:145]
	v_mfma_f32_16x16x32_bf16 v[138:141], v[118:121], v[188:191], v[138:141]
	v_mfma_f32_16x16x32_bf16 v[122:125], v[118:121], v[196:199], v[122:125]
	v_mfma_f32_16x16x32_bf16 v[126:129], v[110:113], v[196:199], v[126:129]
	v_mfma_f32_16x16x32_bf16 v[94:97], v[110:113], v[204:207], v[94:97]
	v_mfma_f32_16x16x32_bf16 v[90:93], v[118:121], v[204:207], v[90:93]
	v_mfma_f32_16x16x32_bf16 v[74:77], v[118:121], v[212:215], v[74:77]
	v_mfma_f32_16x16x32_bf16 v[78:81], v[110:113], v[212:215], v[78:81]
	s_setprio 0
	s_setprio 1
	v_mfma_f32_16x16x32_bf16 v[134:137], v[162:165], v[184:187], v[134:137]
	v_mfma_f32_16x16x32_bf16 v[130:133], v[176:179], v[184:187], v[130:133]
	v_mfma_f32_16x16x32_bf16 v[98:101], v[176:179], v[192:195], v[98:101]
	v_mfma_f32_16x16x32_bf16 v[102:105], v[162:165], v[192:195], v[102:105]
	v_mfma_f32_16x16x32_bf16 v[86:89], v[162:165], v[200:203], v[86:89]
	v_mfma_f32_16x16x32_bf16 v[82:85], v[176:179], v[200:203], v[82:85]
	v_mfma_f32_16x16x32_bf16 v[66:69], v[176:179], v[208:211], v[66:69]
	v_mfma_f32_16x16x32_bf16 v[70:73], v[162:165], v[208:211], v[70:73]
	v_mfma_f32_16x16x32_bf16 v[134:137], v[172:175], v[188:191], v[134:137]
	v_mfma_f32_16x16x32_bf16 v[130:133], v[180:183], v[188:191], v[130:133]
	v_mfma_f32_16x16x32_bf16 v[98:101], v[180:183], v[196:199], v[98:101]
	v_mfma_f32_16x16x32_bf16 v[102:105], v[172:175], v[196:199], v[102:105]
	v_mfma_f32_16x16x32_bf16 v[86:89], v[172:175], v[204:207], v[86:89]
	v_mfma_f32_16x16x32_bf16 v[82:85], v[180:183], v[204:207], v[82:85]
	v_mfma_f32_16x16x32_bf16 v[66:69], v[180:183], v[212:215], v[66:69]
	v_mfma_f32_16x16x32_bf16 v[70:73], v[172:175], v[212:215], v[70:73]
	s_setprio 0
	s_barrier
; #define PG8_STAGE(bufoff, gbase, voff) do { _Pragma("unroll") for (int _i = 0; _i < 2; ++_i) \
;         __builtin_amdgcn_global_load_lds((const unsigned*)((const char*)(gbase) + (voff)[_i]), (LAS unsigned*)(lds + (bufoff) + ldsw + _i * 8192), 16, 0, 0); } while (0)
; #define PG8_LDA(dst, b, h) do { _Pragma("unroll") for (int m = 0; m < 4; ++m) _Pragma("unroll") for (int k = 0; k < 2; ++k) dst[m][k] = *(const LAS bf16x8*)(lds + PG8_SA(b, h) + aoff + m * 2048 + k * 1024); } while (0)
; #define PG8_MMA(ai, bj, At, Bt) do { __builtin_amdgcn_s_setprio(1); _Pragma("unroll") for (int m = 0; m < 4; ++m) _Pragma("unroll") for (int n = 0; n < 2; ++n) _Pragma("unroll") for (int k = 0; k < 2; ++k) \
;         acc[ai][bj][m][n] = __builtin_amdgcn_mfma_f32_16x16x32_bf16(Bt[n][k], At[m][k], acc[ai][bj][m][n], 0, 0, 0); __builtin_amdgcn_s_setprio(0); } while (0)
; #define PG8_WAIT_V(n) asm volatile("s_waitcnt vmcnt(" #n ")" ::: "memory")
; #define PG8_WAIT_L(n) asm volatile("s_waitcnt lgkmcnt(" #n ")" ::: "memory")
; #define PG8_BAR __builtin_amdgcn_s_barrier()
; #define PG8_SCHED __builtin_amdgcn_sched_barrier(0)
; template <class Epi>
; __device__ __forceinline__ void gemm_phase(LAS unsigned char* lds, const Gemm g, int G, int c, const Epi& E) {
;     ...
;             PG8_LDA(At, 1, 1); PG8_STAGE(PG8_SB(1, 0), b3, voffB); PG8_STAGE(PG8_SB(1, 1), b3 + hstepB, voffB); PG8_STAGE(PG8_SA(1, 0), a3, voffA);
;             PG8_WAIT_V(8); PG8_WAIT_L(0); PG8_BAR; PG8_MMA(1, 0, At, B0); PG8_MMA(1, 1, At, B1); PG8_BAR; PG8_SCHED;
;         }
	s_add_i32 s18, s33, s38
	v_lshl_add_u64 v[216:217], v[216:217], 0, s[12:13]
	s_mov_b32 m0, s18
	ds_read_b128 v[184:187], v170 offset:49152
	ds_read_b128 v[188:191], v170 offset:50176
	ds_read_b128 v[192:195], v170 offset:51200
	ds_read_b128 v[196:199], v170 offset:52224
	ds_read_b128 v[200:203], v170 offset:53248
	ds_read_b128 v[204:207], v170 offset:54272
	ds_read_b128 v[208:211], v170 offset:55296
	ds_read_b128 v[212:215], v170 offset:56320
	global_load_lds_dwordx4 v[216:217], off
	s_add_i32 m0, s18, 0x2000
	s_add_u32 s18, s22, 0xb0080
	v_lshl_add_u64 v[216:217], v[218:219], 0, s[12:13]
	s_addc_u32 s19, s23, 0
	s_add_i32 s22, s63, s38
	global_load_lds_dwordx4 v[216:217], off
	v_lshl_add_u64 v[216:217], s[18:19], 0, v[150:151]
	s_mov_b32 m0, s22
	s_nop 0
	global_load_lds_dwordx4 v[216:217], off
	v_lshl_add_u64 v[216:217], s[18:19], 0, v[146:147]
	s_add_i32 m0, s22, 0x2000
	s_nop 0
	global_load_lds_dwordx4 v[216:217], off
	v_lshl_add_u64 v[216:217], v[220:221], 0, s[12:13]
	s_mov_b32 m0, s49
	s_nop 0
	global_load_lds_dwordx4 v[216:217], off
	v_lshl_add_u64 v[216:217], v[222:223], 0, s[12:13]
	s_mov_b32 m0, s50
	s_nop 0
	global_load_lds_dwordx4 v[216:217], off
	s_waitcnt vmcnt(8)
	s_waitcnt lgkmcnt(0)
	s_barrier
	s_setprio 1
	s_waitcnt lgkmcnt(0)
	v_mfma_f32_16x16x32_bf16 v[62:65], v[106:109], v[184:187], v[62:65]
	v_mfma_f32_16x16x32_bf16 v[58:61], v[114:117], v[184:187], v[58:61]
	v_mfma_f32_16x16x32_bf16 v[42:45], v[114:117], v[192:195], v[42:45]
	v_mfma_f32_16x16x32_bf16 v[46:49], v[106:109], v[192:195], v[46:49]
	v_mfma_f32_16x16x32_bf16 v[30:33], v[106:109], v[200:203], v[30:33]
	v_mfma_f32_16x16x32_bf16 v[26:29], v[114:117], v[200:203], v[26:29]
	v_mfma_f32_16x16x32_bf16 v[10:13], v[114:117], v[208:211], v[10:13]
	v_mfma_f32_16x16x32_bf16 v[14:17], v[106:109], v[208:211], v[14:17]
	v_mfma_f32_16x16x32_bf16 v[62:65], v[110:113], v[188:191], v[62:65]
	v_mfma_f32_16x16x32_bf16 v[58:61], v[118:121], v[188:191], v[58:61]
	v_mfma_f32_16x16x32_bf16 v[42:45], v[118:121], v[196:199], v[42:45]
	v_mfma_f32_16x16x32_bf16 v[46:49], v[110:113], v[196:199], v[46:49]
	v_mfma_f32_16x16x32_bf16 v[30:33], v[110:113], v[204:207], v[30:33]
	v_mfma_f32_16x16x32_bf16 v[26:29], v[118:121], v[204:207], v[26:29]
	v_mfma_f32_16x16x32_bf16 v[10:13], v[118:121], v[212:215], v[10:13]
	v_mfma_f32_16x16x32_bf16 v[14:17], v[110:113], v[212:215], v[14:17]
	s_setprio 0
	s_setprio 1
	v_mfma_f32_16x16x32_bf16 v[54:57], v[162:165], v[184:187], v[54:57]
	v_mfma_f32_16x16x32_bf16 v[50:53], v[176:179], v[184:187], v[50:53]
	v_mfma_f32_16x16x32_bf16 v[34:37], v[176:179], v[192:195], v[34:37]
	v_mfma_f32_16x16x32_bf16 v[38:41], v[162:165], v[192:195], v[38:41]
	v_mfma_f32_16x16x32_bf16 v[22:25], v[162:165], v[200:203], v[22:25]
	v_mfma_f32_16x16x32_bf16 v[18:21], v[176:179], v[200:203], v[18:21]
	v_mfma_f32_16x16x32_bf16 v[2:5], v[176:179], v[208:211], v[2:5]
	v_mfma_f32_16x16x32_bf16 v[6:9], v[162:165], v[208:211], v[6:9]
	v_mfma_f32_16x16x32_bf16 v[54:57], v[172:175], v[188:191], v[54:57]
	v_mfma_f32_16x16x32_bf16 v[50:53], v[180:183], v[188:191], v[50:53]
	v_mfma_f32_16x16x32_bf16 v[34:37], v[180:183], v[196:199], v[34:37]
	v_mfma_f32_16x16x32_bf16 v[38:41], v[172:175], v[196:199], v[38:41]
	v_mfma_f32_16x16x32_bf16 v[22:25], v[172:175], v[204:207], v[22:25]
	v_mfma_f32_16x16x32_bf16 v[18:21], v[180:183], v[204:207], v[18:21]
	v_mfma_f32_16x16x32_bf16 v[2:5], v[180:183], v[212:215], v[2:5]
	v_mfma_f32_16x16x32_bf16 v[6:9], v[172:175], v[212:215], v[6:9]
	s_setprio 0
	s_barrier
	s_add_i32 s62, s62, 2
	s_add_u32 s60, s60, 0x100
	s_addc_u32 s61, s61, 0
	s_cmp_gt_u32 s62, 41
	s_mov_b64 s[18:19], s[20:21]
	s_cbranch_scc0 .LBB0_2169
	s_and_b64 vcc, exec, s[14:15]
	s_cbranch_vccz .LBB0_2172
	s_barrier
